# speedup vs baseline: 1.1049x; 1.0292x over previous
; DEV u16 f2bf(float f) { return (u16)(pack2(f, 0.f) & 0xffffu); }
; DEV float bf2f(u16 b) { return __uint_as_float(((unsigned)b) << 16); }
; DEV size_t tixw(long row, int col, int W) { return (size_t)(row >> 8) * (256 * (size_t)W) + (size_t)(col >> 5) * 8192 + (size_t)(row & 255) * 32 + (col & 31); }
; DEV float sigmoidf_(float x) { return 1.f / (1.f + __expf(-x)); }
; DEV void phase_ln(const Params& P, const float* __restrict__ g, const float* __restrict__ bta, u16* __restrict__ xb, bool zero_kc) {
;     ...
;       const float rs = rsqrtf(q[r] * (1.f / 1024.f) + 1e-5f);
;       const int rw = rows[r];
;       float* xr = P.out + (size_t)rw * D;
; #pragma unroll
;       for (int i = 0; i < 4; ++i) {
;         float4 y;
;         y.x = v[r][i].x * rs * gv[i].x + bv[i].x;
;         y.y = v[r][i].y * rs * gv[i].y + bv[i].y;
;         y.z = v[r][i].z * rs * gv[i].z + bv[i].z;
;         y.w = v[r][i].w * rs * gv[i].w + bv[i].w;
;     ...
;     for (int ms = 0; ms < 8; ++ms) {
;       asm volatile("" ::: "memory");
; #pragma unroll
;       for (int ns = 0; ns < 4; ++ns)
; #pragma unroll
;         for (int j = 0; j < 4; ++j) {
;           int row = m0 + wm * 128 + ms * 16 + quad * 4 + j;
;           int col = n0 + wn * 64 + ns * 16 + l15;
;           size_t idx = (size_t)row * D + col;
;           float gate = sigmoidf_(acc[ms][ns][j] + bg[col]);
;           float v = P.out[idx] + psc * gate * bf2f(Pp[idx]);
;           P.out[idx] = v;
;           xbn[tixw(row, col, D)] = f2bf(v);
;         }
.LBB0_66:
	v_or_b32_e32 v0, s14, v183
	v_or_b32_e32 v134, v0, v178
	v_add_u32_e32 v136, s12, v184
	v_lshlrev_b32_e32 v172, 2, v134
	v_lshlrev_b32_e32 v168, 3, v136
	global_load_dword v138, v172, s[8:9]
	global_load_dword v139, v172, s[8:9] offset:64
	global_load_dword v214, v172, s[8:9] offset:128
	global_load_dword v215, v172, s[8:9] offset:192
	v_readlane_b32 s4, v255, 10
	v_readlane_b32 s5, v255, 11
	s_add_u32 s4, s4, 0x2000
	s_addc_u32 s5, s5, 0
	s_nop 1
	global_load_dword v160, v172, s[4:5]
	global_load_dword v161, v172, s[4:5] offset:64
	global_load_dword v162, v172, s[4:5] offset:128
	global_load_dword v163, v172, s[4:5] offset:192
	v_readlane_b32 s4, v255, 12
	v_readlane_b32 s5, v255, 13
	s_add_u32 s4, s4, 0x2000
	s_addc_u32 s5, s5, 0
	s_nop 1
	global_load_dword v164, v172, s[4:5]
	global_load_dword v165, v172, s[4:5] offset:64
	global_load_dword v166, v172, s[4:5] offset:128
	global_load_dword v167, v172, s[4:5] offset:192
	v_readlane_b32 s4, v255, 8
	s_add_i32 s4, s4, 2
	s_and_b32 s4, s4, 3
	s_lshl_b32 s4, s4, 24
	s_add_u32 s4, s4, 0x25080000
	s_add_u32 s4, s38, s4
	s_addc_u32 s5, s39, 0
	v_lshrrev_b32_e32 v137, 5, v134
	v_lshlrev_b32_e32 v137, 14, v137
	v_and_b32_e32 v173, 31, v134
	v_lshl_add_u32 v137, v173, 1, v137
	v_lshrrev_b32_e32 v173, 8, v136
	v_lshl_add_u32 v137, v173, 19, v137
	v_and_b32_e32 v173, 0xff, v136
	v_lshl_add_u32 v137, v173, 6, v137
	v_lshlrev_b32_e32 v136, 12, v136
	v_lshl_add_u32 v136, v134, 2, v136
	v_add_u32_e32 v136, 0x1000, v136
	v_mov_b32_e32 v134, v137
	v_add_u32_e32 v135, 0x4000, v134
	v_mov_b32_e32 v130, v136
	v_lshrrev_b32_e32 v132, 1, v130
	global_load_dword v140, v130, s[86:87] offset:-4096
	global_load_dword v141, v130, s[86:87]
	global_load_dword v142, v130, s[86:87] offset:-4032
	global_load_dword v143, v130, s[86:87] offset:64
	global_load_dword v144, v130, s[86:87] offset:-3968
	global_load_dword v145, v130, s[86:87] offset:128
	global_load_dword v146, v130, s[86:87] offset:-3904
	global_load_dword v147, v130, s[86:87] offset:192
	global_load_ushort v148, v132, s[96:97] offset:-2048
	global_load_ushort v149, v132, s[96:97]
	global_load_ushort v150, v132, s[96:97] offset:-2016
	global_load_ushort v151, v132, s[96:97] offset:32
	global_load_ushort v152, v132, s[96:97] offset:-1984
	global_load_ushort v153, v132, s[96:97] offset:64
	global_load_ushort v154, v132, s[96:97] offset:-1952
	global_load_ushort v155, v132, s[96:97] offset:96
	global_load_dwordx4 v[156:159], v168, s[4:5]
	s_waitcnt vmcnt(0)
	v_sub_f32_e32 v140, v140, v156
	v_mul_f32_e32 v140, v140, v157
	v_fma_f32 v140, v160, v140, v164
	v_add_f32_e32 v126, v126, v138
	v_mul_f32_e32 v126, 0xbfb8aa3b, v126
	v_exp_f32_e32 v126, v126
	v_lshlrev_b32_e32 v148, 16, v148
	v_add_f32_e32 v126, 1.0, v126
	v_div_scale_f32 v172, vcc, v126, v126, 1.0
	v_rcp_f32_e32 v173, v172
	s_nop 0
	v_fma_f32 v174, -v172, v173, 1.0
	v_fmac_f32_e32 v173, v174, v173
	v_div_scale_f32 v174, vcc, 1.0, v126, 1.0
	v_mul_f32_e32 v175, v174, v173
	v_fma_f32 v176, -v172, v175, v174
	v_fmac_f32_e32 v175, v176, v173
	v_fma_f32 v172, -v172, v175, v174
	v_div_fmas_f32 v172, v172, v173, v175
	v_div_fixup_f32 v126, v172, v126, 1.0
	v_mul_f32_e32 v126, v181, v126
	v_fmac_f32_e32 v140, v126, v148
	global_store_dword v130, v140, s[86:87] offset:-4096
	v_cvt_pk_bf16_f32 v126, v140, s0
	global_store_short v134, v126, s[88:89]
	v_sub_f32_e32 v141, v141, v158
	v_mul_f32_e32 v141, v141, v159
	v_fma_f32 v141, v160, v141, v164
	v_add_f32_e32 v127, v127, v138
	v_mul_f32_e32 v127, 0xbfb8aa3b, v127
	v_exp_f32_e32 v127, v127
	v_lshlrev_b32_e32 v149, 16, v149
	v_add_f32_e32 v127, 1.0, v127
	v_div_scale_f32 v172, vcc, v127, v127, 1.0
	v_rcp_f32_e32 v173, v172
	s_nop 0
	v_fma_f32 v174, -v172, v173, 1.0
	v_fmac_f32_e32 v173, v174, v173
	v_div_scale_f32 v174, vcc, 1.0, v127, 1.0
	v_mul_f32_e32 v175, v174, v173
	v_fma_f32 v176, -v172, v175, v174
	v_fmac_f32_e32 v175, v176, v173
	v_fma_f32 v172, -v172, v175, v174
	v_div_fmas_f32 v172, v172, v173, v175
	v_div_fixup_f32 v127, v172, v127, 1.0
	v_mul_f32_e32 v127, v181, v127
	v_fmac_f32_e32 v141, v127, v149
	global_store_dword v130, v141, s[86:87]
	v_cvt_pk_bf16_f32 v127, v141, s0
	global_store_short v134, v127, s[88:89] offset:64
	v_sub_f32_e32 v142, v142, v156
	v_mul_f32_e32 v142, v142, v157
	v_fma_f32 v142, v161, v142, v165
	v_add_f32_e32 v122, v122, v139
	v_mul_f32_e32 v122, 0xbfb8aa3b, v122
	v_exp_f32_e32 v122, v122
	v_lshlrev_b32_e32 v150, 16, v150
	v_add_f32_e32 v122, 1.0, v122
	v_div_scale_f32 v172, vcc, v122, v122, 1.0
	v_rcp_f32_e32 v173, v172
	s_nop 0
	v_fma_f32 v174, -v172, v173, 1.0
	v_fmac_f32_e32 v173, v174, v173
	v_div_scale_f32 v174, vcc, 1.0, v122, 1.0
	v_mul_f32_e32 v175, v174, v173
	v_fma_f32 v176, -v172, v175, v174
	v_fmac_f32_e32 v175, v176, v173
	v_fma_f32 v172, -v172, v175, v174
	v_div_fmas_f32 v172, v172, v173, v175
	v_div_fixup_f32 v122, v172, v122, 1.0
	v_mul_f32_e32 v122, v181, v122
	v_fmac_f32_e32 v142, v122, v150
	global_store_dword v130, v142, s[86:87] offset:-4032
	v_cvt_pk_bf16_f32 v122, v142, s0
	global_store_short v134, v122, s[88:89] offset:32
	v_sub_f32_e32 v143, v143, v158
	v_mul_f32_e32 v143, v143, v159
	v_fma_f32 v143, v161, v143, v165
	v_add_f32_e32 v123, v123, v139
	v_mul_f32_e32 v123, 0xbfb8aa3b, v123
	v_exp_f32_e32 v123, v123
	v_lshlrev_b32_e32 v151, 16, v151
	v_add_f32_e32 v123, 1.0, v123
	v_div_scale_f32 v172, vcc, v123, v123, 1.0
	v_rcp_f32_e32 v173, v172
	s_nop 0
	v_fma_f32 v174, -v172, v173, 1.0
	v_fmac_f32_e32 v173, v174, v173
	v_div_scale_f32 v174, vcc, 1.0, v123, 1.0
	v_mul_f32_e32 v175, v174, v173
	v_fma_f32 v176, -v172, v175, v174
	v_fmac_f32_e32 v175, v176, v173
	v_fma_f32 v172, -v172, v175, v174
; DEV u16 f2bf(float f) { return (u16)(pack2(f, 0.f) & 0xffffu); }
; DEV float bf2f(u16 b) { return __uint_as_float(((unsigned)b) << 16); }
; DEV size_t tixw(long row, int col, int W) { return (size_t)(row >> 8) * (256 * (size_t)W) + (size_t)(col >> 5) * 8192 + (size_t)(row & 255) * 32 + (col & 31); }
; DEV float sigmoidf_(float x) { return 1.f / (1.f + __expf(-x)); }
; DEV void phase_ln(const Params& P, const float* __restrict__ g, const float* __restrict__ bta, u16* __restrict__ xb, bool zero_kc) {
;     ...
;       const float rs = rsqrtf(q[r] * (1.f / 1024.f) + 1e-5f);
;       const int rw = rows[r];
;       float* xr = P.out + (size_t)rw * D;
; #pragma unroll
;       for (int i = 0; i < 4; ++i) {
;         float4 y;
;         y.x = v[r][i].x * rs * gv[i].x + bv[i].x;
;         y.y = v[r][i].y * rs * gv[i].y + bv[i].y;
;         y.z = v[r][i].z * rs * gv[i].z + bv[i].z;
;         y.w = v[r][i].w * rs * gv[i].w + bv[i].w;
;     ...
;       for (int ns = 0; ns < 4; ++ns)
; #pragma unroll
;         for (int j = 0; j < 4; ++j) {
;           int row = m0 + wm * 128 + ms * 16 + quad * 4 + j;
;           int col = n0 + wn * 64 + ns * 16 + l15;
;           size_t idx = (size_t)row * D + col;
;           float gate = sigmoidf_(acc[ms][ns][j] + bg[col]);
;           float v = P.out[idx] + psc * gate * bf2f(Pp[idx]);
;           P.out[idx] = v;
;           xbn[tixw(row, col, D)] = f2bf(v);
;         }
	v_div_fmas_f32 v172, v172, v173, v175
	v_div_fixup_f32 v123, v172, v123, 1.0
	v_mul_f32_e32 v123, v181, v123
	v_fmac_f32_e32 v143, v123, v151
	global_store_dword v130, v143, s[86:87] offset:64
	v_cvt_pk_bf16_f32 v123, v143, s0
	global_store_short v134, v123, s[88:89] offset:96
	v_sub_f32_e32 v144, v144, v156
	v_mul_f32_e32 v144, v144, v157
	v_fma_f32 v144, v162, v144, v166
	v_add_f32_e32 v118, v118, v214
	v_mul_f32_e32 v118, 0xbfb8aa3b, v118
	v_exp_f32_e32 v118, v118
	v_lshlrev_b32_e32 v152, 16, v152
	v_add_f32_e32 v118, 1.0, v118
	v_div_scale_f32 v172, vcc, v118, v118, 1.0
	v_rcp_f32_e32 v173, v172
	s_nop 0
	v_fma_f32 v174, -v172, v173, 1.0
	v_fmac_f32_e32 v173, v174, v173
	v_div_scale_f32 v174, vcc, 1.0, v118, 1.0
	v_mul_f32_e32 v175, v174, v173
	v_fma_f32 v176, -v172, v175, v174
	v_fmac_f32_e32 v175, v176, v173
	v_fma_f32 v172, -v172, v175, v174
	v_div_fmas_f32 v172, v172, v173, v175
	v_div_fixup_f32 v118, v172, v118, 1.0
	v_mul_f32_e32 v118, v181, v118
	v_fmac_f32_e32 v144, v118, v152
	global_store_dword v130, v144, s[86:87] offset:-3968
	v_cvt_pk_bf16_f32 v118, v144, s0
	global_store_short v135, v118, s[88:89]
	v_sub_f32_e32 v145, v145, v158
	v_mul_f32_e32 v145, v145, v159
	v_fma_f32 v145, v162, v145, v166
	v_add_f32_e32 v119, v119, v214
	v_mul_f32_e32 v119, 0xbfb8aa3b, v119
	v_exp_f32_e32 v119, v119
	v_lshlrev_b32_e32 v153, 16, v153
	v_add_f32_e32 v119, 1.0, v119
	v_div_scale_f32 v172, vcc, v119, v119, 1.0
	v_rcp_f32_e32 v173, v172
	s_nop 0
	v_fma_f32 v174, -v172, v173, 1.0
	v_fmac_f32_e32 v173, v174, v173
	v_div_scale_f32 v174, vcc, 1.0, v119, 1.0
	v_mul_f32_e32 v175, v174, v173
	v_fma_f32 v176, -v172, v175, v174
	v_fmac_f32_e32 v175, v176, v173
	v_fma_f32 v172, -v172, v175, v174
	v_div_fmas_f32 v172, v172, v173, v175
	v_div_fixup_f32 v119, v172, v119, 1.0
	v_mul_f32_e32 v119, v181, v119
	v_fmac_f32_e32 v145, v119, v153
	global_store_dword v130, v145, s[86:87] offset:128
	v_cvt_pk_bf16_f32 v119, v145, s0
	global_store_short v135, v119, s[88:89] offset:64
	v_sub_f32_e32 v146, v146, v156
	v_mul_f32_e32 v146, v146, v157
	v_fma_f32 v146, v163, v146, v167
	v_add_f32_e32 v114, v114, v215
	v_mul_f32_e32 v114, 0xbfb8aa3b, v114
	v_exp_f32_e32 v114, v114
	v_lshlrev_b32_e32 v154, 16, v154
	v_add_f32_e32 v114, 1.0, v114
	v_div_scale_f32 v172, vcc, v114, v114, 1.0
	v_rcp_f32_e32 v173, v172
	s_nop 0
	v_fma_f32 v174, -v172, v173, 1.0
	v_fmac_f32_e32 v173, v174, v173
	v_div_scale_f32 v174, vcc, 1.0, v114, 1.0
	v_mul_f32_e32 v175, v174, v173
	v_fma_f32 v176, -v172, v175, v174
	v_fmac_f32_e32 v175, v176, v173
	v_fma_f32 v172, -v172, v175, v174
	v_div_fmas_f32 v172, v172, v173, v175
	v_div_fixup_f32 v114, v172, v114, 1.0
	v_mul_f32_e32 v114, v181, v114
	v_fmac_f32_e32 v146, v114, v154
	global_store_dword v130, v146, s[86:87] offset:-3904
	v_cvt_pk_bf16_f32 v114, v146, s0
	global_store_short v135, v114, s[88:89] offset:32
	v_sub_f32_e32 v147, v147, v158
	v_mul_f32_e32 v147, v147, v159
	v_fma_f32 v147, v163, v147, v167
	v_add_f32_e32 v115, v115, v215
	v_mul_f32_e32 v115, 0xbfb8aa3b, v115
	v_exp_f32_e32 v115, v115
	v_lshlrev_b32_e32 v155, 16, v155
	v_add_f32_e32 v115, 1.0, v115
	v_div_scale_f32 v172, vcc, v115, v115, 1.0
	v_rcp_f32_e32 v173, v172
	s_nop 0
	v_fma_f32 v174, -v172, v173, 1.0
	v_fmac_f32_e32 v173, v174, v173
	v_div_scale_f32 v174, vcc, 1.0, v115, 1.0
	v_mul_f32_e32 v175, v174, v173
	v_fma_f32 v176, -v172, v175, v174
	v_fmac_f32_e32 v175, v176, v173
	v_fma_f32 v172, -v172, v175, v174
	v_div_fmas_f32 v172, v172, v173, v175
	v_div_fixup_f32 v115, v172, v115, 1.0
	v_mul_f32_e32 v115, v181, v115
	v_fmac_f32_e32 v147, v115, v155
	global_store_dword v130, v147, s[86:87] offset:192
	v_cvt_pk_bf16_f32 v115, v147, s0
	global_store_short v135, v115, s[88:89] offset:96
	v_add_u32_e32 v130, 0x2000, v136
	v_lshrrev_b32_e32 v132, 1, v130
	global_load_dword v140, v130, s[86:87] offset:-4096
	global_load_dword v141, v130, s[86:87]
	global_load_dword v142, v130, s[86:87] offset:-4032
	global_load_dword v143, v130, s[86:87] offset:64
	global_load_dword v144, v130, s[86:87] offset:-3968
	global_load_dword v145, v130, s[86:87] offset:128
	global_load_dword v146, v130, s[86:87] offset:-3904
	global_load_dword v147, v130, s[86:87] offset:192
	global_load_ushort v148, v132, s[96:97] offset:-2048
	global_load_ushort v149, v132, s[96:97]
	global_load_ushort v150, v132, s[96:97] offset:-2016
	global_load_ushort v151, v132, s[96:97] offset:32
	global_load_ushort v152, v132, s[96:97] offset:-1984
	global_load_ushort v153, v132, s[96:97] offset:64
	global_load_ushort v154, v132, s[96:97] offset:-1952
	global_load_ushort v155, v132, s[96:97] offset:96
	global_load_dwordx4 v[156:159], v168, s[4:5] offset:16
	s_waitcnt vmcnt(0)
; DEV u16 f2bf(float f) { return (u16)(pack2(f, 0.f) & 0xffffu); }
; DEV float bf2f(u16 b) { return __uint_as_float(((unsigned)b) << 16); }
; DEV size_t tixw(long row, int col, int W) { return (size_t)(row >> 8) * (256 * (size_t)W) + (size_t)(col >> 5) * 8192 + (size_t)(row & 255) * 32 + (col & 31); }
; DEV float sigmoidf_(float x) { return 1.f / (1.f + __expf(-x)); }
; DEV void phase_ln(const Params& P, const float* __restrict__ g, const float* __restrict__ bta, u16* __restrict__ xb, bool zero_kc) {
;     ...
;       const float rs = rsqrtf(q[r] * (1.f / 1024.f) + 1e-5f);
;       const int rw = rows[r];
;       float* xr = P.out + (size_t)rw * D;
; #pragma unroll
;       for (int i = 0; i < 4; ++i) {
;         float4 y;
;         y.x = v[r][i].x * rs * gv[i].x + bv[i].x;
;         y.y = v[r][i].y * rs * gv[i].y + bv[i].y;
;         y.z = v[r][i].z * rs * gv[i].z + bv[i].z;
;         y.w = v[r][i].w * rs * gv[i].w + bv[i].w;
;     ...
;       for (int ns = 0; ns < 4; ++ns)
; #pragma unroll
;         for (int j = 0; j < 4; ++j) {
;           int row = m0 + wm * 128 + ms * 16 + quad * 4 + j;
;           int col = n0 + wn * 64 + ns * 16 + l15;
;           size_t idx = (size_t)row * D + col;
;           float gate = sigmoidf_(acc[ms][ns][j] + bg[col]);
;           float v = P.out[idx] + psc * gate * bf2f(Pp[idx]);
;           P.out[idx] = v;
;           xbn[tixw(row, col, D)] = f2bf(v);
;         }
	v_sub_f32_e32 v140, v140, v156
	v_mul_f32_e32 v140, v140, v157
	v_fma_f32 v140, v160, v140, v164
	v_add_f32_e32 v128, v128, v138
	v_mul_f32_e32 v128, 0xbfb8aa3b, v128
	v_exp_f32_e32 v128, v128
	v_lshlrev_b32_e32 v148, 16, v148
	v_add_f32_e32 v128, 1.0, v128
	v_div_scale_f32 v172, vcc, v128, v128, 1.0
	v_rcp_f32_e32 v173, v172
	s_nop 0
	v_fma_f32 v174, -v172, v173, 1.0
	v_fmac_f32_e32 v173, v174, v173
	v_div_scale_f32 v174, vcc, 1.0, v128, 1.0
	v_mul_f32_e32 v175, v174, v173
	v_fma_f32 v176, -v172, v175, v174
	v_fmac_f32_e32 v175, v176, v173
	v_fma_f32 v172, -v172, v175, v174
	v_div_fmas_f32 v172, v172, v173, v175
	v_div_fixup_f32 v128, v172, v128, 1.0
	v_mul_f32_e32 v128, v181, v128
	v_fmac_f32_e32 v140, v128, v148
	global_store_dword v130, v140, s[86:87] offset:-4096
	v_cvt_pk_bf16_f32 v128, v140, s0
	global_store_short v134, v128, s[88:89] offset:128
	v_sub_f32_e32 v141, v141, v158
	v_mul_f32_e32 v141, v141, v159
	v_fma_f32 v141, v160, v141, v164
	v_add_f32_e32 v129, v129, v138
	v_mul_f32_e32 v129, 0xbfb8aa3b, v129
	v_exp_f32_e32 v129, v129
	v_lshlrev_b32_e32 v149, 16, v149
	v_add_f32_e32 v129, 1.0, v129
	v_div_scale_f32 v172, vcc, v129, v129, 1.0
	v_rcp_f32_e32 v173, v172
	s_nop 0
	v_fma_f32 v174, -v172, v173, 1.0
	v_fmac_f32_e32 v173, v174, v173
	v_div_scale_f32 v174, vcc, 1.0, v129, 1.0
	v_mul_f32_e32 v175, v174, v173
	v_fma_f32 v176, -v172, v175, v174
	v_fmac_f32_e32 v175, v176, v173
	v_fma_f32 v172, -v172, v175, v174
	v_div_fmas_f32 v172, v172, v173, v175
	v_div_fixup_f32 v129, v172, v129, 1.0
	v_mul_f32_e32 v129, v181, v129
	v_fmac_f32_e32 v141, v129, v149
	global_store_dword v130, v141, s[86:87]
	v_cvt_pk_bf16_f32 v129, v141, s0
	global_store_short v134, v129, s[88:89] offset:192
	v_sub_f32_e32 v142, v142, v156
	v_mul_f32_e32 v142, v142, v157
	v_fma_f32 v142, v161, v142, v165
	v_add_f32_e32 v124, v124, v139
	v_mul_f32_e32 v124, 0xbfb8aa3b, v124
	v_exp_f32_e32 v124, v124
	v_lshlrev_b32_e32 v150, 16, v150
	v_add_f32_e32 v124, 1.0, v124
	v_div_scale_f32 v172, vcc, v124, v124, 1.0
	v_rcp_f32_e32 v173, v172
	s_nop 0
	v_fma_f32 v174, -v172, v173, 1.0
	v_fmac_f32_e32 v173, v174, v173
	v_div_scale_f32 v174, vcc, 1.0, v124, 1.0
	v_mul_f32_e32 v175, v174, v173
	v_fma_f32 v176, -v172, v175, v174
	v_fmac_f32_e32 v175, v176, v173
	v_fma_f32 v172, -v172, v175, v174
	v_div_fmas_f32 v172, v172, v173, v175
	v_div_fixup_f32 v124, v172, v124, 1.0
	v_mul_f32_e32 v124, v181, v124
	v_fmac_f32_e32 v142, v124, v150
	global_store_dword v130, v142, s[86:87] offset:-4032
	v_cvt_pk_bf16_f32 v124, v142, s0
	global_store_short v134, v124, s[88:89] offset:160
	v_sub_f32_e32 v143, v143, v158
	v_mul_f32_e32 v143, v143, v159
	v_fma_f32 v143, v161, v143, v165
	v_add_f32_e32 v125, v125, v139
	v_mul_f32_e32 v125, 0xbfb8aa3b, v125
	v_exp_f32_e32 v125, v125
	v_lshlrev_b32_e32 v151, 16, v151
	v_add_f32_e32 v125, 1.0, v125
	v_div_scale_f32 v172, vcc, v125, v125, 1.0
	v_rcp_f32_e32 v173, v172
	s_nop 0
	v_fma_f32 v174, -v172, v173, 1.0
	v_fmac_f32_e32 v173, v174, v173
	v_div_scale_f32 v174, vcc, 1.0, v125, 1.0
	v_mul_f32_e32 v175, v174, v173
	v_fma_f32 v176, -v172, v175, v174
	v_fmac_f32_e32 v175, v176, v173
	v_fma_f32 v172, -v172, v175, v174
	v_div_fmas_f32 v172, v172, v173, v175
	v_div_fixup_f32 v125, v172, v125, 1.0
	v_mul_f32_e32 v125, v181, v125
	v_fmac_f32_e32 v143, v125, v151
	global_store_dword v130, v143, s[86:87] offset:64
	v_cvt_pk_bf16_f32 v125, v143, s0
	global_store_short v134, v125, s[88:89] offset:224
	v_sub_f32_e32 v144, v144, v156
	v_mul_f32_e32 v144, v144, v157
	v_fma_f32 v144, v162, v144, v166
	v_add_f32_e32 v120, v120, v214
	v_mul_f32_e32 v120, 0xbfb8aa3b, v120
	v_exp_f32_e32 v120, v120
	v_lshlrev_b32_e32 v152, 16, v152
	v_add_f32_e32 v120, 1.0, v120
	v_div_scale_f32 v172, vcc, v120, v120, 1.0
	v_rcp_f32_e32 v173, v172
	s_nop 0
	v_fma_f32 v174, -v172, v173, 1.0
	v_fmac_f32_e32 v173, v174, v173
	v_div_scale_f32 v174, vcc, 1.0, v120, 1.0
	v_mul_f32_e32 v175, v174, v173
	v_fma_f32 v176, -v172, v175, v174
	v_fmac_f32_e32 v175, v176, v173
	v_fma_f32 v172, -v172, v175, v174
	v_div_fmas_f32 v172, v172, v173, v175
	v_div_fixup_f32 v120, v172, v120, 1.0
	v_mul_f32_e32 v120, v181, v120
	v_fmac_f32_e32 v144, v120, v152
	global_store_dword v130, v144, s[86:87] offset:-3968
	v_cvt_pk_bf16_f32 v120, v144, s0
	global_store_short v135, v120, s[88:89] offset:128
	v_sub_f32_e32 v145, v145, v158
	v_mul_f32_e32 v145, v145, v159
	v_fma_f32 v145, v162, v145, v166
	v_add_f32_e32 v121, v121, v214
	v_mul_f32_e32 v121, 0xbfb8aa3b, v121
	v_exp_f32_e32 v121, v121
	v_lshlrev_b32_e32 v153, 16, v153
	v_add_f32_e32 v121, 1.0, v121
	v_div_scale_f32 v172, vcc, v121, v121, 1.0
	v_rcp_f32_e32 v173, v172
	s_nop 0
	v_fma_f32 v174, -v172, v173, 1.0
	v_fmac_f32_e32 v173, v174, v173
	v_div_scale_f32 v174, vcc, 1.0, v121, 1.0
	v_mul_f32_e32 v175, v174, v173
	v_fma_f32 v176, -v172, v175, v174
	v_fmac_f32_e32 v175, v176, v173
	v_fma_f32 v172, -v172, v175, v174
	v_div_fmas_f32 v172, v172, v173, v175
	v_div_fixup_f32 v121, v172, v121, 1.0
	v_mul_f32_e32 v121, v181, v121
	v_fmac_f32_e32 v145, v121, v153
	global_store_dword v130, v145, s[86:87] offset:128
	v_cvt_pk_bf16_f32 v121, v145, s0
	global_store_short v135, v121, s[88:89] offset:192
	v_sub_f32_e32 v146, v146, v156
	v_mul_f32_e32 v146, v146, v157
	v_fma_f32 v146, v163, v146, v167
	v_add_f32_e32 v116, v116, v215
	v_mul_f32_e32 v116, 0xbfb8aa3b, v116
	v_exp_f32_e32 v116, v116
	v_lshlrev_b32_e32 v154, 16, v154
	v_add_f32_e32 v116, 1.0, v116
	v_div_scale_f32 v172, vcc, v116, v116, 1.0
	v_rcp_f32_e32 v173, v172
	s_nop 0
	v_fma_f32 v174, -v172, v173, 1.0
	v_fmac_f32_e32 v173, v174, v173
	v_div_scale_f32 v174, vcc, 1.0, v116, 1.0
; DEV u16 f2bf(float f) { return (u16)(pack2(f, 0.f) & 0xffffu); }
; DEV float bf2f(u16 b) { return __uint_as_float(((unsigned)b) << 16); }
; DEV size_t tixw(long row, int col, int W) { return (size_t)(row >> 8) * (256 * (size_t)W) + (size_t)(col >> 5) * 8192 + (size_t)(row & 255) * 32 + (col & 31); }
; DEV float sigmoidf_(float x) { return 1.f / (1.f + __expf(-x)); }
; DEV void phase_ln(const Params& P, const float* __restrict__ g, const float* __restrict__ bta, u16* __restrict__ xb, bool zero_kc) {
;     ...
;       const float rs = rsqrtf(q[r] * (1.f / 1024.f) + 1e-5f);
;       const int rw = rows[r];
;       float* xr = P.out + (size_t)rw * D;
; #pragma unroll
;       for (int i = 0; i < 4; ++i) {
;         float4 y;
;         y.x = v[r][i].x * rs * gv[i].x + bv[i].x;
;         y.y = v[r][i].y * rs * gv[i].y + bv[i].y;
;         y.z = v[r][i].z * rs * gv[i].z + bv[i].z;
;         y.w = v[r][i].w * rs * gv[i].w + bv[i].w;
;     ...
;       for (int ns = 0; ns < 4; ++ns)
; #pragma unroll
;         for (int j = 0; j < 4; ++j) {
;           int row = m0 + wm * 128 + ms * 16 + quad * 4 + j;
;           int col = n0 + wn * 64 + ns * 16 + l15;
;           size_t idx = (size_t)row * D + col;
;           float gate = sigmoidf_(acc[ms][ns][j] + bg[col]);
;           float v = P.out[idx] + psc * gate * bf2f(Pp[idx]);
;           P.out[idx] = v;
;           xbn[tixw(row, col, D)] = f2bf(v);
;         }
	v_mul_f32_e32 v175, v174, v173
	v_fma_f32 v176, -v172, v175, v174
	v_fmac_f32_e32 v175, v176, v173
	v_fma_f32 v172, -v172, v175, v174
	v_div_fmas_f32 v172, v172, v173, v175
	v_div_fixup_f32 v116, v172, v116, 1.0
	v_mul_f32_e32 v116, v181, v116
	v_fmac_f32_e32 v146, v116, v154
	global_store_dword v130, v146, s[86:87] offset:-3904
	v_cvt_pk_bf16_f32 v116, v146, s0
	global_store_short v135, v116, s[88:89] offset:160
	v_sub_f32_e32 v147, v147, v158
	v_mul_f32_e32 v147, v147, v159
	v_fma_f32 v147, v163, v147, v167
	v_add_f32_e32 v117, v117, v215
	v_mul_f32_e32 v117, 0xbfb8aa3b, v117
	v_exp_f32_e32 v117, v117
	v_lshlrev_b32_e32 v155, 16, v155
	v_add_f32_e32 v117, 1.0, v117
	v_div_scale_f32 v172, vcc, v117, v117, 1.0
	v_rcp_f32_e32 v173, v172
	s_nop 0
	v_fma_f32 v174, -v172, v173, 1.0
	v_fmac_f32_e32 v173, v174, v173
	v_div_scale_f32 v174, vcc, 1.0, v117, 1.0
	v_mul_f32_e32 v175, v174, v173
	v_fma_f32 v176, -v172, v175, v174
	v_fmac_f32_e32 v175, v176, v173
	v_fma_f32 v172, -v172, v175, v174
	v_div_fmas_f32 v172, v172, v173, v175
	v_div_fixup_f32 v117, v172, v117, 1.0
	v_mul_f32_e32 v117, v181, v117
	v_fmac_f32_e32 v147, v117, v155
	global_store_dword v130, v147, s[86:87] offset:192
	v_cvt_pk_bf16_f32 v117, v147, s0
	global_store_short v135, v117, s[88:89] offset:224
	v_add_u32_e32 v130, 0x10000, v136
	v_lshrrev_b32_e32 v132, 1, v130
	global_load_dword v140, v130, s[86:87] offset:-4096
	global_load_dword v141, v130, s[86:87]
	global_load_dword v142, v130, s[86:87] offset:-4032
	global_load_dword v143, v130, s[86:87] offset:64
	global_load_dword v144, v130, s[86:87] offset:-3968
	global_load_dword v145, v130, s[86:87] offset:128
	global_load_dword v146, v130, s[86:87] offset:-3904
	global_load_dword v147, v130, s[86:87] offset:192
	global_load_ushort v148, v132, s[96:97] offset:-2048
	global_load_ushort v149, v132, s[96:97]
	global_load_ushort v150, v132, s[96:97] offset:-2016
	global_load_ushort v151, v132, s[96:97] offset:32
	global_load_ushort v152, v132, s[96:97] offset:-1984
	global_load_ushort v153, v132, s[96:97] offset:64
	global_load_ushort v154, v132, s[96:97] offset:-1952
	global_load_ushort v155, v132, s[96:97] offset:96
	global_load_dwordx4 v[156:159], v168, s[4:5] offset:128
	s_waitcnt vmcnt(0)
	v_sub_f32_e32 v140, v140, v156
	v_mul_f32_e32 v140, v140, v157
	v_fma_f32 v140, v160, v140, v164
	v_add_f32_e32 v110, v110, v138
	v_mul_f32_e32 v110, 0xbfb8aa3b, v110
	v_exp_f32_e32 v110, v110
	v_lshlrev_b32_e32 v148, 16, v148
	v_add_f32_e32 v110, 1.0, v110
	v_div_scale_f32 v172, vcc, v110, v110, 1.0
	v_rcp_f32_e32 v173, v172
	s_nop 0
	v_fma_f32 v174, -v172, v173, 1.0
	v_fmac_f32_e32 v173, v174, v173
	v_div_scale_f32 v174, vcc, 1.0, v110, 1.0
	v_mul_f32_e32 v175, v174, v173
	v_fma_f32 v176, -v172, v175, v174
	v_fmac_f32_e32 v175, v176, v173
	v_fma_f32 v172, -v172, v175, v174
	v_div_fmas_f32 v172, v172, v173, v175
	v_div_fixup_f32 v110, v172, v110, 1.0
	v_mul_f32_e32 v110, v181, v110
	v_fmac_f32_e32 v140, v110, v148
	global_store_dword v130, v140, s[86:87] offset:-4096
	v_cvt_pk_bf16_f32 v110, v140, s0
	global_store_short v134, v110, s[88:89] offset:1024
	v_sub_f32_e32 v141, v141, v158
	v_mul_f32_e32 v141, v141, v159
	v_fma_f32 v141, v160, v141, v164
	v_add_f32_e32 v111, v111, v138
	v_mul_f32_e32 v111, 0xbfb8aa3b, v111
	v_exp_f32_e32 v111, v111
	v_lshlrev_b32_e32 v149, 16, v149
	v_add_f32_e32 v111, 1.0, v111
	v_div_scale_f32 v172, vcc, v111, v111, 1.0
	v_rcp_f32_e32 v173, v172
	s_nop 0
	v_fma_f32 v174, -v172, v173, 1.0
	v_fmac_f32_e32 v173, v174, v173
	v_div_scale_f32 v174, vcc, 1.0, v111, 1.0
	v_mul_f32_e32 v175, v174, v173
	v_fma_f32 v176, -v172, v175, v174
	v_fmac_f32_e32 v175, v176, v173
	v_fma_f32 v172, -v172, v175, v174
	v_div_fmas_f32 v172, v172, v173, v175
	v_div_fixup_f32 v111, v172, v111, 1.0
	v_mul_f32_e32 v111, v181, v111
	v_fmac_f32_e32 v141, v111, v149
	global_store_dword v130, v141, s[86:87]
	v_cvt_pk_bf16_f32 v111, v141, s0
	global_store_short v134, v111, s[88:89] offset:1088
	v_sub_f32_e32 v142, v142, v156
	v_mul_f32_e32 v142, v142, v157
	v_fma_f32 v142, v161, v142, v165
	v_add_f32_e32 v106, v106, v139
	v_mul_f32_e32 v106, 0xbfb8aa3b, v106
	v_exp_f32_e32 v106, v106
	v_lshlrev_b32_e32 v150, 16, v150
	v_add_f32_e32 v106, 1.0, v106
	v_div_scale_f32 v172, vcc, v106, v106, 1.0
	v_rcp_f32_e32 v173, v172
	s_nop 0
	v_fma_f32 v174, -v172, v173, 1.0
	v_fmac_f32_e32 v173, v174, v173
	v_div_scale_f32 v174, vcc, 1.0, v106, 1.0
	v_mul_f32_e32 v175, v174, v173
	v_fma_f32 v176, -v172, v175, v174
	v_fmac_f32_e32 v175, v176, v173
	v_fma_f32 v172, -v172, v175, v174
	v_div_fmas_f32 v172, v172, v173, v175
	v_div_fixup_f32 v106, v172, v106, 1.0
	v_mul_f32_e32 v106, v181, v106
	v_fmac_f32_e32 v142, v106, v150
	global_store_dword v130, v142, s[86:87] offset:-4032
	v_cvt_pk_bf16_f32 v106, v142, s0
	global_store_short v134, v106, s[88:89] offset:1056
	v_sub_f32_e32 v143, v143, v158
	v_mul_f32_e32 v143, v143, v159
	v_fma_f32 v143, v161, v143, v165
	v_add_f32_e32 v107, v107, v139
	v_mul_f32_e32 v107, 0xbfb8aa3b, v107
	v_exp_f32_e32 v107, v107
	v_lshlrev_b32_e32 v151, 16, v151
	v_add_f32_e32 v107, 1.0, v107
	v_div_scale_f32 v172, vcc, v107, v107, 1.0
	v_rcp_f32_e32 v173, v172
	s_nop 0
	v_fma_f32 v174, -v172, v173, 1.0
	v_fmac_f32_e32 v173, v174, v173
	v_div_scale_f32 v174, vcc, 1.0, v107, 1.0
	v_mul_f32_e32 v175, v174, v173
	v_fma_f32 v176, -v172, v175, v174
	v_fmac_f32_e32 v175, v176, v173
	v_fma_f32 v172, -v172, v175, v174
	v_div_fmas_f32 v172, v172, v173, v175
	v_div_fixup_f32 v107, v172, v107, 1.0
	v_mul_f32_e32 v107, v181, v107
	v_fmac_f32_e32 v143, v107, v151
	global_store_dword v130, v143, s[86:87] offset:64
	v_cvt_pk_bf16_f32 v107, v143, s0
; DEV u16 f2bf(float f) { return (u16)(pack2(f, 0.f) & 0xffffu); }
; DEV float bf2f(u16 b) { return __uint_as_float(((unsigned)b) << 16); }
; DEV size_t tixw(long row, int col, int W) { return (size_t)(row >> 8) * (256 * (size_t)W) + (size_t)(col >> 5) * 8192 + (size_t)(row & 255) * 32 + (col & 31); }
; DEV float sigmoidf_(float x) { return 1.f / (1.f + __expf(-x)); }
; DEV void phase_ln(const Params& P, const float* __restrict__ g, const float* __restrict__ bta, u16* __restrict__ xb, bool zero_kc) {
;     ...
;       const float rs = rsqrtf(q[r] * (1.f / 1024.f) + 1e-5f);
;       const int rw = rows[r];
;       float* xr = P.out + (size_t)rw * D;
; #pragma unroll
;       for (int i = 0; i < 4; ++i) {
;         float4 y;
;         y.x = v[r][i].x * rs * gv[i].x + bv[i].x;
;         y.y = v[r][i].y * rs * gv[i].y + bv[i].y;
;         y.z = v[r][i].z * rs * gv[i].z + bv[i].z;
;         y.w = v[r][i].w * rs * gv[i].w + bv[i].w;
;     ...
;       for (int ns = 0; ns < 4; ++ns)
; #pragma unroll
;         for (int j = 0; j < 4; ++j) {
;           int row = m0 + wm * 128 + ms * 16 + quad * 4 + j;
;           int col = n0 + wn * 64 + ns * 16 + l15;
;           size_t idx = (size_t)row * D + col;
;           float gate = sigmoidf_(acc[ms][ns][j] + bg[col]);
;           float v = P.out[idx] + psc * gate * bf2f(Pp[idx]);
;           P.out[idx] = v;
;           xbn[tixw(row, col, D)] = f2bf(v);
;         }
	global_store_short v134, v107, s[88:89] offset:1120
	v_sub_f32_e32 v144, v144, v156
	v_mul_f32_e32 v144, v144, v157
	v_fma_f32 v144, v162, v144, v166
	v_add_f32_e32 v102, v102, v214
	v_mul_f32_e32 v102, 0xbfb8aa3b, v102
	v_exp_f32_e32 v102, v102
	v_lshlrev_b32_e32 v152, 16, v152
	v_add_f32_e32 v102, 1.0, v102
	v_div_scale_f32 v172, vcc, v102, v102, 1.0
	v_rcp_f32_e32 v173, v172
	s_nop 0
	v_fma_f32 v174, -v172, v173, 1.0
	v_fmac_f32_e32 v173, v174, v173
	v_div_scale_f32 v174, vcc, 1.0, v102, 1.0
	v_mul_f32_e32 v175, v174, v173
	v_fma_f32 v176, -v172, v175, v174
	v_fmac_f32_e32 v175, v176, v173
	v_fma_f32 v172, -v172, v175, v174
	v_div_fmas_f32 v172, v172, v173, v175
	v_div_fixup_f32 v102, v172, v102, 1.0
	v_mul_f32_e32 v102, v181, v102
	v_fmac_f32_e32 v144, v102, v152
	global_store_dword v130, v144, s[86:87] offset:-3968
	v_cvt_pk_bf16_f32 v102, v144, s0
	global_store_short v135, v102, s[88:89] offset:1024
	v_sub_f32_e32 v145, v145, v158
	v_mul_f32_e32 v145, v145, v159
	v_fma_f32 v145, v162, v145, v166
	v_add_f32_e32 v103, v103, v214
	v_mul_f32_e32 v103, 0xbfb8aa3b, v103
	v_exp_f32_e32 v103, v103
	v_lshlrev_b32_e32 v153, 16, v153
	v_add_f32_e32 v103, 1.0, v103
	v_div_scale_f32 v172, vcc, v103, v103, 1.0
	v_rcp_f32_e32 v173, v172
	s_nop 0
	v_fma_f32 v174, -v172, v173, 1.0
	v_fmac_f32_e32 v173, v174, v173
	v_div_scale_f32 v174, vcc, 1.0, v103, 1.0
	v_mul_f32_e32 v175, v174, v173
	v_fma_f32 v176, -v172, v175, v174
	v_fmac_f32_e32 v175, v176, v173
	v_fma_f32 v172, -v172, v175, v174
	v_div_fmas_f32 v172, v172, v173, v175
	v_div_fixup_f32 v103, v172, v103, 1.0
	v_mul_f32_e32 v103, v181, v103
	v_fmac_f32_e32 v145, v103, v153
	global_store_dword v130, v145, s[86:87] offset:128
	v_cvt_pk_bf16_f32 v103, v145, s0
	global_store_short v135, v103, s[88:89] offset:1088
	v_sub_f32_e32 v146, v146, v156
	v_mul_f32_e32 v146, v146, v157
	v_fma_f32 v146, v163, v146, v167
	v_add_f32_e32 v98, v98, v215
	v_mul_f32_e32 v98, 0xbfb8aa3b, v98
	v_exp_f32_e32 v98, v98
	v_lshlrev_b32_e32 v154, 16, v154
	v_add_f32_e32 v98, 1.0, v98
	v_div_scale_f32 v172, vcc, v98, v98, 1.0
	v_rcp_f32_e32 v173, v172
	s_nop 0
	v_fma_f32 v174, -v172, v173, 1.0
	v_fmac_f32_e32 v173, v174, v173
	v_div_scale_f32 v174, vcc, 1.0, v98, 1.0
	v_mul_f32_e32 v175, v174, v173
	v_fma_f32 v176, -v172, v175, v174
	v_fmac_f32_e32 v175, v176, v173
	v_fma_f32 v172, -v172, v175, v174
	v_div_fmas_f32 v172, v172, v173, v175
	v_div_fixup_f32 v98, v172, v98, 1.0
	v_mul_f32_e32 v98, v181, v98
	v_fmac_f32_e32 v146, v98, v154
	global_store_dword v130, v146, s[86:87] offset:-3904
	v_cvt_pk_bf16_f32 v98, v146, s0
	global_store_short v135, v98, s[88:89] offset:1056
	v_sub_f32_e32 v147, v147, v158
	v_mul_f32_e32 v147, v147, v159
	v_fma_f32 v147, v163, v147, v167
	v_add_f32_e32 v99, v99, v215
	v_mul_f32_e32 v99, 0xbfb8aa3b, v99
	v_exp_f32_e32 v99, v99
	v_lshlrev_b32_e32 v155, 16, v155
	v_add_f32_e32 v99, 1.0, v99
	v_div_scale_f32 v172, vcc, v99, v99, 1.0
	v_rcp_f32_e32 v173, v172
	s_nop 0
	v_fma_f32 v174, -v172, v173, 1.0
	v_fmac_f32_e32 v173, v174, v173
	v_div_scale_f32 v174, vcc, 1.0, v99, 1.0
	v_mul_f32_e32 v175, v174, v173
	v_fma_f32 v176, -v172, v175, v174
	v_fmac_f32_e32 v175, v176, v173
	v_fma_f32 v172, -v172, v175, v174
	v_div_fmas_f32 v172, v172, v173, v175
	v_div_fixup_f32 v99, v172, v99, 1.0
	v_mul_f32_e32 v99, v181, v99
	v_fmac_f32_e32 v147, v99, v155
	global_store_dword v130, v147, s[86:87] offset:192
	v_cvt_pk_bf16_f32 v99, v147, s0
	global_store_short v135, v99, s[88:89] offset:1120
	v_add_u32_e32 v130, 0x12000, v136
	v_lshrrev_b32_e32 v132, 1, v130
	global_load_dword v140, v130, s[86:87] offset:-4096
	global_load_dword v141, v130, s[86:87]
	global_load_dword v142, v130, s[86:87] offset:-4032
	global_load_dword v143, v130, s[86:87] offset:64
	global_load_dword v144, v130, s[86:87] offset:-3968
	global_load_dword v145, v130, s[86:87] offset:128
	global_load_dword v146, v130, s[86:87] offset:-3904
	global_load_dword v147, v130, s[86:87] offset:192
	global_load_ushort v148, v132, s[96:97] offset:-2048
	global_load_ushort v149, v132, s[96:97]
	global_load_ushort v150, v132, s[96:97] offset:-2016
	global_load_ushort v151, v132, s[96:97] offset:32
	global_load_ushort v152, v132, s[96:97] offset:-1984
	global_load_ushort v153, v132, s[96:97] offset:64
	global_load_ushort v154, v132, s[96:97] offset:-1952
	global_load_ushort v155, v132, s[96:97] offset:96
	global_load_dwordx4 v[156:159], v168, s[4:5] offset:144
	s_waitcnt vmcnt(0)
; DEV u16 f2bf(float f) { return (u16)(pack2(f, 0.f) & 0xffffu); }
; DEV float bf2f(u16 b) { return __uint_as_float(((unsigned)b) << 16); }
; DEV size_t tixw(long row, int col, int W) { return (size_t)(row >> 8) * (256 * (size_t)W) + (size_t)(col >> 5) * 8192 + (size_t)(row & 255) * 32 + (col & 31); }
; DEV float sigmoidf_(float x) { return 1.f / (1.f + __expf(-x)); }
; DEV void phase_ln(const Params& P, const float* __restrict__ g, const float* __restrict__ bta, u16* __restrict__ xb, bool zero_kc) {
;     ...
;       const float rs = rsqrtf(q[r] * (1.f / 1024.f) + 1e-5f);
;       const int rw = rows[r];
;       float* xr = P.out + (size_t)rw * D;
; #pragma unroll
;       for (int i = 0; i < 4; ++i) {
;         float4 y;
;         y.x = v[r][i].x * rs * gv[i].x + bv[i].x;
;         y.y = v[r][i].y * rs * gv[i].y + bv[i].y;
;         y.z = v[r][i].z * rs * gv[i].z + bv[i].z;
;         y.w = v[r][i].w * rs * gv[i].w + bv[i].w;
;     ...
;       for (int ns = 0; ns < 4; ++ns)
; #pragma unroll
;         for (int j = 0; j < 4; ++j) {
;           int row = m0 + wm * 128 + ms * 16 + quad * 4 + j;
;           int col = n0 + wn * 64 + ns * 16 + l15;
;           size_t idx = (size_t)row * D + col;
;           float gate = sigmoidf_(acc[ms][ns][j] + bg[col]);
;           float v = P.out[idx] + psc * gate * bf2f(Pp[idx]);
;           P.out[idx] = v;
;           xbn[tixw(row, col, D)] = f2bf(v);
;         }
	v_sub_f32_e32 v140, v140, v156
	v_mul_f32_e32 v140, v140, v157
	v_fma_f32 v140, v160, v140, v164
	v_add_f32_e32 v112, v112, v138
	v_mul_f32_e32 v112, 0xbfb8aa3b, v112
	v_exp_f32_e32 v112, v112
	v_lshlrev_b32_e32 v148, 16, v148
	v_add_f32_e32 v112, 1.0, v112
	v_div_scale_f32 v172, vcc, v112, v112, 1.0
	v_rcp_f32_e32 v173, v172
	s_nop 0
	v_fma_f32 v174, -v172, v173, 1.0
	v_fmac_f32_e32 v173, v174, v173
	v_div_scale_f32 v174, vcc, 1.0, v112, 1.0
	v_mul_f32_e32 v175, v174, v173
	v_fma_f32 v176, -v172, v175, v174
	v_fmac_f32_e32 v175, v176, v173
	v_fma_f32 v172, -v172, v175, v174
	v_div_fmas_f32 v172, v172, v173, v175
	v_div_fixup_f32 v112, v172, v112, 1.0
	v_mul_f32_e32 v112, v181, v112
	v_fmac_f32_e32 v140, v112, v148
	global_store_dword v130, v140, s[86:87] offset:-4096
	v_cvt_pk_bf16_f32 v112, v140, s0
	global_store_short v134, v112, s[88:89] offset:1152
	v_sub_f32_e32 v141, v141, v158
	v_mul_f32_e32 v141, v141, v159
	v_fma_f32 v141, v160, v141, v164
	v_add_f32_e32 v113, v113, v138
	v_mul_f32_e32 v113, 0xbfb8aa3b, v113
	v_exp_f32_e32 v113, v113
	v_lshlrev_b32_e32 v149, 16, v149
	v_add_f32_e32 v113, 1.0, v113
	v_div_scale_f32 v172, vcc, v113, v113, 1.0
	v_rcp_f32_e32 v173, v172
	s_nop 0
	v_fma_f32 v174, -v172, v173, 1.0
	v_fmac_f32_e32 v173, v174, v173
	v_div_scale_f32 v174, vcc, 1.0, v113, 1.0
	v_mul_f32_e32 v175, v174, v173
	v_fma_f32 v176, -v172, v175, v174
	v_fmac_f32_e32 v175, v176, v173
	v_fma_f32 v172, -v172, v175, v174
	v_div_fmas_f32 v172, v172, v173, v175
	v_div_fixup_f32 v113, v172, v113, 1.0
	v_mul_f32_e32 v113, v181, v113
	v_fmac_f32_e32 v141, v113, v149
	global_store_dword v130, v141, s[86:87]
	v_cvt_pk_bf16_f32 v113, v141, s0
	global_store_short v134, v113, s[88:89] offset:1216
	v_sub_f32_e32 v142, v142, v156
	v_mul_f32_e32 v142, v142, v157
	v_fma_f32 v142, v161, v142, v165
	v_add_f32_e32 v108, v108, v139
	v_mul_f32_e32 v108, 0xbfb8aa3b, v108
	v_exp_f32_e32 v108, v108
	v_lshlrev_b32_e32 v150, 16, v150
	v_add_f32_e32 v108, 1.0, v108
	v_div_scale_f32 v172, vcc, v108, v108, 1.0
	v_rcp_f32_e32 v173, v172
	s_nop 0
	v_fma_f32 v174, -v172, v173, 1.0
	v_fmac_f32_e32 v173, v174, v173
	v_div_scale_f32 v174, vcc, 1.0, v108, 1.0
	v_mul_f32_e32 v175, v174, v173
	v_fma_f32 v176, -v172, v175, v174
	v_fmac_f32_e32 v175, v176, v173
	v_fma_f32 v172, -v172, v175, v174
	v_div_fmas_f32 v172, v172, v173, v175
	v_div_fixup_f32 v108, v172, v108, 1.0
	v_mul_f32_e32 v108, v181, v108
	v_fmac_f32_e32 v142, v108, v150
	global_store_dword v130, v142, s[86:87] offset:-4032
	v_cvt_pk_bf16_f32 v108, v142, s0
	global_store_short v134, v108, s[88:89] offset:1184
	v_sub_f32_e32 v143, v143, v158
	v_mul_f32_e32 v143, v143, v159
	v_fma_f32 v143, v161, v143, v165
	v_add_f32_e32 v109, v109, v139
	v_mul_f32_e32 v109, 0xbfb8aa3b, v109
	v_exp_f32_e32 v109, v109
	v_lshlrev_b32_e32 v151, 16, v151
	v_add_f32_e32 v109, 1.0, v109
	v_div_scale_f32 v172, vcc, v109, v109, 1.0
	v_rcp_f32_e32 v173, v172
	s_nop 0
	v_fma_f32 v174, -v172, v173, 1.0
	v_fmac_f32_e32 v173, v174, v173
	v_div_scale_f32 v174, vcc, 1.0, v109, 1.0
	v_mul_f32_e32 v175, v174, v173
	v_fma_f32 v176, -v172, v175, v174
	v_fmac_f32_e32 v175, v176, v173
	v_fma_f32 v172, -v172, v175, v174
	v_div_fmas_f32 v172, v172, v173, v175
	v_div_fixup_f32 v109, v172, v109, 1.0
	v_mul_f32_e32 v109, v181, v109
	v_fmac_f32_e32 v143, v109, v151
	global_store_dword v130, v143, s[86:87] offset:64
	v_cvt_pk_bf16_f32 v109, v143, s0
	global_store_short v134, v109, s[88:89] offset:1248
	v_sub_f32_e32 v144, v144, v156
	v_mul_f32_e32 v144, v144, v157
	v_fma_f32 v144, v162, v144, v166
	v_add_f32_e32 v104, v104, v214
	v_mul_f32_e32 v104, 0xbfb8aa3b, v104
	v_exp_f32_e32 v104, v104
	v_lshlrev_b32_e32 v152, 16, v152
	v_add_f32_e32 v104, 1.0, v104
	v_div_scale_f32 v172, vcc, v104, v104, 1.0
	v_rcp_f32_e32 v173, v172
	s_nop 0
	v_fma_f32 v174, -v172, v173, 1.0
	v_fmac_f32_e32 v173, v174, v173
	v_div_scale_f32 v174, vcc, 1.0, v104, 1.0
	v_mul_f32_e32 v175, v174, v173
	v_fma_f32 v176, -v172, v175, v174
	v_fmac_f32_e32 v175, v176, v173
	v_fma_f32 v172, -v172, v175, v174
	v_div_fmas_f32 v172, v172, v173, v175
	v_div_fixup_f32 v104, v172, v104, 1.0
	v_mul_f32_e32 v104, v181, v104
	v_fmac_f32_e32 v144, v104, v152
	global_store_dword v130, v144, s[86:87] offset:-3968
	v_cvt_pk_bf16_f32 v104, v144, s0
	global_store_short v135, v104, s[88:89] offset:1152
	v_sub_f32_e32 v145, v145, v158
	v_mul_f32_e32 v145, v145, v159
	v_fma_f32 v145, v162, v145, v166
	v_add_f32_e32 v105, v105, v214
	v_mul_f32_e32 v105, 0xbfb8aa3b, v105
	v_exp_f32_e32 v105, v105
	v_lshlrev_b32_e32 v153, 16, v153
	v_add_f32_e32 v105, 1.0, v105
	v_div_scale_f32 v172, vcc, v105, v105, 1.0
	v_rcp_f32_e32 v173, v172
	s_nop 0
	v_fma_f32 v174, -v172, v173, 1.0
	v_fmac_f32_e32 v173, v174, v173
	v_div_scale_f32 v174, vcc, 1.0, v105, 1.0
	v_mul_f32_e32 v175, v174, v173
	v_fma_f32 v176, -v172, v175, v174
	v_fmac_f32_e32 v175, v176, v173
	v_fma_f32 v172, -v172, v175, v174
	v_div_fmas_f32 v172, v172, v173, v175
	v_div_fixup_f32 v105, v172, v105, 1.0
	v_mul_f32_e32 v105, v181, v105
	v_fmac_f32_e32 v145, v105, v153
	global_store_dword v130, v145, s[86:87] offset:128
	v_cvt_pk_bf16_f32 v105, v145, s0
	global_store_short v135, v105, s[88:89] offset:1216
	v_sub_f32_e32 v146, v146, v156
	v_mul_f32_e32 v146, v146, v157
	v_fma_f32 v146, v163, v146, v167
	v_add_f32_e32 v100, v100, v215
	v_mul_f32_e32 v100, 0xbfb8aa3b, v100
	v_exp_f32_e32 v100, v100
	v_lshlrev_b32_e32 v154, 16, v154
	v_add_f32_e32 v100, 1.0, v100
	v_div_scale_f32 v172, vcc, v100, v100, 1.0
	v_rcp_f32_e32 v173, v172
	s_nop 0
	v_fma_f32 v174, -v172, v173, 1.0
	v_fmac_f32_e32 v173, v174, v173
	v_div_scale_f32 v174, vcc, 1.0, v100, 1.0
; DEV u16 f2bf(float f) { return (u16)(pack2(f, 0.f) & 0xffffu); }
; DEV float bf2f(u16 b) { return __uint_as_float(((unsigned)b) << 16); }
; DEV size_t tixw(long row, int col, int W) { return (size_t)(row >> 8) * (256 * (size_t)W) + (size_t)(col >> 5) * 8192 + (size_t)(row & 255) * 32 + (col & 31); }
; DEV float sigmoidf_(float x) { return 1.f / (1.f + __expf(-x)); }
; DEV void phase_ln(const Params& P, const float* __restrict__ g, const float* __restrict__ bta, u16* __restrict__ xb, bool zero_kc) {
;     ...
;       const float rs = rsqrtf(q[r] * (1.f / 1024.f) + 1e-5f);
;       const int rw = rows[r];
;       float* xr = P.out + (size_t)rw * D;
; #pragma unroll
;       for (int i = 0; i < 4; ++i) {
;         float4 y;
;         y.x = v[r][i].x * rs * gv[i].x + bv[i].x;
;         y.y = v[r][i].y * rs * gv[i].y + bv[i].y;
;         y.z = v[r][i].z * rs * gv[i].z + bv[i].z;
;         y.w = v[r][i].w * rs * gv[i].w + bv[i].w;
;     ...
;       for (int ns = 0; ns < 4; ++ns)
; #pragma unroll
;         for (int j = 0; j < 4; ++j) {
;           int row = m0 + wm * 128 + ms * 16 + quad * 4 + j;
;           int col = n0 + wn * 64 + ns * 16 + l15;
;           size_t idx = (size_t)row * D + col;
;           float gate = sigmoidf_(acc[ms][ns][j] + bg[col]);
;           float v = P.out[idx] + psc * gate * bf2f(Pp[idx]);
;           P.out[idx] = v;
;           xbn[tixw(row, col, D)] = f2bf(v);
;         }
	v_mul_f32_e32 v175, v174, v173
	v_fma_f32 v176, -v172, v175, v174
	v_fmac_f32_e32 v175, v176, v173
	v_fma_f32 v172, -v172, v175, v174
	v_div_fmas_f32 v172, v172, v173, v175
	v_div_fixup_f32 v100, v172, v100, 1.0
	v_mul_f32_e32 v100, v181, v100
	v_fmac_f32_e32 v146, v100, v154
	global_store_dword v130, v146, s[86:87] offset:-3904
	v_cvt_pk_bf16_f32 v100, v146, s0
	global_store_short v135, v100, s[88:89] offset:1184
	v_sub_f32_e32 v147, v147, v158
	v_mul_f32_e32 v147, v147, v159
	v_fma_f32 v147, v163, v147, v167
	v_add_f32_e32 v101, v101, v215
	v_mul_f32_e32 v101, 0xbfb8aa3b, v101
	v_exp_f32_e32 v101, v101
	v_lshlrev_b32_e32 v155, 16, v155
	v_add_f32_e32 v101, 1.0, v101
	v_div_scale_f32 v172, vcc, v101, v101, 1.0
	v_rcp_f32_e32 v173, v172
	s_nop 0
	v_fma_f32 v174, -v172, v173, 1.0
	v_fmac_f32_e32 v173, v174, v173
	v_div_scale_f32 v174, vcc, 1.0, v101, 1.0
	v_mul_f32_e32 v175, v174, v173
	v_fma_f32 v176, -v172, v175, v174
	v_fmac_f32_e32 v175, v176, v173
	v_fma_f32 v172, -v172, v175, v174
	v_div_fmas_f32 v172, v172, v173, v175
	v_div_fixup_f32 v101, v172, v101, 1.0
	v_mul_f32_e32 v101, v181, v101
	v_fmac_f32_e32 v147, v101, v155
	global_store_dword v130, v147, s[86:87] offset:192
	v_cvt_pk_bf16_f32 v101, v147, s0
	global_store_short v135, v101, s[88:89] offset:1248
	v_add_u32_e32 v130, 0x20000, v136
	v_lshrrev_b32_e32 v132, 1, v130
	global_load_dword v140, v130, s[86:87] offset:-4096
	global_load_dword v141, v130, s[86:87]
	global_load_dword v142, v130, s[86:87] offset:-4032
	global_load_dword v143, v130, s[86:87] offset:64
	global_load_dword v144, v130, s[86:87] offset:-3968
	global_load_dword v145, v130, s[86:87] offset:128
	global_load_dword v146, v130, s[86:87] offset:-3904
	global_load_dword v147, v130, s[86:87] offset:192
	global_load_ushort v148, v132, s[96:97] offset:-2048
	global_load_ushort v149, v132, s[96:97]
	global_load_ushort v150, v132, s[96:97] offset:-2016
	global_load_ushort v151, v132, s[96:97] offset:32
	global_load_ushort v152, v132, s[96:97] offset:-1984
	global_load_ushort v153, v132, s[96:97] offset:64
	global_load_ushort v154, v132, s[96:97] offset:-1952
	global_load_ushort v155, v132, s[96:97] offset:96
	global_load_dwordx4 v[156:159], v168, s[4:5] offset:256
	s_waitcnt vmcnt(0)
	v_sub_f32_e32 v140, v140, v156
	v_mul_f32_e32 v140, v140, v157
	v_fma_f32 v140, v160, v140, v164
	v_add_f32_e32 v94, v94, v138
	v_mul_f32_e32 v94, 0xbfb8aa3b, v94
	v_exp_f32_e32 v94, v94
	v_lshlrev_b32_e32 v148, 16, v148
	v_add_f32_e32 v94, 1.0, v94
	v_div_scale_f32 v172, vcc, v94, v94, 1.0
	v_rcp_f32_e32 v173, v172
	s_nop 0
	v_fma_f32 v174, -v172, v173, 1.0
	v_fmac_f32_e32 v173, v174, v173
	v_div_scale_f32 v174, vcc, 1.0, v94, 1.0
	v_mul_f32_e32 v175, v174, v173
	v_fma_f32 v176, -v172, v175, v174
	v_fmac_f32_e32 v175, v176, v173
	v_fma_f32 v172, -v172, v175, v174
	v_div_fmas_f32 v172, v172, v173, v175
	v_div_fixup_f32 v94, v172, v94, 1.0
	v_mul_f32_e32 v94, v181, v94
	v_fmac_f32_e32 v140, v94, v148
	global_store_dword v130, v140, s[86:87] offset:-4096
	v_cvt_pk_bf16_f32 v94, v140, s0
	global_store_short v134, v94, s[88:89] offset:2048
	v_sub_f32_e32 v141, v141, v158
	v_mul_f32_e32 v141, v141, v159
	v_fma_f32 v141, v160, v141, v164
	v_add_f32_e32 v95, v95, v138
	v_mul_f32_e32 v95, 0xbfb8aa3b, v95
	v_exp_f32_e32 v95, v95
	v_lshlrev_b32_e32 v149, 16, v149
	v_add_f32_e32 v95, 1.0, v95
	v_div_scale_f32 v172, vcc, v95, v95, 1.0
	v_rcp_f32_e32 v173, v172
	s_nop 0
	v_fma_f32 v174, -v172, v173, 1.0
	v_fmac_f32_e32 v173, v174, v173
	v_div_scale_f32 v174, vcc, 1.0, v95, 1.0
	v_mul_f32_e32 v175, v174, v173
	v_fma_f32 v176, -v172, v175, v174
	v_fmac_f32_e32 v175, v176, v173
	v_fma_f32 v172, -v172, v175, v174
	v_div_fmas_f32 v172, v172, v173, v175
	v_div_fixup_f32 v95, v172, v95, 1.0
	v_mul_f32_e32 v95, v181, v95
	v_fmac_f32_e32 v141, v95, v149
	global_store_dword v130, v141, s[86:87]
	v_cvt_pk_bf16_f32 v95, v141, s0
	global_store_short v134, v95, s[88:89] offset:2112
	v_sub_f32_e32 v142, v142, v156
	v_mul_f32_e32 v142, v142, v157
	v_fma_f32 v142, v161, v142, v165
	v_add_f32_e32 v90, v90, v139
	v_mul_f32_e32 v90, 0xbfb8aa3b, v90
	v_exp_f32_e32 v90, v90
	v_lshlrev_b32_e32 v150, 16, v150
	v_add_f32_e32 v90, 1.0, v90
	v_div_scale_f32 v172, vcc, v90, v90, 1.0
	v_rcp_f32_e32 v173, v172
	s_nop 0
	v_fma_f32 v174, -v172, v173, 1.0
	v_fmac_f32_e32 v173, v174, v173
	v_div_scale_f32 v174, vcc, 1.0, v90, 1.0
	v_mul_f32_e32 v175, v174, v173
	v_fma_f32 v176, -v172, v175, v174
	v_fmac_f32_e32 v175, v176, v173
	v_fma_f32 v172, -v172, v175, v174
	v_div_fmas_f32 v172, v172, v173, v175
	v_div_fixup_f32 v90, v172, v90, 1.0
	v_mul_f32_e32 v90, v181, v90
	v_fmac_f32_e32 v142, v90, v150
	global_store_dword v130, v142, s[86:87] offset:-4032
	v_cvt_pk_bf16_f32 v90, v142, s0
	global_store_short v134, v90, s[88:89] offset:2080
	v_sub_f32_e32 v143, v143, v158
	v_mul_f32_e32 v143, v143, v159
	v_fma_f32 v143, v161, v143, v165
	v_add_f32_e32 v91, v91, v139
	v_mul_f32_e32 v91, 0xbfb8aa3b, v91
	v_exp_f32_e32 v91, v91
	v_lshlrev_b32_e32 v151, 16, v151
	v_add_f32_e32 v91, 1.0, v91
	v_div_scale_f32 v172, vcc, v91, v91, 1.0
	v_rcp_f32_e32 v173, v172
	s_nop 0
	v_fma_f32 v174, -v172, v173, 1.0
	v_fmac_f32_e32 v173, v174, v173
	v_div_scale_f32 v174, vcc, 1.0, v91, 1.0
	v_mul_f32_e32 v175, v174, v173
	v_fma_f32 v176, -v172, v175, v174
	v_fmac_f32_e32 v175, v176, v173
	v_fma_f32 v172, -v172, v175, v174
	v_div_fmas_f32 v172, v172, v173, v175
	v_div_fixup_f32 v91, v172, v91, 1.0
	v_mul_f32_e32 v91, v181, v91
	v_fmac_f32_e32 v143, v91, v151
	global_store_dword v130, v143, s[86:87] offset:64
	v_cvt_pk_bf16_f32 v91, v143, s0
	global_store_short v134, v91, s[88:89] offset:2144
	v_sub_f32_e32 v144, v144, v156
; DEV u16 f2bf(float f) { return (u16)(pack2(f, 0.f) & 0xffffu); }
; DEV float bf2f(u16 b) { return __uint_as_float(((unsigned)b) << 16); }
; DEV size_t tixw(long row, int col, int W) { return (size_t)(row >> 8) * (256 * (size_t)W) + (size_t)(col >> 5) * 8192 + (size_t)(row & 255) * 32 + (col & 31); }
; DEV float sigmoidf_(float x) { return 1.f / (1.f + __expf(-x)); }
; DEV void phase_ln(const Params& P, const float* __restrict__ g, const float* __restrict__ bta, u16* __restrict__ xb, bool zero_kc) {
;     ...
;       const float rs = rsqrtf(q[r] * (1.f / 1024.f) + 1e-5f);
;       const int rw = rows[r];
;       float* xr = P.out + (size_t)rw * D;
; #pragma unroll
;       for (int i = 0; i < 4; ++i) {
;         float4 y;
;         y.x = v[r][i].x * rs * gv[i].x + bv[i].x;
;         y.y = v[r][i].y * rs * gv[i].y + bv[i].y;
;         y.z = v[r][i].z * rs * gv[i].z + bv[i].z;
;         y.w = v[r][i].w * rs * gv[i].w + bv[i].w;
;     ...
;       for (int ns = 0; ns < 4; ++ns)
; #pragma unroll
;         for (int j = 0; j < 4; ++j) {
;           int row = m0 + wm * 128 + ms * 16 + quad * 4 + j;
;           int col = n0 + wn * 64 + ns * 16 + l15;
;           size_t idx = (size_t)row * D + col;
;           float gate = sigmoidf_(acc[ms][ns][j] + bg[col]);
;           float v = P.out[idx] + psc * gate * bf2f(Pp[idx]);
;           P.out[idx] = v;
;           xbn[tixw(row, col, D)] = f2bf(v);
;         }
	v_mul_f32_e32 v144, v144, v157
	v_fma_f32 v144, v162, v144, v166
	v_add_f32_e32 v86, v86, v214
	v_mul_f32_e32 v86, 0xbfb8aa3b, v86
	v_exp_f32_e32 v86, v86
	v_lshlrev_b32_e32 v152, 16, v152
	v_add_f32_e32 v86, 1.0, v86
	v_div_scale_f32 v172, vcc, v86, v86, 1.0
	v_rcp_f32_e32 v173, v172
	s_nop 0
	v_fma_f32 v174, -v172, v173, 1.0
	v_fmac_f32_e32 v173, v174, v173
	v_div_scale_f32 v174, vcc, 1.0, v86, 1.0
	v_mul_f32_e32 v175, v174, v173
	v_fma_f32 v176, -v172, v175, v174
	v_fmac_f32_e32 v175, v176, v173
	v_fma_f32 v172, -v172, v175, v174
	v_div_fmas_f32 v172, v172, v173, v175
	v_div_fixup_f32 v86, v172, v86, 1.0
	v_mul_f32_e32 v86, v181, v86
	v_fmac_f32_e32 v144, v86, v152
	global_store_dword v130, v144, s[86:87] offset:-3968
	v_cvt_pk_bf16_f32 v86, v144, s0
	global_store_short v135, v86, s[88:89] offset:2048
	v_sub_f32_e32 v145, v145, v158
	v_mul_f32_e32 v145, v145, v159
	v_fma_f32 v145, v162, v145, v166
	v_add_f32_e32 v87, v87, v214
	v_mul_f32_e32 v87, 0xbfb8aa3b, v87
	v_exp_f32_e32 v87, v87
	v_lshlrev_b32_e32 v153, 16, v153
	v_add_f32_e32 v87, 1.0, v87
	v_div_scale_f32 v172, vcc, v87, v87, 1.0
	v_rcp_f32_e32 v173, v172
	s_nop 0
	v_fma_f32 v174, -v172, v173, 1.0
	v_fmac_f32_e32 v173, v174, v173
	v_div_scale_f32 v174, vcc, 1.0, v87, 1.0
	v_mul_f32_e32 v175, v174, v173
	v_fma_f32 v176, -v172, v175, v174
	v_fmac_f32_e32 v175, v176, v173
	v_fma_f32 v172, -v172, v175, v174
	v_div_fmas_f32 v172, v172, v173, v175
	v_div_fixup_f32 v87, v172, v87, 1.0
	v_mul_f32_e32 v87, v181, v87
	v_fmac_f32_e32 v145, v87, v153
	global_store_dword v130, v145, s[86:87] offset:128
	v_cvt_pk_bf16_f32 v87, v145, s0
	global_store_short v135, v87, s[88:89] offset:2112
	v_sub_f32_e32 v146, v146, v156
	v_mul_f32_e32 v146, v146, v157
	v_fma_f32 v146, v163, v146, v167
	v_add_f32_e32 v82, v82, v215
	v_mul_f32_e32 v82, 0xbfb8aa3b, v82
	v_exp_f32_e32 v82, v82
	v_lshlrev_b32_e32 v154, 16, v154
	v_add_f32_e32 v82, 1.0, v82
	v_div_scale_f32 v172, vcc, v82, v82, 1.0
	v_rcp_f32_e32 v173, v172
	s_nop 0
	v_fma_f32 v174, -v172, v173, 1.0
	v_fmac_f32_e32 v173, v174, v173
	v_div_scale_f32 v174, vcc, 1.0, v82, 1.0
	v_mul_f32_e32 v175, v174, v173
	v_fma_f32 v176, -v172, v175, v174
	v_fmac_f32_e32 v175, v176, v173
	v_fma_f32 v172, -v172, v175, v174
	v_div_fmas_f32 v172, v172, v173, v175
	v_div_fixup_f32 v82, v172, v82, 1.0
	v_mul_f32_e32 v82, v181, v82
	v_fmac_f32_e32 v146, v82, v154
	global_store_dword v130, v146, s[86:87] offset:-3904
	v_cvt_pk_bf16_f32 v82, v146, s0
	global_store_short v135, v82, s[88:89] offset:2080
	v_sub_f32_e32 v147, v147, v158
	v_mul_f32_e32 v147, v147, v159
	v_fma_f32 v147, v163, v147, v167
	v_add_f32_e32 v83, v83, v215
	v_mul_f32_e32 v83, 0xbfb8aa3b, v83
	v_exp_f32_e32 v83, v83
	v_lshlrev_b32_e32 v155, 16, v155
	v_add_f32_e32 v83, 1.0, v83
	v_div_scale_f32 v172, vcc, v83, v83, 1.0
	v_rcp_f32_e32 v173, v172
	s_nop 0
	v_fma_f32 v174, -v172, v173, 1.0
	v_fmac_f32_e32 v173, v174, v173
	v_div_scale_f32 v174, vcc, 1.0, v83, 1.0
	v_mul_f32_e32 v175, v174, v173
	v_fma_f32 v176, -v172, v175, v174
	v_fmac_f32_e32 v175, v176, v173
	v_fma_f32 v172, -v172, v175, v174
	v_div_fmas_f32 v172, v172, v173, v175
	v_div_fixup_f32 v83, v172, v83, 1.0
	v_mul_f32_e32 v83, v181, v83
	v_fmac_f32_e32 v147, v83, v155
	global_store_dword v130, v147, s[86:87] offset:192
	v_cvt_pk_bf16_f32 v83, v147, s0
	global_store_short v135, v83, s[88:89] offset:2144
	v_add_u32_e32 v130, 0x22000, v136
	v_lshrrev_b32_e32 v132, 1, v130
	global_load_dword v140, v130, s[86:87] offset:-4096
	global_load_dword v141, v130, s[86:87]
	global_load_dword v142, v130, s[86:87] offset:-4032
	global_load_dword v143, v130, s[86:87] offset:64
	global_load_dword v144, v130, s[86:87] offset:-3968
	global_load_dword v145, v130, s[86:87] offset:128
	global_load_dword v146, v130, s[86:87] offset:-3904
	global_load_dword v147, v130, s[86:87] offset:192
	global_load_ushort v148, v132, s[96:97] offset:-2048
	global_load_ushort v149, v132, s[96:97]
	global_load_ushort v150, v132, s[96:97] offset:-2016
	global_load_ushort v151, v132, s[96:97] offset:32
	global_load_ushort v152, v132, s[96:97] offset:-1984
	global_load_ushort v153, v132, s[96:97] offset:64
	global_load_ushort v154, v132, s[96:97] offset:-1952
	global_load_ushort v155, v132, s[96:97] offset:96
	global_load_dwordx4 v[156:159], v168, s[4:5] offset:272
	s_waitcnt vmcnt(0)
; DEV u16 f2bf(float f) { return (u16)(pack2(f, 0.f) & 0xffffu); }
; DEV float bf2f(u16 b) { return __uint_as_float(((unsigned)b) << 16); }
; DEV size_t tixw(long row, int col, int W) { return (size_t)(row >> 8) * (256 * (size_t)W) + (size_t)(col >> 5) * 8192 + (size_t)(row & 255) * 32 + (col & 31); }
; DEV float sigmoidf_(float x) { return 1.f / (1.f + __expf(-x)); }
; DEV void phase_ln(const Params& P, const float* __restrict__ g, const float* __restrict__ bta, u16* __restrict__ xb, bool zero_kc) {
;     ...
;         y.x = v[r][i].x * rs * gv[i].x + bv[i].x;
;         y.y = v[r][i].y * rs * gv[i].y + bv[i].y;
;         y.z = v[r][i].z * rs * gv[i].z + bv[i].z;
;         y.w = v[r][i].w * rs * gv[i].w + bv[i].w;
;     ...
;       for (int ns = 0; ns < 4; ++ns)
; #pragma unroll
;         for (int j = 0; j < 4; ++j) {
;           int row = m0 + wm * 128 + ms * 16 + quad * 4 + j;
;           int col = n0 + wn * 64 + ns * 16 + l15;
;           size_t idx = (size_t)row * D + col;
;           float gate = sigmoidf_(acc[ms][ns][j] + bg[col]);
;           float v = P.out[idx] + psc * gate * bf2f(Pp[idx]);
;           P.out[idx] = v;
;           xbn[tixw(row, col, D)] = f2bf(v);
;         }
	v_sub_f32_e32 v140, v140, v156
	v_mul_f32_e32 v140, v140, v157
	v_fma_f32 v140, v160, v140, v164
	v_add_f32_e32 v96, v96, v138
	v_mul_f32_e32 v96, 0xbfb8aa3b, v96
	v_exp_f32_e32 v96, v96
	v_lshlrev_b32_e32 v148, 16, v148
	v_add_f32_e32 v96, 1.0, v96
	v_div_scale_f32 v172, vcc, v96, v96, 1.0
	v_rcp_f32_e32 v173, v172
	s_nop 0
	v_fma_f32 v174, -v172, v173, 1.0
	v_fmac_f32_e32 v173, v174, v173
	v_div_scale_f32 v174, vcc, 1.0, v96, 1.0
	v_mul_f32_e32 v175, v174, v173
	v_fma_f32 v176, -v172, v175, v174
	v_fmac_f32_e32 v175, v176, v173
	v_fma_f32 v172, -v172, v175, v174
	v_div_fmas_f32 v172, v172, v173, v175
	v_div_fixup_f32 v96, v172, v96, 1.0
	v_mul_f32_e32 v96, v181, v96
	v_fmac_f32_e32 v140, v96, v148
	global_store_dword v130, v140, s[86:87] offset:-4096
	v_cvt_pk_bf16_f32 v96, v140, s0
	global_store_short v134, v96, s[88:89] offset:2176
	v_sub_f32_e32 v141, v141, v158
	v_mul_f32_e32 v141, v141, v159
	v_fma_f32 v141, v160, v141, v164
	v_add_f32_e32 v97, v97, v138
	v_mul_f32_e32 v97, 0xbfb8aa3b, v97
	v_exp_f32_e32 v97, v97
	v_lshlrev_b32_e32 v149, 16, v149
	v_add_f32_e32 v97, 1.0, v97
	v_div_scale_f32 v172, vcc, v97, v97, 1.0
	v_rcp_f32_e32 v173, v172
	s_nop 0
	v_fma_f32 v174, -v172, v173, 1.0
	v_fmac_f32_e32 v173, v174, v173
	v_div_scale_f32 v174, vcc, 1.0, v97, 1.0
	v_mul_f32_e32 v175, v174, v173
	v_fma_f32 v176, -v172, v175, v174
	v_fmac_f32_e32 v175, v176, v173
	v_fma_f32 v172, -v172, v175, v174
	v_div_fmas_f32 v172, v172, v173, v175
	v_div_fixup_f32 v97, v172, v97, 1.0
	v_mul_f32_e32 v97, v181, v97
	v_fmac_f32_e32 v141, v97, v149
	global_store_dword v130, v141, s[86:87]
	v_cvt_pk_bf16_f32 v97, v141, s0
	global_store_short v134, v97, s[88:89] offset:2240
	v_sub_f32_e32 v142, v142, v156
	v_mul_f32_e32 v142, v142, v157
	v_fma_f32 v142, v161, v142, v165
	v_add_f32_e32 v92, v92, v139
	v_mul_f32_e32 v92, 0xbfb8aa3b, v92
	v_exp_f32_e32 v92, v92
	v_lshlrev_b32_e32 v150, 16, v150
	v_add_f32_e32 v92, 1.0, v92
	v_div_scale_f32 v172, vcc, v92, v92, 1.0
	v_rcp_f32_e32 v173, v172
	s_nop 0
	v_fma_f32 v174, -v172, v173, 1.0
	v_fmac_f32_e32 v173, v174, v173
	v_div_scale_f32 v174, vcc, 1.0, v92, 1.0
	v_mul_f32_e32 v175, v174, v173
	v_fma_f32 v176, -v172, v175, v174
	v_fmac_f32_e32 v175, v176, v173
	v_fma_f32 v172, -v172, v175, v174
	v_div_fmas_f32 v172, v172, v173, v175
	v_div_fixup_f32 v92, v172, v92, 1.0
	v_mul_f32_e32 v92, v181, v92
	v_fmac_f32_e32 v142, v92, v150
	global_store_dword v130, v142, s[86:87] offset:-4032
	v_cvt_pk_bf16_f32 v92, v142, s0
	global_store_short v134, v92, s[88:89] offset:2208
	v_sub_f32_e32 v143, v143, v158
	v_mul_f32_e32 v143, v143, v159
	v_fma_f32 v143, v161, v143, v165
	v_add_f32_e32 v93, v93, v139
	v_mul_f32_e32 v93, 0xbfb8aa3b, v93
	v_exp_f32_e32 v93, v93
	v_lshlrev_b32_e32 v151, 16, v151
	v_add_f32_e32 v93, 1.0, v93
	v_div_scale_f32 v172, vcc, v93, v93, 1.0
	v_rcp_f32_e32 v173, v172
	s_nop 0
	v_fma_f32 v174, -v172, v173, 1.0
	v_fmac_f32_e32 v173, v174, v173
	v_div_scale_f32 v174, vcc, 1.0, v93, 1.0
	v_mul_f32_e32 v175, v174, v173
	v_fma_f32 v176, -v172, v175, v174
	v_fmac_f32_e32 v175, v176, v173
	v_fma_f32 v172, -v172, v175, v174
	v_div_fmas_f32 v172, v172, v173, v175
	v_div_fixup_f32 v93, v172, v93, 1.0
	v_mul_f32_e32 v93, v181, v93
	v_fmac_f32_e32 v143, v93, v151
	global_store_dword v130, v143, s[86:87] offset:64
	v_cvt_pk_bf16_f32 v93, v143, s0
	global_store_short v134, v93, s[88:89] offset:2272
	v_sub_f32_e32 v144, v144, v156
	v_mul_f32_e32 v144, v144, v157
	v_fma_f32 v144, v162, v144, v166
	v_add_f32_e32 v88, v88, v214
	v_mul_f32_e32 v88, 0xbfb8aa3b, v88
	v_exp_f32_e32 v88, v88
	v_lshlrev_b32_e32 v152, 16, v152
	v_add_f32_e32 v88, 1.0, v88
	v_div_scale_f32 v172, vcc, v88, v88, 1.0
	v_rcp_f32_e32 v173, v172
	s_nop 0
	v_fma_f32 v174, -v172, v173, 1.0
	v_fmac_f32_e32 v173, v174, v173
	v_div_scale_f32 v174, vcc, 1.0, v88, 1.0
	v_mul_f32_e32 v175, v174, v173
	v_fma_f32 v176, -v172, v175, v174
	v_fmac_f32_e32 v175, v176, v173
	v_fma_f32 v172, -v172, v175, v174
	v_div_fmas_f32 v172, v172, v173, v175
	v_div_fixup_f32 v88, v172, v88, 1.0
	v_mul_f32_e32 v88, v181, v88
	v_fmac_f32_e32 v144, v88, v152
	global_store_dword v130, v144, s[86:87] offset:-3968
	v_cvt_pk_bf16_f32 v88, v144, s0
	global_store_short v135, v88, s[88:89] offset:2176
	v_sub_f32_e32 v145, v145, v158
	v_mul_f32_e32 v145, v145, v159
	v_fma_f32 v145, v162, v145, v166
	v_add_f32_e32 v89, v89, v214
	v_mul_f32_e32 v89, 0xbfb8aa3b, v89
	v_exp_f32_e32 v89, v89
	v_lshlrev_b32_e32 v153, 16, v153
	v_add_f32_e32 v89, 1.0, v89
	v_div_scale_f32 v172, vcc, v89, v89, 1.0
	v_rcp_f32_e32 v173, v172
	s_nop 0
	v_fma_f32 v174, -v172, v173, 1.0
	v_fmac_f32_e32 v173, v174, v173
	v_div_scale_f32 v174, vcc, 1.0, v89, 1.0
	v_mul_f32_e32 v175, v174, v173
	v_fma_f32 v176, -v172, v175, v174
	v_fmac_f32_e32 v175, v176, v173
	v_fma_f32 v172, -v172, v175, v174
	v_div_fmas_f32 v172, v172, v173, v175
	v_div_fixup_f32 v89, v172, v89, 1.0
	v_mul_f32_e32 v89, v181, v89
	v_fmac_f32_e32 v145, v89, v153
	global_store_dword v130, v145, s[86:87] offset:128
	v_cvt_pk_bf16_f32 v89, v145, s0
	global_store_short v135, v89, s[88:89] offset:2240
	v_sub_f32_e32 v146, v146, v156
	v_mul_f32_e32 v146, v146, v157
	v_fma_f32 v146, v163, v146, v167
	v_add_f32_e32 v84, v84, v215
	v_mul_f32_e32 v84, 0xbfb8aa3b, v84
	v_exp_f32_e32 v84, v84
	v_lshlrev_b32_e32 v154, 16, v154
	v_add_f32_e32 v84, 1.0, v84
	v_div_scale_f32 v172, vcc, v84, v84, 1.0
	v_rcp_f32_e32 v173, v172
	s_nop 0
	v_fma_f32 v174, -v172, v173, 1.0
	v_fmac_f32_e32 v173, v174, v173
	v_div_scale_f32 v174, vcc, 1.0, v84, 1.0
	v_mul_f32_e32 v175, v174, v173
	v_fma_f32 v176, -v172, v175, v174
	v_fmac_f32_e32 v175, v176, v173
	v_fma_f32 v172, -v172, v175, v174
; DEV u16 f2bf(float f) { return (u16)(pack2(f, 0.f) & 0xffffu); }
; DEV float bf2f(u16 b) { return __uint_as_float(((unsigned)b) << 16); }
; DEV size_t tixw(long row, int col, int W) { return (size_t)(row >> 8) * (256 * (size_t)W) + (size_t)(col >> 5) * 8192 + (size_t)(row & 255) * 32 + (col & 31); }
; DEV float sigmoidf_(float x) { return 1.f / (1.f + __expf(-x)); }
; DEV void phase_ln(const Params& P, const float* __restrict__ g, const float* __restrict__ bta, u16* __restrict__ xb, bool zero_kc) {
;     ...
;         y.x = v[r][i].x * rs * gv[i].x + bv[i].x;
;         y.y = v[r][i].y * rs * gv[i].y + bv[i].y;
;         y.z = v[r][i].z * rs * gv[i].z + bv[i].z;
;         y.w = v[r][i].w * rs * gv[i].w + bv[i].w;
;     ...
;       for (int ns = 0; ns < 4; ++ns)
; #pragma unroll
;         for (int j = 0; j < 4; ++j) {
;           int row = m0 + wm * 128 + ms * 16 + quad * 4 + j;
;           int col = n0 + wn * 64 + ns * 16 + l15;
;           size_t idx = (size_t)row * D + col;
;           float gate = sigmoidf_(acc[ms][ns][j] + bg[col]);
;           float v = P.out[idx] + psc * gate * bf2f(Pp[idx]);
;           P.out[idx] = v;
;           xbn[tixw(row, col, D)] = f2bf(v);
;         }
	v_div_fmas_f32 v172, v172, v173, v175
	v_div_fixup_f32 v84, v172, v84, 1.0
	v_mul_f32_e32 v84, v181, v84
	v_fmac_f32_e32 v146, v84, v154
	global_store_dword v130, v146, s[86:87] offset:-3904
	v_cvt_pk_bf16_f32 v84, v146, s0
	global_store_short v135, v84, s[88:89] offset:2208
	v_sub_f32_e32 v147, v147, v158
	v_mul_f32_e32 v147, v147, v159
	v_fma_f32 v147, v163, v147, v167
	v_add_f32_e32 v85, v85, v215
	v_mul_f32_e32 v85, 0xbfb8aa3b, v85
	v_exp_f32_e32 v85, v85
	v_lshlrev_b32_e32 v155, 16, v155
	v_add_f32_e32 v85, 1.0, v85
	v_div_scale_f32 v172, vcc, v85, v85, 1.0
	v_rcp_f32_e32 v173, v172
	s_nop 0
	v_fma_f32 v174, -v172, v173, 1.0
	v_fmac_f32_e32 v173, v174, v173
	v_div_scale_f32 v174, vcc, 1.0, v85, 1.0
	v_mul_f32_e32 v175, v174, v173
	v_fma_f32 v176, -v172, v175, v174
	v_fmac_f32_e32 v175, v176, v173
	v_fma_f32 v172, -v172, v175, v174
	v_div_fmas_f32 v172, v172, v173, v175
	v_div_fixup_f32 v85, v172, v85, 1.0
	v_mul_f32_e32 v85, v181, v85
	v_fmac_f32_e32 v147, v85, v155
	global_store_dword v130, v147, s[86:87] offset:192
	v_cvt_pk_bf16_f32 v85, v147, s0
	global_store_short v135, v85, s[88:89] offset:2272
	v_add_u32_e32 v130, 0x30000, v136
	v_lshrrev_b32_e32 v132, 1, v130
	global_load_dword v140, v130, s[86:87] offset:-4096
	global_load_dword v141, v130, s[86:87]
	global_load_dword v142, v130, s[86:87] offset:-4032
	global_load_dword v143, v130, s[86:87] offset:64
	global_load_dword v144, v130, s[86:87] offset:-3968
	global_load_dword v145, v130, s[86:87] offset:128
	global_load_dword v146, v130, s[86:87] offset:-3904
	global_load_dword v147, v130, s[86:87] offset:192
	global_load_ushort v148, v132, s[96:97] offset:-2048
	global_load_ushort v149, v132, s[96:97]
	global_load_ushort v150, v132, s[96:97] offset:-2016
	global_load_ushort v151, v132, s[96:97] offset:32
	global_load_ushort v152, v132, s[96:97] offset:-1984
	global_load_ushort v153, v132, s[96:97] offset:64
	global_load_ushort v154, v132, s[96:97] offset:-1952
	global_load_ushort v155, v132, s[96:97] offset:96
	global_load_dwordx4 v[156:159], v168, s[4:5] offset:384
	s_waitcnt vmcnt(0)
	v_sub_f32_e32 v140, v140, v156
	v_mul_f32_e32 v140, v140, v157
	v_fma_f32 v140, v160, v140, v164
	v_add_f32_e32 v78, v78, v138
	v_mul_f32_e32 v78, 0xbfb8aa3b, v78
	v_exp_f32_e32 v78, v78
	v_lshlrev_b32_e32 v148, 16, v148
	v_add_f32_e32 v78, 1.0, v78
	v_div_scale_f32 v172, vcc, v78, v78, 1.0
	v_rcp_f32_e32 v173, v172
	s_nop 0
	v_fma_f32 v174, -v172, v173, 1.0
	v_fmac_f32_e32 v173, v174, v173
	v_div_scale_f32 v174, vcc, 1.0, v78, 1.0
	v_mul_f32_e32 v175, v174, v173
	v_fma_f32 v176, -v172, v175, v174
	v_fmac_f32_e32 v175, v176, v173
	v_fma_f32 v172, -v172, v175, v174
	v_div_fmas_f32 v172, v172, v173, v175
	v_div_fixup_f32 v78, v172, v78, 1.0
	v_mul_f32_e32 v78, v181, v78
	v_fmac_f32_e32 v140, v78, v148
	global_store_dword v130, v140, s[86:87] offset:-4096
	v_cvt_pk_bf16_f32 v78, v140, s0
	global_store_short v134, v78, s[88:89] offset:3072
	v_sub_f32_e32 v141, v141, v158
	v_mul_f32_e32 v141, v141, v159
	v_fma_f32 v141, v160, v141, v164
	v_add_f32_e32 v79, v79, v138
	v_mul_f32_e32 v79, 0xbfb8aa3b, v79
	v_exp_f32_e32 v79, v79
	v_lshlrev_b32_e32 v149, 16, v149
	v_add_f32_e32 v79, 1.0, v79
	v_div_scale_f32 v172, vcc, v79, v79, 1.0
	v_rcp_f32_e32 v173, v172
	s_nop 0
	v_fma_f32 v174, -v172, v173, 1.0
	v_fmac_f32_e32 v173, v174, v173
	v_div_scale_f32 v174, vcc, 1.0, v79, 1.0
	v_mul_f32_e32 v175, v174, v173
	v_fma_f32 v176, -v172, v175, v174
	v_fmac_f32_e32 v175, v176, v173
	v_fma_f32 v172, -v172, v175, v174
	v_div_fmas_f32 v172, v172, v173, v175
	v_div_fixup_f32 v79, v172, v79, 1.0
	v_mul_f32_e32 v79, v181, v79
	v_fmac_f32_e32 v141, v79, v149
	global_store_dword v130, v141, s[86:87]
	v_cvt_pk_bf16_f32 v79, v141, s0
	global_store_short v134, v79, s[88:89] offset:3136
	v_sub_f32_e32 v142, v142, v156
	v_mul_f32_e32 v142, v142, v157
	v_fma_f32 v142, v161, v142, v165
	v_add_f32_e32 v74, v74, v139
	v_mul_f32_e32 v74, 0xbfb8aa3b, v74
	v_exp_f32_e32 v74, v74
	v_lshlrev_b32_e32 v150, 16, v150
	v_add_f32_e32 v74, 1.0, v74
	v_div_scale_f32 v172, vcc, v74, v74, 1.0
	v_rcp_f32_e32 v173, v172
	s_nop 0
	v_fma_f32 v174, -v172, v173, 1.0
	v_fmac_f32_e32 v173, v174, v173
	v_div_scale_f32 v174, vcc, 1.0, v74, 1.0
	v_mul_f32_e32 v175, v174, v173
	v_fma_f32 v176, -v172, v175, v174
	v_fmac_f32_e32 v175, v176, v173
	v_fma_f32 v172, -v172, v175, v174
	v_div_fmas_f32 v172, v172, v173, v175
	v_div_fixup_f32 v74, v172, v74, 1.0
	v_mul_f32_e32 v74, v181, v74
	v_fmac_f32_e32 v142, v74, v150
	global_store_dword v130, v142, s[86:87] offset:-4032
	v_cvt_pk_bf16_f32 v74, v142, s0
	global_store_short v134, v74, s[88:89] offset:3104
	v_sub_f32_e32 v143, v143, v158
	v_mul_f32_e32 v143, v143, v159
	v_fma_f32 v143, v161, v143, v165
	v_add_f32_e32 v75, v75, v139
	v_mul_f32_e32 v75, 0xbfb8aa3b, v75
	v_exp_f32_e32 v75, v75
	v_lshlrev_b32_e32 v151, 16, v151
	v_add_f32_e32 v75, 1.0, v75
	v_div_scale_f32 v172, vcc, v75, v75, 1.0
	v_rcp_f32_e32 v173, v172
	s_nop 0
	v_fma_f32 v174, -v172, v173, 1.0
	v_fmac_f32_e32 v173, v174, v173
	v_div_scale_f32 v174, vcc, 1.0, v75, 1.0
	v_mul_f32_e32 v175, v174, v173
	v_fma_f32 v176, -v172, v175, v174
	v_fmac_f32_e32 v175, v176, v173
	v_fma_f32 v172, -v172, v175, v174
	v_div_fmas_f32 v172, v172, v173, v175
	v_div_fixup_f32 v75, v172, v75, 1.0
	v_mul_f32_e32 v75, v181, v75
	v_fmac_f32_e32 v143, v75, v151
	global_store_dword v130, v143, s[86:87] offset:64
	v_cvt_pk_bf16_f32 v75, v143, s0
	global_store_short v134, v75, s[88:89] offset:3168
	v_sub_f32_e32 v144, v144, v156
	v_mul_f32_e32 v144, v144, v157
	v_fma_f32 v144, v162, v144, v166
	v_add_f32_e32 v70, v70, v214
	v_mul_f32_e32 v70, 0xbfb8aa3b, v70
	v_exp_f32_e32 v70, v70
; DEV u16 f2bf(float f) { return (u16)(pack2(f, 0.f) & 0xffffu); }
; DEV float bf2f(u16 b) { return __uint_as_float(((unsigned)b) << 16); }
; DEV size_t tixw(long row, int col, int W) { return (size_t)(row >> 8) * (256 * (size_t)W) + (size_t)(col >> 5) * 8192 + (size_t)(row & 255) * 32 + (col & 31); }
; DEV float sigmoidf_(float x) { return 1.f / (1.f + __expf(-x)); }
; DEV void phase_ln(const Params& P, const float* __restrict__ g, const float* __restrict__ bta, u16* __restrict__ xb, bool zero_kc) {
;     ...
;         y.x = v[r][i].x * rs * gv[i].x + bv[i].x;
;         y.y = v[r][i].y * rs * gv[i].y + bv[i].y;
;         y.z = v[r][i].z * rs * gv[i].z + bv[i].z;
;         y.w = v[r][i].w * rs * gv[i].w + bv[i].w;
;     ...
;       for (int ns = 0; ns < 4; ++ns)
; #pragma unroll
;         for (int j = 0; j < 4; ++j) {
;           int row = m0 + wm * 128 + ms * 16 + quad * 4 + j;
;           int col = n0 + wn * 64 + ns * 16 + l15;
;           size_t idx = (size_t)row * D + col;
;           float gate = sigmoidf_(acc[ms][ns][j] + bg[col]);
;           float v = P.out[idx] + psc * gate * bf2f(Pp[idx]);
;           P.out[idx] = v;
;           xbn[tixw(row, col, D)] = f2bf(v);
;         }
	v_lshlrev_b32_e32 v152, 16, v152
	v_add_f32_e32 v70, 1.0, v70
	v_div_scale_f32 v172, vcc, v70, v70, 1.0
	v_rcp_f32_e32 v173, v172
	s_nop 0
	v_fma_f32 v174, -v172, v173, 1.0
	v_fmac_f32_e32 v173, v174, v173
	v_div_scale_f32 v174, vcc, 1.0, v70, 1.0
	v_mul_f32_e32 v175, v174, v173
	v_fma_f32 v176, -v172, v175, v174
	v_fmac_f32_e32 v175, v176, v173
	v_fma_f32 v172, -v172, v175, v174
	v_div_fmas_f32 v172, v172, v173, v175
	v_div_fixup_f32 v70, v172, v70, 1.0
	v_mul_f32_e32 v70, v181, v70
	v_fmac_f32_e32 v144, v70, v152
	global_store_dword v130, v144, s[86:87] offset:-3968
	v_cvt_pk_bf16_f32 v70, v144, s0
	global_store_short v135, v70, s[88:89] offset:3072
	v_sub_f32_e32 v145, v145, v158
	v_mul_f32_e32 v145, v145, v159
	v_fma_f32 v145, v162, v145, v166
	v_add_f32_e32 v71, v71, v214
	v_mul_f32_e32 v71, 0xbfb8aa3b, v71
	v_exp_f32_e32 v71, v71
	v_lshlrev_b32_e32 v153, 16, v153
	v_add_f32_e32 v71, 1.0, v71
	v_div_scale_f32 v172, vcc, v71, v71, 1.0
	v_rcp_f32_e32 v173, v172
	s_nop 0
	v_fma_f32 v174, -v172, v173, 1.0
	v_fmac_f32_e32 v173, v174, v173
	v_div_scale_f32 v174, vcc, 1.0, v71, 1.0
	v_mul_f32_e32 v175, v174, v173
	v_fma_f32 v176, -v172, v175, v174
	v_fmac_f32_e32 v175, v176, v173
	v_fma_f32 v172, -v172, v175, v174
	v_div_fmas_f32 v172, v172, v173, v175
	v_div_fixup_f32 v71, v172, v71, 1.0
	v_mul_f32_e32 v71, v181, v71
	v_fmac_f32_e32 v145, v71, v153
	global_store_dword v130, v145, s[86:87] offset:128
	v_cvt_pk_bf16_f32 v71, v145, s0
	global_store_short v135, v71, s[88:89] offset:3136
	v_sub_f32_e32 v146, v146, v156
	v_mul_f32_e32 v146, v146, v157
	v_fma_f32 v146, v163, v146, v167
	v_add_f32_e32 v66, v66, v215
	v_mul_f32_e32 v66, 0xbfb8aa3b, v66
	v_exp_f32_e32 v66, v66
	v_lshlrev_b32_e32 v154, 16, v154
	v_add_f32_e32 v66, 1.0, v66
	v_div_scale_f32 v172, vcc, v66, v66, 1.0
	v_rcp_f32_e32 v173, v172
	s_nop 0
	v_fma_f32 v174, -v172, v173, 1.0
	v_fmac_f32_e32 v173, v174, v173
	v_div_scale_f32 v174, vcc, 1.0, v66, 1.0
	v_mul_f32_e32 v175, v174, v173
	v_fma_f32 v176, -v172, v175, v174
	v_fmac_f32_e32 v175, v176, v173
	v_fma_f32 v172, -v172, v175, v174
	v_div_fmas_f32 v172, v172, v173, v175
	v_div_fixup_f32 v66, v172, v66, 1.0
	v_mul_f32_e32 v66, v181, v66
	v_fmac_f32_e32 v146, v66, v154
	global_store_dword v130, v146, s[86:87] offset:-3904
	v_cvt_pk_bf16_f32 v66, v146, s0
	global_store_short v135, v66, s[88:89] offset:3104
	v_sub_f32_e32 v147, v147, v158
	v_mul_f32_e32 v147, v147, v159
	v_fma_f32 v147, v163, v147, v167
	v_add_f32_e32 v67, v67, v215
	v_mul_f32_e32 v67, 0xbfb8aa3b, v67
	v_exp_f32_e32 v67, v67
	v_lshlrev_b32_e32 v155, 16, v155
	v_add_f32_e32 v67, 1.0, v67
	v_div_scale_f32 v172, vcc, v67, v67, 1.0
	v_rcp_f32_e32 v173, v172
	s_nop 0
	v_fma_f32 v174, -v172, v173, 1.0
	v_fmac_f32_e32 v173, v174, v173
	v_div_scale_f32 v174, vcc, 1.0, v67, 1.0
	v_mul_f32_e32 v175, v174, v173
	v_fma_f32 v176, -v172, v175, v174
	v_fmac_f32_e32 v175, v176, v173
	v_fma_f32 v172, -v172, v175, v174
	v_div_fmas_f32 v172, v172, v173, v175
	v_div_fixup_f32 v67, v172, v67, 1.0
	v_mul_f32_e32 v67, v181, v67
	v_fmac_f32_e32 v147, v67, v155
	global_store_dword v130, v147, s[86:87] offset:192
	v_cvt_pk_bf16_f32 v67, v147, s0
	global_store_short v135, v67, s[88:89] offset:3168
	v_add_u32_e32 v130, 0x32000, v136
	v_lshrrev_b32_e32 v132, 1, v130
	global_load_dword v140, v130, s[86:87] offset:-4096
	global_load_dword v141, v130, s[86:87]
	global_load_dword v142, v130, s[86:87] offset:-4032
	global_load_dword v143, v130, s[86:87] offset:64
	global_load_dword v144, v130, s[86:87] offset:-3968
	global_load_dword v145, v130, s[86:87] offset:128
	global_load_dword v146, v130, s[86:87] offset:-3904
	global_load_dword v147, v130, s[86:87] offset:192
	global_load_ushort v148, v132, s[96:97] offset:-2048
	global_load_ushort v149, v132, s[96:97]
	global_load_ushort v150, v132, s[96:97] offset:-2016
	global_load_ushort v151, v132, s[96:97] offset:32
	global_load_ushort v152, v132, s[96:97] offset:-1984
	global_load_ushort v153, v132, s[96:97] offset:64
	global_load_ushort v154, v132, s[96:97] offset:-1952
	global_load_ushort v155, v132, s[96:97] offset:96
	global_load_dwordx4 v[156:159], v168, s[4:5] offset:400
	s_waitcnt vmcnt(0)
	v_sub_f32_e32 v140, v140, v156
	v_mul_f32_e32 v140, v140, v157
	v_fma_f32 v140, v160, v140, v164
	v_add_f32_e32 v80, v80, v138
	v_mul_f32_e32 v80, 0xbfb8aa3b, v80
	v_exp_f32_e32 v80, v80
	v_lshlrev_b32_e32 v148, 16, v148
	v_add_f32_e32 v80, 1.0, v80
	v_div_scale_f32 v172, vcc, v80, v80, 1.0
	v_rcp_f32_e32 v173, v172
	s_nop 0
	v_fma_f32 v174, -v172, v173, 1.0
	v_fmac_f32_e32 v173, v174, v173
	v_div_scale_f32 v174, vcc, 1.0, v80, 1.0
	v_mul_f32_e32 v175, v174, v173
	v_fma_f32 v176, -v172, v175, v174
	v_fmac_f32_e32 v175, v176, v173
	v_fma_f32 v172, -v172, v175, v174
	v_div_fmas_f32 v172, v172, v173, v175
	v_div_fixup_f32 v80, v172, v80, 1.0
	v_mul_f32_e32 v80, v181, v80
	v_fmac_f32_e32 v140, v80, v148
	global_store_dword v130, v140, s[86:87] offset:-4096
	v_cvt_pk_bf16_f32 v80, v140, s0
	global_store_short v134, v80, s[88:89] offset:3200
	v_sub_f32_e32 v141, v141, v158
	v_mul_f32_e32 v141, v141, v159
	v_fma_f32 v141, v160, v141, v164
	v_add_f32_e32 v81, v81, v138
	v_mul_f32_e32 v81, 0xbfb8aa3b, v81
	v_exp_f32_e32 v81, v81
	v_lshlrev_b32_e32 v149, 16, v149
	v_add_f32_e32 v81, 1.0, v81
	v_div_scale_f32 v172, vcc, v81, v81, 1.0
	v_rcp_f32_e32 v173, v172
	s_nop 0
	v_fma_f32 v174, -v172, v173, 1.0
	v_fmac_f32_e32 v173, v174, v173
	v_div_scale_f32 v174, vcc, 1.0, v81, 1.0
	v_mul_f32_e32 v175, v174, v173
	v_fma_f32 v176, -v172, v175, v174
	v_fmac_f32_e32 v175, v176, v173
	v_fma_f32 v172, -v172, v175, v174
	v_div_fmas_f32 v172, v172, v173, v175
; DEV u16 f2bf(float f) { return (u16)(pack2(f, 0.f) & 0xffffu); }
; DEV float bf2f(u16 b) { return __uint_as_float(((unsigned)b) << 16); }
; DEV size_t tixw(long row, int col, int W) { return (size_t)(row >> 8) * (256 * (size_t)W) + (size_t)(col >> 5) * 8192 + (size_t)(row & 255) * 32 + (col & 31); }
; DEV float sigmoidf_(float x) { return 1.f / (1.f + __expf(-x)); }
; DEV void phase_ln(const Params& P, const float* __restrict__ g, const float* __restrict__ bta, u16* __restrict__ xb, bool zero_kc) {
;     ...
;         y.x = v[r][i].x * rs * gv[i].x + bv[i].x;
;         y.y = v[r][i].y * rs * gv[i].y + bv[i].y;
;         y.z = v[r][i].z * rs * gv[i].z + bv[i].z;
;         y.w = v[r][i].w * rs * gv[i].w + bv[i].w;
;     ...
;       for (int ns = 0; ns < 4; ++ns)
; #pragma unroll
;         for (int j = 0; j < 4; ++j) {
;           int row = m0 + wm * 128 + ms * 16 + quad * 4 + j;
;           int col = n0 + wn * 64 + ns * 16 + l15;
;           size_t idx = (size_t)row * D + col;
;           float gate = sigmoidf_(acc[ms][ns][j] + bg[col]);
;           float v = P.out[idx] + psc * gate * bf2f(Pp[idx]);
;           P.out[idx] = v;
;           xbn[tixw(row, col, D)] = f2bf(v);
;         }
	v_div_fixup_f32 v81, v172, v81, 1.0
	v_mul_f32_e32 v81, v181, v81
	v_fmac_f32_e32 v141, v81, v149
	global_store_dword v130, v141, s[86:87]
	v_cvt_pk_bf16_f32 v81, v141, s0
	global_store_short v134, v81, s[88:89] offset:3264
	v_sub_f32_e32 v142, v142, v156
	v_mul_f32_e32 v142, v142, v157
	v_fma_f32 v142, v161, v142, v165
	v_add_f32_e32 v76, v76, v139
	v_mul_f32_e32 v76, 0xbfb8aa3b, v76
	v_exp_f32_e32 v76, v76
	v_lshlrev_b32_e32 v150, 16, v150
	v_add_f32_e32 v76, 1.0, v76
	v_div_scale_f32 v172, vcc, v76, v76, 1.0
	v_rcp_f32_e32 v173, v172
	s_nop 0
	v_fma_f32 v174, -v172, v173, 1.0
	v_fmac_f32_e32 v173, v174, v173
	v_div_scale_f32 v174, vcc, 1.0, v76, 1.0
	v_mul_f32_e32 v175, v174, v173
	v_fma_f32 v176, -v172, v175, v174
	v_fmac_f32_e32 v175, v176, v173
	v_fma_f32 v172, -v172, v175, v174
	v_div_fmas_f32 v172, v172, v173, v175
	v_div_fixup_f32 v76, v172, v76, 1.0
	v_mul_f32_e32 v76, v181, v76
	v_fmac_f32_e32 v142, v76, v150
	global_store_dword v130, v142, s[86:87] offset:-4032
	v_cvt_pk_bf16_f32 v76, v142, s0
	global_store_short v134, v76, s[88:89] offset:3232
	v_sub_f32_e32 v143, v143, v158
	v_mul_f32_e32 v143, v143, v159
	v_fma_f32 v143, v161, v143, v165
	v_add_f32_e32 v77, v77, v139
	v_mul_f32_e32 v77, 0xbfb8aa3b, v77
	v_exp_f32_e32 v77, v77
	v_lshlrev_b32_e32 v151, 16, v151
	v_add_f32_e32 v77, 1.0, v77
	v_div_scale_f32 v172, vcc, v77, v77, 1.0
	v_rcp_f32_e32 v173, v172
	s_nop 0
	v_fma_f32 v174, -v172, v173, 1.0
	v_fmac_f32_e32 v173, v174, v173
	v_div_scale_f32 v174, vcc, 1.0, v77, 1.0
	v_mul_f32_e32 v175, v174, v173
	v_fma_f32 v176, -v172, v175, v174
	v_fmac_f32_e32 v175, v176, v173
	v_fma_f32 v172, -v172, v175, v174
	v_div_fmas_f32 v172, v172, v173, v175
	v_div_fixup_f32 v77, v172, v77, 1.0
	v_mul_f32_e32 v77, v181, v77
	v_fmac_f32_e32 v143, v77, v151
	global_store_dword v130, v143, s[86:87] offset:64
	v_cvt_pk_bf16_f32 v77, v143, s0
	global_store_short v134, v77, s[88:89] offset:3296
	v_sub_f32_e32 v144, v144, v156
	v_mul_f32_e32 v144, v144, v157
	v_fma_f32 v144, v162, v144, v166
	v_add_f32_e32 v72, v72, v214
	v_mul_f32_e32 v72, 0xbfb8aa3b, v72
	v_exp_f32_e32 v72, v72
	v_lshlrev_b32_e32 v152, 16, v152
	v_add_f32_e32 v72, 1.0, v72
	v_div_scale_f32 v172, vcc, v72, v72, 1.0
	v_rcp_f32_e32 v173, v172
	s_nop 0
	v_fma_f32 v174, -v172, v173, 1.0
	v_fmac_f32_e32 v173, v174, v173
	v_div_scale_f32 v174, vcc, 1.0, v72, 1.0
	v_mul_f32_e32 v175, v174, v173
	v_fma_f32 v176, -v172, v175, v174
	v_fmac_f32_e32 v175, v176, v173
	v_fma_f32 v172, -v172, v175, v174
	v_div_fmas_f32 v172, v172, v173, v175
	v_div_fixup_f32 v72, v172, v72, 1.0
	v_mul_f32_e32 v72, v181, v72
	v_fmac_f32_e32 v144, v72, v152
	global_store_dword v130, v144, s[86:87] offset:-3968
	v_cvt_pk_bf16_f32 v72, v144, s0
	global_store_short v135, v72, s[88:89] offset:3200
	v_sub_f32_e32 v145, v145, v158
	v_mul_f32_e32 v145, v145, v159
	v_fma_f32 v145, v162, v145, v166
	v_add_f32_e32 v73, v73, v214
	v_mul_f32_e32 v73, 0xbfb8aa3b, v73
	v_exp_f32_e32 v73, v73
	v_lshlrev_b32_e32 v153, 16, v153
	v_add_f32_e32 v73, 1.0, v73
	v_div_scale_f32 v172, vcc, v73, v73, 1.0
	v_rcp_f32_e32 v173, v172
	s_nop 0
	v_fma_f32 v174, -v172, v173, 1.0
	v_fmac_f32_e32 v173, v174, v173
	v_div_scale_f32 v174, vcc, 1.0, v73, 1.0
	v_mul_f32_e32 v175, v174, v173
	v_fma_f32 v176, -v172, v175, v174
	v_fmac_f32_e32 v175, v176, v173
	v_fma_f32 v172, -v172, v175, v174
	v_div_fmas_f32 v172, v172, v173, v175
	v_div_fixup_f32 v73, v172, v73, 1.0
	v_mul_f32_e32 v73, v181, v73
	v_fmac_f32_e32 v145, v73, v153
	global_store_dword v130, v145, s[86:87] offset:128
	v_cvt_pk_bf16_f32 v73, v145, s0
	global_store_short v135, v73, s[88:89] offset:3264
	v_sub_f32_e32 v146, v146, v156
	v_mul_f32_e32 v146, v146, v157
	v_fma_f32 v146, v163, v146, v167
	v_add_f32_e32 v68, v68, v215
	v_mul_f32_e32 v68, 0xbfb8aa3b, v68
	v_exp_f32_e32 v68, v68
	v_lshlrev_b32_e32 v154, 16, v154
	v_add_f32_e32 v68, 1.0, v68
	v_div_scale_f32 v172, vcc, v68, v68, 1.0
	v_rcp_f32_e32 v173, v172
	s_nop 0
	v_fma_f32 v174, -v172, v173, 1.0
	v_fmac_f32_e32 v173, v174, v173
	v_div_scale_f32 v174, vcc, 1.0, v68, 1.0
	v_mul_f32_e32 v175, v174, v173
	v_fma_f32 v176, -v172, v175, v174
	v_fmac_f32_e32 v175, v176, v173
	v_fma_f32 v172, -v172, v175, v174
	v_div_fmas_f32 v172, v172, v173, v175
	v_div_fixup_f32 v68, v172, v68, 1.0
	v_mul_f32_e32 v68, v181, v68
	v_fmac_f32_e32 v146, v68, v154
	global_store_dword v130, v146, s[86:87] offset:-3904
	v_cvt_pk_bf16_f32 v68, v146, s0
	global_store_short v135, v68, s[88:89] offset:3232
	v_sub_f32_e32 v147, v147, v158
	v_mul_f32_e32 v147, v147, v159
	v_fma_f32 v147, v163, v147, v167
	v_add_f32_e32 v69, v69, v215
	v_mul_f32_e32 v69, 0xbfb8aa3b, v69
	v_exp_f32_e32 v69, v69
	v_lshlrev_b32_e32 v155, 16, v155
	v_add_f32_e32 v69, 1.0, v69
	v_div_scale_f32 v172, vcc, v69, v69, 1.0
	v_rcp_f32_e32 v173, v172
	s_nop 0
	v_fma_f32 v174, -v172, v173, 1.0
	v_fmac_f32_e32 v173, v174, v173
	v_div_scale_f32 v174, vcc, 1.0, v69, 1.0
	v_mul_f32_e32 v175, v174, v173
	v_fma_f32 v176, -v172, v175, v174
	v_fmac_f32_e32 v175, v176, v173
	v_fma_f32 v172, -v172, v175, v174
	v_div_fmas_f32 v172, v172, v173, v175
	v_div_fixup_f32 v69, v172, v69, 1.0
	v_mul_f32_e32 v69, v181, v69
	v_fmac_f32_e32 v147, v69, v155
	global_store_dword v130, v147, s[86:87] offset:192
	v_cvt_pk_bf16_f32 v69, v147, s0
	global_store_short v135, v69, s[88:89] offset:3296
	v_add_u32_e32 v134, 0x1000, v137
	v_add_u32_e32 v135, 0x4000, v134
	v_add_u32_e32 v130, 0x40000, v136
	v_lshrrev_b32_e32 v132, 1, v130
	global_load_dword v140, v130, s[86:87] offset:-4096
	global_load_dword v141, v130, s[86:87]
	global_load_dword v142, v130, s[86:87] offset:-4032
	global_load_dword v143, v130, s[86:87] offset:64
	global_load_dword v144, v130, s[86:87] offset:-3968
	global_load_dword v145, v130, s[86:87] offset:128
	global_load_dword v146, v130, s[86:87] offset:-3904
	global_load_dword v147, v130, s[86:87] offset:192
	global_load_ushort v148, v132, s[96:97] offset:-2048
	global_load_ushort v149, v132, s[96:97]
	global_load_ushort v150, v132, s[96:97] offset:-2016
	global_load_ushort v151, v132, s[96:97] offset:32
	global_load_ushort v152, v132, s[96:97] offset:-1984
	global_load_ushort v153, v132, s[96:97] offset:64
	global_load_ushort v154, v132, s[96:97] offset:-1952
	global_load_ushort v155, v132, s[96:97] offset:96
	global_load_dwordx4 v[156:159], v168, s[4:5] offset:512
	s_waitcnt vmcnt(0)
; DEV u16 f2bf(float f) { return (u16)(pack2(f, 0.f) & 0xffffu); }
; DEV float bf2f(u16 b) { return __uint_as_float(((unsigned)b) << 16); }
; DEV size_t tixw(long row, int col, int W) { return (size_t)(row >> 8) * (256 * (size_t)W) + (size_t)(col >> 5) * 8192 + (size_t)(row & 255) * 32 + (col & 31); }
; DEV float sigmoidf_(float x) { return 1.f / (1.f + __expf(-x)); }
; DEV void phase_ln(const Params& P, const float* __restrict__ g, const float* __restrict__ bta, u16* __restrict__ xb, bool zero_kc) {
;     ...
;         y.x = v[r][i].x * rs * gv[i].x + bv[i].x;
;         y.y = v[r][i].y * rs * gv[i].y + bv[i].y;
;         y.z = v[r][i].z * rs * gv[i].z + bv[i].z;
;         y.w = v[r][i].w * rs * gv[i].w + bv[i].w;
;     ...
;       for (int ns = 0; ns < 4; ++ns)
; #pragma unroll
;         for (int j = 0; j < 4; ++j) {
;           int row = m0 + wm * 128 + ms * 16 + quad * 4 + j;
;           int col = n0 + wn * 64 + ns * 16 + l15;
;           size_t idx = (size_t)row * D + col;
;           float gate = sigmoidf_(acc[ms][ns][j] + bg[col]);
;           float v = P.out[idx] + psc * gate * bf2f(Pp[idx]);
;           P.out[idx] = v;
;           xbn[tixw(row, col, D)] = f2bf(v);
;         }
	v_sub_f32_e32 v140, v140, v156
	v_mul_f32_e32 v140, v140, v157
	v_fma_f32 v140, v160, v140, v164
	v_add_f32_e32 v62, v62, v138
	v_mul_f32_e32 v62, 0xbfb8aa3b, v62
	v_exp_f32_e32 v62, v62
	v_lshlrev_b32_e32 v148, 16, v148
	v_add_f32_e32 v62, 1.0, v62
	v_div_scale_f32 v172, vcc, v62, v62, 1.0
	v_rcp_f32_e32 v173, v172
	s_nop 0
	v_fma_f32 v174, -v172, v173, 1.0
	v_fmac_f32_e32 v173, v174, v173
	v_div_scale_f32 v174, vcc, 1.0, v62, 1.0
	v_mul_f32_e32 v175, v174, v173
	v_fma_f32 v176, -v172, v175, v174
	v_fmac_f32_e32 v175, v176, v173
	v_fma_f32 v172, -v172, v175, v174
	v_div_fmas_f32 v172, v172, v173, v175
	v_div_fixup_f32 v62, v172, v62, 1.0
	v_mul_f32_e32 v62, v181, v62
	v_fmac_f32_e32 v140, v62, v148
	global_store_dword v130, v140, s[86:87] offset:-4096
	v_cvt_pk_bf16_f32 v62, v140, s0
	global_store_short v134, v62, s[88:89]
	v_sub_f32_e32 v141, v141, v158
	v_mul_f32_e32 v141, v141, v159
	v_fma_f32 v141, v160, v141, v164
	v_add_f32_e32 v63, v63, v138
	v_mul_f32_e32 v63, 0xbfb8aa3b, v63
	v_exp_f32_e32 v63, v63
	v_lshlrev_b32_e32 v149, 16, v149
	v_add_f32_e32 v63, 1.0, v63
	v_div_scale_f32 v172, vcc, v63, v63, 1.0
	v_rcp_f32_e32 v173, v172
	s_nop 0
	v_fma_f32 v174, -v172, v173, 1.0
	v_fmac_f32_e32 v173, v174, v173
	v_div_scale_f32 v174, vcc, 1.0, v63, 1.0
	v_mul_f32_e32 v175, v174, v173
	v_fma_f32 v176, -v172, v175, v174
	v_fmac_f32_e32 v175, v176, v173
	v_fma_f32 v172, -v172, v175, v174
	v_div_fmas_f32 v172, v172, v173, v175
	v_div_fixup_f32 v63, v172, v63, 1.0
	v_mul_f32_e32 v63, v181, v63
	v_fmac_f32_e32 v141, v63, v149
	global_store_dword v130, v141, s[86:87]
	v_cvt_pk_bf16_f32 v63, v141, s0
	global_store_short v134, v63, s[88:89] offset:64
	v_sub_f32_e32 v142, v142, v156
	v_mul_f32_e32 v142, v142, v157
	v_fma_f32 v142, v161, v142, v165
	v_add_f32_e32 v58, v58, v139
	v_mul_f32_e32 v58, 0xbfb8aa3b, v58
	v_exp_f32_e32 v58, v58
	v_lshlrev_b32_e32 v150, 16, v150
	v_add_f32_e32 v58, 1.0, v58
	v_div_scale_f32 v172, vcc, v58, v58, 1.0
	v_rcp_f32_e32 v173, v172
	s_nop 0
	v_fma_f32 v174, -v172, v173, 1.0
	v_fmac_f32_e32 v173, v174, v173
	v_div_scale_f32 v174, vcc, 1.0, v58, 1.0
	v_mul_f32_e32 v175, v174, v173
	v_fma_f32 v176, -v172, v175, v174
	v_fmac_f32_e32 v175, v176, v173
	v_fma_f32 v172, -v172, v175, v174
	v_div_fmas_f32 v172, v172, v173, v175
	v_div_fixup_f32 v58, v172, v58, 1.0
	v_mul_f32_e32 v58, v181, v58
	v_fmac_f32_e32 v142, v58, v150
	global_store_dword v130, v142, s[86:87] offset:-4032
	v_cvt_pk_bf16_f32 v58, v142, s0
	global_store_short v134, v58, s[88:89] offset:32
	v_sub_f32_e32 v143, v143, v158
	v_mul_f32_e32 v143, v143, v159
	v_fma_f32 v143, v161, v143, v165
	v_add_f32_e32 v59, v59, v139
	v_mul_f32_e32 v59, 0xbfb8aa3b, v59
	v_exp_f32_e32 v59, v59
	v_lshlrev_b32_e32 v151, 16, v151
	v_add_f32_e32 v59, 1.0, v59
	v_div_scale_f32 v172, vcc, v59, v59, 1.0
	v_rcp_f32_e32 v173, v172
	s_nop 0
	v_fma_f32 v174, -v172, v173, 1.0
	v_fmac_f32_e32 v173, v174, v173
	v_div_scale_f32 v174, vcc, 1.0, v59, 1.0
	v_mul_f32_e32 v175, v174, v173
	v_fma_f32 v176, -v172, v175, v174
	v_fmac_f32_e32 v175, v176, v173
	v_fma_f32 v172, -v172, v175, v174
	v_div_fmas_f32 v172, v172, v173, v175
	v_div_fixup_f32 v59, v172, v59, 1.0
	v_mul_f32_e32 v59, v181, v59
	v_fmac_f32_e32 v143, v59, v151
	global_store_dword v130, v143, s[86:87] offset:64
	v_cvt_pk_bf16_f32 v59, v143, s0
	global_store_short v134, v59, s[88:89] offset:96
	v_sub_f32_e32 v144, v144, v156
	v_mul_f32_e32 v144, v144, v157
	v_fma_f32 v144, v162, v144, v166
	v_add_f32_e32 v54, v54, v214
	v_mul_f32_e32 v54, 0xbfb8aa3b, v54
	v_exp_f32_e32 v54, v54
	v_lshlrev_b32_e32 v152, 16, v152
	v_add_f32_e32 v54, 1.0, v54
	v_div_scale_f32 v172, vcc, v54, v54, 1.0
	v_rcp_f32_e32 v173, v172
	s_nop 0
	v_fma_f32 v174, -v172, v173, 1.0
	v_fmac_f32_e32 v173, v174, v173
	v_div_scale_f32 v174, vcc, 1.0, v54, 1.0
	v_mul_f32_e32 v175, v174, v173
	v_fma_f32 v176, -v172, v175, v174
	v_fmac_f32_e32 v175, v176, v173
	v_fma_f32 v172, -v172, v175, v174
	v_div_fmas_f32 v172, v172, v173, v175
	v_div_fixup_f32 v54, v172, v54, 1.0
	v_mul_f32_e32 v54, v181, v54
	v_fmac_f32_e32 v144, v54, v152
	global_store_dword v130, v144, s[86:87] offset:-3968
	v_cvt_pk_bf16_f32 v54, v144, s0
	global_store_short v135, v54, s[88:89]
	v_sub_f32_e32 v145, v145, v158
	v_mul_f32_e32 v145, v145, v159
	v_fma_f32 v145, v162, v145, v166
	v_add_f32_e32 v55, v55, v214
	v_mul_f32_e32 v55, 0xbfb8aa3b, v55
	v_exp_f32_e32 v55, v55
	v_lshlrev_b32_e32 v153, 16, v153
	v_add_f32_e32 v55, 1.0, v55
	v_div_scale_f32 v172, vcc, v55, v55, 1.0
	v_rcp_f32_e32 v173, v172
	s_nop 0
	v_fma_f32 v174, -v172, v173, 1.0
	v_fmac_f32_e32 v173, v174, v173
	v_div_scale_f32 v174, vcc, 1.0, v55, 1.0
	v_mul_f32_e32 v175, v174, v173
	v_fma_f32 v176, -v172, v175, v174
	v_fmac_f32_e32 v175, v176, v173
	v_fma_f32 v172, -v172, v175, v174
	v_div_fmas_f32 v172, v172, v173, v175
	v_div_fixup_f32 v55, v172, v55, 1.0
	v_mul_f32_e32 v55, v181, v55
	v_fmac_f32_e32 v145, v55, v153
	global_store_dword v130, v145, s[86:87] offset:128
	v_cvt_pk_bf16_f32 v55, v145, s0
	global_store_short v135, v55, s[88:89] offset:64
	v_sub_f32_e32 v146, v146, v156
	v_mul_f32_e32 v146, v146, v157
	v_fma_f32 v146, v163, v146, v167
	v_add_f32_e32 v50, v50, v215
	v_mul_f32_e32 v50, 0xbfb8aa3b, v50
	v_exp_f32_e32 v50, v50
	v_lshlrev_b32_e32 v154, 16, v154
	v_add_f32_e32 v50, 1.0, v50
	v_div_scale_f32 v172, vcc, v50, v50, 1.0
	v_rcp_f32_e32 v173, v172
	s_nop 0
	v_fma_f32 v174, -v172, v173, 1.0
	v_fmac_f32_e32 v173, v174, v173
	v_div_scale_f32 v174, vcc, 1.0, v50, 1.0
	v_mul_f32_e32 v175, v174, v173
	v_fma_f32 v176, -v172, v175, v174
	v_fmac_f32_e32 v175, v176, v173
	v_fma_f32 v172, -v172, v175, v174
	v_div_fmas_f32 v172, v172, v173, v175
; DEV u16 f2bf(float f) { return (u16)(pack2(f, 0.f) & 0xffffu); }
; DEV float bf2f(u16 b) { return __uint_as_float(((unsigned)b) << 16); }
; DEV size_t tixw(long row, int col, int W) { return (size_t)(row >> 8) * (256 * (size_t)W) + (size_t)(col >> 5) * 8192 + (size_t)(row & 255) * 32 + (col & 31); }
; DEV float sigmoidf_(float x) { return 1.f / (1.f + __expf(-x)); }
; DEV void phase_ln(const Params& P, const float* __restrict__ g, const float* __restrict__ bta, u16* __restrict__ xb, bool zero_kc) {
;     ...
;         y.x = v[r][i].x * rs * gv[i].x + bv[i].x;
;         y.y = v[r][i].y * rs * gv[i].y + bv[i].y;
;         y.z = v[r][i].z * rs * gv[i].z + bv[i].z;
;         y.w = v[r][i].w * rs * gv[i].w + bv[i].w;
;     ...
;       for (int ns = 0; ns < 4; ++ns)
; #pragma unroll
;         for (int j = 0; j < 4; ++j) {
;           int row = m0 + wm * 128 + ms * 16 + quad * 4 + j;
;           int col = n0 + wn * 64 + ns * 16 + l15;
;           size_t idx = (size_t)row * D + col;
;           float gate = sigmoidf_(acc[ms][ns][j] + bg[col]);
;           float v = P.out[idx] + psc * gate * bf2f(Pp[idx]);
;           P.out[idx] = v;
;           xbn[tixw(row, col, D)] = f2bf(v);
;         }
	v_div_fixup_f32 v50, v172, v50, 1.0
	v_mul_f32_e32 v50, v181, v50
	v_fmac_f32_e32 v146, v50, v154
	global_store_dword v130, v146, s[86:87] offset:-3904
	v_cvt_pk_bf16_f32 v50, v146, s0
	global_store_short v135, v50, s[88:89] offset:32
	v_sub_f32_e32 v147, v147, v158
	v_mul_f32_e32 v147, v147, v159
	v_fma_f32 v147, v163, v147, v167
	v_add_f32_e32 v51, v51, v215
	v_mul_f32_e32 v51, 0xbfb8aa3b, v51
	v_exp_f32_e32 v51, v51
	v_lshlrev_b32_e32 v155, 16, v155
	v_add_f32_e32 v51, 1.0, v51
	v_div_scale_f32 v172, vcc, v51, v51, 1.0
	v_rcp_f32_e32 v173, v172
	s_nop 0
	v_fma_f32 v174, -v172, v173, 1.0
	v_fmac_f32_e32 v173, v174, v173
	v_div_scale_f32 v174, vcc, 1.0, v51, 1.0
	v_mul_f32_e32 v175, v174, v173
	v_fma_f32 v176, -v172, v175, v174
	v_fmac_f32_e32 v175, v176, v173
	v_fma_f32 v172, -v172, v175, v174
	v_div_fmas_f32 v172, v172, v173, v175
	v_div_fixup_f32 v51, v172, v51, 1.0
	v_mul_f32_e32 v51, v181, v51
	v_fmac_f32_e32 v147, v51, v155
	global_store_dword v130, v147, s[86:87] offset:192
	v_cvt_pk_bf16_f32 v51, v147, s0
	global_store_short v135, v51, s[88:89] offset:96
	v_add_u32_e32 v130, 0x42000, v136
	v_lshrrev_b32_e32 v132, 1, v130
	global_load_dword v140, v130, s[86:87] offset:-4096
	global_load_dword v141, v130, s[86:87]
	global_load_dword v142, v130, s[86:87] offset:-4032
	global_load_dword v143, v130, s[86:87] offset:64
	global_load_dword v144, v130, s[86:87] offset:-3968
	global_load_dword v145, v130, s[86:87] offset:128
	global_load_dword v146, v130, s[86:87] offset:-3904
	global_load_dword v147, v130, s[86:87] offset:192
	global_load_ushort v148, v132, s[96:97] offset:-2048
	global_load_ushort v149, v132, s[96:97]
	global_load_ushort v150, v132, s[96:97] offset:-2016
	global_load_ushort v151, v132, s[96:97] offset:32
	global_load_ushort v152, v132, s[96:97] offset:-1984
	global_load_ushort v153, v132, s[96:97] offset:64
	global_load_ushort v154, v132, s[96:97] offset:-1952
	global_load_ushort v155, v132, s[96:97] offset:96
	global_load_dwordx4 v[156:159], v168, s[4:5] offset:528
	s_waitcnt vmcnt(0)
	v_sub_f32_e32 v140, v140, v156
	v_mul_f32_e32 v140, v140, v157
	v_fma_f32 v140, v160, v140, v164
	v_add_f32_e32 v64, v64, v138
	v_mul_f32_e32 v64, 0xbfb8aa3b, v64
	v_exp_f32_e32 v64, v64
	v_lshlrev_b32_e32 v148, 16, v148
	v_add_f32_e32 v64, 1.0, v64
	v_div_scale_f32 v172, vcc, v64, v64, 1.0
	v_rcp_f32_e32 v173, v172
	s_nop 0
	v_fma_f32 v174, -v172, v173, 1.0
	v_fmac_f32_e32 v173, v174, v173
	v_div_scale_f32 v174, vcc, 1.0, v64, 1.0
	v_mul_f32_e32 v175, v174, v173
	v_fma_f32 v176, -v172, v175, v174
	v_fmac_f32_e32 v175, v176, v173
	v_fma_f32 v172, -v172, v175, v174
	v_div_fmas_f32 v172, v172, v173, v175
	v_div_fixup_f32 v64, v172, v64, 1.0
	v_mul_f32_e32 v64, v181, v64
	v_fmac_f32_e32 v140, v64, v148
	global_store_dword v130, v140, s[86:87] offset:-4096
	v_cvt_pk_bf16_f32 v64, v140, s0
	global_store_short v134, v64, s[88:89] offset:128
	v_sub_f32_e32 v141, v141, v158
	v_mul_f32_e32 v141, v141, v159
	v_fma_f32 v141, v160, v141, v164
	v_add_f32_e32 v65, v65, v138
	v_mul_f32_e32 v65, 0xbfb8aa3b, v65
	v_exp_f32_e32 v65, v65
	v_lshlrev_b32_e32 v149, 16, v149
	v_add_f32_e32 v65, 1.0, v65
	v_div_scale_f32 v172, vcc, v65, v65, 1.0
	v_rcp_f32_e32 v173, v172
	s_nop 0
	v_fma_f32 v174, -v172, v173, 1.0
	v_fmac_f32_e32 v173, v174, v173
	v_div_scale_f32 v174, vcc, 1.0, v65, 1.0
	v_mul_f32_e32 v175, v174, v173
	v_fma_f32 v176, -v172, v175, v174
	v_fmac_f32_e32 v175, v176, v173
	v_fma_f32 v172, -v172, v175, v174
	v_div_fmas_f32 v172, v172, v173, v175
	v_div_fixup_f32 v65, v172, v65, 1.0
	v_mul_f32_e32 v65, v181, v65
	v_fmac_f32_e32 v141, v65, v149
	global_store_dword v130, v141, s[86:87]
	v_cvt_pk_bf16_f32 v65, v141, s0
	global_store_short v134, v65, s[88:89] offset:192
	v_sub_f32_e32 v142, v142, v156
	v_mul_f32_e32 v142, v142, v157
	v_fma_f32 v142, v161, v142, v165
	v_add_f32_e32 v60, v60, v139
	v_mul_f32_e32 v60, 0xbfb8aa3b, v60
	v_exp_f32_e32 v60, v60
	v_lshlrev_b32_e32 v150, 16, v150
	v_add_f32_e32 v60, 1.0, v60
	v_div_scale_f32 v172, vcc, v60, v60, 1.0
	v_rcp_f32_e32 v173, v172
	s_nop 0
	v_fma_f32 v174, -v172, v173, 1.0
	v_fmac_f32_e32 v173, v174, v173
	v_div_scale_f32 v174, vcc, 1.0, v60, 1.0
	v_mul_f32_e32 v175, v174, v173
	v_fma_f32 v176, -v172, v175, v174
	v_fmac_f32_e32 v175, v176, v173
	v_fma_f32 v172, -v172, v175, v174
	v_div_fmas_f32 v172, v172, v173, v175
	v_div_fixup_f32 v60, v172, v60, 1.0
	v_mul_f32_e32 v60, v181, v60
	v_fmac_f32_e32 v142, v60, v150
	global_store_dword v130, v142, s[86:87] offset:-4032
	v_cvt_pk_bf16_f32 v60, v142, s0
	global_store_short v134, v60, s[88:89] offset:160
	v_sub_f32_e32 v143, v143, v158
	v_mul_f32_e32 v143, v143, v159
	v_fma_f32 v143, v161, v143, v165
	v_add_f32_e32 v61, v61, v139
	v_mul_f32_e32 v61, 0xbfb8aa3b, v61
	v_exp_f32_e32 v61, v61
	v_lshlrev_b32_e32 v151, 16, v151
	v_add_f32_e32 v61, 1.0, v61
	v_div_scale_f32 v172, vcc, v61, v61, 1.0
	v_rcp_f32_e32 v173, v172
	s_nop 0
	v_fma_f32 v174, -v172, v173, 1.0
	v_fmac_f32_e32 v173, v174, v173
	v_div_scale_f32 v174, vcc, 1.0, v61, 1.0
	v_mul_f32_e32 v175, v174, v173
	v_fma_f32 v176, -v172, v175, v174
	v_fmac_f32_e32 v175, v176, v173
	v_fma_f32 v172, -v172, v175, v174
	v_div_fmas_f32 v172, v172, v173, v175
	v_div_fixup_f32 v61, v172, v61, 1.0
	v_mul_f32_e32 v61, v181, v61
	v_fmac_f32_e32 v143, v61, v151
	global_store_dword v130, v143, s[86:87] offset:64
	v_cvt_pk_bf16_f32 v61, v143, s0
	global_store_short v134, v61, s[88:89] offset:224
	v_sub_f32_e32 v144, v144, v156
	v_mul_f32_e32 v144, v144, v157
	v_fma_f32 v144, v162, v144, v166
	v_add_f32_e32 v56, v56, v214
	v_mul_f32_e32 v56, 0xbfb8aa3b, v56
	v_exp_f32_e32 v56, v56
	v_lshlrev_b32_e32 v152, 16, v152
; DEV u16 f2bf(float f) { return (u16)(pack2(f, 0.f) & 0xffffu); }
; DEV float bf2f(u16 b) { return __uint_as_float(((unsigned)b) << 16); }
; DEV size_t tixw(long row, int col, int W) { return (size_t)(row >> 8) * (256 * (size_t)W) + (size_t)(col >> 5) * 8192 + (size_t)(row & 255) * 32 + (col & 31); }
; DEV float sigmoidf_(float x) { return 1.f / (1.f + __expf(-x)); }
; DEV void phase_ln(const Params& P, const float* __restrict__ g, const float* __restrict__ bta, u16* __restrict__ xb, bool zero_kc) {
;     ...
;         y.x = v[r][i].x * rs * gv[i].x + bv[i].x;
;         y.y = v[r][i].y * rs * gv[i].y + bv[i].y;
;         y.z = v[r][i].z * rs * gv[i].z + bv[i].z;
;         y.w = v[r][i].w * rs * gv[i].w + bv[i].w;
;     ...
;       for (int ns = 0; ns < 4; ++ns)
; #pragma unroll
;         for (int j = 0; j < 4; ++j) {
;           int row = m0 + wm * 128 + ms * 16 + quad * 4 + j;
;           int col = n0 + wn * 64 + ns * 16 + l15;
;           size_t idx = (size_t)row * D + col;
;           float gate = sigmoidf_(acc[ms][ns][j] + bg[col]);
;           float v = P.out[idx] + psc * gate * bf2f(Pp[idx]);
;           P.out[idx] = v;
;           xbn[tixw(row, col, D)] = f2bf(v);
;         }
	v_add_f32_e32 v56, 1.0, v56
	v_div_scale_f32 v172, vcc, v56, v56, 1.0
	v_rcp_f32_e32 v173, v172
	s_nop 0
	v_fma_f32 v174, -v172, v173, 1.0
	v_fmac_f32_e32 v173, v174, v173
	v_div_scale_f32 v174, vcc, 1.0, v56, 1.0
	v_mul_f32_e32 v175, v174, v173
	v_fma_f32 v176, -v172, v175, v174
	v_fmac_f32_e32 v175, v176, v173
	v_fma_f32 v172, -v172, v175, v174
	v_div_fmas_f32 v172, v172, v173, v175
	v_div_fixup_f32 v56, v172, v56, 1.0
	v_mul_f32_e32 v56, v181, v56
	v_fmac_f32_e32 v144, v56, v152
	global_store_dword v130, v144, s[86:87] offset:-3968
	v_cvt_pk_bf16_f32 v56, v144, s0
	global_store_short v135, v56, s[88:89] offset:128
	v_sub_f32_e32 v145, v145, v158
	v_mul_f32_e32 v145, v145, v159
	v_fma_f32 v145, v162, v145, v166
	v_add_f32_e32 v57, v57, v214
	v_mul_f32_e32 v57, 0xbfb8aa3b, v57
	v_exp_f32_e32 v57, v57
	v_lshlrev_b32_e32 v153, 16, v153
	v_add_f32_e32 v57, 1.0, v57
	v_div_scale_f32 v172, vcc, v57, v57, 1.0
	v_rcp_f32_e32 v173, v172
	s_nop 0
	v_fma_f32 v174, -v172, v173, 1.0
	v_fmac_f32_e32 v173, v174, v173
	v_div_scale_f32 v174, vcc, 1.0, v57, 1.0
	v_mul_f32_e32 v175, v174, v173
	v_fma_f32 v176, -v172, v175, v174
	v_fmac_f32_e32 v175, v176, v173
	v_fma_f32 v172, -v172, v175, v174
	v_div_fmas_f32 v172, v172, v173, v175
	v_div_fixup_f32 v57, v172, v57, 1.0
	v_mul_f32_e32 v57, v181, v57
	v_fmac_f32_e32 v145, v57, v153
	global_store_dword v130, v145, s[86:87] offset:128
	v_cvt_pk_bf16_f32 v57, v145, s0
	global_store_short v135, v57, s[88:89] offset:192
	v_sub_f32_e32 v146, v146, v156
	v_mul_f32_e32 v146, v146, v157
	v_fma_f32 v146, v163, v146, v167
	v_add_f32_e32 v52, v52, v215
	v_mul_f32_e32 v52, 0xbfb8aa3b, v52
	v_exp_f32_e32 v52, v52
	v_lshlrev_b32_e32 v154, 16, v154
	v_add_f32_e32 v52, 1.0, v52
	v_div_scale_f32 v172, vcc, v52, v52, 1.0
	v_rcp_f32_e32 v173, v172
	s_nop 0
	v_fma_f32 v174, -v172, v173, 1.0
	v_fmac_f32_e32 v173, v174, v173
	v_div_scale_f32 v174, vcc, 1.0, v52, 1.0
	v_mul_f32_e32 v175, v174, v173
	v_fma_f32 v176, -v172, v175, v174
	v_fmac_f32_e32 v175, v176, v173
	v_fma_f32 v172, -v172, v175, v174
	v_div_fmas_f32 v172, v172, v173, v175
	v_div_fixup_f32 v52, v172, v52, 1.0
	v_mul_f32_e32 v52, v181, v52
	v_fmac_f32_e32 v146, v52, v154
	global_store_dword v130, v146, s[86:87] offset:-3904
	v_cvt_pk_bf16_f32 v52, v146, s0
	global_store_short v135, v52, s[88:89] offset:160
	v_sub_f32_e32 v147, v147, v158
	v_mul_f32_e32 v147, v147, v159
	v_fma_f32 v147, v163, v147, v167
	v_add_f32_e32 v53, v53, v215
	v_mul_f32_e32 v53, 0xbfb8aa3b, v53
	v_exp_f32_e32 v53, v53
	v_lshlrev_b32_e32 v155, 16, v155
	v_add_f32_e32 v53, 1.0, v53
	v_div_scale_f32 v172, vcc, v53, v53, 1.0
	v_rcp_f32_e32 v173, v172
	s_nop 0
	v_fma_f32 v174, -v172, v173, 1.0
	v_fmac_f32_e32 v173, v174, v173
	v_div_scale_f32 v174, vcc, 1.0, v53, 1.0
	v_mul_f32_e32 v175, v174, v173
	v_fma_f32 v176, -v172, v175, v174
	v_fmac_f32_e32 v175, v176, v173
	v_fma_f32 v172, -v172, v175, v174
	v_div_fmas_f32 v172, v172, v173, v175
	v_div_fixup_f32 v53, v172, v53, 1.0
	v_mul_f32_e32 v53, v181, v53
	v_fmac_f32_e32 v147, v53, v155
	global_store_dword v130, v147, s[86:87] offset:192
	v_cvt_pk_bf16_f32 v53, v147, s0
	global_store_short v135, v53, s[88:89] offset:224
	v_add_u32_e32 v130, 0x50000, v136
	v_lshrrev_b32_e32 v132, 1, v130
	global_load_dword v140, v130, s[86:87] offset:-4096
	global_load_dword v141, v130, s[86:87]
	global_load_dword v142, v130, s[86:87] offset:-4032
	global_load_dword v143, v130, s[86:87] offset:64
	global_load_dword v144, v130, s[86:87] offset:-3968
	global_load_dword v145, v130, s[86:87] offset:128
	global_load_dword v146, v130, s[86:87] offset:-3904
	global_load_dword v147, v130, s[86:87] offset:192
	global_load_ushort v148, v132, s[96:97] offset:-2048
	global_load_ushort v149, v132, s[96:97]
	global_load_ushort v150, v132, s[96:97] offset:-2016
	global_load_ushort v151, v132, s[96:97] offset:32
	global_load_ushort v152, v132, s[96:97] offset:-1984
	global_load_ushort v153, v132, s[96:97] offset:64
	global_load_ushort v154, v132, s[96:97] offset:-1952
	global_load_ushort v155, v132, s[96:97] offset:96
	global_load_dwordx4 v[156:159], v168, s[4:5] offset:640
	s_waitcnt vmcnt(0)
	v_sub_f32_e32 v140, v140, v156
	v_mul_f32_e32 v140, v140, v157
	v_fma_f32 v140, v160, v140, v164
	v_add_f32_e32 v46, v46, v138
	v_mul_f32_e32 v46, 0xbfb8aa3b, v46
	v_exp_f32_e32 v46, v46
	v_lshlrev_b32_e32 v148, 16, v148
	v_add_f32_e32 v46, 1.0, v46
	v_div_scale_f32 v172, vcc, v46, v46, 1.0
	v_rcp_f32_e32 v173, v172
	s_nop 0
	v_fma_f32 v174, -v172, v173, 1.0
	v_fmac_f32_e32 v173, v174, v173
	v_div_scale_f32 v174, vcc, 1.0, v46, 1.0
	v_mul_f32_e32 v175, v174, v173
	v_fma_f32 v176, -v172, v175, v174
	v_fmac_f32_e32 v175, v176, v173
	v_fma_f32 v172, -v172, v175, v174
	v_div_fmas_f32 v172, v172, v173, v175
	v_div_fixup_f32 v46, v172, v46, 1.0
	v_mul_f32_e32 v46, v181, v46
	v_fmac_f32_e32 v140, v46, v148
	global_store_dword v130, v140, s[86:87] offset:-4096
	v_cvt_pk_bf16_f32 v46, v140, s0
	global_store_short v134, v46, s[88:89] offset:1024
	v_sub_f32_e32 v141, v141, v158
	v_mul_f32_e32 v141, v141, v159
	v_fma_f32 v141, v160, v141, v164
	v_add_f32_e32 v47, v47, v138
	v_mul_f32_e32 v47, 0xbfb8aa3b, v47
	v_exp_f32_e32 v47, v47
	v_lshlrev_b32_e32 v149, 16, v149
	v_add_f32_e32 v47, 1.0, v47
	v_div_scale_f32 v172, vcc, v47, v47, 1.0
	v_rcp_f32_e32 v173, v172
	s_nop 0
	v_fma_f32 v174, -v172, v173, 1.0
	v_fmac_f32_e32 v173, v174, v173
	v_div_scale_f32 v174, vcc, 1.0, v47, 1.0
	v_mul_f32_e32 v175, v174, v173
	v_fma_f32 v176, -v172, v175, v174
	v_fmac_f32_e32 v175, v176, v173
	v_fma_f32 v172, -v172, v175, v174
	v_div_fmas_f32 v172, v172, v173, v175
	v_div_fixup_f32 v47, v172, v47, 1.0
	v_mul_f32_e32 v47, v181, v47
; DEV u16 f2bf(float f) { return (u16)(pack2(f, 0.f) & 0xffffu); }
; DEV float bf2f(u16 b) { return __uint_as_float(((unsigned)b) << 16); }
; DEV size_t tixw(long row, int col, int W) { return (size_t)(row >> 8) * (256 * (size_t)W) + (size_t)(col >> 5) * 8192 + (size_t)(row & 255) * 32 + (col & 31); }
; DEV float sigmoidf_(float x) { return 1.f / (1.f + __expf(-x)); }
; DEV void phase_ln(const Params& P, const float* __restrict__ g, const float* __restrict__ bta, u16* __restrict__ xb, bool zero_kc) {
;     ...
;         y.x = v[r][i].x * rs * gv[i].x + bv[i].x;
;         y.y = v[r][i].y * rs * gv[i].y + bv[i].y;
;         y.z = v[r][i].z * rs * gv[i].z + bv[i].z;
;         y.w = v[r][i].w * rs * gv[i].w + bv[i].w;
;     ...
;       for (int ns = 0; ns < 4; ++ns)
; #pragma unroll
;         for (int j = 0; j < 4; ++j) {
;           int row = m0 + wm * 128 + ms * 16 + quad * 4 + j;
;           int col = n0 + wn * 64 + ns * 16 + l15;
;           size_t idx = (size_t)row * D + col;
;           float gate = sigmoidf_(acc[ms][ns][j] + bg[col]);
;           float v = P.out[idx] + psc * gate * bf2f(Pp[idx]);
;           P.out[idx] = v;
;           xbn[tixw(row, col, D)] = f2bf(v);
;         }
	v_fmac_f32_e32 v141, v47, v149
	global_store_dword v130, v141, s[86:87]
	v_cvt_pk_bf16_f32 v47, v141, s0
	global_store_short v134, v47, s[88:89] offset:1088
	v_sub_f32_e32 v142, v142, v156
	v_mul_f32_e32 v142, v142, v157
	v_fma_f32 v142, v161, v142, v165
	v_add_f32_e32 v42, v42, v139
	v_mul_f32_e32 v42, 0xbfb8aa3b, v42
	v_exp_f32_e32 v42, v42
	v_lshlrev_b32_e32 v150, 16, v150
	v_add_f32_e32 v42, 1.0, v42
	v_div_scale_f32 v172, vcc, v42, v42, 1.0
	v_rcp_f32_e32 v173, v172
	s_nop 0
	v_fma_f32 v174, -v172, v173, 1.0
	v_fmac_f32_e32 v173, v174, v173
	v_div_scale_f32 v174, vcc, 1.0, v42, 1.0
	v_mul_f32_e32 v175, v174, v173
	v_fma_f32 v176, -v172, v175, v174
	v_fmac_f32_e32 v175, v176, v173
	v_fma_f32 v172, -v172, v175, v174
	v_div_fmas_f32 v172, v172, v173, v175
	v_div_fixup_f32 v42, v172, v42, 1.0
	v_mul_f32_e32 v42, v181, v42
	v_fmac_f32_e32 v142, v42, v150
	global_store_dword v130, v142, s[86:87] offset:-4032
	v_cvt_pk_bf16_f32 v42, v142, s0
	global_store_short v134, v42, s[88:89] offset:1056
	v_sub_f32_e32 v143, v143, v158
	v_mul_f32_e32 v143, v143, v159
	v_fma_f32 v143, v161, v143, v165
	v_add_f32_e32 v43, v43, v139
	v_mul_f32_e32 v43, 0xbfb8aa3b, v43
	v_exp_f32_e32 v43, v43
	v_lshlrev_b32_e32 v151, 16, v151
	v_add_f32_e32 v43, 1.0, v43
	v_div_scale_f32 v172, vcc, v43, v43, 1.0
	v_rcp_f32_e32 v173, v172
	s_nop 0
	v_fma_f32 v174, -v172, v173, 1.0
	v_fmac_f32_e32 v173, v174, v173
	v_div_scale_f32 v174, vcc, 1.0, v43, 1.0
	v_mul_f32_e32 v175, v174, v173
	v_fma_f32 v176, -v172, v175, v174
	v_fmac_f32_e32 v175, v176, v173
	v_fma_f32 v172, -v172, v175, v174
	v_div_fmas_f32 v172, v172, v173, v175
	v_div_fixup_f32 v43, v172, v43, 1.0
	v_mul_f32_e32 v43, v181, v43
	v_fmac_f32_e32 v143, v43, v151
	global_store_dword v130, v143, s[86:87] offset:64
	v_cvt_pk_bf16_f32 v43, v143, s0
	global_store_short v134, v43, s[88:89] offset:1120
	v_sub_f32_e32 v144, v144, v156
	v_mul_f32_e32 v144, v144, v157
	v_fma_f32 v144, v162, v144, v166
	v_add_f32_e32 v38, v38, v214
	v_mul_f32_e32 v38, 0xbfb8aa3b, v38
	v_exp_f32_e32 v38, v38
	v_lshlrev_b32_e32 v152, 16, v152
	v_add_f32_e32 v38, 1.0, v38
	v_div_scale_f32 v172, vcc, v38, v38, 1.0
	v_rcp_f32_e32 v173, v172
	s_nop 0
	v_fma_f32 v174, -v172, v173, 1.0
	v_fmac_f32_e32 v173, v174, v173
	v_div_scale_f32 v174, vcc, 1.0, v38, 1.0
	v_mul_f32_e32 v175, v174, v173
	v_fma_f32 v176, -v172, v175, v174
	v_fmac_f32_e32 v175, v176, v173
	v_fma_f32 v172, -v172, v175, v174
	v_div_fmas_f32 v172, v172, v173, v175
	v_div_fixup_f32 v38, v172, v38, 1.0
	v_mul_f32_e32 v38, v181, v38
	v_fmac_f32_e32 v144, v38, v152
	global_store_dword v130, v144, s[86:87] offset:-3968
	v_cvt_pk_bf16_f32 v38, v144, s0
	global_store_short v135, v38, s[88:89] offset:1024
	v_sub_f32_e32 v145, v145, v158
	v_mul_f32_e32 v145, v145, v159
	v_fma_f32 v145, v162, v145, v166
	v_add_f32_e32 v39, v39, v214
	v_mul_f32_e32 v39, 0xbfb8aa3b, v39
	v_exp_f32_e32 v39, v39
	v_lshlrev_b32_e32 v153, 16, v153
	v_add_f32_e32 v39, 1.0, v39
	v_div_scale_f32 v172, vcc, v39, v39, 1.0
	v_rcp_f32_e32 v173, v172
	s_nop 0
	v_fma_f32 v174, -v172, v173, 1.0
	v_fmac_f32_e32 v173, v174, v173
	v_div_scale_f32 v174, vcc, 1.0, v39, 1.0
	v_mul_f32_e32 v175, v174, v173
	v_fma_f32 v176, -v172, v175, v174
	v_fmac_f32_e32 v175, v176, v173
	v_fma_f32 v172, -v172, v175, v174
	v_div_fmas_f32 v172, v172, v173, v175
	v_div_fixup_f32 v39, v172, v39, 1.0
	v_mul_f32_e32 v39, v181, v39
	v_fmac_f32_e32 v145, v39, v153
	global_store_dword v130, v145, s[86:87] offset:128
	v_cvt_pk_bf16_f32 v39, v145, s0
	global_store_short v135, v39, s[88:89] offset:1088
	v_sub_f32_e32 v146, v146, v156
	v_mul_f32_e32 v146, v146, v157
	v_fma_f32 v146, v163, v146, v167
	v_add_f32_e32 v34, v34, v215
	v_mul_f32_e32 v34, 0xbfb8aa3b, v34
	v_exp_f32_e32 v34, v34
	v_lshlrev_b32_e32 v154, 16, v154
	v_add_f32_e32 v34, 1.0, v34
	v_div_scale_f32 v172, vcc, v34, v34, 1.0
	v_rcp_f32_e32 v173, v172
	s_nop 0
	v_fma_f32 v174, -v172, v173, 1.0
	v_fmac_f32_e32 v173, v174, v173
	v_div_scale_f32 v174, vcc, 1.0, v34, 1.0
	v_mul_f32_e32 v175, v174, v173
	v_fma_f32 v176, -v172, v175, v174
	v_fmac_f32_e32 v175, v176, v173
	v_fma_f32 v172, -v172, v175, v174
	v_div_fmas_f32 v172, v172, v173, v175
	v_div_fixup_f32 v34, v172, v34, 1.0
	v_mul_f32_e32 v34, v181, v34
	v_fmac_f32_e32 v146, v34, v154
	global_store_dword v130, v146, s[86:87] offset:-3904
	v_cvt_pk_bf16_f32 v34, v146, s0
	global_store_short v135, v34, s[88:89] offset:1056
	v_sub_f32_e32 v147, v147, v158
	v_mul_f32_e32 v147, v147, v159
	v_fma_f32 v147, v163, v147, v167
	v_add_f32_e32 v35, v35, v215
	v_mul_f32_e32 v35, 0xbfb8aa3b, v35
	v_exp_f32_e32 v35, v35
	v_lshlrev_b32_e32 v155, 16, v155
	v_add_f32_e32 v35, 1.0, v35
	v_div_scale_f32 v172, vcc, v35, v35, 1.0
	v_rcp_f32_e32 v173, v172
	s_nop 0
	v_fma_f32 v174, -v172, v173, 1.0
	v_fmac_f32_e32 v173, v174, v173
	v_div_scale_f32 v174, vcc, 1.0, v35, 1.0
	v_mul_f32_e32 v175, v174, v173
	v_fma_f32 v176, -v172, v175, v174
	v_fmac_f32_e32 v175, v176, v173
	v_fma_f32 v172, -v172, v175, v174
	v_div_fmas_f32 v172, v172, v173, v175
	v_div_fixup_f32 v35, v172, v35, 1.0
	v_mul_f32_e32 v35, v181, v35
	v_fmac_f32_e32 v147, v35, v155
	global_store_dword v130, v147, s[86:87] offset:192
	v_cvt_pk_bf16_f32 v35, v147, s0
	global_store_short v135, v35, s[88:89] offset:1120
	v_add_u32_e32 v130, 0x52000, v136
	v_lshrrev_b32_e32 v132, 1, v130
	global_load_dword v140, v130, s[86:87] offset:-4096
	global_load_dword v141, v130, s[86:87]
	global_load_dword v142, v130, s[86:87] offset:-4032
	global_load_dword v143, v130, s[86:87] offset:64
	global_load_dword v144, v130, s[86:87] offset:-3968
	global_load_dword v145, v130, s[86:87] offset:128
	global_load_dword v146, v130, s[86:87] offset:-3904
	global_load_dword v147, v130, s[86:87] offset:192
	global_load_ushort v148, v132, s[96:97] offset:-2048
	global_load_ushort v149, v132, s[96:97]
	global_load_ushort v150, v132, s[96:97] offset:-2016
	global_load_ushort v151, v132, s[96:97] offset:32
	global_load_ushort v152, v132, s[96:97] offset:-1984
	global_load_ushort v153, v132, s[96:97] offset:64
	global_load_ushort v154, v132, s[96:97] offset:-1952
	global_load_ushort v155, v132, s[96:97] offset:96
	global_load_dwordx4 v[156:159], v168, s[4:5] offset:656
	s_waitcnt vmcnt(0)
; DEV u16 f2bf(float f) { return (u16)(pack2(f, 0.f) & 0xffffu); }
; DEV float bf2f(u16 b) { return __uint_as_float(((unsigned)b) << 16); }
; DEV size_t tixw(long row, int col, int W) { return (size_t)(row >> 8) * (256 * (size_t)W) + (size_t)(col >> 5) * 8192 + (size_t)(row & 255) * 32 + (col & 31); }
; DEV float sigmoidf_(float x) { return 1.f / (1.f + __expf(-x)); }
; DEV void phase_ln(const Params& P, const float* __restrict__ g, const float* __restrict__ bta, u16* __restrict__ xb, bool zero_kc) {
;     ...
;         y.x = v[r][i].x * rs * gv[i].x + bv[i].x;
;         y.y = v[r][i].y * rs * gv[i].y + bv[i].y;
;         y.z = v[r][i].z * rs * gv[i].z + bv[i].z;
;         y.w = v[r][i].w * rs * gv[i].w + bv[i].w;
;     ...
;       for (int ns = 0; ns < 4; ++ns)
; #pragma unroll
;         for (int j = 0; j < 4; ++j) {
;           int row = m0 + wm * 128 + ms * 16 + quad * 4 + j;
;           int col = n0 + wn * 64 + ns * 16 + l15;
;           size_t idx = (size_t)row * D + col;
;           float gate = sigmoidf_(acc[ms][ns][j] + bg[col]);
;           float v = P.out[idx] + psc * gate * bf2f(Pp[idx]);
;           P.out[idx] = v;
;           xbn[tixw(row, col, D)] = f2bf(v);
;         }
	v_sub_f32_e32 v140, v140, v156
	v_mul_f32_e32 v140, v140, v157
	v_fma_f32 v140, v160, v140, v164
	v_add_f32_e32 v48, v48, v138
	v_mul_f32_e32 v48, 0xbfb8aa3b, v48
	v_exp_f32_e32 v48, v48
	v_lshlrev_b32_e32 v148, 16, v148
	v_add_f32_e32 v48, 1.0, v48
	v_div_scale_f32 v172, vcc, v48, v48, 1.0
	v_rcp_f32_e32 v173, v172
	s_nop 0
	v_fma_f32 v174, -v172, v173, 1.0
	v_fmac_f32_e32 v173, v174, v173
	v_div_scale_f32 v174, vcc, 1.0, v48, 1.0
	v_mul_f32_e32 v175, v174, v173
	v_fma_f32 v176, -v172, v175, v174
	v_fmac_f32_e32 v175, v176, v173
	v_fma_f32 v172, -v172, v175, v174
	v_div_fmas_f32 v172, v172, v173, v175
	v_div_fixup_f32 v48, v172, v48, 1.0
	v_mul_f32_e32 v48, v181, v48
	v_fmac_f32_e32 v140, v48, v148
	global_store_dword v130, v140, s[86:87] offset:-4096
	v_cvt_pk_bf16_f32 v48, v140, s0
	global_store_short v134, v48, s[88:89] offset:1152
	v_sub_f32_e32 v141, v141, v158
	v_mul_f32_e32 v141, v141, v159
	v_fma_f32 v141, v160, v141, v164
	v_add_f32_e32 v49, v49, v138
	v_mul_f32_e32 v49, 0xbfb8aa3b, v49
	v_exp_f32_e32 v49, v49
	v_lshlrev_b32_e32 v149, 16, v149
	v_add_f32_e32 v49, 1.0, v49
	v_div_scale_f32 v172, vcc, v49, v49, 1.0
	v_rcp_f32_e32 v173, v172
	s_nop 0
	v_fma_f32 v174, -v172, v173, 1.0
	v_fmac_f32_e32 v173, v174, v173
	v_div_scale_f32 v174, vcc, 1.0, v49, 1.0
	v_mul_f32_e32 v175, v174, v173
	v_fma_f32 v176, -v172, v175, v174
	v_fmac_f32_e32 v175, v176, v173
	v_fma_f32 v172, -v172, v175, v174
	v_div_fmas_f32 v172, v172, v173, v175
	v_div_fixup_f32 v49, v172, v49, 1.0
	v_mul_f32_e32 v49, v181, v49
	v_fmac_f32_e32 v141, v49, v149
	global_store_dword v130, v141, s[86:87]
	v_cvt_pk_bf16_f32 v49, v141, s0
	global_store_short v134, v49, s[88:89] offset:1216
	v_sub_f32_e32 v142, v142, v156
	v_mul_f32_e32 v142, v142, v157
	v_fma_f32 v142, v161, v142, v165
	v_add_f32_e32 v44, v44, v139
	v_mul_f32_e32 v44, 0xbfb8aa3b, v44
	v_exp_f32_e32 v44, v44
	v_lshlrev_b32_e32 v150, 16, v150
	v_add_f32_e32 v44, 1.0, v44
	v_div_scale_f32 v172, vcc, v44, v44, 1.0
	v_rcp_f32_e32 v173, v172
	s_nop 0
	v_fma_f32 v174, -v172, v173, 1.0
	v_fmac_f32_e32 v173, v174, v173
	v_div_scale_f32 v174, vcc, 1.0, v44, 1.0
	v_mul_f32_e32 v175, v174, v173
	v_fma_f32 v176, -v172, v175, v174
	v_fmac_f32_e32 v175, v176, v173
	v_fma_f32 v172, -v172, v175, v174
	v_div_fmas_f32 v172, v172, v173, v175
	v_div_fixup_f32 v44, v172, v44, 1.0
	v_mul_f32_e32 v44, v181, v44
	v_fmac_f32_e32 v142, v44, v150
	global_store_dword v130, v142, s[86:87] offset:-4032
	v_cvt_pk_bf16_f32 v44, v142, s0
	global_store_short v134, v44, s[88:89] offset:1184
	v_sub_f32_e32 v143, v143, v158
	v_mul_f32_e32 v143, v143, v159
	v_fma_f32 v143, v161, v143, v165
	v_add_f32_e32 v45, v45, v139
	v_mul_f32_e32 v45, 0xbfb8aa3b, v45
	v_exp_f32_e32 v45, v45
	v_lshlrev_b32_e32 v151, 16, v151
	v_add_f32_e32 v45, 1.0, v45
	v_div_scale_f32 v172, vcc, v45, v45, 1.0
	v_rcp_f32_e32 v173, v172
	s_nop 0
	v_fma_f32 v174, -v172, v173, 1.0
	v_fmac_f32_e32 v173, v174, v173
	v_div_scale_f32 v174, vcc, 1.0, v45, 1.0
	v_mul_f32_e32 v175, v174, v173
	v_fma_f32 v176, -v172, v175, v174
	v_fmac_f32_e32 v175, v176, v173
	v_fma_f32 v172, -v172, v175, v174
	v_div_fmas_f32 v172, v172, v173, v175
	v_div_fixup_f32 v45, v172, v45, 1.0
	v_mul_f32_e32 v45, v181, v45
	v_fmac_f32_e32 v143, v45, v151
	global_store_dword v130, v143, s[86:87] offset:64
	v_cvt_pk_bf16_f32 v45, v143, s0
	global_store_short v134, v45, s[88:89] offset:1248
	v_sub_f32_e32 v144, v144, v156
	v_mul_f32_e32 v144, v144, v157
	v_fma_f32 v144, v162, v144, v166
	v_add_f32_e32 v40, v40, v214
	v_mul_f32_e32 v40, 0xbfb8aa3b, v40
	v_exp_f32_e32 v40, v40
	v_lshlrev_b32_e32 v152, 16, v152
	v_add_f32_e32 v40, 1.0, v40
	v_div_scale_f32 v172, vcc, v40, v40, 1.0
	v_rcp_f32_e32 v173, v172
	s_nop 0
	v_fma_f32 v174, -v172, v173, 1.0
	v_fmac_f32_e32 v173, v174, v173
	v_div_scale_f32 v174, vcc, 1.0, v40, 1.0
	v_mul_f32_e32 v175, v174, v173
	v_fma_f32 v176, -v172, v175, v174
	v_fmac_f32_e32 v175, v176, v173
	v_fma_f32 v172, -v172, v175, v174
	v_div_fmas_f32 v172, v172, v173, v175
	v_div_fixup_f32 v40, v172, v40, 1.0
	v_mul_f32_e32 v40, v181, v40
	v_fmac_f32_e32 v144, v40, v152
	global_store_dword v130, v144, s[86:87] offset:-3968
	v_cvt_pk_bf16_f32 v40, v144, s0
	global_store_short v135, v40, s[88:89] offset:1152
	v_sub_f32_e32 v145, v145, v158
	v_mul_f32_e32 v145, v145, v159
	v_fma_f32 v145, v162, v145, v166
	v_add_f32_e32 v41, v41, v214
	v_mul_f32_e32 v41, 0xbfb8aa3b, v41
	v_exp_f32_e32 v41, v41
	v_lshlrev_b32_e32 v153, 16, v153
	v_add_f32_e32 v41, 1.0, v41
	v_div_scale_f32 v172, vcc, v41, v41, 1.0
	v_rcp_f32_e32 v173, v172
	s_nop 0
	v_fma_f32 v174, -v172, v173, 1.0
	v_fmac_f32_e32 v173, v174, v173
	v_div_scale_f32 v174, vcc, 1.0, v41, 1.0
	v_mul_f32_e32 v175, v174, v173
	v_fma_f32 v176, -v172, v175, v174
	v_fmac_f32_e32 v175, v176, v173
	v_fma_f32 v172, -v172, v175, v174
	v_div_fmas_f32 v172, v172, v173, v175
	v_div_fixup_f32 v41, v172, v41, 1.0
	v_mul_f32_e32 v41, v181, v41
	v_fmac_f32_e32 v145, v41, v153
	global_store_dword v130, v145, s[86:87] offset:128
	v_cvt_pk_bf16_f32 v41, v145, s0
	global_store_short v135, v41, s[88:89] offset:1216
	v_sub_f32_e32 v146, v146, v156
	v_mul_f32_e32 v146, v146, v157
	v_fma_f32 v146, v163, v146, v167
	v_add_f32_e32 v36, v36, v215
	v_mul_f32_e32 v36, 0xbfb8aa3b, v36
	v_exp_f32_e32 v36, v36
	v_lshlrev_b32_e32 v154, 16, v154
	v_add_f32_e32 v36, 1.0, v36
	v_div_scale_f32 v172, vcc, v36, v36, 1.0
	v_rcp_f32_e32 v173, v172
	s_nop 0
	v_fma_f32 v174, -v172, v173, 1.0
	v_fmac_f32_e32 v173, v174, v173
	v_div_scale_f32 v174, vcc, 1.0, v36, 1.0
	v_mul_f32_e32 v175, v174, v173
	v_fma_f32 v176, -v172, v175, v174
	v_fmac_f32_e32 v175, v176, v173
	v_fma_f32 v172, -v172, v175, v174
; DEV u16 f2bf(float f) { return (u16)(pack2(f, 0.f) & 0xffffu); }
; DEV float bf2f(u16 b) { return __uint_as_float(((unsigned)b) << 16); }
; DEV size_t tixw(long row, int col, int W) { return (size_t)(row >> 8) * (256 * (size_t)W) + (size_t)(col >> 5) * 8192 + (size_t)(row & 255) * 32 + (col & 31); }
; DEV float sigmoidf_(float x) { return 1.f / (1.f + __expf(-x)); }
; DEV void phase_ln(const Params& P, const float* __restrict__ g, const float* __restrict__ bta, u16* __restrict__ xb, bool zero_kc) {
;     ...
;         y.x = v[r][i].x * rs * gv[i].x + bv[i].x;
;         y.y = v[r][i].y * rs * gv[i].y + bv[i].y;
;         y.z = v[r][i].z * rs * gv[i].z + bv[i].z;
;         y.w = v[r][i].w * rs * gv[i].w + bv[i].w;
;     ...
;       for (int ns = 0; ns < 4; ++ns)
; #pragma unroll
;         for (int j = 0; j < 4; ++j) {
;           int row = m0 + wm * 128 + ms * 16 + quad * 4 + j;
;           int col = n0 + wn * 64 + ns * 16 + l15;
;           size_t idx = (size_t)row * D + col;
;           float gate = sigmoidf_(acc[ms][ns][j] + bg[col]);
;           float v = P.out[idx] + psc * gate * bf2f(Pp[idx]);
;           P.out[idx] = v;
;           xbn[tixw(row, col, D)] = f2bf(v);
;         }
	v_div_fmas_f32 v172, v172, v173, v175
	v_div_fixup_f32 v36, v172, v36, 1.0
	v_mul_f32_e32 v36, v181, v36
	v_fmac_f32_e32 v146, v36, v154
	global_store_dword v130, v146, s[86:87] offset:-3904
	v_cvt_pk_bf16_f32 v36, v146, s0
	global_store_short v135, v36, s[88:89] offset:1184
	v_sub_f32_e32 v147, v147, v158
	v_mul_f32_e32 v147, v147, v159
	v_fma_f32 v147, v163, v147, v167
	v_add_f32_e32 v37, v37, v215
	v_mul_f32_e32 v37, 0xbfb8aa3b, v37
	v_exp_f32_e32 v37, v37
	v_lshlrev_b32_e32 v155, 16, v155
	v_add_f32_e32 v37, 1.0, v37
	v_div_scale_f32 v172, vcc, v37, v37, 1.0
	v_rcp_f32_e32 v173, v172
	s_nop 0
	v_fma_f32 v174, -v172, v173, 1.0
	v_fmac_f32_e32 v173, v174, v173
	v_div_scale_f32 v174, vcc, 1.0, v37, 1.0
	v_mul_f32_e32 v175, v174, v173
	v_fma_f32 v176, -v172, v175, v174
	v_fmac_f32_e32 v175, v176, v173
	v_fma_f32 v172, -v172, v175, v174
	v_div_fmas_f32 v172, v172, v173, v175
	v_div_fixup_f32 v37, v172, v37, 1.0
	v_mul_f32_e32 v37, v181, v37
	v_fmac_f32_e32 v147, v37, v155
	global_store_dword v130, v147, s[86:87] offset:192
	v_cvt_pk_bf16_f32 v37, v147, s0
	global_store_short v135, v37, s[88:89] offset:1248
	v_add_u32_e32 v130, 0x60000, v136
	v_lshrrev_b32_e32 v132, 1, v130
	global_load_dword v140, v130, s[86:87] offset:-4096
	global_load_dword v141, v130, s[86:87]
	global_load_dword v142, v130, s[86:87] offset:-4032
	global_load_dword v143, v130, s[86:87] offset:64
	global_load_dword v144, v130, s[86:87] offset:-3968
	global_load_dword v145, v130, s[86:87] offset:128
	global_load_dword v146, v130, s[86:87] offset:-3904
	global_load_dword v147, v130, s[86:87] offset:192
	global_load_ushort v148, v132, s[96:97] offset:-2048
	global_load_ushort v149, v132, s[96:97]
	global_load_ushort v150, v132, s[96:97] offset:-2016
	global_load_ushort v151, v132, s[96:97] offset:32
	global_load_ushort v152, v132, s[96:97] offset:-1984
	global_load_ushort v153, v132, s[96:97] offset:64
	global_load_ushort v154, v132, s[96:97] offset:-1952
	global_load_ushort v155, v132, s[96:97] offset:96
	global_load_dwordx4 v[156:159], v168, s[4:5] offset:768
	s_waitcnt vmcnt(0)
	v_sub_f32_e32 v140, v140, v156
	v_mul_f32_e32 v140, v140, v157
	v_fma_f32 v140, v160, v140, v164
	v_add_f32_e32 v30, v30, v138
	v_mul_f32_e32 v30, 0xbfb8aa3b, v30
	v_exp_f32_e32 v30, v30
	v_lshlrev_b32_e32 v148, 16, v148
	v_add_f32_e32 v30, 1.0, v30
	v_div_scale_f32 v172, vcc, v30, v30, 1.0
	v_rcp_f32_e32 v173, v172
	s_nop 0
	v_fma_f32 v174, -v172, v173, 1.0
	v_fmac_f32_e32 v173, v174, v173
	v_div_scale_f32 v174, vcc, 1.0, v30, 1.0
	v_mul_f32_e32 v175, v174, v173
	v_fma_f32 v176, -v172, v175, v174
	v_fmac_f32_e32 v175, v176, v173
	v_fma_f32 v172, -v172, v175, v174
	v_div_fmas_f32 v172, v172, v173, v175
	v_div_fixup_f32 v30, v172, v30, 1.0
	v_mul_f32_e32 v30, v181, v30
	v_fmac_f32_e32 v140, v30, v148
	global_store_dword v130, v140, s[86:87] offset:-4096
	v_cvt_pk_bf16_f32 v30, v140, s0
	global_store_short v134, v30, s[88:89] offset:2048
	v_sub_f32_e32 v141, v141, v158
	v_mul_f32_e32 v141, v141, v159
	v_fma_f32 v141, v160, v141, v164
	v_add_f32_e32 v31, v31, v138
	v_mul_f32_e32 v31, 0xbfb8aa3b, v31
	v_exp_f32_e32 v31, v31
	v_lshlrev_b32_e32 v149, 16, v149
	v_add_f32_e32 v31, 1.0, v31
	v_div_scale_f32 v172, vcc, v31, v31, 1.0
	v_rcp_f32_e32 v173, v172
	s_nop 0
	v_fma_f32 v174, -v172, v173, 1.0
	v_fmac_f32_e32 v173, v174, v173
	v_div_scale_f32 v174, vcc, 1.0, v31, 1.0
	v_mul_f32_e32 v175, v174, v173
	v_fma_f32 v176, -v172, v175, v174
	v_fmac_f32_e32 v175, v176, v173
	v_fma_f32 v172, -v172, v175, v174
	v_div_fmas_f32 v172, v172, v173, v175
	v_div_fixup_f32 v31, v172, v31, 1.0
	v_mul_f32_e32 v31, v181, v31
	v_fmac_f32_e32 v141, v31, v149
	global_store_dword v130, v141, s[86:87]
	v_cvt_pk_bf16_f32 v31, v141, s0
	global_store_short v134, v31, s[88:89] offset:2112
	v_sub_f32_e32 v142, v142, v156
	v_mul_f32_e32 v142, v142, v157
	v_fma_f32 v142, v161, v142, v165
	v_add_f32_e32 v26, v26, v139
	v_mul_f32_e32 v26, 0xbfb8aa3b, v26
	v_exp_f32_e32 v26, v26
	v_lshlrev_b32_e32 v150, 16, v150
	v_add_f32_e32 v26, 1.0, v26
	v_div_scale_f32 v172, vcc, v26, v26, 1.0
	v_rcp_f32_e32 v173, v172
	s_nop 0
	v_fma_f32 v174, -v172, v173, 1.0
	v_fmac_f32_e32 v173, v174, v173
	v_div_scale_f32 v174, vcc, 1.0, v26, 1.0
	v_mul_f32_e32 v175, v174, v173
	v_fma_f32 v176, -v172, v175, v174
	v_fmac_f32_e32 v175, v176, v173
	v_fma_f32 v172, -v172, v175, v174
	v_div_fmas_f32 v172, v172, v173, v175
	v_div_fixup_f32 v26, v172, v26, 1.0
	v_mul_f32_e32 v26, v181, v26
	v_fmac_f32_e32 v142, v26, v150
	global_store_dword v130, v142, s[86:87] offset:-4032
	v_cvt_pk_bf16_f32 v26, v142, s0
	global_store_short v134, v26, s[88:89] offset:2080
	v_sub_f32_e32 v143, v143, v158
	v_mul_f32_e32 v143, v143, v159
	v_fma_f32 v143, v161, v143, v165
	v_add_f32_e32 v27, v27, v139
	v_mul_f32_e32 v27, 0xbfb8aa3b, v27
	v_exp_f32_e32 v27, v27
	v_lshlrev_b32_e32 v151, 16, v151
	v_add_f32_e32 v27, 1.0, v27
	v_div_scale_f32 v172, vcc, v27, v27, 1.0
	v_rcp_f32_e32 v173, v172
	s_nop 0
	v_fma_f32 v174, -v172, v173, 1.0
	v_fmac_f32_e32 v173, v174, v173
	v_div_scale_f32 v174, vcc, 1.0, v27, 1.0
	v_mul_f32_e32 v175, v174, v173
	v_fma_f32 v176, -v172, v175, v174
	v_fmac_f32_e32 v175, v176, v173
	v_fma_f32 v172, -v172, v175, v174
	v_div_fmas_f32 v172, v172, v173, v175
	v_div_fixup_f32 v27, v172, v27, 1.0
	v_mul_f32_e32 v27, v181, v27
	v_fmac_f32_e32 v143, v27, v151
	global_store_dword v130, v143, s[86:87] offset:64
	v_cvt_pk_bf16_f32 v27, v143, s0
	global_store_short v134, v27, s[88:89] offset:2144
	v_sub_f32_e32 v144, v144, v156
	v_mul_f32_e32 v144, v144, v157
	v_fma_f32 v144, v162, v144, v166
	v_add_f32_e32 v22, v22, v214
	v_mul_f32_e32 v22, 0xbfb8aa3b, v22
	v_exp_f32_e32 v22, v22
; DEV u16 f2bf(float f) { return (u16)(pack2(f, 0.f) & 0xffffu); }
; DEV float bf2f(u16 b) { return __uint_as_float(((unsigned)b) << 16); }
; DEV size_t tixw(long row, int col, int W) { return (size_t)(row >> 8) * (256 * (size_t)W) + (size_t)(col >> 5) * 8192 + (size_t)(row & 255) * 32 + (col & 31); }
; DEV float sigmoidf_(float x) { return 1.f / (1.f + __expf(-x)); }
; DEV void phase_ln(const Params& P, const float* __restrict__ g, const float* __restrict__ bta, u16* __restrict__ xb, bool zero_kc) {
;     ...
;         y.x = v[r][i].x * rs * gv[i].x + bv[i].x;
;         y.y = v[r][i].y * rs * gv[i].y + bv[i].y;
;         y.z = v[r][i].z * rs * gv[i].z + bv[i].z;
;         y.w = v[r][i].w * rs * gv[i].w + bv[i].w;
;     ...
;       for (int ns = 0; ns < 4; ++ns)
; #pragma unroll
;         for (int j = 0; j < 4; ++j) {
;           int row = m0 + wm * 128 + ms * 16 + quad * 4 + j;
;           int col = n0 + wn * 64 + ns * 16 + l15;
;           size_t idx = (size_t)row * D + col;
;           float gate = sigmoidf_(acc[ms][ns][j] + bg[col]);
;           float v = P.out[idx] + psc * gate * bf2f(Pp[idx]);
;           P.out[idx] = v;
;           xbn[tixw(row, col, D)] = f2bf(v);
;         }
	v_lshlrev_b32_e32 v152, 16, v152
	v_add_f32_e32 v22, 1.0, v22
	v_div_scale_f32 v172, vcc, v22, v22, 1.0
	v_rcp_f32_e32 v173, v172
	s_nop 0
	v_fma_f32 v174, -v172, v173, 1.0
	v_fmac_f32_e32 v173, v174, v173
	v_div_scale_f32 v174, vcc, 1.0, v22, 1.0
	v_mul_f32_e32 v175, v174, v173
	v_fma_f32 v176, -v172, v175, v174
	v_fmac_f32_e32 v175, v176, v173
	v_fma_f32 v172, -v172, v175, v174
	v_div_fmas_f32 v172, v172, v173, v175
	v_div_fixup_f32 v22, v172, v22, 1.0
	v_mul_f32_e32 v22, v181, v22
	v_fmac_f32_e32 v144, v22, v152
	global_store_dword v130, v144, s[86:87] offset:-3968
	v_cvt_pk_bf16_f32 v22, v144, s0
	global_store_short v135, v22, s[88:89] offset:2048
	v_sub_f32_e32 v145, v145, v158
	v_mul_f32_e32 v145, v145, v159
	v_fma_f32 v145, v162, v145, v166
	v_add_f32_e32 v23, v23, v214
	v_mul_f32_e32 v23, 0xbfb8aa3b, v23
	v_exp_f32_e32 v23, v23
	v_lshlrev_b32_e32 v153, 16, v153
	v_add_f32_e32 v23, 1.0, v23
	v_div_scale_f32 v172, vcc, v23, v23, 1.0
	v_rcp_f32_e32 v173, v172
	s_nop 0
	v_fma_f32 v174, -v172, v173, 1.0
	v_fmac_f32_e32 v173, v174, v173
	v_div_scale_f32 v174, vcc, 1.0, v23, 1.0
	v_mul_f32_e32 v175, v174, v173
	v_fma_f32 v176, -v172, v175, v174
	v_fmac_f32_e32 v175, v176, v173
	v_fma_f32 v172, -v172, v175, v174
	v_div_fmas_f32 v172, v172, v173, v175
	v_div_fixup_f32 v23, v172, v23, 1.0
	v_mul_f32_e32 v23, v181, v23
	v_fmac_f32_e32 v145, v23, v153
	global_store_dword v130, v145, s[86:87] offset:128
	v_cvt_pk_bf16_f32 v23, v145, s0
	global_store_short v135, v23, s[88:89] offset:2112
	v_sub_f32_e32 v146, v146, v156
	v_mul_f32_e32 v146, v146, v157
	v_fma_f32 v146, v163, v146, v167
	v_add_f32_e32 v18, v18, v215
	v_mul_f32_e32 v18, 0xbfb8aa3b, v18
	v_exp_f32_e32 v18, v18
	v_lshlrev_b32_e32 v154, 16, v154
	v_add_f32_e32 v18, 1.0, v18
	v_div_scale_f32 v172, vcc, v18, v18, 1.0
	v_rcp_f32_e32 v173, v172
	s_nop 0
	v_fma_f32 v174, -v172, v173, 1.0
	v_fmac_f32_e32 v173, v174, v173
	v_div_scale_f32 v174, vcc, 1.0, v18, 1.0
	v_mul_f32_e32 v175, v174, v173
	v_fma_f32 v176, -v172, v175, v174
	v_fmac_f32_e32 v175, v176, v173
	v_fma_f32 v172, -v172, v175, v174
	v_div_fmas_f32 v172, v172, v173, v175
	v_div_fixup_f32 v18, v172, v18, 1.0
	v_mul_f32_e32 v18, v181, v18
	v_fmac_f32_e32 v146, v18, v154
	global_store_dword v130, v146, s[86:87] offset:-3904
	v_cvt_pk_bf16_f32 v18, v146, s0
	global_store_short v135, v18, s[88:89] offset:2080
	v_sub_f32_e32 v147, v147, v158
	v_mul_f32_e32 v147, v147, v159
	v_fma_f32 v147, v163, v147, v167
	v_add_f32_e32 v19, v19, v215
	v_mul_f32_e32 v19, 0xbfb8aa3b, v19
	v_exp_f32_e32 v19, v19
	v_lshlrev_b32_e32 v155, 16, v155
	v_add_f32_e32 v19, 1.0, v19
	v_div_scale_f32 v172, vcc, v19, v19, 1.0
	v_rcp_f32_e32 v173, v172
	s_nop 0
	v_fma_f32 v174, -v172, v173, 1.0
	v_fmac_f32_e32 v173, v174, v173
	v_div_scale_f32 v174, vcc, 1.0, v19, 1.0
	v_mul_f32_e32 v175, v174, v173
	v_fma_f32 v176, -v172, v175, v174
	v_fmac_f32_e32 v175, v176, v173
	v_fma_f32 v172, -v172, v175, v174
	v_div_fmas_f32 v172, v172, v173, v175
	v_div_fixup_f32 v19, v172, v19, 1.0
	v_mul_f32_e32 v19, v181, v19
	v_fmac_f32_e32 v147, v19, v155
	global_store_dword v130, v147, s[86:87] offset:192
	v_cvt_pk_bf16_f32 v19, v147, s0
	global_store_short v135, v19, s[88:89] offset:2144
	v_add_u32_e32 v130, 0x62000, v136
	v_lshrrev_b32_e32 v132, 1, v130
	global_load_dword v140, v130, s[86:87] offset:-4096
	global_load_dword v141, v130, s[86:87]
	global_load_dword v142, v130, s[86:87] offset:-4032
	global_load_dword v143, v130, s[86:87] offset:64
	global_load_dword v144, v130, s[86:87] offset:-3968
	global_load_dword v145, v130, s[86:87] offset:128
	global_load_dword v146, v130, s[86:87] offset:-3904
	global_load_dword v147, v130, s[86:87] offset:192
	global_load_ushort v148, v132, s[96:97] offset:-2048
	global_load_ushort v149, v132, s[96:97]
	global_load_ushort v150, v132, s[96:97] offset:-2016
	global_load_ushort v151, v132, s[96:97] offset:32
	global_load_ushort v152, v132, s[96:97] offset:-1984
	global_load_ushort v153, v132, s[96:97] offset:64
	global_load_ushort v154, v132, s[96:97] offset:-1952
	global_load_ushort v155, v132, s[96:97] offset:96
	global_load_dwordx4 v[156:159], v168, s[4:5] offset:784
	s_waitcnt vmcnt(0)
	v_sub_f32_e32 v140, v140, v156
	v_mul_f32_e32 v140, v140, v157
	v_fma_f32 v140, v160, v140, v164
	v_add_f32_e32 v32, v32, v138
	v_mul_f32_e32 v32, 0xbfb8aa3b, v32
	v_exp_f32_e32 v32, v32
	v_lshlrev_b32_e32 v148, 16, v148
	v_add_f32_e32 v32, 1.0, v32
	v_div_scale_f32 v172, vcc, v32, v32, 1.0
	v_rcp_f32_e32 v173, v172
	s_nop 0
	v_fma_f32 v174, -v172, v173, 1.0
	v_fmac_f32_e32 v173, v174, v173
	v_div_scale_f32 v174, vcc, 1.0, v32, 1.0
	v_mul_f32_e32 v175, v174, v173
	v_fma_f32 v176, -v172, v175, v174
	v_fmac_f32_e32 v175, v176, v173
	v_fma_f32 v172, -v172, v175, v174
	v_div_fmas_f32 v172, v172, v173, v175
	v_div_fixup_f32 v32, v172, v32, 1.0
	v_mul_f32_e32 v32, v181, v32
	v_fmac_f32_e32 v140, v32, v148
	global_store_dword v130, v140, s[86:87] offset:-4096
	v_cvt_pk_bf16_f32 v32, v140, s0
	global_store_short v134, v32, s[88:89] offset:2176
	v_sub_f32_e32 v141, v141, v158
	v_mul_f32_e32 v141, v141, v159
	v_fma_f32 v141, v160, v141, v164
	v_add_f32_e32 v33, v33, v138
	v_mul_f32_e32 v33, 0xbfb8aa3b, v33
	v_exp_f32_e32 v33, v33
	v_lshlrev_b32_e32 v149, 16, v149
	v_add_f32_e32 v33, 1.0, v33
	v_div_scale_f32 v172, vcc, v33, v33, 1.0
	v_rcp_f32_e32 v173, v172
	s_nop 0
	v_fma_f32 v174, -v172, v173, 1.0
	v_fmac_f32_e32 v173, v174, v173
	v_div_scale_f32 v174, vcc, 1.0, v33, 1.0
	v_mul_f32_e32 v175, v174, v173
	v_fma_f32 v176, -v172, v175, v174
	v_fmac_f32_e32 v175, v176, v173
	v_fma_f32 v172, -v172, v175, v174
	v_div_fmas_f32 v172, v172, v173, v175
; DEV u16 f2bf(float f) { return (u16)(pack2(f, 0.f) & 0xffffu); }
; DEV float bf2f(u16 b) { return __uint_as_float(((unsigned)b) << 16); }
; DEV size_t tixw(long row, int col, int W) { return (size_t)(row >> 8) * (256 * (size_t)W) + (size_t)(col >> 5) * 8192 + (size_t)(row & 255) * 32 + (col & 31); }
; DEV float sigmoidf_(float x) { return 1.f / (1.f + __expf(-x)); }
; DEV void phase_ln(const Params& P, const float* __restrict__ g, const float* __restrict__ bta, u16* __restrict__ xb, bool zero_kc) {
;     ...
;         y.x = v[r][i].x * rs * gv[i].x + bv[i].x;
;         y.y = v[r][i].y * rs * gv[i].y + bv[i].y;
;         y.z = v[r][i].z * rs * gv[i].z + bv[i].z;
;         y.w = v[r][i].w * rs * gv[i].w + bv[i].w;
;     ...
;       for (int ns = 0; ns < 4; ++ns)
; #pragma unroll
;         for (int j = 0; j < 4; ++j) {
;           int row = m0 + wm * 128 + ms * 16 + quad * 4 + j;
;           int col = n0 + wn * 64 + ns * 16 + l15;
;           size_t idx = (size_t)row * D + col;
;           float gate = sigmoidf_(acc[ms][ns][j] + bg[col]);
;           float v = P.out[idx] + psc * gate * bf2f(Pp[idx]);
;           P.out[idx] = v;
;           xbn[tixw(row, col, D)] = f2bf(v);
;         }
	v_div_fixup_f32 v33, v172, v33, 1.0
	v_mul_f32_e32 v33, v181, v33
	v_fmac_f32_e32 v141, v33, v149
	global_store_dword v130, v141, s[86:87]
	v_cvt_pk_bf16_f32 v33, v141, s0
	global_store_short v134, v33, s[88:89] offset:2240
	v_sub_f32_e32 v142, v142, v156
	v_mul_f32_e32 v142, v142, v157
	v_fma_f32 v142, v161, v142, v165
	v_add_f32_e32 v28, v28, v139
	v_mul_f32_e32 v28, 0xbfb8aa3b, v28
	v_exp_f32_e32 v28, v28
	v_lshlrev_b32_e32 v150, 16, v150
	v_add_f32_e32 v28, 1.0, v28
	v_div_scale_f32 v172, vcc, v28, v28, 1.0
	v_rcp_f32_e32 v173, v172
	s_nop 0
	v_fma_f32 v174, -v172, v173, 1.0
	v_fmac_f32_e32 v173, v174, v173
	v_div_scale_f32 v174, vcc, 1.0, v28, 1.0
	v_mul_f32_e32 v175, v174, v173
	v_fma_f32 v176, -v172, v175, v174
	v_fmac_f32_e32 v175, v176, v173
	v_fma_f32 v172, -v172, v175, v174
	v_div_fmas_f32 v172, v172, v173, v175
	v_div_fixup_f32 v28, v172, v28, 1.0
	v_mul_f32_e32 v28, v181, v28
	v_fmac_f32_e32 v142, v28, v150
	global_store_dword v130, v142, s[86:87] offset:-4032
	v_cvt_pk_bf16_f32 v28, v142, s0
	global_store_short v134, v28, s[88:89] offset:2208
	v_sub_f32_e32 v143, v143, v158
	v_mul_f32_e32 v143, v143, v159
	v_fma_f32 v143, v161, v143, v165
	v_add_f32_e32 v29, v29, v139
	v_mul_f32_e32 v29, 0xbfb8aa3b, v29
	v_exp_f32_e32 v29, v29
	v_lshlrev_b32_e32 v151, 16, v151
	v_add_f32_e32 v29, 1.0, v29
	v_div_scale_f32 v172, vcc, v29, v29, 1.0
	v_rcp_f32_e32 v173, v172
	s_nop 0
	v_fma_f32 v174, -v172, v173, 1.0
	v_fmac_f32_e32 v173, v174, v173
	v_div_scale_f32 v174, vcc, 1.0, v29, 1.0
	v_mul_f32_e32 v175, v174, v173
	v_fma_f32 v176, -v172, v175, v174
	v_fmac_f32_e32 v175, v176, v173
	v_fma_f32 v172, -v172, v175, v174
	v_div_fmas_f32 v172, v172, v173, v175
	v_div_fixup_f32 v29, v172, v29, 1.0
	v_mul_f32_e32 v29, v181, v29
	v_fmac_f32_e32 v143, v29, v151
	global_store_dword v130, v143, s[86:87] offset:64
	v_cvt_pk_bf16_f32 v29, v143, s0
	global_store_short v134, v29, s[88:89] offset:2272
	v_sub_f32_e32 v144, v144, v156
	v_mul_f32_e32 v144, v144, v157
	v_fma_f32 v144, v162, v144, v166
	v_add_f32_e32 v24, v24, v214
	v_mul_f32_e32 v24, 0xbfb8aa3b, v24
	v_exp_f32_e32 v24, v24
	v_lshlrev_b32_e32 v152, 16, v152
	v_add_f32_e32 v24, 1.0, v24
	v_div_scale_f32 v172, vcc, v24, v24, 1.0
	v_rcp_f32_e32 v173, v172
	s_nop 0
	v_fma_f32 v174, -v172, v173, 1.0
	v_fmac_f32_e32 v173, v174, v173
	v_div_scale_f32 v174, vcc, 1.0, v24, 1.0
	v_mul_f32_e32 v175, v174, v173
	v_fma_f32 v176, -v172, v175, v174
	v_fmac_f32_e32 v175, v176, v173
	v_fma_f32 v172, -v172, v175, v174
	v_div_fmas_f32 v172, v172, v173, v175
	v_div_fixup_f32 v24, v172, v24, 1.0
	v_mul_f32_e32 v24, v181, v24
	v_fmac_f32_e32 v144, v24, v152
	global_store_dword v130, v144, s[86:87] offset:-3968
	v_cvt_pk_bf16_f32 v24, v144, s0
	global_store_short v135, v24, s[88:89] offset:2176
	v_sub_f32_e32 v145, v145, v158
	v_mul_f32_e32 v145, v145, v159
	v_fma_f32 v145, v162, v145, v166
	v_add_f32_e32 v25, v25, v214
	v_mul_f32_e32 v25, 0xbfb8aa3b, v25
	v_exp_f32_e32 v25, v25
	v_lshlrev_b32_e32 v153, 16, v153
	v_add_f32_e32 v25, 1.0, v25
	v_div_scale_f32 v172, vcc, v25, v25, 1.0
	v_rcp_f32_e32 v173, v172
	s_nop 0
	v_fma_f32 v174, -v172, v173, 1.0
	v_fmac_f32_e32 v173, v174, v173
	v_div_scale_f32 v174, vcc, 1.0, v25, 1.0
	v_mul_f32_e32 v175, v174, v173
	v_fma_f32 v176, -v172, v175, v174
	v_fmac_f32_e32 v175, v176, v173
	v_fma_f32 v172, -v172, v175, v174
	v_div_fmas_f32 v172, v172, v173, v175
	v_div_fixup_f32 v25, v172, v25, 1.0
	v_mul_f32_e32 v25, v181, v25
	v_fmac_f32_e32 v145, v25, v153
	global_store_dword v130, v145, s[86:87] offset:128
	v_cvt_pk_bf16_f32 v25, v145, s0
	global_store_short v135, v25, s[88:89] offset:2240
	v_sub_f32_e32 v146, v146, v156
	v_mul_f32_e32 v146, v146, v157
	v_fma_f32 v146, v163, v146, v167
	v_add_f32_e32 v20, v20, v215
	v_mul_f32_e32 v20, 0xbfb8aa3b, v20
	v_exp_f32_e32 v20, v20
	v_lshlrev_b32_e32 v154, 16, v154
	v_add_f32_e32 v20, 1.0, v20
	v_div_scale_f32 v172, vcc, v20, v20, 1.0
	v_rcp_f32_e32 v173, v172
	s_nop 0
	v_fma_f32 v174, -v172, v173, 1.0
	v_fmac_f32_e32 v173, v174, v173
	v_div_scale_f32 v174, vcc, 1.0, v20, 1.0
	v_mul_f32_e32 v175, v174, v173
	v_fma_f32 v176, -v172, v175, v174
	v_fmac_f32_e32 v175, v176, v173
	v_fma_f32 v172, -v172, v175, v174
	v_div_fmas_f32 v172, v172, v173, v175
	v_div_fixup_f32 v20, v172, v20, 1.0
	v_mul_f32_e32 v20, v181, v20
	v_fmac_f32_e32 v146, v20, v154
	global_store_dword v130, v146, s[86:87] offset:-3904
	v_cvt_pk_bf16_f32 v20, v146, s0
	global_store_short v135, v20, s[88:89] offset:2208
	v_sub_f32_e32 v147, v147, v158
	v_mul_f32_e32 v147, v147, v159
	v_fma_f32 v147, v163, v147, v167
	v_add_f32_e32 v21, v21, v215
	v_mul_f32_e32 v21, 0xbfb8aa3b, v21
	v_exp_f32_e32 v21, v21
	v_lshlrev_b32_e32 v155, 16, v155
	v_add_f32_e32 v21, 1.0, v21
	v_div_scale_f32 v172, vcc, v21, v21, 1.0
	v_rcp_f32_e32 v173, v172
	s_nop 0
	v_fma_f32 v174, -v172, v173, 1.0
	v_fmac_f32_e32 v173, v174, v173
	v_div_scale_f32 v174, vcc, 1.0, v21, 1.0
	v_mul_f32_e32 v175, v174, v173
	v_fma_f32 v176, -v172, v175, v174
	v_fmac_f32_e32 v175, v176, v173
	v_fma_f32 v172, -v172, v175, v174
	v_div_fmas_f32 v172, v172, v173, v175
	v_div_fixup_f32 v21, v172, v21, 1.0
	v_mul_f32_e32 v21, v181, v21
	v_fmac_f32_e32 v147, v21, v155
	global_store_dword v130, v147, s[86:87] offset:192
	v_cvt_pk_bf16_f32 v21, v147, s0
	global_store_short v135, v21, s[88:89] offset:2272
	v_add_u32_e32 v130, 0x70000, v136
	v_lshrrev_b32_e32 v132, 1, v130
	global_load_dword v140, v130, s[86:87] offset:-4096
	global_load_dword v141, v130, s[86:87]
	global_load_dword v142, v130, s[86:87] offset:-4032
	global_load_dword v143, v130, s[86:87] offset:64
	global_load_dword v144, v130, s[86:87] offset:-3968
	global_load_dword v145, v130, s[86:87] offset:128
	global_load_dword v146, v130, s[86:87] offset:-3904
	global_load_dword v147, v130, s[86:87] offset:192
	global_load_ushort v148, v132, s[96:97] offset:-2048
	global_load_ushort v149, v132, s[96:97]
	global_load_ushort v150, v132, s[96:97] offset:-2016
	global_load_ushort v151, v132, s[96:97] offset:32
	global_load_ushort v152, v132, s[96:97] offset:-1984
	global_load_ushort v153, v132, s[96:97] offset:64
	global_load_ushort v154, v132, s[96:97] offset:-1952
	global_load_ushort v155, v132, s[96:97] offset:96
	global_load_dwordx4 v[156:159], v168, s[4:5] offset:896
	s_waitcnt vmcnt(0)
; DEV u16 f2bf(float f) { return (u16)(pack2(f, 0.f) & 0xffffu); }
; DEV float bf2f(u16 b) { return __uint_as_float(((unsigned)b) << 16); }
; DEV size_t tixw(long row, int col, int W) { return (size_t)(row >> 8) * (256 * (size_t)W) + (size_t)(col >> 5) * 8192 + (size_t)(row & 255) * 32 + (col & 31); }
; DEV float sigmoidf_(float x) { return 1.f / (1.f + __expf(-x)); }
; DEV void phase_ln(const Params& P, const float* __restrict__ g, const float* __restrict__ bta, u16* __restrict__ xb, bool zero_kc) {
;     ...
;         y.x = v[r][i].x * rs * gv[i].x + bv[i].x;
;         y.y = v[r][i].y * rs * gv[i].y + bv[i].y;
;         y.z = v[r][i].z * rs * gv[i].z + bv[i].z;
;         y.w = v[r][i].w * rs * gv[i].w + bv[i].w;
;     ...
;       for (int ns = 0; ns < 4; ++ns)
; #pragma unroll
;         for (int j = 0; j < 4; ++j) {
;           int row = m0 + wm * 128 + ms * 16 + quad * 4 + j;
;           int col = n0 + wn * 64 + ns * 16 + l15;
;           size_t idx = (size_t)row * D + col;
;           float gate = sigmoidf_(acc[ms][ns][j] + bg[col]);
;           float v = P.out[idx] + psc * gate * bf2f(Pp[idx]);
;           P.out[idx] = v;
;           xbn[tixw(row, col, D)] = f2bf(v);
;         }
	v_sub_f32_e32 v140, v140, v156
	v_mul_f32_e32 v140, v140, v157
	v_fma_f32 v140, v160, v140, v164
	v_add_f32_e32 v14, v14, v138
	v_mul_f32_e32 v14, 0xbfb8aa3b, v14
	v_exp_f32_e32 v14, v14
	v_lshlrev_b32_e32 v148, 16, v148
	v_add_f32_e32 v14, 1.0, v14
	v_div_scale_f32 v172, vcc, v14, v14, 1.0
	v_rcp_f32_e32 v173, v172
	s_nop 0
	v_fma_f32 v174, -v172, v173, 1.0
	v_fmac_f32_e32 v173, v174, v173
	v_div_scale_f32 v174, vcc, 1.0, v14, 1.0
	v_mul_f32_e32 v175, v174, v173
	v_fma_f32 v176, -v172, v175, v174
	v_fmac_f32_e32 v175, v176, v173
	v_fma_f32 v172, -v172, v175, v174
	v_div_fmas_f32 v172, v172, v173, v175
	v_div_fixup_f32 v14, v172, v14, 1.0
	v_mul_f32_e32 v14, v181, v14
	v_fmac_f32_e32 v140, v14, v148
	global_store_dword v130, v140, s[86:87] offset:-4096
	v_cvt_pk_bf16_f32 v14, v140, s0
	global_store_short v134, v14, s[88:89] offset:3072
	v_sub_f32_e32 v141, v141, v158
	v_mul_f32_e32 v141, v141, v159
	v_fma_f32 v141, v160, v141, v164
	v_add_f32_e32 v15, v15, v138
	v_mul_f32_e32 v15, 0xbfb8aa3b, v15
	v_exp_f32_e32 v15, v15
	v_lshlrev_b32_e32 v149, 16, v149
	v_add_f32_e32 v15, 1.0, v15
	v_div_scale_f32 v172, vcc, v15, v15, 1.0
	v_rcp_f32_e32 v173, v172
	s_nop 0
	v_fma_f32 v174, -v172, v173, 1.0
	v_fmac_f32_e32 v173, v174, v173
	v_div_scale_f32 v174, vcc, 1.0, v15, 1.0
	v_mul_f32_e32 v175, v174, v173
	v_fma_f32 v176, -v172, v175, v174
	v_fmac_f32_e32 v175, v176, v173
	v_fma_f32 v172, -v172, v175, v174
	v_div_fmas_f32 v172, v172, v173, v175
	v_div_fixup_f32 v15, v172, v15, 1.0
	v_mul_f32_e32 v15, v181, v15
	v_fmac_f32_e32 v141, v15, v149
	global_store_dword v130, v141, s[86:87]
	v_cvt_pk_bf16_f32 v15, v141, s0
	global_store_short v134, v15, s[88:89] offset:3136
	v_sub_f32_e32 v142, v142, v156
	v_mul_f32_e32 v142, v142, v157
	v_fma_f32 v142, v161, v142, v165
	v_add_f32_e32 v10, v10, v139
	v_mul_f32_e32 v10, 0xbfb8aa3b, v10
	v_exp_f32_e32 v10, v10
	v_lshlrev_b32_e32 v150, 16, v150
	v_add_f32_e32 v10, 1.0, v10
	v_div_scale_f32 v172, vcc, v10, v10, 1.0
	v_rcp_f32_e32 v173, v172
	s_nop 0
	v_fma_f32 v174, -v172, v173, 1.0
	v_fmac_f32_e32 v173, v174, v173
	v_div_scale_f32 v174, vcc, 1.0, v10, 1.0
	v_mul_f32_e32 v175, v174, v173
	v_fma_f32 v176, -v172, v175, v174
	v_fmac_f32_e32 v175, v176, v173
	v_fma_f32 v172, -v172, v175, v174
	v_div_fmas_f32 v172, v172, v173, v175
	v_div_fixup_f32 v10, v172, v10, 1.0
	v_mul_f32_e32 v10, v181, v10
	v_fmac_f32_e32 v142, v10, v150
	global_store_dword v130, v142, s[86:87] offset:-4032
	v_cvt_pk_bf16_f32 v10, v142, s0
	global_store_short v134, v10, s[88:89] offset:3104
	v_sub_f32_e32 v143, v143, v158
	v_mul_f32_e32 v143, v143, v159
	v_fma_f32 v143, v161, v143, v165
	v_add_f32_e32 v11, v11, v139
	v_mul_f32_e32 v11, 0xbfb8aa3b, v11
	v_exp_f32_e32 v11, v11
	v_lshlrev_b32_e32 v151, 16, v151
	v_add_f32_e32 v11, 1.0, v11
	v_div_scale_f32 v172, vcc, v11, v11, 1.0
	v_rcp_f32_e32 v173, v172
	s_nop 0
	v_fma_f32 v174, -v172, v173, 1.0
	v_fmac_f32_e32 v173, v174, v173
	v_div_scale_f32 v174, vcc, 1.0, v11, 1.0
	v_mul_f32_e32 v175, v174, v173
	v_fma_f32 v176, -v172, v175, v174
	v_fmac_f32_e32 v175, v176, v173
	v_fma_f32 v172, -v172, v175, v174
	v_div_fmas_f32 v172, v172, v173, v175
	v_div_fixup_f32 v11, v172, v11, 1.0
	v_mul_f32_e32 v11, v181, v11
	v_fmac_f32_e32 v143, v11, v151
	global_store_dword v130, v143, s[86:87] offset:64
	v_cvt_pk_bf16_f32 v11, v143, s0
	global_store_short v134, v11, s[88:89] offset:3168
	v_sub_f32_e32 v144, v144, v156
	v_mul_f32_e32 v144, v144, v157
	v_fma_f32 v144, v162, v144, v166
	v_add_f32_e32 v6, v6, v214
	v_mul_f32_e32 v6, 0xbfb8aa3b, v6
	v_exp_f32_e32 v6, v6
	v_lshlrev_b32_e32 v152, 16, v152
	v_add_f32_e32 v6, 1.0, v6
	v_div_scale_f32 v172, vcc, v6, v6, 1.0
	v_rcp_f32_e32 v173, v172
	s_nop 0
	v_fma_f32 v174, -v172, v173, 1.0
	v_fmac_f32_e32 v173, v174, v173
	v_div_scale_f32 v174, vcc, 1.0, v6, 1.0
	v_mul_f32_e32 v175, v174, v173
	v_fma_f32 v176, -v172, v175, v174
	v_fmac_f32_e32 v175, v176, v173
	v_fma_f32 v172, -v172, v175, v174
	v_div_fmas_f32 v172, v172, v173, v175
	v_div_fixup_f32 v6, v172, v6, 1.0
	v_mul_f32_e32 v6, v181, v6
	v_fmac_f32_e32 v144, v6, v152
	global_store_dword v130, v144, s[86:87] offset:-3968
	v_cvt_pk_bf16_f32 v6, v144, s0
	global_store_short v135, v6, s[88:89] offset:3072
	v_sub_f32_e32 v145, v145, v158
	v_mul_f32_e32 v145, v145, v159
	v_fma_f32 v145, v162, v145, v166
	v_add_f32_e32 v7, v7, v214
	v_mul_f32_e32 v7, 0xbfb8aa3b, v7
	v_exp_f32_e32 v7, v7
	v_lshlrev_b32_e32 v153, 16, v153
	v_add_f32_e32 v7, 1.0, v7
	v_div_scale_f32 v172, vcc, v7, v7, 1.0
	v_rcp_f32_e32 v173, v172
	s_nop 0
	v_fma_f32 v174, -v172, v173, 1.0
	v_fmac_f32_e32 v173, v174, v173
	v_div_scale_f32 v174, vcc, 1.0, v7, 1.0
	v_mul_f32_e32 v175, v174, v173
	v_fma_f32 v176, -v172, v175, v174
	v_fmac_f32_e32 v175, v176, v173
	v_fma_f32 v172, -v172, v175, v174
	v_div_fmas_f32 v172, v172, v173, v175
	v_div_fixup_f32 v7, v172, v7, 1.0
	v_mul_f32_e32 v7, v181, v7
	v_fmac_f32_e32 v145, v7, v153
	global_store_dword v130, v145, s[86:87] offset:128
	v_cvt_pk_bf16_f32 v7, v145, s0
	global_store_short v135, v7, s[88:89] offset:3136
	v_sub_f32_e32 v146, v146, v156
	v_mul_f32_e32 v146, v146, v157
	v_fma_f32 v146, v163, v146, v167
	v_add_f32_e32 v2, v2, v215
	v_mul_f32_e32 v2, 0xbfb8aa3b, v2
	v_exp_f32_e32 v2, v2
	v_lshlrev_b32_e32 v154, 16, v154
	v_add_f32_e32 v2, 1.0, v2
	v_div_scale_f32 v172, vcc, v2, v2, 1.0
	v_rcp_f32_e32 v173, v172
	s_nop 0
	v_fma_f32 v174, -v172, v173, 1.0
	v_fmac_f32_e32 v173, v174, v173
	v_div_scale_f32 v174, vcc, 1.0, v2, 1.0
	v_mul_f32_e32 v175, v174, v173
	v_fma_f32 v176, -v172, v175, v174
	v_fmac_f32_e32 v175, v176, v173
	v_fma_f32 v172, -v172, v175, v174
	v_div_fmas_f32 v172, v172, v173, v175
; DEV u16 f2bf(float f) { return (u16)(pack2(f, 0.f) & 0xffffu); }
; DEV float bf2f(u16 b) { return __uint_as_float(((unsigned)b) << 16); }
; DEV size_t tixw(long row, int col, int W) { return (size_t)(row >> 8) * (256 * (size_t)W) + (size_t)(col >> 5) * 8192 + (size_t)(row & 255) * 32 + (col & 31); }
; DEV float sigmoidf_(float x) { return 1.f / (1.f + __expf(-x)); }
; DEV void phase_ln(const Params& P, const float* __restrict__ g, const float* __restrict__ bta, u16* __restrict__ xb, bool zero_kc) {
;     ...
;         y.x = v[r][i].x * rs * gv[i].x + bv[i].x;
;         y.y = v[r][i].y * rs * gv[i].y + bv[i].y;
;         y.z = v[r][i].z * rs * gv[i].z + bv[i].z;
;         y.w = v[r][i].w * rs * gv[i].w + bv[i].w;
;     ...
;       for (int ns = 0; ns < 4; ++ns)
; #pragma unroll
;         for (int j = 0; j < 4; ++j) {
;           int row = m0 + wm * 128 + ms * 16 + quad * 4 + j;
;           int col = n0 + wn * 64 + ns * 16 + l15;
;           size_t idx = (size_t)row * D + col;
;           float gate = sigmoidf_(acc[ms][ns][j] + bg[col]);
;           float v = P.out[idx] + psc * gate * bf2f(Pp[idx]);
;           P.out[idx] = v;
;           xbn[tixw(row, col, D)] = f2bf(v);
;         }
	v_div_fixup_f32 v2, v172, v2, 1.0
	v_mul_f32_e32 v2, v181, v2
	v_fmac_f32_e32 v146, v2, v154
	global_store_dword v130, v146, s[86:87] offset:-3904
	v_cvt_pk_bf16_f32 v2, v146, s0
	global_store_short v135, v2, s[88:89] offset:3104
	v_sub_f32_e32 v147, v147, v158
	v_mul_f32_e32 v147, v147, v159
	v_fma_f32 v147, v163, v147, v167
	v_add_f32_e32 v3, v3, v215
	v_mul_f32_e32 v3, 0xbfb8aa3b, v3
	v_exp_f32_e32 v3, v3
	v_lshlrev_b32_e32 v155, 16, v155
	v_add_f32_e32 v3, 1.0, v3
	v_div_scale_f32 v172, vcc, v3, v3, 1.0
	v_rcp_f32_e32 v173, v172
	s_nop 0
	v_fma_f32 v174, -v172, v173, 1.0
	v_fmac_f32_e32 v173, v174, v173
	v_div_scale_f32 v174, vcc, 1.0, v3, 1.0
	v_mul_f32_e32 v175, v174, v173
	v_fma_f32 v176, -v172, v175, v174
	v_fmac_f32_e32 v175, v176, v173
	v_fma_f32 v172, -v172, v175, v174
	v_div_fmas_f32 v172, v172, v173, v175
	v_div_fixup_f32 v3, v172, v3, 1.0
	v_mul_f32_e32 v3, v181, v3
	v_fmac_f32_e32 v147, v3, v155
	global_store_dword v130, v147, s[86:87] offset:192
	v_cvt_pk_bf16_f32 v3, v147, s0
	global_store_short v135, v3, s[88:89] offset:3168
	v_add_u32_e32 v130, 0x72000, v136
	v_lshrrev_b32_e32 v132, 1, v130
	global_load_dword v140, v130, s[86:87] offset:-4096
	global_load_dword v141, v130, s[86:87]
	global_load_dword v142, v130, s[86:87] offset:-4032
	global_load_dword v143, v130, s[86:87] offset:64
	global_load_dword v144, v130, s[86:87] offset:-3968
	global_load_dword v145, v130, s[86:87] offset:128
	global_load_dword v146, v130, s[86:87] offset:-3904
	global_load_dword v147, v130, s[86:87] offset:192
	global_load_ushort v148, v132, s[96:97] offset:-2048
	global_load_ushort v149, v132, s[96:97]
	global_load_ushort v150, v132, s[96:97] offset:-2016
	global_load_ushort v151, v132, s[96:97] offset:32
	global_load_ushort v152, v132, s[96:97] offset:-1984
	global_load_ushort v153, v132, s[96:97] offset:64
	global_load_ushort v154, v132, s[96:97] offset:-1952
	global_load_ushort v155, v132, s[96:97] offset:96
	global_load_dwordx4 v[156:159], v168, s[4:5] offset:912
	s_waitcnt vmcnt(0)
; DEV u16 f2bf(float f) { return (u16)(pack2(f, 0.f) & 0xffffu); }
; DEV float bf2f(u16 b) { return __uint_as_float(((unsigned)b) << 16); }
; DEV size_t tixw(long row, int col, int W) { return (size_t)(row >> 8) * (256 * (size_t)W) + (size_t)(col >> 5) * 8192 + (size_t)(row & 255) * 32 + (col & 31); }
; DEV float sigmoidf_(float x) { return 1.f / (1.f + __expf(-x)); }
; DEV void phase_ln(const Params& P, const float* __restrict__ g, const float* __restrict__ bta, u16* __restrict__ xb, bool zero_kc) {
;     ...
;         y.x = v[r][i].x * rs * gv[i].x + bv[i].x;
;         y.y = v[r][i].y * rs * gv[i].y + bv[i].y;
;         y.z = v[r][i].z * rs * gv[i].z + bv[i].z;
;         y.w = v[r][i].w * rs * gv[i].w + bv[i].w;
;     ...
;       for (int ns = 0; ns < 4; ++ns)
; #pragma unroll
;         for (int j = 0; j < 4; ++j) {
;           int row = m0 + wm * 128 + ms * 16 + quad * 4 + j;
;           int col = n0 + wn * 64 + ns * 16 + l15;
;           size_t idx = (size_t)row * D + col;
;           float gate = sigmoidf_(acc[ms][ns][j] + bg[col]);
;           float v = P.out[idx] + psc * gate * bf2f(Pp[idx]);
;           P.out[idx] = v;
;           xbn[tixw(row, col, D)] = f2bf(v);
;         }
	v_sub_f32_e32 v140, v140, v156
	v_mul_f32_e32 v140, v140, v157
	v_fma_f32 v140, v160, v140, v164
	v_add_f32_e32 v16, v16, v138
	v_mul_f32_e32 v16, 0xbfb8aa3b, v16
	v_exp_f32_e32 v16, v16
	v_lshlrev_b32_e32 v148, 16, v148
	v_add_f32_e32 v16, 1.0, v16
	v_div_scale_f32 v172, vcc, v16, v16, 1.0
	v_rcp_f32_e32 v173, v172
	s_nop 0
	v_fma_f32 v174, -v172, v173, 1.0
	v_fmac_f32_e32 v173, v174, v173
	v_div_scale_f32 v174, vcc, 1.0, v16, 1.0
	v_mul_f32_e32 v175, v174, v173
	v_fma_f32 v176, -v172, v175, v174
	v_fmac_f32_e32 v175, v176, v173
	v_fma_f32 v172, -v172, v175, v174
	v_div_fmas_f32 v172, v172, v173, v175
	v_div_fixup_f32 v16, v172, v16, 1.0
	v_mul_f32_e32 v16, v181, v16
	v_fmac_f32_e32 v140, v16, v148
	global_store_dword v130, v140, s[86:87] offset:-4096
	v_cvt_pk_bf16_f32 v16, v140, s0
	global_store_short v134, v16, s[88:89] offset:3200
	v_sub_f32_e32 v141, v141, v158
	v_mul_f32_e32 v141, v141, v159
	v_fma_f32 v141, v160, v141, v164
	v_add_f32_e32 v17, v17, v138
	v_mul_f32_e32 v17, 0xbfb8aa3b, v17
	v_exp_f32_e32 v17, v17
	v_lshlrev_b32_e32 v149, 16, v149
	v_add_f32_e32 v17, 1.0, v17
	v_div_scale_f32 v172, vcc, v17, v17, 1.0
	v_rcp_f32_e32 v173, v172
	s_nop 0
	v_fma_f32 v174, -v172, v173, 1.0
	v_fmac_f32_e32 v173, v174, v173
	v_div_scale_f32 v174, vcc, 1.0, v17, 1.0
	v_mul_f32_e32 v175, v174, v173
	v_fma_f32 v176, -v172, v175, v174
	v_fmac_f32_e32 v175, v176, v173
	v_fma_f32 v172, -v172, v175, v174
	v_div_fmas_f32 v172, v172, v173, v175
	v_div_fixup_f32 v17, v172, v17, 1.0
	v_mul_f32_e32 v17, v181, v17
	v_fmac_f32_e32 v141, v17, v149
	global_store_dword v130, v141, s[86:87]
	v_cvt_pk_bf16_f32 v17, v141, s0
	global_store_short v134, v17, s[88:89] offset:3264
	v_sub_f32_e32 v142, v142, v156
	v_mul_f32_e32 v142, v142, v157
	v_fma_f32 v142, v161, v142, v165
	v_add_f32_e32 v12, v12, v139
	v_mul_f32_e32 v12, 0xbfb8aa3b, v12
	v_exp_f32_e32 v12, v12
	v_lshlrev_b32_e32 v150, 16, v150
	v_add_f32_e32 v12, 1.0, v12
	v_div_scale_f32 v172, vcc, v12, v12, 1.0
	v_rcp_f32_e32 v173, v172
	s_nop 0
	v_fma_f32 v174, -v172, v173, 1.0
	v_fmac_f32_e32 v173, v174, v173
	v_div_scale_f32 v174, vcc, 1.0, v12, 1.0
	v_mul_f32_e32 v175, v174, v173
	v_fma_f32 v176, -v172, v175, v174
	v_fmac_f32_e32 v175, v176, v173
	v_fma_f32 v172, -v172, v175, v174
	v_div_fmas_f32 v172, v172, v173, v175
	v_div_fixup_f32 v12, v172, v12, 1.0
	v_mul_f32_e32 v12, v181, v12
	v_fmac_f32_e32 v142, v12, v150
	global_store_dword v130, v142, s[86:87] offset:-4032
	v_cvt_pk_bf16_f32 v12, v142, s0
	global_store_short v134, v12, s[88:89] offset:3232
	v_sub_f32_e32 v143, v143, v158
	v_mul_f32_e32 v143, v143, v159
	v_fma_f32 v143, v161, v143, v165
	v_add_f32_e32 v13, v13, v139
	v_mul_f32_e32 v13, 0xbfb8aa3b, v13
	v_exp_f32_e32 v13, v13
	v_lshlrev_b32_e32 v151, 16, v151
	v_add_f32_e32 v13, 1.0, v13
	v_div_scale_f32 v172, vcc, v13, v13, 1.0
	v_rcp_f32_e32 v173, v172
	s_nop 0
	v_fma_f32 v174, -v172, v173, 1.0
	v_fmac_f32_e32 v173, v174, v173
	v_div_scale_f32 v174, vcc, 1.0, v13, 1.0
	v_mul_f32_e32 v175, v174, v173
	v_fma_f32 v176, -v172, v175, v174
	v_fmac_f32_e32 v175, v176, v173
	v_fma_f32 v172, -v172, v175, v174
	v_div_fmas_f32 v172, v172, v173, v175
	v_div_fixup_f32 v13, v172, v13, 1.0
	v_mul_f32_e32 v13, v181, v13
	v_fmac_f32_e32 v143, v13, v151
	global_store_dword v130, v143, s[86:87] offset:64
	v_cvt_pk_bf16_f32 v13, v143, s0
	global_store_short v134, v13, s[88:89] offset:3296
	v_sub_f32_e32 v144, v144, v156
	v_mul_f32_e32 v144, v144, v157
	v_fma_f32 v144, v162, v144, v166
	v_add_f32_e32 v8, v8, v214
	v_mul_f32_e32 v8, 0xbfb8aa3b, v8
	v_exp_f32_e32 v8, v8
	v_lshlrev_b32_e32 v152, 16, v152
	v_add_f32_e32 v8, 1.0, v8
	v_div_scale_f32 v172, vcc, v8, v8, 1.0
	v_rcp_f32_e32 v173, v172
	s_nop 0
	v_fma_f32 v174, -v172, v173, 1.0
	v_fmac_f32_e32 v173, v174, v173
	v_div_scale_f32 v174, vcc, 1.0, v8, 1.0
	v_mul_f32_e32 v175, v174, v173
	v_fma_f32 v176, -v172, v175, v174
	v_fmac_f32_e32 v175, v176, v173
	v_fma_f32 v172, -v172, v175, v174
	v_div_fmas_f32 v172, v172, v173, v175
	v_div_fixup_f32 v8, v172, v8, 1.0
	v_mul_f32_e32 v8, v181, v8
	v_fmac_f32_e32 v144, v8, v152
	global_store_dword v130, v144, s[86:87] offset:-3968
	v_cvt_pk_bf16_f32 v8, v144, s0
	global_store_short v135, v8, s[88:89] offset:3200
	v_sub_f32_e32 v145, v145, v158
	v_mul_f32_e32 v145, v145, v159
	v_fma_f32 v145, v162, v145, v166
	v_add_f32_e32 v9, v9, v214
	v_mul_f32_e32 v9, 0xbfb8aa3b, v9
	v_exp_f32_e32 v9, v9
	v_lshlrev_b32_e32 v153, 16, v153
	v_add_f32_e32 v9, 1.0, v9
	v_div_scale_f32 v172, vcc, v9, v9, 1.0
	v_rcp_f32_e32 v173, v172
	s_nop 0
	v_fma_f32 v174, -v172, v173, 1.0
	v_fmac_f32_e32 v173, v174, v173
	v_div_scale_f32 v174, vcc, 1.0, v9, 1.0
	v_mul_f32_e32 v175, v174, v173
	v_fma_f32 v176, -v172, v175, v174
	v_fmac_f32_e32 v175, v176, v173
	v_fma_f32 v172, -v172, v175, v174
	v_div_fmas_f32 v172, v172, v173, v175
	v_div_fixup_f32 v9, v172, v9, 1.0
	v_mul_f32_e32 v9, v181, v9
	v_fmac_f32_e32 v145, v9, v153
	global_store_dword v130, v145, s[86:87] offset:128
	v_cvt_pk_bf16_f32 v9, v145, s0
	global_store_short v135, v9, s[88:89] offset:3264
	v_sub_f32_e32 v146, v146, v156
	v_mul_f32_e32 v146, v146, v157
	v_fma_f32 v146, v163, v146, v167
	v_add_f32_e32 v4, v4, v215
	v_mul_f32_e32 v4, 0xbfb8aa3b, v4
	v_exp_f32_e32 v4, v4
	v_lshlrev_b32_e32 v154, 16, v154
	v_add_f32_e32 v4, 1.0, v4
	v_div_scale_f32 v172, vcc, v4, v4, 1.0
	v_rcp_f32_e32 v173, v172
	s_nop 0
	v_fma_f32 v174, -v172, v173, 1.0
	v_fmac_f32_e32 v173, v174, v173
	v_div_scale_f32 v174, vcc, 1.0, v4, 1.0
	v_mul_f32_e32 v175, v174, v173
	v_fma_f32 v176, -v172, v175, v174
	v_fmac_f32_e32 v175, v176, v173
	v_fma_f32 v172, -v172, v175, v174
	v_div_fmas_f32 v172, v172, v173, v175
	v_div_fixup_f32 v4, v172, v4, 1.0
	v_mul_f32_e32 v4, v181, v4
	v_fmac_f32_e32 v146, v4, v154
	global_store_dword v130, v146, s[86:87] offset:-3904
	v_cvt_pk_bf16_f32 v4, v146, s0
	global_store_short v135, v4, s[88:89] offset:3232
	v_sub_f32_e32 v147, v147, v158
	v_mul_f32_e32 v147, v147, v159
	v_fma_f32 v147, v163, v147, v167
	v_add_f32_e32 v5, v5, v215
	v_mul_f32_e32 v5, 0xbfb8aa3b, v5
	v_exp_f32_e32 v5, v5
	v_lshlrev_b32_e32 v155, 16, v155
	v_add_f32_e32 v5, 1.0, v5
	v_div_scale_f32 v172, vcc, v5, v5, 1.0
	v_rcp_f32_e32 v173, v172
	s_nop 0
	v_fma_f32 v174, -v172, v173, 1.0
	v_fmac_f32_e32 v173, v174, v173
	v_div_scale_f32 v174, vcc, 1.0, v5, 1.0
	v_mul_f32_e32 v175, v174, v173
	v_fma_f32 v176, -v172, v175, v174
	v_fmac_f32_e32 v175, v176, v173
	v_fma_f32 v172, -v172, v175, v174
	v_div_fmas_f32 v172, v172, v173, v175
	v_div_fixup_f32 v5, v172, v5, 1.0
	v_mul_f32_e32 v5, v181, v5
	v_fmac_f32_e32 v147, v5, v155
	global_store_dword v130, v147, s[86:87] offset:192
	v_cvt_pk_bf16_f32 v5, v147, s0
	global_store_short v135, v5, s[88:89] offset:3296
	s_and_b64 vcc, exec, s[10:11]
	s_cbranch_vccnz .LBB0_91

; DEV void phase_ln(const Params& P, const float* __restrict__ g, const float* __restrict__ bta, u16* __restrict__ xb, bool zero_kc) {
;     ...
;   for (int row = gw; row < T; row += 2 * nw) {
;     const bool hasB = (row + nw) < T;
;     const int rows[2] = {row, hasB ? row + nw : row};
;     float4 v[2][4];
; #pragma unroll
;     for (int r = 0; r < 2; ++r) {
;       const float* xr = P.out + (size_t)rows[r] * D + lane * 4;
; #pragma unroll
;       for (int i = 0; i < 4; ++i) v[r][i] = *(const float4*)(xr + i * 256);
;     }
;     float s[2] = {0.f, 0.f};
; #pragma unroll
;     for (int r = 0; r < 2; ++r)
; #pragma unroll
;       for (int i = 0; i < 4; ++i) s[r] += v[r][i].x + v[r][i].y + v[r][i].z + v[r][i].w;
; #pragma unroll
;     for (int o = 32; o >= 1; o >>= 1) {
;       s[0] += __shfl_xor(s[0], o);
;       s[1] += __shfl_xor(s[1], o);
;     }
.LBB0_95:
.LBB0_96:
	v_readfirstlane_b32 s4, v34
	v_readlane_b32 s5, v254, 3
	s_mul_i32 s4, s4, 4
	s_mul_i32 s5, s5, 4
	v_and_b32_e32 v35, 63, v210
	v_lshlrev_b32_e32 v35, 4, v35
	v_add_u32_e32 v36, v52, v0
	v_add_u32_e32 v37, 0x20000, v36
	v_add_u32_e32 v38, 0x40000, v36
	v_add_u32_e32 v39, 0x60000, v36
	v_readlane_b32 s12, v255, 8
	s_add_i32 s12, s12, 2
	s_and_b32 s12, s12, 3
	s_lshl_b32 s12, s12, 24
	s_add_u32 s12, s12, 0x25080000
	s_add_u32 s12, s38, s12
	s_addc_u32 s13, s39, 0
.Lln_loop_1:
	s_add_i32 s8, s4, 0
	s_min_i32 s8, s8, 0x7fff
	s_lshl_b32 s8, s8, 12
	v_add_u32_e32 v72, s8, v35
	global_load_dwordx4 v[108:111], v72, s[86:87]
	global_load_dwordx4 v[112:115], v72, s[86:87] offset:1024
	global_load_dwordx4 v[116:119], v72, s[86:87] offset:2048
	global_load_dwordx4 v[120:123], v72, s[86:87] offset:3072
	s_add_i32 s8, s4, 1
	s_min_i32 s8, s8, 0x7fff
	s_lshl_b32 s8, s8, 12
	v_add_u32_e32 v73, s8, v35
	global_load_dwordx4 v[124:127], v73, s[86:87]
	global_load_dwordx4 v[128:131], v73, s[86:87] offset:1024
	global_load_dwordx4 v[132:135], v73, s[86:87] offset:2048
	global_load_dwordx4 v[136:139], v73, s[86:87] offset:3072
	s_add_i32 s8, s4, 2
	s_min_i32 s8, s8, 0x7fff
	s_lshl_b32 s8, s8, 12
	v_add_u32_e32 v74, s8, v35
	global_load_dwordx4 v[140:143], v74, s[86:87]
	global_load_dwordx4 v[144:147], v74, s[86:87] offset:1024
	global_load_dwordx4 v[148:151], v74, s[86:87] offset:2048
	global_load_dwordx4 v[152:155], v74, s[86:87] offset:3072
	s_add_i32 s8, s4, 3
	s_min_i32 s8, s8, 0x7fff
	s_lshl_b32 s8, s8, 12
	v_add_u32_e32 v75, s8, v35
	global_load_dwordx4 v[156:159], v75, s[86:87]
	global_load_dwordx4 v[160:163], v75, s[86:87] offset:1024
	global_load_dwordx4 v[164:167], v75, s[86:87] offset:2048
	global_load_dwordx4 v[168:171], v75, s[86:87] offset:3072
	s_waitcnt vmcnt(0)
	v_add_f32_e32 v42, v108, v109
	v_add_f32_e32 v42, v42, v110
	v_add_f32_e32 v42, v42, v111
	v_add_f32_e32 v60, v112, v113
	v_add_f32_e32 v60, v60, v114
	v_add_f32_e32 v60, v60, v115
	v_add_f32_e32 v42, v42, v60
	v_add_f32_e32 v60, v116, v117
	v_add_f32_e32 v60, v60, v118
	v_add_f32_e32 v60, v60, v119
	v_add_f32_e32 v42, v42, v60
	v_add_f32_e32 v60, v120, v121
	v_add_f32_e32 v60, v60, v122
	v_add_f32_e32 v60, v60, v123
	v_add_f32_e32 v42, v42, v60
	v_add_f32_e32 v43, v124, v125
	v_add_f32_e32 v43, v43, v126
	v_add_f32_e32 v43, v43, v127
	v_add_f32_e32 v61, v128, v129
	v_add_f32_e32 v61, v61, v130
	v_add_f32_e32 v61, v61, v131
	v_add_f32_e32 v43, v43, v61
	v_add_f32_e32 v61, v132, v133
	v_add_f32_e32 v61, v61, v134
	v_add_f32_e32 v61, v61, v135
	v_add_f32_e32 v43, v43, v61
	v_add_f32_e32 v61, v136, v137
	v_add_f32_e32 v61, v61, v138
	v_add_f32_e32 v61, v61, v139
	v_add_f32_e32 v43, v43, v61
	v_add_f32_e32 v44, v140, v141
	v_add_f32_e32 v44, v44, v142
	v_add_f32_e32 v44, v44, v143
	v_add_f32_e32 v62, v144, v145
	v_add_f32_e32 v62, v62, v146
	v_add_f32_e32 v62, v62, v147
	v_add_f32_e32 v44, v44, v62
	v_add_f32_e32 v62, v148, v149
	v_add_f32_e32 v62, v62, v150
	v_add_f32_e32 v62, v62, v151
	v_add_f32_e32 v44, v44, v62
	v_add_f32_e32 v62, v152, v153
	v_add_f32_e32 v62, v62, v154
	v_add_f32_e32 v62, v62, v155
	v_add_f32_e32 v44, v44, v62
	v_add_f32_e32 v45, v156, v157
	v_add_f32_e32 v45, v45, v158
	v_add_f32_e32 v45, v45, v159
	v_add_f32_e32 v63, v160, v161
	v_add_f32_e32 v63, v63, v162
	v_add_f32_e32 v63, v63, v163
	v_add_f32_e32 v45, v45, v63
	v_add_f32_e32 v63, v164, v165
	v_add_f32_e32 v63, v63, v166
	v_add_f32_e32 v63, v63, v167
	v_add_f32_e32 v45, v45, v63
	v_add_f32_e32 v63, v168, v169
	v_add_f32_e32 v63, v63, v170
	v_add_f32_e32 v63, v63, v171
	v_add_f32_e32 v45, v45, v63
	ds_bpermute_b32 v60, v96, v42
	ds_bpermute_b32 v61, v96, v43
	ds_bpermute_b32 v62, v96, v44
	ds_bpermute_b32 v63, v96, v45
	s_waitcnt lgkmcnt(3)
	v_add_f32_e32 v42, v42, v60
	s_waitcnt lgkmcnt(2)
	v_add_f32_e32 v43, v43, v61
	s_waitcnt lgkmcnt(1)
	v_add_f32_e32 v44, v44, v62
	s_waitcnt lgkmcnt(0)
	v_add_f32_e32 v45, v45, v63
	ds_bpermute_b32 v60, v97, v42
	ds_bpermute_b32 v61, v97, v43
	ds_bpermute_b32 v62, v97, v44
	ds_bpermute_b32 v63, v97, v45
	s_waitcnt lgkmcnt(3)
	v_add_f32_e32 v42, v42, v60
	s_waitcnt lgkmcnt(2)
	v_add_f32_e32 v43, v43, v61
	s_waitcnt lgkmcnt(1)
	v_add_f32_e32 v44, v44, v62
	s_waitcnt lgkmcnt(0)
	v_add_f32_e32 v45, v45, v63
	ds_bpermute_b32 v60, v98, v42
	ds_bpermute_b32 v61, v98, v43
	ds_bpermute_b32 v62, v98, v44
	ds_bpermute_b32 v63, v98, v45
	s_waitcnt lgkmcnt(3)
	v_add_f32_e32 v42, v42, v60
	s_waitcnt lgkmcnt(2)
	v_add_f32_e32 v43, v43, v61
	s_waitcnt lgkmcnt(1)
	v_add_f32_e32 v44, v44, v62
	s_waitcnt lgkmcnt(0)
	v_add_f32_e32 v45, v45, v63
	ds_bpermute_b32 v60, v99, v42
	ds_bpermute_b32 v61, v99, v43
	ds_bpermute_b32 v62, v99, v44
	ds_bpermute_b32 v63, v99, v45
	s_waitcnt lgkmcnt(3)
	v_add_f32_e32 v42, v42, v60
	s_waitcnt lgkmcnt(2)
	v_add_f32_e32 v43, v43, v61
	s_waitcnt lgkmcnt(1)
	v_add_f32_e32 v44, v44, v62
	s_waitcnt lgkmcnt(0)
	v_add_f32_e32 v45, v45, v63
	ds_bpermute_b32 v60, v100, v42
	ds_bpermute_b32 v61, v100, v43
	ds_bpermute_b32 v62, v100, v44
	ds_bpermute_b32 v63, v100, v45
	s_waitcnt lgkmcnt(3)
	v_add_f32_e32 v42, v42, v60
	s_waitcnt lgkmcnt(2)
	v_add_f32_e32 v43, v43, v61
	s_waitcnt lgkmcnt(1)
	v_add_f32_e32 v44, v44, v62
	s_waitcnt lgkmcnt(0)
	v_add_f32_e32 v45, v45, v63
	ds_bpermute_b32 v60, v101, v42
	ds_bpermute_b32 v61, v101, v43
	ds_bpermute_b32 v62, v101, v44
	ds_bpermute_b32 v63, v101, v45
	s_waitcnt lgkmcnt(3)
	v_add_f32_e32 v42, v42, v60
	s_waitcnt lgkmcnt(2)
	v_add_f32_e32 v43, v43, v61
	s_waitcnt lgkmcnt(1)
	v_add_f32_e32 v44, v44, v62
	s_waitcnt lgkmcnt(0)
; DEV void phase_ln(const Params& P, const float* __restrict__ g, const float* __restrict__ bta, u16* __restrict__ xb, bool zero_kc) {
;     ...
;     float q[2] = {0.f, 0.f};
; #pragma unroll
;     for (int r = 0; r < 2; ++r) {
;       const float mu = s[r] * (1.f / 1024.f);
; #pragma unroll
;       for (int i = 0; i < 4; ++i) {
;         v[r][i].x -= mu; v[r][i].y -= mu; v[r][i].z -= mu; v[r][i].w -= mu;
;         q[r] += v[r][i].x * v[r][i].x + v[r][i].y * v[r][i].y + v[r][i].z * v[r][i].z + v[r][i].w * v[r][i].w;
;       }
;     }
; #pragma unroll
;     for (int o = 32; o >= 1; o >>= 1) {
;       q[0] += __shfl_xor(q[0], o);
;       q[1] += __shfl_xor(q[1], o);
;     }
	v_add_f32_e32 v45, v45, v63
	v_mul_f32_e32 v42, 0x3a800000, v42
	v_mul_f32_e32 v43, 0x3a800000, v43
	v_mul_f32_e32 v44, 0x3a800000, v44
	v_mul_f32_e32 v45, 0x3a800000, v45
	v_sub_f32_e32 v108, v108, v42
	v_sub_f32_e32 v109, v109, v42
	v_sub_f32_e32 v110, v110, v42
	v_sub_f32_e32 v111, v111, v42
	v_mul_f32_e32 v46, v108, v108
	v_fmac_f32_e32 v46, v109, v109
	v_fmac_f32_e32 v46, v110, v110
	v_fmac_f32_e32 v46, v111, v111
	v_sub_f32_e32 v112, v112, v42
	v_sub_f32_e32 v113, v113, v42
	v_sub_f32_e32 v114, v114, v42
	v_sub_f32_e32 v115, v115, v42
	v_mul_f32_e32 v60, v112, v112
	v_fmac_f32_e32 v60, v113, v113
	v_fmac_f32_e32 v60, v114, v114
	v_fmac_f32_e32 v60, v115, v115
	v_add_f32_e32 v46, v46, v60
	v_sub_f32_e32 v116, v116, v42
	v_sub_f32_e32 v117, v117, v42
	v_sub_f32_e32 v118, v118, v42
	v_sub_f32_e32 v119, v119, v42
	v_mul_f32_e32 v60, v116, v116
	v_fmac_f32_e32 v60, v117, v117
	v_fmac_f32_e32 v60, v118, v118
	v_fmac_f32_e32 v60, v119, v119
	v_add_f32_e32 v46, v46, v60
	v_sub_f32_e32 v120, v120, v42
	v_sub_f32_e32 v121, v121, v42
	v_sub_f32_e32 v122, v122, v42
	v_sub_f32_e32 v123, v123, v42
	v_mul_f32_e32 v60, v120, v120
	v_fmac_f32_e32 v60, v121, v121
	v_fmac_f32_e32 v60, v122, v122
	v_fmac_f32_e32 v60, v123, v123
	v_add_f32_e32 v46, v46, v60
	v_sub_f32_e32 v124, v124, v43
	v_sub_f32_e32 v125, v125, v43
	v_sub_f32_e32 v126, v126, v43
	v_sub_f32_e32 v127, v127, v43
	v_mul_f32_e32 v48, v124, v124
	v_fmac_f32_e32 v48, v125, v125
	v_fmac_f32_e32 v48, v126, v126
	v_fmac_f32_e32 v48, v127, v127
	v_sub_f32_e32 v128, v128, v43
	v_sub_f32_e32 v129, v129, v43
	v_sub_f32_e32 v130, v130, v43
	v_sub_f32_e32 v131, v131, v43
	v_mul_f32_e32 v61, v128, v128
	v_fmac_f32_e32 v61, v129, v129
	v_fmac_f32_e32 v61, v130, v130
	v_fmac_f32_e32 v61, v131, v131
	v_add_f32_e32 v48, v48, v61
	v_sub_f32_e32 v132, v132, v43
	v_sub_f32_e32 v133, v133, v43
	v_sub_f32_e32 v134, v134, v43
	v_sub_f32_e32 v135, v135, v43
	v_mul_f32_e32 v61, v132, v132
	v_fmac_f32_e32 v61, v133, v133
	v_fmac_f32_e32 v61, v134, v134
	v_fmac_f32_e32 v61, v135, v135
	v_add_f32_e32 v48, v48, v61
	v_sub_f32_e32 v136, v136, v43
	v_sub_f32_e32 v137, v137, v43
	v_sub_f32_e32 v138, v138, v43
	v_sub_f32_e32 v139, v139, v43
	v_mul_f32_e32 v61, v136, v136
	v_fmac_f32_e32 v61, v137, v137
	v_fmac_f32_e32 v61, v138, v138
	v_fmac_f32_e32 v61, v139, v139
	v_add_f32_e32 v48, v48, v61
	v_sub_f32_e32 v140, v140, v44
	v_sub_f32_e32 v141, v141, v44
	v_sub_f32_e32 v142, v142, v44
	v_sub_f32_e32 v143, v143, v44
	v_mul_f32_e32 v50, v140, v140
	v_fmac_f32_e32 v50, v141, v141
	v_fmac_f32_e32 v50, v142, v142
	v_fmac_f32_e32 v50, v143, v143
	v_sub_f32_e32 v144, v144, v44
	v_sub_f32_e32 v145, v145, v44
	v_sub_f32_e32 v146, v146, v44
	v_sub_f32_e32 v147, v147, v44
	v_mul_f32_e32 v62, v144, v144
	v_fmac_f32_e32 v62, v145, v145
	v_fmac_f32_e32 v62, v146, v146
	v_fmac_f32_e32 v62, v147, v147
	v_add_f32_e32 v50, v50, v62
	v_sub_f32_e32 v148, v148, v44
	v_sub_f32_e32 v149, v149, v44
	v_sub_f32_e32 v150, v150, v44
	v_sub_f32_e32 v151, v151, v44
	v_mul_f32_e32 v62, v148, v148
	v_fmac_f32_e32 v62, v149, v149
	v_fmac_f32_e32 v62, v150, v150
	v_fmac_f32_e32 v62, v151, v151
	v_add_f32_e32 v50, v50, v62
	v_sub_f32_e32 v152, v152, v44
	v_sub_f32_e32 v153, v153, v44
	v_sub_f32_e32 v154, v154, v44
	v_sub_f32_e32 v155, v155, v44
	v_mul_f32_e32 v62, v152, v152
	v_fmac_f32_e32 v62, v153, v153
	v_fmac_f32_e32 v62, v154, v154
	v_fmac_f32_e32 v62, v155, v155
	v_add_f32_e32 v50, v50, v62
	v_sub_f32_e32 v156, v156, v45
	v_sub_f32_e32 v157, v157, v45
	v_sub_f32_e32 v158, v158, v45
	v_sub_f32_e32 v159, v159, v45
	v_mul_f32_e32 v52, v156, v156
	v_fmac_f32_e32 v52, v157, v157
	v_fmac_f32_e32 v52, v158, v158
	v_fmac_f32_e32 v52, v159, v159
	v_sub_f32_e32 v160, v160, v45
	v_sub_f32_e32 v161, v161, v45
	v_sub_f32_e32 v162, v162, v45
	v_sub_f32_e32 v163, v163, v45
	v_mul_f32_e32 v63, v160, v160
	v_fmac_f32_e32 v63, v161, v161
	v_fmac_f32_e32 v63, v162, v162
	v_fmac_f32_e32 v63, v163, v163
	v_add_f32_e32 v52, v52, v63
	v_sub_f32_e32 v164, v164, v45
	v_sub_f32_e32 v165, v165, v45
	v_sub_f32_e32 v166, v166, v45
	v_sub_f32_e32 v167, v167, v45
	v_mul_f32_e32 v63, v164, v164
	v_fmac_f32_e32 v63, v165, v165
	v_fmac_f32_e32 v63, v166, v166
	v_fmac_f32_e32 v63, v167, v167
	v_add_f32_e32 v52, v52, v63
	v_sub_f32_e32 v168, v168, v45
	v_sub_f32_e32 v169, v169, v45
	v_sub_f32_e32 v170, v170, v45
	v_sub_f32_e32 v171, v171, v45
	v_mul_f32_e32 v63, v168, v168
	v_fmac_f32_e32 v63, v169, v169
	v_fmac_f32_e32 v63, v170, v170
	v_fmac_f32_e32 v63, v171, v171
	v_add_f32_e32 v52, v52, v63
	ds_bpermute_b32 v60, v96, v46
	ds_bpermute_b32 v61, v96, v48
	ds_bpermute_b32 v62, v96, v50
	ds_bpermute_b32 v63, v96, v52
	s_waitcnt lgkmcnt(3)
	v_add_f32_e32 v46, v46, v60
	s_waitcnt lgkmcnt(2)
	v_add_f32_e32 v48, v48, v61
	s_waitcnt lgkmcnt(1)
	v_add_f32_e32 v50, v50, v62
	s_waitcnt lgkmcnt(0)
	v_add_f32_e32 v52, v52, v63
	ds_bpermute_b32 v60, v97, v46
	ds_bpermute_b32 v61, v97, v48
	ds_bpermute_b32 v62, v97, v50
	ds_bpermute_b32 v63, v97, v52
	s_waitcnt lgkmcnt(3)
	v_add_f32_e32 v46, v46, v60
	s_waitcnt lgkmcnt(2)
	v_add_f32_e32 v48, v48, v61
	s_waitcnt lgkmcnt(1)
	v_add_f32_e32 v50, v50, v62
	s_waitcnt lgkmcnt(0)
	v_add_f32_e32 v52, v52, v63
	ds_bpermute_b32 v60, v98, v46
	ds_bpermute_b32 v61, v98, v48
	ds_bpermute_b32 v62, v98, v50
	ds_bpermute_b32 v63, v98, v52
	s_waitcnt lgkmcnt(3)
	v_add_f32_e32 v46, v46, v60
	s_waitcnt lgkmcnt(2)
	v_add_f32_e32 v48, v48, v61
	s_waitcnt lgkmcnt(1)
	v_add_f32_e32 v50, v50, v62
	s_waitcnt lgkmcnt(0)
	v_add_f32_e32 v52, v52, v63
	ds_bpermute_b32 v60, v99, v46
	ds_bpermute_b32 v61, v99, v48
	ds_bpermute_b32 v62, v99, v50
	ds_bpermute_b32 v63, v99, v52
	s_waitcnt lgkmcnt(3)
; DEV void phase_ln(const Params& P, const float* __restrict__ g, const float* __restrict__ bta, u16* __restrict__ xb, bool zero_kc) {
;     ...
; #pragma unroll
;     for (int r = 0; r < 2; ++r) {
;       if (r == 1 && !hasB) break;
;       const float rs = rsqrtf(q[r] * (1.f / 1024.f) + 1e-5f);
;       const int rw = rows[r];
;       float* xr = P.out + (size_t)rw * D;
; #pragma unroll
;       for (int i = 0; i < 4; ++i) {
;         float4 y;
;         y.x = v[r][i].x * rs * gv[i].x + bv[i].x;
;         y.y = v[r][i].y * rs * gv[i].y + bv[i].y;
;         y.z = v[r][i].z * rs * gv[i].z + bv[i].z;
;         y.w = v[r][i].w * rs * gv[i].w + bv[i].w;
;         *(float4*)(xr + i * 256 + lane * 4) = y;
;         const int col = i * 256 + lane * 4;
;         *(uint2*)(xb + (size_t)(rw >> 8) * (256 * D) + (size_t)(col >> 5) * 8192 + (rw & 255) * 32 + (col & 31)) = make_uint2(pack2(y.x, y.y), pack2(y.z, y.w));
;       }
;     }
	v_add_f32_e32 v46, v46, v60
	s_waitcnt lgkmcnt(2)
	v_add_f32_e32 v48, v48, v61
	s_waitcnt lgkmcnt(1)
	v_add_f32_e32 v50, v50, v62
	s_waitcnt lgkmcnt(0)
	v_add_f32_e32 v52, v52, v63
	ds_bpermute_b32 v60, v100, v46
	ds_bpermute_b32 v61, v100, v48
	ds_bpermute_b32 v62, v100, v50
	ds_bpermute_b32 v63, v100, v52
	s_waitcnt lgkmcnt(3)
	v_add_f32_e32 v46, v46, v60
	s_waitcnt lgkmcnt(2)
	v_add_f32_e32 v48, v48, v61
	s_waitcnt lgkmcnt(1)
	v_add_f32_e32 v50, v50, v62
	s_waitcnt lgkmcnt(0)
	v_add_f32_e32 v52, v52, v63
	ds_bpermute_b32 v60, v101, v46
	ds_bpermute_b32 v61, v101, v48
	ds_bpermute_b32 v62, v101, v50
	ds_bpermute_b32 v63, v101, v52
	s_waitcnt lgkmcnt(3)
	v_add_f32_e32 v46, v46, v60
	s_waitcnt lgkmcnt(2)
	v_add_f32_e32 v48, v48, v61
	s_waitcnt lgkmcnt(1)
	v_add_f32_e32 v50, v50, v62
	s_waitcnt lgkmcnt(0)
	v_add_f32_e32 v52, v52, v63
	s_mov_b32 s2, 0x800000
	v_fmamk_f32 v46, v46, 0x3a800000, v216
	v_cmp_gt_f32_e32 vcc, s2, v46
	v_mul_f32_e32 v60, 0x4b800000, v46
	s_nop 1
	v_cndmask_b32_e32 v46, v46, v60, vcc
	v_rsq_f32_e32 v46, v46
	s_nop 0
	v_mul_f32_e32 v60, 0x45800000, v46
	s_nop 0
	v_cndmask_b32_e32 v46, v46, v60, vcc
	v_fmamk_f32 v48, v48, 0x3a800000, v216
	v_cmp_gt_f32_e32 vcc, s2, v48
	v_mul_f32_e32 v61, 0x4b800000, v48
	s_nop 1
	v_cndmask_b32_e32 v48, v48, v61, vcc
	v_rsq_f32_e32 v48, v48
	s_nop 0
	v_mul_f32_e32 v61, 0x45800000, v48
	s_nop 0
	v_cndmask_b32_e32 v48, v48, v61, vcc
	v_fmamk_f32 v50, v50, 0x3a800000, v216
	v_cmp_gt_f32_e32 vcc, s2, v50
	v_mul_f32_e32 v62, 0x4b800000, v50
	s_nop 1
	v_cndmask_b32_e32 v50, v50, v62, vcc
	v_rsq_f32_e32 v50, v50
	s_nop 0
	v_mul_f32_e32 v62, 0x45800000, v50
	s_nop 0
	v_cndmask_b32_e32 v50, v50, v62, vcc
	v_fmamk_f32 v52, v52, 0x3a800000, v216
	v_cmp_gt_f32_e32 vcc, s2, v52
	v_mul_f32_e32 v63, 0x4b800000, v52
	s_nop 1
	v_cndmask_b32_e32 v52, v52, v63, vcc
	v_rsq_f32_e32 v52, v52
	s_nop 0
	v_mul_f32_e32 v63, 0x45800000, v52
	s_nop 0
	v_cndmask_b32_e32 v52, v52, v63, vcc
	s_add_i32 s9, s4, 0
	s_cmp_lt_i32 s9, 0x8000
	s_cbranch_scc0 .Lln_skip_1_0
	s_lshr_b32 s8, s9, 8
	s_lshl_b32 s8, s8, 19
	s_and_b32 s2, s9, 0xff
	s_lshl_b32 s2, s2, 6
	s_add_i32 s8, s8, s2
	v_mov_b32_e32 v64, v42
	v_mov_b32_e32 v65, v46
	s_lshl_b32 s2, s9, 3
	v_mov_b32_e32 v70, s2
	global_store_dwordx2 v70, v[64:65], s[12:13]
	v_pk_mul_f32 v[64:65], v[108:109], v[46:47] op_sel_hi:[1,0]
	v_pk_mul_f32 v[66:67], v[110:111], v[46:47] op_sel_hi:[1,0]
	v_pk_fma_f32 v[64:65], v[2:3], v[64:65], v[6:7]
	v_pk_fma_f32 v[66:67], v[4:5], v[66:67], v[8:9]
	v_add_u32_e32 v70, s8, v36
	v_cvt_pk_bf16_f32 v68, v64, v65
	v_cvt_pk_bf16_f32 v69, v66, v67
	global_store_dwordx2 v70, v[68:69], s[42:43]
	v_pk_mul_f32 v[64:65], v[112:113], v[46:47] op_sel_hi:[1,0]
	v_pk_mul_f32 v[66:67], v[114:115], v[46:47] op_sel_hi:[1,0]
	v_pk_fma_f32 v[64:65], v[10:11], v[64:65], v[18:19]
	v_pk_fma_f32 v[66:67], v[12:13], v[66:67], v[20:21]
	v_add_u32_e32 v70, s8, v37
	v_cvt_pk_bf16_f32 v68, v64, v65
	v_cvt_pk_bf16_f32 v69, v66, v67
	global_store_dwordx2 v70, v[68:69], s[42:43]
	v_pk_mul_f32 v[64:65], v[116:117], v[46:47] op_sel_hi:[1,0]
	v_pk_mul_f32 v[66:67], v[118:119], v[46:47] op_sel_hi:[1,0]
	v_pk_fma_f32 v[64:65], v[14:15], v[64:65], v[22:23]
	v_pk_fma_f32 v[66:67], v[16:17], v[66:67], v[24:25]
	v_add_u32_e32 v70, s8, v38
	v_cvt_pk_bf16_f32 v68, v64, v65
	v_cvt_pk_bf16_f32 v69, v66, v67
	global_store_dwordx2 v70, v[68:69], s[42:43]
	v_pk_mul_f32 v[64:65], v[120:121], v[46:47] op_sel_hi:[1,0]
	v_pk_mul_f32 v[66:67], v[122:123], v[46:47] op_sel_hi:[1,0]
	v_pk_fma_f32 v[64:65], v[26:27], v[64:65], v[30:31]
	v_pk_fma_f32 v[66:67], v[28:29], v[66:67], v[32:33]
	v_add_u32_e32 v70, s8, v39
	v_cvt_pk_bf16_f32 v68, v64, v65
	v_cvt_pk_bf16_f32 v69, v66, v67
	global_store_dwordx2 v70, v[68:69], s[42:43]
; DEV void phase_ln(const Params& P, const float* __restrict__ g, const float* __restrict__ bta, u16* __restrict__ xb, bool zero_kc) {
;     ...
; #pragma unroll
;     for (int r = 0; r < 2; ++r) {
;       if (r == 1 && !hasB) break;
;       const float rs = rsqrtf(q[r] * (1.f / 1024.f) + 1e-5f);
;       const int rw = rows[r];
;       float* xr = P.out + (size_t)rw * D;
; #pragma unroll
;       for (int i = 0; i < 4; ++i) {
;         float4 y;
;         y.x = v[r][i].x * rs * gv[i].x + bv[i].x;
;         y.y = v[r][i].y * rs * gv[i].y + bv[i].y;
;         y.z = v[r][i].z * rs * gv[i].z + bv[i].z;
;         y.w = v[r][i].w * rs * gv[i].w + bv[i].w;
;         *(float4*)(xr + i * 256 + lane * 4) = y;
;         const int col = i * 256 + lane * 4;
;         *(uint2*)(xb + (size_t)(rw >> 8) * (256 * D) + (size_t)(col >> 5) * 8192 + (rw & 255) * 32 + (col & 31)) = make_uint2(pack2(y.x, y.y), pack2(y.z, y.w));
;       }
;     }
.Lln_skip_1_0:
	s_add_i32 s9, s4, 1
	s_cmp_lt_i32 s9, 0x8000
	s_cbranch_scc0 .Lln_skip_1_1
	s_lshr_b32 s8, s9, 8
	s_lshl_b32 s8, s8, 19
	s_and_b32 s2, s9, 0xff
	s_lshl_b32 s2, s2, 6
	s_add_i32 s8, s8, s2
	v_mov_b32_e32 v64, v43
	v_mov_b32_e32 v65, v48
	s_lshl_b32 s2, s9, 3
	v_mov_b32_e32 v70, s2
	global_store_dwordx2 v70, v[64:65], s[12:13]
	v_pk_mul_f32 v[64:65], v[124:125], v[48:49] op_sel_hi:[1,0]
	v_pk_mul_f32 v[66:67], v[126:127], v[48:49] op_sel_hi:[1,0]
	v_pk_fma_f32 v[64:65], v[2:3], v[64:65], v[6:7]
	v_pk_fma_f32 v[66:67], v[4:5], v[66:67], v[8:9]
	v_add_u32_e32 v70, s8, v36
	v_cvt_pk_bf16_f32 v68, v64, v65
	v_cvt_pk_bf16_f32 v69, v66, v67
	global_store_dwordx2 v70, v[68:69], s[42:43]
	v_pk_mul_f32 v[64:65], v[128:129], v[48:49] op_sel_hi:[1,0]
	v_pk_mul_f32 v[66:67], v[130:131], v[48:49] op_sel_hi:[1,0]
	v_pk_fma_f32 v[64:65], v[10:11], v[64:65], v[18:19]
	v_pk_fma_f32 v[66:67], v[12:13], v[66:67], v[20:21]
	v_add_u32_e32 v70, s8, v37
	v_cvt_pk_bf16_f32 v68, v64, v65
	v_cvt_pk_bf16_f32 v69, v66, v67
	global_store_dwordx2 v70, v[68:69], s[42:43]
	v_pk_mul_f32 v[64:65], v[132:133], v[48:49] op_sel_hi:[1,0]
	v_pk_mul_f32 v[66:67], v[134:135], v[48:49] op_sel_hi:[1,0]
	v_pk_fma_f32 v[64:65], v[14:15], v[64:65], v[22:23]
	v_pk_fma_f32 v[66:67], v[16:17], v[66:67], v[24:25]
	v_add_u32_e32 v70, s8, v38
	v_cvt_pk_bf16_f32 v68, v64, v65
	v_cvt_pk_bf16_f32 v69, v66, v67
	global_store_dwordx2 v70, v[68:69], s[42:43]
	v_pk_mul_f32 v[64:65], v[136:137], v[48:49] op_sel_hi:[1,0]
	v_pk_mul_f32 v[66:67], v[138:139], v[48:49] op_sel_hi:[1,0]
	v_pk_fma_f32 v[64:65], v[26:27], v[64:65], v[30:31]
	v_pk_fma_f32 v[66:67], v[28:29], v[66:67], v[32:33]
	v_add_u32_e32 v70, s8, v39
	v_cvt_pk_bf16_f32 v68, v64, v65
	v_cvt_pk_bf16_f32 v69, v66, v67
	global_store_dwordx2 v70, v[68:69], s[42:43]
.Lln_skip_1_1:
	s_add_i32 s9, s4, 2
	s_cmp_lt_i32 s9, 0x8000
	s_cbranch_scc0 .Lln_skip_1_2
	s_lshr_b32 s8, s9, 8
	s_lshl_b32 s8, s8, 19
	s_and_b32 s2, s9, 0xff
	s_lshl_b32 s2, s2, 6
	s_add_i32 s8, s8, s2
	v_mov_b32_e32 v64, v44
	v_mov_b32_e32 v65, v50
	s_lshl_b32 s2, s9, 3
	v_mov_b32_e32 v70, s2
	global_store_dwordx2 v70, v[64:65], s[12:13]
	v_pk_mul_f32 v[64:65], v[140:141], v[50:51] op_sel_hi:[1,0]
	v_pk_mul_f32 v[66:67], v[142:143], v[50:51] op_sel_hi:[1,0]
	v_pk_fma_f32 v[64:65], v[2:3], v[64:65], v[6:7]
	v_pk_fma_f32 v[66:67], v[4:5], v[66:67], v[8:9]
	v_add_u32_e32 v70, s8, v36
	v_cvt_pk_bf16_f32 v68, v64, v65
	v_cvt_pk_bf16_f32 v69, v66, v67
	global_store_dwordx2 v70, v[68:69], s[42:43]
	v_pk_mul_f32 v[64:65], v[144:145], v[50:51] op_sel_hi:[1,0]
	v_pk_mul_f32 v[66:67], v[146:147], v[50:51] op_sel_hi:[1,0]
	v_pk_fma_f32 v[64:65], v[10:11], v[64:65], v[18:19]
	v_pk_fma_f32 v[66:67], v[12:13], v[66:67], v[20:21]
	v_add_u32_e32 v70, s8, v37
	v_cvt_pk_bf16_f32 v68, v64, v65
	v_cvt_pk_bf16_f32 v69, v66, v67
	global_store_dwordx2 v70, v[68:69], s[42:43]
	v_pk_mul_f32 v[64:65], v[148:149], v[50:51] op_sel_hi:[1,0]
	v_pk_mul_f32 v[66:67], v[150:151], v[50:51] op_sel_hi:[1,0]
	v_pk_fma_f32 v[64:65], v[14:15], v[64:65], v[22:23]
	v_pk_fma_f32 v[66:67], v[16:17], v[66:67], v[24:25]
	v_add_u32_e32 v70, s8, v38
	v_cvt_pk_bf16_f32 v68, v64, v65
	v_cvt_pk_bf16_f32 v69, v66, v67
	global_store_dwordx2 v70, v[68:69], s[42:43]
	v_pk_mul_f32 v[64:65], v[152:153], v[50:51] op_sel_hi:[1,0]
	v_pk_mul_f32 v[66:67], v[154:155], v[50:51] op_sel_hi:[1,0]
	v_pk_fma_f32 v[64:65], v[26:27], v[64:65], v[30:31]
	v_pk_fma_f32 v[66:67], v[28:29], v[66:67], v[32:33]
	v_add_u32_e32 v70, s8, v39
	v_cvt_pk_bf16_f32 v68, v64, v65
	v_cvt_pk_bf16_f32 v69, v66, v67
	global_store_dwordx2 v70, v[68:69], s[42:43]
.Lln_skip_1_2:
	s_add_i32 s9, s4, 3
	s_cmp_lt_i32 s9, 0x8000
	s_cbranch_scc0 .Lln_skip_1_3
	s_lshr_b32 s8, s9, 8
	s_lshl_b32 s8, s8, 19
	s_and_b32 s2, s9, 0xff
	s_lshl_b32 s2, s2, 6
	s_add_i32 s8, s8, s2
	v_mov_b32_e32 v64, v45
	v_mov_b32_e32 v65, v52
	s_lshl_b32 s2, s9, 3
	v_mov_b32_e32 v70, s2
	global_store_dwordx2 v70, v[64:65], s[12:13]
	v_pk_mul_f32 v[64:65], v[156:157], v[52:53] op_sel_hi:[1,0]
	v_pk_mul_f32 v[66:67], v[158:159], v[52:53] op_sel_hi:[1,0]
	v_pk_fma_f32 v[64:65], v[2:3], v[64:65], v[6:7]
	v_pk_fma_f32 v[66:67], v[4:5], v[66:67], v[8:9]
	v_add_u32_e32 v70, s8, v36
	v_cvt_pk_bf16_f32 v68, v64, v65
	v_cvt_pk_bf16_f32 v69, v66, v67
	global_store_dwordx2 v70, v[68:69], s[42:43]
	v_pk_mul_f32 v[64:65], v[160:161], v[52:53] op_sel_hi:[1,0]
	v_pk_mul_f32 v[66:67], v[162:163], v[52:53] op_sel_hi:[1,0]
	v_pk_fma_f32 v[64:65], v[10:11], v[64:65], v[18:19]
	v_pk_fma_f32 v[66:67], v[12:13], v[66:67], v[20:21]
	v_add_u32_e32 v70, s8, v37
	v_cvt_pk_bf16_f32 v68, v64, v65
	v_cvt_pk_bf16_f32 v69, v66, v67
	global_store_dwordx2 v70, v[68:69], s[42:43]
	v_pk_mul_f32 v[64:65], v[164:165], v[52:53] op_sel_hi:[1,0]
	v_pk_mul_f32 v[66:67], v[166:167], v[52:53] op_sel_hi:[1,0]
	v_pk_fma_f32 v[64:65], v[14:15], v[64:65], v[22:23]
	v_pk_fma_f32 v[66:67], v[16:17], v[66:67], v[24:25]
	v_add_u32_e32 v70, s8, v38
	v_cvt_pk_bf16_f32 v68, v64, v65
	v_cvt_pk_bf16_f32 v69, v66, v67
	global_store_dwordx2 v70, v[68:69], s[42:43]
	v_pk_mul_f32 v[64:65], v[168:169], v[52:53] op_sel_hi:[1,0]
	v_pk_mul_f32 v[66:67], v[170:171], v[52:53] op_sel_hi:[1,0]
	v_pk_fma_f32 v[64:65], v[26:27], v[64:65], v[30:31]
	v_pk_fma_f32 v[66:67], v[28:29], v[66:67], v[32:33]
	v_add_u32_e32 v70, s8, v39
	v_cvt_pk_bf16_f32 v68, v64, v65
	v_cvt_pk_bf16_f32 v69, v66, v67
	global_store_dwordx2 v70, v[68:69], s[42:43]

; DEV void phase_ln(const Params& P, const float* __restrict__ g, const float* __restrict__ bta, u16* __restrict__ xb, bool zero_kc) {
;     ...
;         y.x = v[r][i].x * rs * gv[i].x + bv[i].x;
;         y.y = v[r][i].y * rs * gv[i].y + bv[i].y;
;         y.z = v[r][i].z * rs * gv[i].z + bv[i].z;
;         y.w = v[r][i].w * rs * gv[i].w + bv[i].w;
;     ...
; #pragma unroll
;     for (int ms = 0; ms < 8; ++ms) {
;       asm volatile("" ::: "memory");
; #pragma unroll
;       for (int ns = 0; ns < 4; ++ns)
; #pragma unroll
;         for (int j = 0; j < 4; ++j) {
;           int row = m0 + wm * 128 + ms * 16 + quad * 4 + j;
;           int col = n0 + wn * 64 + ns * 16 + l15;
;           const size_t xi = (size_t)row * D + col;
;           const float xv = xin ? xin[xi] : P.out[xi];
;           P.out[xi] = alpha * xv + sc * acc[ms][ns][j];
;         }
.LBB0_105:
	v_add_u32_e32 v136, s12, v207
	v_lshl_or_b32 v130, s13, 7, v239
	v_lshlrev_b32_e32 v132, 3, v136
	v_lshlrev_b32_e32 v133, 2, v130
	v_lshlrev_b32_e32 v136, 12, v136
	v_lshl_add_u32 v138, v130, 2, v136
	v_add_u32_e32 v138, 0x1000, v138
	s_and_b64 vcc, exec, s[8:9]
	v_readlane_b32 s4, v255, 10
	v_readlane_b32 s5, v255, 11
	s_add_u32 s4, s4, 0x1000
	s_addc_u32 s5, s5, 0
	s_nop 1
	global_load_dword v164, v133, s[4:5]
	global_load_dword v165, v133, s[4:5] offset:64
	global_load_dword v166, v133, s[4:5] offset:128
	global_load_dword v167, v133, s[4:5] offset:192
	v_readlane_b32 s4, v255, 12
	v_readlane_b32 s5, v255, 13
	s_add_u32 s4, s4, 0x1000
	s_addc_u32 s5, s5, 0
	s_nop 1
	global_load_dword v168, v133, s[4:5]
	global_load_dword v169, v133, s[4:5] offset:64
	global_load_dword v170, v133, s[4:5] offset:128
	global_load_dword v171, v133, s[4:5] offset:192
	v_readlane_b32 s4, v255, 8
	s_add_i32 s4, s4, 2
	s_and_b32 s4, s4, 3
	s_lshl_b32 s4, s4, 24
	s_add_u32 s4, s4, 0x25040000
	s_add_u32 s4, s38, s4
	s_addc_u32 s5, s39, 0
	s_nop 1
	v_mov_b32_e32 v130, v138
	global_load_dword v140, v130, s[86:87] offset:-4096
	global_load_dword v141, v130, s[86:87] offset:-4032
	global_load_dword v142, v130, s[86:87] offset:-3968
	global_load_dword v143, v130, s[86:87] offset:-3904
	global_load_dword v144, v130, s[86:87]
	global_load_dword v145, v130, s[86:87] offset:64
	global_load_dword v146, v130, s[86:87] offset:128
	global_load_dword v147, v130, s[86:87] offset:192
	global_load_dwordx4 v[156:159], v132, s[4:5]
	v_add_u32_e32 v131, 0x2000, v138
	global_load_dword v148, v131, s[86:87] offset:-4096
	global_load_dword v149, v131, s[86:87] offset:-4032
	global_load_dword v150, v131, s[86:87] offset:-3968
	global_load_dword v151, v131, s[86:87] offset:-3904
	global_load_dword v152, v131, s[86:87]
	global_load_dword v153, v131, s[86:87] offset:64
	global_load_dword v154, v131, s[86:87] offset:128
	global_load_dword v155, v131, s[86:87] offset:192
	global_load_dwordx4 v[160:163], v132, s[4:5] offset:16
	s_waitcnt vmcnt(9)
	v_sub_f32_e32 v140, v140, v156
	v_mul_f32_e32 v140, v140, v157
	v_fma_f32 v140, v164, v140, v168
	v_mul_f32_e32 v140, v212, v140
	v_fmac_f32_e32 v140, v211, v126
	global_store_dword v130, v140, s[86:87] offset:-4096
	v_sub_f32_e32 v141, v141, v156
	v_mul_f32_e32 v141, v141, v157
	v_fma_f32 v141, v165, v141, v169
	v_mul_f32_e32 v141, v212, v141
	v_fmac_f32_e32 v141, v211, v122
	global_store_dword v130, v141, s[86:87] offset:-4032
	v_sub_f32_e32 v142, v142, v156
	v_mul_f32_e32 v142, v142, v157
	v_fma_f32 v142, v166, v142, v170
	v_mul_f32_e32 v142, v212, v142
	v_fmac_f32_e32 v142, v211, v118
	global_store_dword v130, v142, s[86:87] offset:-3968
	v_sub_f32_e32 v143, v143, v156
	v_mul_f32_e32 v143, v143, v157
	v_fma_f32 v143, v167, v143, v171
	v_mul_f32_e32 v143, v212, v143
	v_fmac_f32_e32 v143, v211, v114
	global_store_dword v130, v143, s[86:87] offset:-3904
	v_sub_f32_e32 v144, v144, v158
	v_mul_f32_e32 v144, v144, v159
	v_fma_f32 v144, v164, v144, v168
	v_mul_f32_e32 v144, v212, v144
	v_fmac_f32_e32 v144, v211, v127
	global_store_dword v130, v144, s[86:87]
	v_sub_f32_e32 v145, v145, v158
	v_mul_f32_e32 v145, v145, v159
	v_fma_f32 v145, v165, v145, v169
	v_mul_f32_e32 v145, v212, v145
	v_fmac_f32_e32 v145, v211, v123
	global_store_dword v130, v145, s[86:87] offset:64
	v_sub_f32_e32 v146, v146, v158
	v_mul_f32_e32 v146, v146, v159
	v_fma_f32 v146, v166, v146, v170
	v_mul_f32_e32 v146, v212, v146
	v_fmac_f32_e32 v146, v211, v119
	global_store_dword v130, v146, s[86:87] offset:128
	v_sub_f32_e32 v147, v147, v158
	v_mul_f32_e32 v147, v147, v159
	v_fma_f32 v147, v167, v147, v171
	v_mul_f32_e32 v147, v212, v147
	v_fmac_f32_e32 v147, v211, v115
	global_store_dword v130, v147, s[86:87] offset:192
	v_add_u32_e32 v130, 0x10000, v138
	global_load_dword v140, v130, s[86:87] offset:-4096
	global_load_dword v141, v130, s[86:87] offset:-4032
	global_load_dword v142, v130, s[86:87] offset:-3968
	global_load_dword v143, v130, s[86:87] offset:-3904
	global_load_dword v144, v130, s[86:87]
	global_load_dword v145, v130, s[86:87] offset:64
	global_load_dword v146, v130, s[86:87] offset:128
	global_load_dword v147, v130, s[86:87] offset:192
	global_load_dwordx4 v[156:159], v132, s[4:5] offset:128
	s_waitcnt vmcnt(17)
	v_sub_f32_e32 v148, v148, v160
	v_mul_f32_e32 v148, v148, v161
	v_fma_f32 v148, v164, v148, v168
	v_mul_f32_e32 v148, v212, v148
	v_fmac_f32_e32 v148, v211, v128
	global_store_dword v131, v148, s[86:87] offset:-4096
	v_sub_f32_e32 v149, v149, v160
	v_mul_f32_e32 v149, v149, v161
	v_fma_f32 v149, v165, v149, v169
	v_mul_f32_e32 v149, v212, v149
	v_fmac_f32_e32 v149, v211, v124
	global_store_dword v131, v149, s[86:87] offset:-4032
	v_sub_f32_e32 v150, v150, v160
	v_mul_f32_e32 v150, v150, v161
	v_fma_f32 v150, v166, v150, v170
	v_mul_f32_e32 v150, v212, v150
	v_fmac_f32_e32 v150, v211, v120
	global_store_dword v131, v150, s[86:87] offset:-3968
	v_sub_f32_e32 v151, v151, v160
	v_mul_f32_e32 v151, v151, v161
	v_fma_f32 v151, v167, v151, v171
	v_mul_f32_e32 v151, v212, v151
	v_fmac_f32_e32 v151, v211, v116
	global_store_dword v131, v151, s[86:87] offset:-3904
	v_sub_f32_e32 v152, v152, v162
	v_mul_f32_e32 v152, v152, v163
	v_fma_f32 v152, v164, v152, v168
	v_mul_f32_e32 v152, v212, v152
	v_fmac_f32_e32 v152, v211, v129
	global_store_dword v131, v152, s[86:87]
	v_sub_f32_e32 v153, v153, v162
	v_mul_f32_e32 v153, v153, v163
	v_fma_f32 v153, v165, v153, v169
	v_mul_f32_e32 v153, v212, v153
	v_fmac_f32_e32 v153, v211, v125
	global_store_dword v131, v153, s[86:87] offset:64
	v_sub_f32_e32 v154, v154, v162
	v_mul_f32_e32 v154, v154, v163
	v_fma_f32 v154, v166, v154, v170
	v_mul_f32_e32 v154, v212, v154
	v_fmac_f32_e32 v154, v211, v121
	global_store_dword v131, v154, s[86:87] offset:128
	v_sub_f32_e32 v155, v155, v162
	v_mul_f32_e32 v155, v155, v163
	v_fma_f32 v155, v167, v155, v171
	v_mul_f32_e32 v155, v212, v155
	v_fmac_f32_e32 v155, v211, v117
	global_store_dword v131, v155, s[86:87] offset:192
	v_add_u32_e32 v131, 0x12000, v138
	global_load_dword v148, v131, s[86:87] offset:-4096
	global_load_dword v149, v131, s[86:87] offset:-4032
	global_load_dword v150, v131, s[86:87] offset:-3968
	global_load_dword v151, v131, s[86:87] offset:-3904
	global_load_dword v152, v131, s[86:87]
	global_load_dword v153, v131, s[86:87] offset:64
	global_load_dword v154, v131, s[86:87] offset:128
	global_load_dword v155, v131, s[86:87] offset:192
	global_load_dwordx4 v[160:163], v132, s[4:5] offset:144
	s_waitcnt vmcnt(17)
; DEV void phase_ln(const Params& P, const float* __restrict__ g, const float* __restrict__ bta, u16* __restrict__ xb, bool zero_kc) {
;     ...
;         y.x = v[r][i].x * rs * gv[i].x + bv[i].x;
;         y.y = v[r][i].y * rs * gv[i].y + bv[i].y;
;         y.z = v[r][i].z * rs * gv[i].z + bv[i].z;
;         y.w = v[r][i].w * rs * gv[i].w + bv[i].w;
;     ...
; #pragma unroll
;     for (int ms = 0; ms < 8; ++ms) {
;       asm volatile("" ::: "memory");
; #pragma unroll
;       for (int ns = 0; ns < 4; ++ns)
; #pragma unroll
;         for (int j = 0; j < 4; ++j) {
;           int row = m0 + wm * 128 + ms * 16 + quad * 4 + j;
;           int col = n0 + wn * 64 + ns * 16 + l15;
;           const size_t xi = (size_t)row * D + col;
;           const float xv = xin ? xin[xi] : P.out[xi];
;           P.out[xi] = alpha * xv + sc * acc[ms][ns][j];
;         }
	v_sub_f32_e32 v140, v140, v156
	v_mul_f32_e32 v140, v140, v157
	v_fma_f32 v140, v164, v140, v168
	v_mul_f32_e32 v140, v212, v140
	v_fmac_f32_e32 v140, v211, v110
	global_store_dword v130, v140, s[86:87] offset:-4096
	v_sub_f32_e32 v141, v141, v156
	v_mul_f32_e32 v141, v141, v157
	v_fma_f32 v141, v165, v141, v169
	v_mul_f32_e32 v141, v212, v141
	v_fmac_f32_e32 v141, v211, v106
	global_store_dword v130, v141, s[86:87] offset:-4032
	v_sub_f32_e32 v142, v142, v156
	v_mul_f32_e32 v142, v142, v157
	v_fma_f32 v142, v166, v142, v170
	v_mul_f32_e32 v142, v212, v142
	v_fmac_f32_e32 v142, v211, v102
	global_store_dword v130, v142, s[86:87] offset:-3968
	v_sub_f32_e32 v143, v143, v156
	v_mul_f32_e32 v143, v143, v157
	v_fma_f32 v143, v167, v143, v171
	v_mul_f32_e32 v143, v212, v143
	v_fmac_f32_e32 v143, v211, v98
	global_store_dword v130, v143, s[86:87] offset:-3904
	v_sub_f32_e32 v144, v144, v158
	v_mul_f32_e32 v144, v144, v159
	v_fma_f32 v144, v164, v144, v168
	v_mul_f32_e32 v144, v212, v144
	v_fmac_f32_e32 v144, v211, v111
	global_store_dword v130, v144, s[86:87]
	v_sub_f32_e32 v145, v145, v158
	v_mul_f32_e32 v145, v145, v159
	v_fma_f32 v145, v165, v145, v169
	v_mul_f32_e32 v145, v212, v145
	v_fmac_f32_e32 v145, v211, v107
	global_store_dword v130, v145, s[86:87] offset:64
	v_sub_f32_e32 v146, v146, v158
	v_mul_f32_e32 v146, v146, v159
	v_fma_f32 v146, v166, v146, v170
	v_mul_f32_e32 v146, v212, v146
	v_fmac_f32_e32 v146, v211, v103
	global_store_dword v130, v146, s[86:87] offset:128
	v_sub_f32_e32 v147, v147, v158
	v_mul_f32_e32 v147, v147, v159
	v_fma_f32 v147, v167, v147, v171
	v_mul_f32_e32 v147, v212, v147
	v_fmac_f32_e32 v147, v211, v99
	global_store_dword v130, v147, s[86:87] offset:192
	v_add_u32_e32 v130, 0x20000, v138
	global_load_dword v140, v130, s[86:87] offset:-4096
	global_load_dword v141, v130, s[86:87] offset:-4032
	global_load_dword v142, v130, s[86:87] offset:-3968
	global_load_dword v143, v130, s[86:87] offset:-3904
	global_load_dword v144, v130, s[86:87]
	global_load_dword v145, v130, s[86:87] offset:64
	global_load_dword v146, v130, s[86:87] offset:128
	global_load_dword v147, v130, s[86:87] offset:192
	global_load_dwordx4 v[156:159], v132, s[4:5] offset:256
	s_waitcnt vmcnt(17)
	v_sub_f32_e32 v148, v148, v160
	v_mul_f32_e32 v148, v148, v161
	v_fma_f32 v148, v164, v148, v168
	v_mul_f32_e32 v148, v212, v148
	v_fmac_f32_e32 v148, v211, v112
	global_store_dword v131, v148, s[86:87] offset:-4096
	v_sub_f32_e32 v149, v149, v160
	v_mul_f32_e32 v149, v149, v161
	v_fma_f32 v149, v165, v149, v169
	v_mul_f32_e32 v149, v212, v149
	v_fmac_f32_e32 v149, v211, v108
	global_store_dword v131, v149, s[86:87] offset:-4032
	v_sub_f32_e32 v150, v150, v160
	v_mul_f32_e32 v150, v150, v161
	v_fma_f32 v150, v166, v150, v170
	v_mul_f32_e32 v150, v212, v150
	v_fmac_f32_e32 v150, v211, v104
	global_store_dword v131, v150, s[86:87] offset:-3968
	v_sub_f32_e32 v151, v151, v160
	v_mul_f32_e32 v151, v151, v161
	v_fma_f32 v151, v167, v151, v171
	v_mul_f32_e32 v151, v212, v151
	v_fmac_f32_e32 v151, v211, v100
	global_store_dword v131, v151, s[86:87] offset:-3904
	v_sub_f32_e32 v152, v152, v162
	v_mul_f32_e32 v152, v152, v163
	v_fma_f32 v152, v164, v152, v168
	v_mul_f32_e32 v152, v212, v152
	v_fmac_f32_e32 v152, v211, v113
	global_store_dword v131, v152, s[86:87]
	v_sub_f32_e32 v153, v153, v162
	v_mul_f32_e32 v153, v153, v163
	v_fma_f32 v153, v165, v153, v169
	v_mul_f32_e32 v153, v212, v153
	v_fmac_f32_e32 v153, v211, v109
	global_store_dword v131, v153, s[86:87] offset:64
	v_sub_f32_e32 v154, v154, v162
	v_mul_f32_e32 v154, v154, v163
	v_fma_f32 v154, v166, v154, v170
	v_mul_f32_e32 v154, v212, v154
	v_fmac_f32_e32 v154, v211, v105
	global_store_dword v131, v154, s[86:87] offset:128
	v_sub_f32_e32 v155, v155, v162
	v_mul_f32_e32 v155, v155, v163
	v_fma_f32 v155, v167, v155, v171
	v_mul_f32_e32 v155, v212, v155
	v_fmac_f32_e32 v155, v211, v101
	global_store_dword v131, v155, s[86:87] offset:192
	v_add_u32_e32 v131, 0x22000, v138
	global_load_dword v148, v131, s[86:87] offset:-4096
	global_load_dword v149, v131, s[86:87] offset:-4032
	global_load_dword v150, v131, s[86:87] offset:-3968
	global_load_dword v151, v131, s[86:87] offset:-3904
	global_load_dword v152, v131, s[86:87]
	global_load_dword v153, v131, s[86:87] offset:64
	global_load_dword v154, v131, s[86:87] offset:128
	global_load_dword v155, v131, s[86:87] offset:192
	global_load_dwordx4 v[160:163], v132, s[4:5] offset:272
	s_waitcnt vmcnt(17)
	v_sub_f32_e32 v140, v140, v156
	v_mul_f32_e32 v140, v140, v157
	v_fma_f32 v140, v164, v140, v168
	v_mul_f32_e32 v140, v212, v140
	v_fmac_f32_e32 v140, v211, v94
	global_store_dword v130, v140, s[86:87] offset:-4096
	v_sub_f32_e32 v141, v141, v156
	v_mul_f32_e32 v141, v141, v157
	v_fma_f32 v141, v165, v141, v169
	v_mul_f32_e32 v141, v212, v141
	v_fmac_f32_e32 v141, v211, v90
	global_store_dword v130, v141, s[86:87] offset:-4032
	v_sub_f32_e32 v142, v142, v156
	v_mul_f32_e32 v142, v142, v157
	v_fma_f32 v142, v166, v142, v170
	v_mul_f32_e32 v142, v212, v142
	v_fmac_f32_e32 v142, v211, v86
	global_store_dword v130, v142, s[86:87] offset:-3968
	v_sub_f32_e32 v143, v143, v156
	v_mul_f32_e32 v143, v143, v157
	v_fma_f32 v143, v167, v143, v171
	v_mul_f32_e32 v143, v212, v143
	v_fmac_f32_e32 v143, v211, v82
	global_store_dword v130, v143, s[86:87] offset:-3904
	v_sub_f32_e32 v144, v144, v158
	v_mul_f32_e32 v144, v144, v159
	v_fma_f32 v144, v164, v144, v168
	v_mul_f32_e32 v144, v212, v144
	v_fmac_f32_e32 v144, v211, v95
	global_store_dword v130, v144, s[86:87]
	v_sub_f32_e32 v145, v145, v158
	v_mul_f32_e32 v145, v145, v159
	v_fma_f32 v145, v165, v145, v169
	v_mul_f32_e32 v145, v212, v145
	v_fmac_f32_e32 v145, v211, v91
	global_store_dword v130, v145, s[86:87] offset:64
	v_sub_f32_e32 v146, v146, v158
	v_mul_f32_e32 v146, v146, v159
	v_fma_f32 v146, v166, v146, v170
	v_mul_f32_e32 v146, v212, v146
	v_fmac_f32_e32 v146, v211, v87
	global_store_dword v130, v146, s[86:87] offset:128
	v_sub_f32_e32 v147, v147, v158
	v_mul_f32_e32 v147, v147, v159
	v_fma_f32 v147, v167, v147, v171
	v_mul_f32_e32 v147, v212, v147
	v_fmac_f32_e32 v147, v211, v83
	global_store_dword v130, v147, s[86:87] offset:192
	v_add_u32_e32 v130, 0x30000, v138
	global_load_dword v140, v130, s[86:87] offset:-4096
	global_load_dword v141, v130, s[86:87] offset:-4032
	global_load_dword v142, v130, s[86:87] offset:-3968
	global_load_dword v143, v130, s[86:87] offset:-3904
	global_load_dword v144, v130, s[86:87]
	global_load_dword v145, v130, s[86:87] offset:64
	global_load_dword v146, v130, s[86:87] offset:128
	global_load_dword v147, v130, s[86:87] offset:192
	global_load_dwordx4 v[156:159], v132, s[4:5] offset:384
	s_waitcnt vmcnt(17)
; DEV void phase_ln(const Params& P, const float* __restrict__ g, const float* __restrict__ bta, u16* __restrict__ xb, bool zero_kc) {
;     ...
;         y.x = v[r][i].x * rs * gv[i].x + bv[i].x;
;         y.y = v[r][i].y * rs * gv[i].y + bv[i].y;
;         y.z = v[r][i].z * rs * gv[i].z + bv[i].z;
;         y.w = v[r][i].w * rs * gv[i].w + bv[i].w;
;     ...
; #pragma unroll
;     for (int ms = 0; ms < 8; ++ms) {
;       asm volatile("" ::: "memory");
; #pragma unroll
;       for (int ns = 0; ns < 4; ++ns)
; #pragma unroll
;         for (int j = 0; j < 4; ++j) {
;           int row = m0 + wm * 128 + ms * 16 + quad * 4 + j;
;           int col = n0 + wn * 64 + ns * 16 + l15;
;           const size_t xi = (size_t)row * D + col;
;           const float xv = xin ? xin[xi] : P.out[xi];
;           P.out[xi] = alpha * xv + sc * acc[ms][ns][j];
;         }
	v_sub_f32_e32 v148, v148, v160
	v_mul_f32_e32 v148, v148, v161
	v_fma_f32 v148, v164, v148, v168
	v_mul_f32_e32 v148, v212, v148
	v_fmac_f32_e32 v148, v211, v96
	global_store_dword v131, v148, s[86:87] offset:-4096
	v_sub_f32_e32 v149, v149, v160
	v_mul_f32_e32 v149, v149, v161
	v_fma_f32 v149, v165, v149, v169
	v_mul_f32_e32 v149, v212, v149
	v_fmac_f32_e32 v149, v211, v92
	global_store_dword v131, v149, s[86:87] offset:-4032
	v_sub_f32_e32 v150, v150, v160
	v_mul_f32_e32 v150, v150, v161
	v_fma_f32 v150, v166, v150, v170
	v_mul_f32_e32 v150, v212, v150
	v_fmac_f32_e32 v150, v211, v88
	global_store_dword v131, v150, s[86:87] offset:-3968
	v_sub_f32_e32 v151, v151, v160
	v_mul_f32_e32 v151, v151, v161
	v_fma_f32 v151, v167, v151, v171
	v_mul_f32_e32 v151, v212, v151
	v_fmac_f32_e32 v151, v211, v84
	global_store_dword v131, v151, s[86:87] offset:-3904
	v_sub_f32_e32 v152, v152, v162
	v_mul_f32_e32 v152, v152, v163
	v_fma_f32 v152, v164, v152, v168
	v_mul_f32_e32 v152, v212, v152
	v_fmac_f32_e32 v152, v211, v97
	global_store_dword v131, v152, s[86:87]
	v_sub_f32_e32 v153, v153, v162
	v_mul_f32_e32 v153, v153, v163
	v_fma_f32 v153, v165, v153, v169
	v_mul_f32_e32 v153, v212, v153
	v_fmac_f32_e32 v153, v211, v93
	global_store_dword v131, v153, s[86:87] offset:64
	v_sub_f32_e32 v154, v154, v162
	v_mul_f32_e32 v154, v154, v163
	v_fma_f32 v154, v166, v154, v170
	v_mul_f32_e32 v154, v212, v154
	v_fmac_f32_e32 v154, v211, v89
	global_store_dword v131, v154, s[86:87] offset:128
	v_sub_f32_e32 v155, v155, v162
	v_mul_f32_e32 v155, v155, v163
	v_fma_f32 v155, v167, v155, v171
	v_mul_f32_e32 v155, v212, v155
	v_fmac_f32_e32 v155, v211, v85
	global_store_dword v131, v155, s[86:87] offset:192
	v_add_u32_e32 v131, 0x32000, v138
	global_load_dword v148, v131, s[86:87] offset:-4096
	global_load_dword v149, v131, s[86:87] offset:-4032
	global_load_dword v150, v131, s[86:87] offset:-3968
	global_load_dword v151, v131, s[86:87] offset:-3904
	global_load_dword v152, v131, s[86:87]
	global_load_dword v153, v131, s[86:87] offset:64
	global_load_dword v154, v131, s[86:87] offset:128
	global_load_dword v155, v131, s[86:87] offset:192
	global_load_dwordx4 v[160:163], v132, s[4:5] offset:400
	s_waitcnt vmcnt(17)
	v_sub_f32_e32 v140, v140, v156
	v_mul_f32_e32 v140, v140, v157
	v_fma_f32 v140, v164, v140, v168
	v_mul_f32_e32 v140, v212, v140
	v_fmac_f32_e32 v140, v211, v78
	global_store_dword v130, v140, s[86:87] offset:-4096
	v_sub_f32_e32 v141, v141, v156
	v_mul_f32_e32 v141, v141, v157
	v_fma_f32 v141, v165, v141, v169
	v_mul_f32_e32 v141, v212, v141
	v_fmac_f32_e32 v141, v211, v74
	global_store_dword v130, v141, s[86:87] offset:-4032
	v_sub_f32_e32 v142, v142, v156
	v_mul_f32_e32 v142, v142, v157
	v_fma_f32 v142, v166, v142, v170
	v_mul_f32_e32 v142, v212, v142
	v_fmac_f32_e32 v142, v211, v70
	global_store_dword v130, v142, s[86:87] offset:-3968
	v_sub_f32_e32 v143, v143, v156
	v_mul_f32_e32 v143, v143, v157
	v_fma_f32 v143, v167, v143, v171
	v_mul_f32_e32 v143, v212, v143
	v_fmac_f32_e32 v143, v211, v66
	global_store_dword v130, v143, s[86:87] offset:-3904
	v_sub_f32_e32 v144, v144, v158
	v_mul_f32_e32 v144, v144, v159
	v_fma_f32 v144, v164, v144, v168
	v_mul_f32_e32 v144, v212, v144
	v_fmac_f32_e32 v144, v211, v79
	global_store_dword v130, v144, s[86:87]
	v_sub_f32_e32 v145, v145, v158
	v_mul_f32_e32 v145, v145, v159
	v_fma_f32 v145, v165, v145, v169
	v_mul_f32_e32 v145, v212, v145
	v_fmac_f32_e32 v145, v211, v75
	global_store_dword v130, v145, s[86:87] offset:64
	v_sub_f32_e32 v146, v146, v158
	v_mul_f32_e32 v146, v146, v159
	v_fma_f32 v146, v166, v146, v170
	v_mul_f32_e32 v146, v212, v146
	v_fmac_f32_e32 v146, v211, v71
	global_store_dword v130, v146, s[86:87] offset:128
	v_sub_f32_e32 v147, v147, v158
	v_mul_f32_e32 v147, v147, v159
	v_fma_f32 v147, v167, v147, v171
	v_mul_f32_e32 v147, v212, v147
	v_fmac_f32_e32 v147, v211, v67
	global_store_dword v130, v147, s[86:87] offset:192
	v_add_u32_e32 v130, 0x40000, v138
	global_load_dword v140, v130, s[86:87] offset:-4096
	global_load_dword v141, v130, s[86:87] offset:-4032
	global_load_dword v142, v130, s[86:87] offset:-3968
	global_load_dword v143, v130, s[86:87] offset:-3904
	global_load_dword v144, v130, s[86:87]
	global_load_dword v145, v130, s[86:87] offset:64
	global_load_dword v146, v130, s[86:87] offset:128
	global_load_dword v147, v130, s[86:87] offset:192
	global_load_dwordx4 v[156:159], v132, s[4:5] offset:512
	s_waitcnt vmcnt(17)
	v_sub_f32_e32 v148, v148, v160
	v_mul_f32_e32 v148, v148, v161
	v_fma_f32 v148, v164, v148, v168
	v_mul_f32_e32 v148, v212, v148
	v_fmac_f32_e32 v148, v211, v80
	global_store_dword v131, v148, s[86:87] offset:-4096
	v_sub_f32_e32 v149, v149, v160
	v_mul_f32_e32 v149, v149, v161
	v_fma_f32 v149, v165, v149, v169
	v_mul_f32_e32 v149, v212, v149
	v_fmac_f32_e32 v149, v211, v76
	global_store_dword v131, v149, s[86:87] offset:-4032
	v_sub_f32_e32 v150, v150, v160
	v_mul_f32_e32 v150, v150, v161
	v_fma_f32 v150, v166, v150, v170
	v_mul_f32_e32 v150, v212, v150
	v_fmac_f32_e32 v150, v211, v72
	global_store_dword v131, v150, s[86:87] offset:-3968
	v_sub_f32_e32 v151, v151, v160
	v_mul_f32_e32 v151, v151, v161
	v_fma_f32 v151, v167, v151, v171
	v_mul_f32_e32 v151, v212, v151
	v_fmac_f32_e32 v151, v211, v68
	global_store_dword v131, v151, s[86:87] offset:-3904
	v_sub_f32_e32 v152, v152, v162
	v_mul_f32_e32 v152, v152, v163
	v_fma_f32 v152, v164, v152, v168
	v_mul_f32_e32 v152, v212, v152
	v_fmac_f32_e32 v152, v211, v81
	global_store_dword v131, v152, s[86:87]
	v_sub_f32_e32 v153, v153, v162
	v_mul_f32_e32 v153, v153, v163
	v_fma_f32 v153, v165, v153, v169
	v_mul_f32_e32 v153, v212, v153
	v_fmac_f32_e32 v153, v211, v77
	global_store_dword v131, v153, s[86:87] offset:64
	v_sub_f32_e32 v154, v154, v162
	v_mul_f32_e32 v154, v154, v163
	v_fma_f32 v154, v166, v154, v170
	v_mul_f32_e32 v154, v212, v154
	v_fmac_f32_e32 v154, v211, v73
	global_store_dword v131, v154, s[86:87] offset:128
	v_sub_f32_e32 v155, v155, v162
	v_mul_f32_e32 v155, v155, v163
	v_fma_f32 v155, v167, v155, v171
	v_mul_f32_e32 v155, v212, v155
	v_fmac_f32_e32 v155, v211, v69
	global_store_dword v131, v155, s[86:87] offset:192
	v_add_u32_e32 v131, 0x42000, v138
	global_load_dword v148, v131, s[86:87] offset:-4096
	global_load_dword v149, v131, s[86:87] offset:-4032
	global_load_dword v150, v131, s[86:87] offset:-3968
	global_load_dword v151, v131, s[86:87] offset:-3904
	global_load_dword v152, v131, s[86:87]
	global_load_dword v153, v131, s[86:87] offset:64
	global_load_dword v154, v131, s[86:87] offset:128
	global_load_dword v155, v131, s[86:87] offset:192
	global_load_dwordx4 v[160:163], v132, s[4:5] offset:528
	s_waitcnt vmcnt(17)
; DEV void phase_ln(const Params& P, const float* __restrict__ g, const float* __restrict__ bta, u16* __restrict__ xb, bool zero_kc) {
;     ...
;         y.x = v[r][i].x * rs * gv[i].x + bv[i].x;
;         y.y = v[r][i].y * rs * gv[i].y + bv[i].y;
;         y.z = v[r][i].z * rs * gv[i].z + bv[i].z;
;         y.w = v[r][i].w * rs * gv[i].w + bv[i].w;
;     ...
; #pragma unroll
;     for (int ms = 0; ms < 8; ++ms) {
;       asm volatile("" ::: "memory");
; #pragma unroll
;       for (int ns = 0; ns < 4; ++ns)
; #pragma unroll
;         for (int j = 0; j < 4; ++j) {
;           int row = m0 + wm * 128 + ms * 16 + quad * 4 + j;
;           int col = n0 + wn * 64 + ns * 16 + l15;
;           const size_t xi = (size_t)row * D + col;
;           const float xv = xin ? xin[xi] : P.out[xi];
;           P.out[xi] = alpha * xv + sc * acc[ms][ns][j];
;         }
	v_sub_f32_e32 v140, v140, v156
	v_mul_f32_e32 v140, v140, v157
	v_fma_f32 v140, v164, v140, v168
	v_mul_f32_e32 v140, v212, v140
	v_fmac_f32_e32 v140, v211, v62
	global_store_dword v130, v140, s[86:87] offset:-4096
	v_sub_f32_e32 v141, v141, v156
	v_mul_f32_e32 v141, v141, v157
	v_fma_f32 v141, v165, v141, v169
	v_mul_f32_e32 v141, v212, v141
	v_fmac_f32_e32 v141, v211, v58
	global_store_dword v130, v141, s[86:87] offset:-4032
	v_sub_f32_e32 v142, v142, v156
	v_mul_f32_e32 v142, v142, v157
	v_fma_f32 v142, v166, v142, v170
	v_mul_f32_e32 v142, v212, v142
	v_fmac_f32_e32 v142, v211, v54
	global_store_dword v130, v142, s[86:87] offset:-3968
	v_sub_f32_e32 v143, v143, v156
	v_mul_f32_e32 v143, v143, v157
	v_fma_f32 v143, v167, v143, v171
	v_mul_f32_e32 v143, v212, v143
	v_fmac_f32_e32 v143, v211, v50
	global_store_dword v130, v143, s[86:87] offset:-3904
	v_sub_f32_e32 v144, v144, v158
	v_mul_f32_e32 v144, v144, v159
	v_fma_f32 v144, v164, v144, v168
	v_mul_f32_e32 v144, v212, v144
	v_fmac_f32_e32 v144, v211, v63
	global_store_dword v130, v144, s[86:87]
	v_sub_f32_e32 v145, v145, v158
	v_mul_f32_e32 v145, v145, v159
	v_fma_f32 v145, v165, v145, v169
	v_mul_f32_e32 v145, v212, v145
	v_fmac_f32_e32 v145, v211, v59
	global_store_dword v130, v145, s[86:87] offset:64
	v_sub_f32_e32 v146, v146, v158
	v_mul_f32_e32 v146, v146, v159
	v_fma_f32 v146, v166, v146, v170
	v_mul_f32_e32 v146, v212, v146
	v_fmac_f32_e32 v146, v211, v55
	global_store_dword v130, v146, s[86:87] offset:128
	v_sub_f32_e32 v147, v147, v158
	v_mul_f32_e32 v147, v147, v159
	v_fma_f32 v147, v167, v147, v171
	v_mul_f32_e32 v147, v212, v147
	v_fmac_f32_e32 v147, v211, v51
	global_store_dword v130, v147, s[86:87] offset:192
	v_add_u32_e32 v130, 0x50000, v138
	global_load_dword v140, v130, s[86:87] offset:-4096
	global_load_dword v141, v130, s[86:87] offset:-4032
	global_load_dword v142, v130, s[86:87] offset:-3968
	global_load_dword v143, v130, s[86:87] offset:-3904
	global_load_dword v144, v130, s[86:87]
	global_load_dword v145, v130, s[86:87] offset:64
	global_load_dword v146, v130, s[86:87] offset:128
	global_load_dword v147, v130, s[86:87] offset:192
	global_load_dwordx4 v[156:159], v132, s[4:5] offset:640
	s_waitcnt vmcnt(17)
	v_sub_f32_e32 v148, v148, v160
	v_mul_f32_e32 v148, v148, v161
	v_fma_f32 v148, v164, v148, v168
	v_mul_f32_e32 v148, v212, v148
	v_fmac_f32_e32 v148, v211, v64
	global_store_dword v131, v148, s[86:87] offset:-4096
	v_sub_f32_e32 v149, v149, v160
	v_mul_f32_e32 v149, v149, v161
	v_fma_f32 v149, v165, v149, v169
	v_mul_f32_e32 v149, v212, v149
	v_fmac_f32_e32 v149, v211, v60
	global_store_dword v131, v149, s[86:87] offset:-4032
	v_sub_f32_e32 v150, v150, v160
	v_mul_f32_e32 v150, v150, v161
	v_fma_f32 v150, v166, v150, v170
	v_mul_f32_e32 v150, v212, v150
	v_fmac_f32_e32 v150, v211, v56
	global_store_dword v131, v150, s[86:87] offset:-3968
	v_sub_f32_e32 v151, v151, v160
	v_mul_f32_e32 v151, v151, v161
	v_fma_f32 v151, v167, v151, v171
	v_mul_f32_e32 v151, v212, v151
	v_fmac_f32_e32 v151, v211, v52
	global_store_dword v131, v151, s[86:87] offset:-3904
	v_sub_f32_e32 v152, v152, v162
	v_mul_f32_e32 v152, v152, v163
	v_fma_f32 v152, v164, v152, v168
	v_mul_f32_e32 v152, v212, v152
	v_fmac_f32_e32 v152, v211, v65
	global_store_dword v131, v152, s[86:87]
	v_sub_f32_e32 v153, v153, v162
	v_mul_f32_e32 v153, v153, v163
	v_fma_f32 v153, v165, v153, v169
	v_mul_f32_e32 v153, v212, v153
	v_fmac_f32_e32 v153, v211, v61
	global_store_dword v131, v153, s[86:87] offset:64
	v_sub_f32_e32 v154, v154, v162
	v_mul_f32_e32 v154, v154, v163
	v_fma_f32 v154, v166, v154, v170
	v_mul_f32_e32 v154, v212, v154
	v_fmac_f32_e32 v154, v211, v57
	global_store_dword v131, v154, s[86:87] offset:128
	v_sub_f32_e32 v155, v155, v162
	v_mul_f32_e32 v155, v155, v163
	v_fma_f32 v155, v167, v155, v171
	v_mul_f32_e32 v155, v212, v155
	v_fmac_f32_e32 v155, v211, v53
	global_store_dword v131, v155, s[86:87] offset:192
	v_add_u32_e32 v131, 0x52000, v138
	global_load_dword v148, v131, s[86:87] offset:-4096
	global_load_dword v149, v131, s[86:87] offset:-4032
	global_load_dword v150, v131, s[86:87] offset:-3968
	global_load_dword v151, v131, s[86:87] offset:-3904
	global_load_dword v152, v131, s[86:87]
	global_load_dword v153, v131, s[86:87] offset:64
	global_load_dword v154, v131, s[86:87] offset:128
	global_load_dword v155, v131, s[86:87] offset:192
	global_load_dwordx4 v[160:163], v132, s[4:5] offset:656
	s_waitcnt vmcnt(17)
	v_sub_f32_e32 v140, v140, v156
	v_mul_f32_e32 v140, v140, v157
	v_fma_f32 v140, v164, v140, v168
	v_mul_f32_e32 v140, v212, v140
	v_fmac_f32_e32 v140, v211, v46
	global_store_dword v130, v140, s[86:87] offset:-4096
	v_sub_f32_e32 v141, v141, v156
	v_mul_f32_e32 v141, v141, v157
	v_fma_f32 v141, v165, v141, v169
	v_mul_f32_e32 v141, v212, v141
	v_fmac_f32_e32 v141, v211, v42
	global_store_dword v130, v141, s[86:87] offset:-4032
	v_sub_f32_e32 v142, v142, v156
	v_mul_f32_e32 v142, v142, v157
	v_fma_f32 v142, v166, v142, v170
	v_mul_f32_e32 v142, v212, v142
	v_fmac_f32_e32 v142, v211, v38
	global_store_dword v130, v142, s[86:87] offset:-3968
	v_sub_f32_e32 v143, v143, v156
	v_mul_f32_e32 v143, v143, v157
	v_fma_f32 v143, v167, v143, v171
	v_mul_f32_e32 v143, v212, v143
	v_fmac_f32_e32 v143, v211, v34
	global_store_dword v130, v143, s[86:87] offset:-3904
	v_sub_f32_e32 v144, v144, v158
	v_mul_f32_e32 v144, v144, v159
	v_fma_f32 v144, v164, v144, v168
	v_mul_f32_e32 v144, v212, v144
	v_fmac_f32_e32 v144, v211, v47
	global_store_dword v130, v144, s[86:87]
	v_sub_f32_e32 v145, v145, v158
	v_mul_f32_e32 v145, v145, v159
	v_fma_f32 v145, v165, v145, v169
	v_mul_f32_e32 v145, v212, v145
	v_fmac_f32_e32 v145, v211, v43
	global_store_dword v130, v145, s[86:87] offset:64
	v_sub_f32_e32 v146, v146, v158
	v_mul_f32_e32 v146, v146, v159
	v_fma_f32 v146, v166, v146, v170
	v_mul_f32_e32 v146, v212, v146
	v_fmac_f32_e32 v146, v211, v39
	global_store_dword v130, v146, s[86:87] offset:128
	v_sub_f32_e32 v147, v147, v158
	v_mul_f32_e32 v147, v147, v159
	v_fma_f32 v147, v167, v147, v171
	v_mul_f32_e32 v147, v212, v147
	v_fmac_f32_e32 v147, v211, v35
	global_store_dword v130, v147, s[86:87] offset:192
	v_add_u32_e32 v130, 0x60000, v138
	global_load_dword v140, v130, s[86:87] offset:-4096
	global_load_dword v141, v130, s[86:87] offset:-4032
	global_load_dword v142, v130, s[86:87] offset:-3968
	global_load_dword v143, v130, s[86:87] offset:-3904
	global_load_dword v144, v130, s[86:87]
	global_load_dword v145, v130, s[86:87] offset:64
	global_load_dword v146, v130, s[86:87] offset:128
	global_load_dword v147, v130, s[86:87] offset:192
	global_load_dwordx4 v[156:159], v132, s[4:5] offset:768
	s_waitcnt vmcnt(17)
; DEV void phase_ln(const Params& P, const float* __restrict__ g, const float* __restrict__ bta, u16* __restrict__ xb, bool zero_kc) {
;     ...
;         y.x = v[r][i].x * rs * gv[i].x + bv[i].x;
;         y.y = v[r][i].y * rs * gv[i].y + bv[i].y;
;         y.z = v[r][i].z * rs * gv[i].z + bv[i].z;
;         y.w = v[r][i].w * rs * gv[i].w + bv[i].w;
;     ...
; #pragma unroll
;     for (int ms = 0; ms < 8; ++ms) {
;       asm volatile("" ::: "memory");
; #pragma unroll
;       for (int ns = 0; ns < 4; ++ns)
; #pragma unroll
;         for (int j = 0; j < 4; ++j) {
;           int row = m0 + wm * 128 + ms * 16 + quad * 4 + j;
;           int col = n0 + wn * 64 + ns * 16 + l15;
;           const size_t xi = (size_t)row * D + col;
;           const float xv = xin ? xin[xi] : P.out[xi];
;           P.out[xi] = alpha * xv + sc * acc[ms][ns][j];
;         }
	v_sub_f32_e32 v148, v148, v160
	v_mul_f32_e32 v148, v148, v161
	v_fma_f32 v148, v164, v148, v168
	v_mul_f32_e32 v148, v212, v148
	v_fmac_f32_e32 v148, v211, v48
	global_store_dword v131, v148, s[86:87] offset:-4096
	v_sub_f32_e32 v149, v149, v160
	v_mul_f32_e32 v149, v149, v161
	v_fma_f32 v149, v165, v149, v169
	v_mul_f32_e32 v149, v212, v149
	v_fmac_f32_e32 v149, v211, v44
	global_store_dword v131, v149, s[86:87] offset:-4032
	v_sub_f32_e32 v150, v150, v160
	v_mul_f32_e32 v150, v150, v161
	v_fma_f32 v150, v166, v150, v170
	v_mul_f32_e32 v150, v212, v150
	v_fmac_f32_e32 v150, v211, v40
	global_store_dword v131, v150, s[86:87] offset:-3968
	v_sub_f32_e32 v151, v151, v160
	v_mul_f32_e32 v151, v151, v161
	v_fma_f32 v151, v167, v151, v171
	v_mul_f32_e32 v151, v212, v151
	v_fmac_f32_e32 v151, v211, v36
	global_store_dword v131, v151, s[86:87] offset:-3904
	v_sub_f32_e32 v152, v152, v162
	v_mul_f32_e32 v152, v152, v163
	v_fma_f32 v152, v164, v152, v168
	v_mul_f32_e32 v152, v212, v152
	v_fmac_f32_e32 v152, v211, v49
	global_store_dword v131, v152, s[86:87]
	v_sub_f32_e32 v153, v153, v162
	v_mul_f32_e32 v153, v153, v163
	v_fma_f32 v153, v165, v153, v169
	v_mul_f32_e32 v153, v212, v153
	v_fmac_f32_e32 v153, v211, v45
	global_store_dword v131, v153, s[86:87] offset:64
	v_sub_f32_e32 v154, v154, v162
	v_mul_f32_e32 v154, v154, v163
	v_fma_f32 v154, v166, v154, v170
	v_mul_f32_e32 v154, v212, v154
	v_fmac_f32_e32 v154, v211, v41
	global_store_dword v131, v154, s[86:87] offset:128
	v_sub_f32_e32 v155, v155, v162
	v_mul_f32_e32 v155, v155, v163
	v_fma_f32 v155, v167, v155, v171
	v_mul_f32_e32 v155, v212, v155
	v_fmac_f32_e32 v155, v211, v37
	global_store_dword v131, v155, s[86:87] offset:192
	v_add_u32_e32 v131, 0x62000, v138
	global_load_dword v148, v131, s[86:87] offset:-4096
	global_load_dword v149, v131, s[86:87] offset:-4032
	global_load_dword v150, v131, s[86:87] offset:-3968
	global_load_dword v151, v131, s[86:87] offset:-3904
	global_load_dword v152, v131, s[86:87]
	global_load_dword v153, v131, s[86:87] offset:64
	global_load_dword v154, v131, s[86:87] offset:128
	global_load_dword v155, v131, s[86:87] offset:192
	global_load_dwordx4 v[160:163], v132, s[4:5] offset:784
	s_waitcnt vmcnt(17)
	v_sub_f32_e32 v140, v140, v156
	v_mul_f32_e32 v140, v140, v157
	v_fma_f32 v140, v164, v140, v168
	v_mul_f32_e32 v140, v212, v140
	v_fmac_f32_e32 v140, v211, v30
	global_store_dword v130, v140, s[86:87] offset:-4096
	v_sub_f32_e32 v141, v141, v156
	v_mul_f32_e32 v141, v141, v157
	v_fma_f32 v141, v165, v141, v169
	v_mul_f32_e32 v141, v212, v141
	v_fmac_f32_e32 v141, v211, v26
	global_store_dword v130, v141, s[86:87] offset:-4032
	v_sub_f32_e32 v142, v142, v156
	v_mul_f32_e32 v142, v142, v157
	v_fma_f32 v142, v166, v142, v170
	v_mul_f32_e32 v142, v212, v142
	v_fmac_f32_e32 v142, v211, v22
	global_store_dword v130, v142, s[86:87] offset:-3968
	v_sub_f32_e32 v143, v143, v156
	v_mul_f32_e32 v143, v143, v157
	v_fma_f32 v143, v167, v143, v171
	v_mul_f32_e32 v143, v212, v143
	v_fmac_f32_e32 v143, v211, v18
	global_store_dword v130, v143, s[86:87] offset:-3904
	v_sub_f32_e32 v144, v144, v158
	v_mul_f32_e32 v144, v144, v159
	v_fma_f32 v144, v164, v144, v168
	v_mul_f32_e32 v144, v212, v144
	v_fmac_f32_e32 v144, v211, v31
	global_store_dword v130, v144, s[86:87]
	v_sub_f32_e32 v145, v145, v158
	v_mul_f32_e32 v145, v145, v159
	v_fma_f32 v145, v165, v145, v169
	v_mul_f32_e32 v145, v212, v145
	v_fmac_f32_e32 v145, v211, v27
	global_store_dword v130, v145, s[86:87] offset:64
	v_sub_f32_e32 v146, v146, v158
	v_mul_f32_e32 v146, v146, v159
	v_fma_f32 v146, v166, v146, v170
	v_mul_f32_e32 v146, v212, v146
	v_fmac_f32_e32 v146, v211, v23
	global_store_dword v130, v146, s[86:87] offset:128
	v_sub_f32_e32 v147, v147, v158
	v_mul_f32_e32 v147, v147, v159
	v_fma_f32 v147, v167, v147, v171
	v_mul_f32_e32 v147, v212, v147
	v_fmac_f32_e32 v147, v211, v19
	global_store_dword v130, v147, s[86:87] offset:192
	v_add_u32_e32 v130, 0x70000, v138
	global_load_dword v140, v130, s[86:87] offset:-4096
	global_load_dword v141, v130, s[86:87] offset:-4032
	global_load_dword v142, v130, s[86:87] offset:-3968
	global_load_dword v143, v130, s[86:87] offset:-3904
	global_load_dword v144, v130, s[86:87]
	global_load_dword v145, v130, s[86:87] offset:64
	global_load_dword v146, v130, s[86:87] offset:128
	global_load_dword v147, v130, s[86:87] offset:192
	global_load_dwordx4 v[156:159], v132, s[4:5] offset:896
	s_waitcnt vmcnt(17)
; DEV void phase_ln(const Params& P, const float* __restrict__ g, const float* __restrict__ bta, u16* __restrict__ xb, bool zero_kc) {
;     ...
;         y.x = v[r][i].x * rs * gv[i].x + bv[i].x;
;         y.y = v[r][i].y * rs * gv[i].y + bv[i].y;
;         y.z = v[r][i].z * rs * gv[i].z + bv[i].z;
;         y.w = v[r][i].w * rs * gv[i].w + bv[i].w;
;     ...
; #pragma unroll
;     for (int ms = 0; ms < 8; ++ms) {
;       asm volatile("" ::: "memory");
; #pragma unroll
;       for (int ns = 0; ns < 4; ++ns)
; #pragma unroll
;         for (int j = 0; j < 4; ++j) {
;           int row = m0 + wm * 128 + ms * 16 + quad * 4 + j;
;           int col = n0 + wn * 64 + ns * 16 + l15;
;           const size_t xi = (size_t)row * D + col;
;           const float xv = xin ? xin[xi] : P.out[xi];
;           P.out[xi] = alpha * xv + sc * acc[ms][ns][j];
;         }
	v_sub_f32_e32 v148, v148, v160
	v_mul_f32_e32 v148, v148, v161
	v_fma_f32 v148, v164, v148, v168
	v_mul_f32_e32 v148, v212, v148
	v_fmac_f32_e32 v148, v211, v32
	global_store_dword v131, v148, s[86:87] offset:-4096
	v_sub_f32_e32 v149, v149, v160
	v_mul_f32_e32 v149, v149, v161
	v_fma_f32 v149, v165, v149, v169
	v_mul_f32_e32 v149, v212, v149
	v_fmac_f32_e32 v149, v211, v28
	global_store_dword v131, v149, s[86:87] offset:-4032
	v_sub_f32_e32 v150, v150, v160
	v_mul_f32_e32 v150, v150, v161
	v_fma_f32 v150, v166, v150, v170
	v_mul_f32_e32 v150, v212, v150
	v_fmac_f32_e32 v150, v211, v24
	global_store_dword v131, v150, s[86:87] offset:-3968
	v_sub_f32_e32 v151, v151, v160
	v_mul_f32_e32 v151, v151, v161
	v_fma_f32 v151, v167, v151, v171
	v_mul_f32_e32 v151, v212, v151
	v_fmac_f32_e32 v151, v211, v20
	global_store_dword v131, v151, s[86:87] offset:-3904
	v_sub_f32_e32 v152, v152, v162
	v_mul_f32_e32 v152, v152, v163
	v_fma_f32 v152, v164, v152, v168
	v_mul_f32_e32 v152, v212, v152
	v_fmac_f32_e32 v152, v211, v33
	global_store_dword v131, v152, s[86:87]
	v_sub_f32_e32 v153, v153, v162
	v_mul_f32_e32 v153, v153, v163
	v_fma_f32 v153, v165, v153, v169
	v_mul_f32_e32 v153, v212, v153
	v_fmac_f32_e32 v153, v211, v29
	global_store_dword v131, v153, s[86:87] offset:64
	v_sub_f32_e32 v154, v154, v162
	v_mul_f32_e32 v154, v154, v163
	v_fma_f32 v154, v166, v154, v170
	v_mul_f32_e32 v154, v212, v154
	v_fmac_f32_e32 v154, v211, v25
	global_store_dword v131, v154, s[86:87] offset:128
	v_sub_f32_e32 v155, v155, v162
	v_mul_f32_e32 v155, v155, v163
	v_fma_f32 v155, v167, v155, v171
	v_mul_f32_e32 v155, v212, v155
	v_fmac_f32_e32 v155, v211, v21
	global_store_dword v131, v155, s[86:87] offset:192
	v_add_u32_e32 v131, 0x72000, v138
	global_load_dword v148, v131, s[86:87] offset:-4096
	global_load_dword v149, v131, s[86:87] offset:-4032
	global_load_dword v150, v131, s[86:87] offset:-3968
	global_load_dword v151, v131, s[86:87] offset:-3904
	global_load_dword v152, v131, s[86:87]
	global_load_dword v153, v131, s[86:87] offset:64
	global_load_dword v154, v131, s[86:87] offset:128
	global_load_dword v155, v131, s[86:87] offset:192
	global_load_dwordx4 v[160:163], v132, s[4:5] offset:912
	s_waitcnt vmcnt(17)
	v_sub_f32_e32 v140, v140, v156
	v_mul_f32_e32 v140, v140, v157
	v_fma_f32 v140, v164, v140, v168
	v_mul_f32_e32 v140, v212, v140
	v_fmac_f32_e32 v140, v211, v14
	global_store_dword v130, v140, s[86:87] offset:-4096
	v_sub_f32_e32 v141, v141, v156
	v_mul_f32_e32 v141, v141, v157
	v_fma_f32 v141, v165, v141, v169
	v_mul_f32_e32 v141, v212, v141
	v_fmac_f32_e32 v141, v211, v10
	global_store_dword v130, v141, s[86:87] offset:-4032
	v_sub_f32_e32 v142, v142, v156
	v_mul_f32_e32 v142, v142, v157
	v_fma_f32 v142, v166, v142, v170
	v_mul_f32_e32 v142, v212, v142
	v_fmac_f32_e32 v142, v211, v6
	global_store_dword v130, v142, s[86:87] offset:-3968
	v_sub_f32_e32 v143, v143, v156
	v_mul_f32_e32 v143, v143, v157
	v_fma_f32 v143, v167, v143, v171
	v_mul_f32_e32 v143, v212, v143
	v_fmac_f32_e32 v143, v211, v2
	global_store_dword v130, v143, s[86:87] offset:-3904
	v_sub_f32_e32 v144, v144, v158
	v_mul_f32_e32 v144, v144, v159
	v_fma_f32 v144, v164, v144, v168
	v_mul_f32_e32 v144, v212, v144
	v_fmac_f32_e32 v144, v211, v15
	global_store_dword v130, v144, s[86:87]
	v_sub_f32_e32 v145, v145, v158
	v_mul_f32_e32 v145, v145, v159
	v_fma_f32 v145, v165, v145, v169
	v_mul_f32_e32 v145, v212, v145
	v_fmac_f32_e32 v145, v211, v11
	global_store_dword v130, v145, s[86:87] offset:64
	v_sub_f32_e32 v146, v146, v158
	v_mul_f32_e32 v146, v146, v159
	v_fma_f32 v146, v166, v146, v170
	v_mul_f32_e32 v146, v212, v146
	v_fmac_f32_e32 v146, v211, v7
	global_store_dword v130, v146, s[86:87] offset:128
	v_sub_f32_e32 v147, v147, v158
	v_mul_f32_e32 v147, v147, v159
	v_fma_f32 v147, v167, v147, v171
	v_mul_f32_e32 v147, v212, v147
	v_fmac_f32_e32 v147, v211, v3
	global_store_dword v130, v147, s[86:87] offset:192
	s_waitcnt vmcnt(8)
	v_sub_f32_e32 v148, v148, v160
	v_mul_f32_e32 v148, v148, v161
	v_fma_f32 v148, v164, v148, v168
	v_mul_f32_e32 v148, v212, v148
	v_fmac_f32_e32 v148, v211, v16
	global_store_dword v131, v148, s[86:87] offset:-4096
	v_sub_f32_e32 v149, v149, v160
	v_mul_f32_e32 v149, v149, v161
	v_fma_f32 v149, v165, v149, v169
	v_mul_f32_e32 v149, v212, v149
	v_fmac_f32_e32 v149, v211, v12
	global_store_dword v131, v149, s[86:87] offset:-4032
	v_sub_f32_e32 v150, v150, v160
	v_mul_f32_e32 v150, v150, v161
	v_fma_f32 v150, v166, v150, v170
	v_mul_f32_e32 v150, v212, v150
	v_fmac_f32_e32 v150, v211, v8
	global_store_dword v131, v150, s[86:87] offset:-3968
	v_sub_f32_e32 v151, v151, v160
	v_mul_f32_e32 v151, v151, v161
	v_fma_f32 v151, v167, v151, v171
	v_mul_f32_e32 v151, v212, v151
	v_fmac_f32_e32 v151, v211, v4
	global_store_dword v131, v151, s[86:87] offset:-3904
	v_sub_f32_e32 v152, v152, v162
	v_mul_f32_e32 v152, v152, v163
	v_fma_f32 v152, v164, v152, v168
	v_mul_f32_e32 v152, v212, v152
	v_fmac_f32_e32 v152, v211, v17
	global_store_dword v131, v152, s[86:87]
	v_sub_f32_e32 v153, v153, v162
	v_mul_f32_e32 v153, v153, v163
	v_fma_f32 v153, v165, v153, v169
	v_mul_f32_e32 v153, v212, v153
	v_fmac_f32_e32 v153, v211, v13
	global_store_dword v131, v153, s[86:87] offset:64
	v_sub_f32_e32 v154, v154, v162
	v_mul_f32_e32 v154, v154, v163
	v_fma_f32 v154, v166, v154, v170
	v_mul_f32_e32 v154, v212, v154
	v_fmac_f32_e32 v154, v211, v9
	global_store_dword v131, v154, s[86:87] offset:128
	v_sub_f32_e32 v155, v155, v162
	v_mul_f32_e32 v155, v155, v163
	v_fma_f32 v155, v167, v155, v171
	v_mul_f32_e32 v155, v212, v155
	v_fmac_f32_e32 v155, v211, v5
	global_store_dword v131, v155, s[86:87] offset:192
	s_cbranch_vccnz .LBB0_130

; DEV void phase_ln(const Params& P, const float* __restrict__ g, const float* __restrict__ bta, u16* __restrict__ xb, bool zero_kc) {
;     ...
;         y.x = v[r][i].x * rs * gv[i].x + bv[i].x;
;         y.y = v[r][i].y * rs * gv[i].y + bv[i].y;
;         y.z = v[r][i].z * rs * gv[i].z + bv[i].z;
;         y.w = v[r][i].w * rs * gv[i].w + bv[i].w;
;     ...
; #pragma unroll
;     for (int ms = 0; ms < 8; ++ms) {
;       asm volatile("" ::: "memory");
; #pragma unroll
;       for (int ns = 0; ns < 4; ++ns)
; #pragma unroll
;         for (int j = 0; j < 4; ++j) {
;           int row = m0 + wm * 128 + ms * 16 + quad * 4 + j;
;           int col = n0 + wn * 64 + ns * 16 + l15;
;           const size_t xi = (size_t)row * D + col;
;           const float xv = xin ? xin[xi] : P.out[xi];
;           P.out[xi] = alpha * xv + sc * acc[ms][ns][j];
;         }
.LBB0_134:
	v_add_u32_e32 v136, s12, v183
	v_or_b32_e32 v130, s13, v178
	v_lshlrev_b32_e32 v132, 3, v136
	v_lshlrev_b32_e32 v133, 2, v130
	v_lshlrev_b32_e32 v136, 12, v136
	v_lshl_add_u32 v138, v130, 2, v136
	v_add_u32_e32 v138, 0x1000, v138
	s_and_b64 vcc, exec, s[8:9]
	v_readlane_b32 s4, v255, 10
	v_readlane_b32 s5, v255, 11
	s_add_u32 s4, s4, 0x1000
	s_addc_u32 s5, s5, 0
	s_nop 1
	global_load_dword v164, v133, s[4:5]
	global_load_dword v165, v133, s[4:5] offset:64
	global_load_dword v166, v133, s[4:5] offset:128
	global_load_dword v167, v133, s[4:5] offset:192
	v_readlane_b32 s4, v255, 12
	v_readlane_b32 s5, v255, 13
	s_add_u32 s4, s4, 0x1000
	s_addc_u32 s5, s5, 0
	s_nop 1
	global_load_dword v168, v133, s[4:5]
	global_load_dword v169, v133, s[4:5] offset:64
	global_load_dword v170, v133, s[4:5] offset:128
	global_load_dword v171, v133, s[4:5] offset:192
	v_readlane_b32 s4, v255, 8
	s_add_i32 s4, s4, 2
	s_and_b32 s4, s4, 3
	s_lshl_b32 s4, s4, 24
	s_add_u32 s4, s4, 0x25040000
	s_add_u32 s4, s38, s4
	s_addc_u32 s5, s39, 0
	s_nop 1
	v_mov_b32_e32 v130, v138
	global_load_dword v140, v130, s[86:87] offset:-4096
	global_load_dword v141, v130, s[86:87] offset:-4032
	global_load_dword v142, v130, s[86:87] offset:-3968
	global_load_dword v143, v130, s[86:87] offset:-3904
	global_load_dword v144, v130, s[86:87]
	global_load_dword v145, v130, s[86:87] offset:64
	global_load_dword v146, v130, s[86:87] offset:128
	global_load_dword v147, v130, s[86:87] offset:192
	global_load_dwordx4 v[156:159], v132, s[4:5]
	v_add_u32_e32 v131, 0x2000, v138
	global_load_dword v148, v131, s[86:87] offset:-4096
	global_load_dword v149, v131, s[86:87] offset:-4032
	global_load_dword v150, v131, s[86:87] offset:-3968
	global_load_dword v151, v131, s[86:87] offset:-3904
	global_load_dword v152, v131, s[86:87]
	global_load_dword v153, v131, s[86:87] offset:64
	global_load_dword v154, v131, s[86:87] offset:128
	global_load_dword v155, v131, s[86:87] offset:192
	global_load_dwordx4 v[160:163], v132, s[4:5] offset:16
	s_waitcnt vmcnt(9)
	v_sub_f32_e32 v140, v140, v156
	v_mul_f32_e32 v140, v140, v157
	v_fma_f32 v140, v164, v140, v168
	v_mul_f32_e32 v140, v212, v140
	v_fmac_f32_e32 v140, v211, v126
	global_store_dword v130, v140, s[86:87] offset:-4096
	v_sub_f32_e32 v141, v141, v156
	v_mul_f32_e32 v141, v141, v157
	v_fma_f32 v141, v165, v141, v169
	v_mul_f32_e32 v141, v212, v141
	v_fmac_f32_e32 v141, v211, v122
	global_store_dword v130, v141, s[86:87] offset:-4032
	v_sub_f32_e32 v142, v142, v156
	v_mul_f32_e32 v142, v142, v157
	v_fma_f32 v142, v166, v142, v170
	v_mul_f32_e32 v142, v212, v142
	v_fmac_f32_e32 v142, v211, v118
	global_store_dword v130, v142, s[86:87] offset:-3968
	v_sub_f32_e32 v143, v143, v156
	v_mul_f32_e32 v143, v143, v157
	v_fma_f32 v143, v167, v143, v171
	v_mul_f32_e32 v143, v212, v143
	v_fmac_f32_e32 v143, v211, v114
	global_store_dword v130, v143, s[86:87] offset:-3904
	v_sub_f32_e32 v144, v144, v158
	v_mul_f32_e32 v144, v144, v159
	v_fma_f32 v144, v164, v144, v168
	v_mul_f32_e32 v144, v212, v144
	v_fmac_f32_e32 v144, v211, v127
	global_store_dword v130, v144, s[86:87]
	v_sub_f32_e32 v145, v145, v158
	v_mul_f32_e32 v145, v145, v159
	v_fma_f32 v145, v165, v145, v169
	v_mul_f32_e32 v145, v212, v145
	v_fmac_f32_e32 v145, v211, v123
	global_store_dword v130, v145, s[86:87] offset:64
	v_sub_f32_e32 v146, v146, v158
	v_mul_f32_e32 v146, v146, v159
	v_fma_f32 v146, v166, v146, v170
	v_mul_f32_e32 v146, v212, v146
	v_fmac_f32_e32 v146, v211, v119
	global_store_dword v130, v146, s[86:87] offset:128
	v_sub_f32_e32 v147, v147, v158
	v_mul_f32_e32 v147, v147, v159
	v_fma_f32 v147, v167, v147, v171
	v_mul_f32_e32 v147, v212, v147
	v_fmac_f32_e32 v147, v211, v115
	global_store_dword v130, v147, s[86:87] offset:192
	v_add_u32_e32 v130, 0x10000, v138
	global_load_dword v140, v130, s[86:87] offset:-4096
	global_load_dword v141, v130, s[86:87] offset:-4032
	global_load_dword v142, v130, s[86:87] offset:-3968
	global_load_dword v143, v130, s[86:87] offset:-3904
	global_load_dword v144, v130, s[86:87]
	global_load_dword v145, v130, s[86:87] offset:64
	global_load_dword v146, v130, s[86:87] offset:128
	global_load_dword v147, v130, s[86:87] offset:192
	global_load_dwordx4 v[156:159], v132, s[4:5] offset:128
	s_waitcnt vmcnt(17)
	v_sub_f32_e32 v148, v148, v160
	v_mul_f32_e32 v148, v148, v161
	v_fma_f32 v148, v164, v148, v168
	v_mul_f32_e32 v148, v212, v148
	v_fmac_f32_e32 v148, v211, v128
	global_store_dword v131, v148, s[86:87] offset:-4096
	v_sub_f32_e32 v149, v149, v160
	v_mul_f32_e32 v149, v149, v161
	v_fma_f32 v149, v165, v149, v169
	v_mul_f32_e32 v149, v212, v149
	v_fmac_f32_e32 v149, v211, v124
	global_store_dword v131, v149, s[86:87] offset:-4032
	v_sub_f32_e32 v150, v150, v160
	v_mul_f32_e32 v150, v150, v161
	v_fma_f32 v150, v166, v150, v170
	v_mul_f32_e32 v150, v212, v150
	v_fmac_f32_e32 v150, v211, v120
	global_store_dword v131, v150, s[86:87] offset:-3968
	v_sub_f32_e32 v151, v151, v160
	v_mul_f32_e32 v151, v151, v161
	v_fma_f32 v151, v167, v151, v171
	v_mul_f32_e32 v151, v212, v151
	v_fmac_f32_e32 v151, v211, v116
	global_store_dword v131, v151, s[86:87] offset:-3904
	v_sub_f32_e32 v152, v152, v162
	v_mul_f32_e32 v152, v152, v163
	v_fma_f32 v152, v164, v152, v168
	v_mul_f32_e32 v152, v212, v152
	v_fmac_f32_e32 v152, v211, v129
	global_store_dword v131, v152, s[86:87]
	v_sub_f32_e32 v153, v153, v162
	v_mul_f32_e32 v153, v153, v163
	v_fma_f32 v153, v165, v153, v169
	v_mul_f32_e32 v153, v212, v153
	v_fmac_f32_e32 v153, v211, v125
	global_store_dword v131, v153, s[86:87] offset:64
	v_sub_f32_e32 v154, v154, v162
	v_mul_f32_e32 v154, v154, v163
	v_fma_f32 v154, v166, v154, v170
	v_mul_f32_e32 v154, v212, v154
	v_fmac_f32_e32 v154, v211, v121
	global_store_dword v131, v154, s[86:87] offset:128
	v_sub_f32_e32 v155, v155, v162
	v_mul_f32_e32 v155, v155, v163
	v_fma_f32 v155, v167, v155, v171
	v_mul_f32_e32 v155, v212, v155
	v_fmac_f32_e32 v155, v211, v117
	global_store_dword v131, v155, s[86:87] offset:192
	v_add_u32_e32 v131, 0x12000, v138
	global_load_dword v148, v131, s[86:87] offset:-4096
	global_load_dword v149, v131, s[86:87] offset:-4032
	global_load_dword v150, v131, s[86:87] offset:-3968
	global_load_dword v151, v131, s[86:87] offset:-3904
	global_load_dword v152, v131, s[86:87]
	global_load_dword v153, v131, s[86:87] offset:64
	global_load_dword v154, v131, s[86:87] offset:128
	global_load_dword v155, v131, s[86:87] offset:192
	global_load_dwordx4 v[160:163], v132, s[4:5] offset:144
	s_waitcnt vmcnt(17)
; DEV void phase_ln(const Params& P, const float* __restrict__ g, const float* __restrict__ bta, u16* __restrict__ xb, bool zero_kc) {
;     ...
;         y.x = v[r][i].x * rs * gv[i].x + bv[i].x;
;         y.y = v[r][i].y * rs * gv[i].y + bv[i].y;
;         y.z = v[r][i].z * rs * gv[i].z + bv[i].z;
;         y.w = v[r][i].w * rs * gv[i].w + bv[i].w;
;     ...
; #pragma unroll
;     for (int ms = 0; ms < 8; ++ms) {
;       asm volatile("" ::: "memory");
; #pragma unroll
;       for (int ns = 0; ns < 4; ++ns)
; #pragma unroll
;         for (int j = 0; j < 4; ++j) {
;           int row = m0 + wm * 128 + ms * 16 + quad * 4 + j;
;           int col = n0 + wn * 64 + ns * 16 + l15;
;           const size_t xi = (size_t)row * D + col;
;           const float xv = xin ? xin[xi] : P.out[xi];
;           P.out[xi] = alpha * xv + sc * acc[ms][ns][j];
;         }
	v_sub_f32_e32 v140, v140, v156
	v_mul_f32_e32 v140, v140, v157
	v_fma_f32 v140, v164, v140, v168
	v_mul_f32_e32 v140, v212, v140
	v_fmac_f32_e32 v140, v211, v110
	global_store_dword v130, v140, s[86:87] offset:-4096
	v_sub_f32_e32 v141, v141, v156
	v_mul_f32_e32 v141, v141, v157
	v_fma_f32 v141, v165, v141, v169
	v_mul_f32_e32 v141, v212, v141
	v_fmac_f32_e32 v141, v211, v106
	global_store_dword v130, v141, s[86:87] offset:-4032
	v_sub_f32_e32 v142, v142, v156
	v_mul_f32_e32 v142, v142, v157
	v_fma_f32 v142, v166, v142, v170
	v_mul_f32_e32 v142, v212, v142
	v_fmac_f32_e32 v142, v211, v102
	global_store_dword v130, v142, s[86:87] offset:-3968
	v_sub_f32_e32 v143, v143, v156
	v_mul_f32_e32 v143, v143, v157
	v_fma_f32 v143, v167, v143, v171
	v_mul_f32_e32 v143, v212, v143
	v_fmac_f32_e32 v143, v211, v98
	global_store_dword v130, v143, s[86:87] offset:-3904
	v_sub_f32_e32 v144, v144, v158
	v_mul_f32_e32 v144, v144, v159
	v_fma_f32 v144, v164, v144, v168
	v_mul_f32_e32 v144, v212, v144
	v_fmac_f32_e32 v144, v211, v111
	global_store_dword v130, v144, s[86:87]
	v_sub_f32_e32 v145, v145, v158
	v_mul_f32_e32 v145, v145, v159
	v_fma_f32 v145, v165, v145, v169
	v_mul_f32_e32 v145, v212, v145
	v_fmac_f32_e32 v145, v211, v107
	global_store_dword v130, v145, s[86:87] offset:64
	v_sub_f32_e32 v146, v146, v158
	v_mul_f32_e32 v146, v146, v159
	v_fma_f32 v146, v166, v146, v170
	v_mul_f32_e32 v146, v212, v146
	v_fmac_f32_e32 v146, v211, v103
	global_store_dword v130, v146, s[86:87] offset:128
	v_sub_f32_e32 v147, v147, v158
	v_mul_f32_e32 v147, v147, v159
	v_fma_f32 v147, v167, v147, v171
	v_mul_f32_e32 v147, v212, v147
	v_fmac_f32_e32 v147, v211, v99
	global_store_dword v130, v147, s[86:87] offset:192
	v_add_u32_e32 v130, 0x20000, v138
	global_load_dword v140, v130, s[86:87] offset:-4096
	global_load_dword v141, v130, s[86:87] offset:-4032
	global_load_dword v142, v130, s[86:87] offset:-3968
	global_load_dword v143, v130, s[86:87] offset:-3904
	global_load_dword v144, v130, s[86:87]
	global_load_dword v145, v130, s[86:87] offset:64
	global_load_dword v146, v130, s[86:87] offset:128
	global_load_dword v147, v130, s[86:87] offset:192
	global_load_dwordx4 v[156:159], v132, s[4:5] offset:256
	s_waitcnt vmcnt(17)
	v_sub_f32_e32 v148, v148, v160
	v_mul_f32_e32 v148, v148, v161
	v_fma_f32 v148, v164, v148, v168
	v_mul_f32_e32 v148, v212, v148
	v_fmac_f32_e32 v148, v211, v112
	global_store_dword v131, v148, s[86:87] offset:-4096
	v_sub_f32_e32 v149, v149, v160
	v_mul_f32_e32 v149, v149, v161
	v_fma_f32 v149, v165, v149, v169
	v_mul_f32_e32 v149, v212, v149
	v_fmac_f32_e32 v149, v211, v108
	global_store_dword v131, v149, s[86:87] offset:-4032
	v_sub_f32_e32 v150, v150, v160
	v_mul_f32_e32 v150, v150, v161
	v_fma_f32 v150, v166, v150, v170
	v_mul_f32_e32 v150, v212, v150
	v_fmac_f32_e32 v150, v211, v104
	global_store_dword v131, v150, s[86:87] offset:-3968
	v_sub_f32_e32 v151, v151, v160
	v_mul_f32_e32 v151, v151, v161
	v_fma_f32 v151, v167, v151, v171
	v_mul_f32_e32 v151, v212, v151
	v_fmac_f32_e32 v151, v211, v100
	global_store_dword v131, v151, s[86:87] offset:-3904
	v_sub_f32_e32 v152, v152, v162
	v_mul_f32_e32 v152, v152, v163
	v_fma_f32 v152, v164, v152, v168
	v_mul_f32_e32 v152, v212, v152
	v_fmac_f32_e32 v152, v211, v113
	global_store_dword v131, v152, s[86:87]
	v_sub_f32_e32 v153, v153, v162
	v_mul_f32_e32 v153, v153, v163
	v_fma_f32 v153, v165, v153, v169
	v_mul_f32_e32 v153, v212, v153
	v_fmac_f32_e32 v153, v211, v109
	global_store_dword v131, v153, s[86:87] offset:64
	v_sub_f32_e32 v154, v154, v162
	v_mul_f32_e32 v154, v154, v163
	v_fma_f32 v154, v166, v154, v170
	v_mul_f32_e32 v154, v212, v154
	v_fmac_f32_e32 v154, v211, v105
	global_store_dword v131, v154, s[86:87] offset:128
	v_sub_f32_e32 v155, v155, v162
	v_mul_f32_e32 v155, v155, v163
	v_fma_f32 v155, v167, v155, v171
	v_mul_f32_e32 v155, v212, v155
	v_fmac_f32_e32 v155, v211, v101
	global_store_dword v131, v155, s[86:87] offset:192
	v_add_u32_e32 v131, 0x22000, v138
	global_load_dword v148, v131, s[86:87] offset:-4096
	global_load_dword v149, v131, s[86:87] offset:-4032
	global_load_dword v150, v131, s[86:87] offset:-3968
	global_load_dword v151, v131, s[86:87] offset:-3904
	global_load_dword v152, v131, s[86:87]
	global_load_dword v153, v131, s[86:87] offset:64
	global_load_dword v154, v131, s[86:87] offset:128
	global_load_dword v155, v131, s[86:87] offset:192
	global_load_dwordx4 v[160:163], v132, s[4:5] offset:272
	s_waitcnt vmcnt(17)
	v_sub_f32_e32 v140, v140, v156
	v_mul_f32_e32 v140, v140, v157
	v_fma_f32 v140, v164, v140, v168
	v_mul_f32_e32 v140, v212, v140
	v_fmac_f32_e32 v140, v211, v94
	global_store_dword v130, v140, s[86:87] offset:-4096
	v_sub_f32_e32 v141, v141, v156
	v_mul_f32_e32 v141, v141, v157
	v_fma_f32 v141, v165, v141, v169
	v_mul_f32_e32 v141, v212, v141
	v_fmac_f32_e32 v141, v211, v90
	global_store_dword v130, v141, s[86:87] offset:-4032
	v_sub_f32_e32 v142, v142, v156
	v_mul_f32_e32 v142, v142, v157
	v_fma_f32 v142, v166, v142, v170
	v_mul_f32_e32 v142, v212, v142
	v_fmac_f32_e32 v142, v211, v86
	global_store_dword v130, v142, s[86:87] offset:-3968
	v_sub_f32_e32 v143, v143, v156
	v_mul_f32_e32 v143, v143, v157
	v_fma_f32 v143, v167, v143, v171
	v_mul_f32_e32 v143, v212, v143
	v_fmac_f32_e32 v143, v211, v82
	global_store_dword v130, v143, s[86:87] offset:-3904
	v_sub_f32_e32 v144, v144, v158
	v_mul_f32_e32 v144, v144, v159
	v_fma_f32 v144, v164, v144, v168
	v_mul_f32_e32 v144, v212, v144
	v_fmac_f32_e32 v144, v211, v95
	global_store_dword v130, v144, s[86:87]
	v_sub_f32_e32 v145, v145, v158
	v_mul_f32_e32 v145, v145, v159
	v_fma_f32 v145, v165, v145, v169
	v_mul_f32_e32 v145, v212, v145
	v_fmac_f32_e32 v145, v211, v91
	global_store_dword v130, v145, s[86:87] offset:64
	v_sub_f32_e32 v146, v146, v158
	v_mul_f32_e32 v146, v146, v159
	v_fma_f32 v146, v166, v146, v170
	v_mul_f32_e32 v146, v212, v146
	v_fmac_f32_e32 v146, v211, v87
	global_store_dword v130, v146, s[86:87] offset:128
	v_sub_f32_e32 v147, v147, v158
	v_mul_f32_e32 v147, v147, v159
	v_fma_f32 v147, v167, v147, v171
	v_mul_f32_e32 v147, v212, v147
	v_fmac_f32_e32 v147, v211, v83
	global_store_dword v130, v147, s[86:87] offset:192
	v_add_u32_e32 v130, 0x30000, v138
	global_load_dword v140, v130, s[86:87] offset:-4096
	global_load_dword v141, v130, s[86:87] offset:-4032
	global_load_dword v142, v130, s[86:87] offset:-3968
	global_load_dword v143, v130, s[86:87] offset:-3904
	global_load_dword v144, v130, s[86:87]
	global_load_dword v145, v130, s[86:87] offset:64
	global_load_dword v146, v130, s[86:87] offset:128
	global_load_dword v147, v130, s[86:87] offset:192
	global_load_dwordx4 v[156:159], v132, s[4:5] offset:384
	s_waitcnt vmcnt(17)
; DEV void phase_ln(const Params& P, const float* __restrict__ g, const float* __restrict__ bta, u16* __restrict__ xb, bool zero_kc) {
;     ...
;         y.x = v[r][i].x * rs * gv[i].x + bv[i].x;
;         y.y = v[r][i].y * rs * gv[i].y + bv[i].y;
;         y.z = v[r][i].z * rs * gv[i].z + bv[i].z;
;         y.w = v[r][i].w * rs * gv[i].w + bv[i].w;
;     ...
; #pragma unroll
;     for (int ms = 0; ms < 8; ++ms) {
;       asm volatile("" ::: "memory");
; #pragma unroll
;       for (int ns = 0; ns < 4; ++ns)
; #pragma unroll
;         for (int j = 0; j < 4; ++j) {
;           int row = m0 + wm * 128 + ms * 16 + quad * 4 + j;
;           int col = n0 + wn * 64 + ns * 16 + l15;
;           const size_t xi = (size_t)row * D + col;
;           const float xv = xin ? xin[xi] : P.out[xi];
;           P.out[xi] = alpha * xv + sc * acc[ms][ns][j];
;         }
	v_sub_f32_e32 v148, v148, v160
	v_mul_f32_e32 v148, v148, v161
	v_fma_f32 v148, v164, v148, v168
	v_mul_f32_e32 v148, v212, v148
	v_fmac_f32_e32 v148, v211, v96
	global_store_dword v131, v148, s[86:87] offset:-4096
	v_sub_f32_e32 v149, v149, v160
	v_mul_f32_e32 v149, v149, v161
	v_fma_f32 v149, v165, v149, v169
	v_mul_f32_e32 v149, v212, v149
	v_fmac_f32_e32 v149, v211, v92
	global_store_dword v131, v149, s[86:87] offset:-4032
	v_sub_f32_e32 v150, v150, v160
	v_mul_f32_e32 v150, v150, v161
	v_fma_f32 v150, v166, v150, v170
	v_mul_f32_e32 v150, v212, v150
	v_fmac_f32_e32 v150, v211, v88
	global_store_dword v131, v150, s[86:87] offset:-3968
	v_sub_f32_e32 v151, v151, v160
	v_mul_f32_e32 v151, v151, v161
	v_fma_f32 v151, v167, v151, v171
	v_mul_f32_e32 v151, v212, v151
	v_fmac_f32_e32 v151, v211, v84
	global_store_dword v131, v151, s[86:87] offset:-3904
	v_sub_f32_e32 v152, v152, v162
	v_mul_f32_e32 v152, v152, v163
	v_fma_f32 v152, v164, v152, v168
	v_mul_f32_e32 v152, v212, v152
	v_fmac_f32_e32 v152, v211, v97
	global_store_dword v131, v152, s[86:87]
	v_sub_f32_e32 v153, v153, v162
	v_mul_f32_e32 v153, v153, v163
	v_fma_f32 v153, v165, v153, v169
	v_mul_f32_e32 v153, v212, v153
	v_fmac_f32_e32 v153, v211, v93
	global_store_dword v131, v153, s[86:87] offset:64
	v_sub_f32_e32 v154, v154, v162
	v_mul_f32_e32 v154, v154, v163
	v_fma_f32 v154, v166, v154, v170
	v_mul_f32_e32 v154, v212, v154
	v_fmac_f32_e32 v154, v211, v89
	global_store_dword v131, v154, s[86:87] offset:128
	v_sub_f32_e32 v155, v155, v162
	v_mul_f32_e32 v155, v155, v163
	v_fma_f32 v155, v167, v155, v171
	v_mul_f32_e32 v155, v212, v155
	v_fmac_f32_e32 v155, v211, v85
	global_store_dword v131, v155, s[86:87] offset:192
	v_add_u32_e32 v131, 0x32000, v138
	global_load_dword v148, v131, s[86:87] offset:-4096
	global_load_dword v149, v131, s[86:87] offset:-4032
	global_load_dword v150, v131, s[86:87] offset:-3968
	global_load_dword v151, v131, s[86:87] offset:-3904
	global_load_dword v152, v131, s[86:87]
	global_load_dword v153, v131, s[86:87] offset:64
	global_load_dword v154, v131, s[86:87] offset:128
	global_load_dword v155, v131, s[86:87] offset:192
	global_load_dwordx4 v[160:163], v132, s[4:5] offset:400
	s_waitcnt vmcnt(17)
	v_sub_f32_e32 v140, v140, v156
	v_mul_f32_e32 v140, v140, v157
	v_fma_f32 v140, v164, v140, v168
	v_mul_f32_e32 v140, v212, v140
	v_fmac_f32_e32 v140, v211, v78
	global_store_dword v130, v140, s[86:87] offset:-4096
	v_sub_f32_e32 v141, v141, v156
	v_mul_f32_e32 v141, v141, v157
	v_fma_f32 v141, v165, v141, v169
	v_mul_f32_e32 v141, v212, v141
	v_fmac_f32_e32 v141, v211, v74
	global_store_dword v130, v141, s[86:87] offset:-4032
	v_sub_f32_e32 v142, v142, v156
	v_mul_f32_e32 v142, v142, v157
	v_fma_f32 v142, v166, v142, v170
	v_mul_f32_e32 v142, v212, v142
	v_fmac_f32_e32 v142, v211, v70
	global_store_dword v130, v142, s[86:87] offset:-3968
	v_sub_f32_e32 v143, v143, v156
	v_mul_f32_e32 v143, v143, v157
	v_fma_f32 v143, v167, v143, v171
	v_mul_f32_e32 v143, v212, v143
	v_fmac_f32_e32 v143, v211, v66
	global_store_dword v130, v143, s[86:87] offset:-3904
	v_sub_f32_e32 v144, v144, v158
	v_mul_f32_e32 v144, v144, v159
	v_fma_f32 v144, v164, v144, v168
	v_mul_f32_e32 v144, v212, v144
	v_fmac_f32_e32 v144, v211, v79
	global_store_dword v130, v144, s[86:87]
	v_sub_f32_e32 v145, v145, v158
	v_mul_f32_e32 v145, v145, v159
	v_fma_f32 v145, v165, v145, v169
	v_mul_f32_e32 v145, v212, v145
	v_fmac_f32_e32 v145, v211, v75
	global_store_dword v130, v145, s[86:87] offset:64
	v_sub_f32_e32 v146, v146, v158
	v_mul_f32_e32 v146, v146, v159
	v_fma_f32 v146, v166, v146, v170
	v_mul_f32_e32 v146, v212, v146
	v_fmac_f32_e32 v146, v211, v71
	global_store_dword v130, v146, s[86:87] offset:128
	v_sub_f32_e32 v147, v147, v158
	v_mul_f32_e32 v147, v147, v159
	v_fma_f32 v147, v167, v147, v171
	v_mul_f32_e32 v147, v212, v147
	v_fmac_f32_e32 v147, v211, v67
	global_store_dword v130, v147, s[86:87] offset:192
	v_add_u32_e32 v130, 0x40000, v138
	global_load_dword v140, v130, s[86:87] offset:-4096
	global_load_dword v141, v130, s[86:87] offset:-4032
	global_load_dword v142, v130, s[86:87] offset:-3968
	global_load_dword v143, v130, s[86:87] offset:-3904
	global_load_dword v144, v130, s[86:87]
	global_load_dword v145, v130, s[86:87] offset:64
	global_load_dword v146, v130, s[86:87] offset:128
	global_load_dword v147, v130, s[86:87] offset:192
	global_load_dwordx4 v[156:159], v132, s[4:5] offset:512
	s_waitcnt vmcnt(17)
	v_sub_f32_e32 v148, v148, v160
	v_mul_f32_e32 v148, v148, v161
	v_fma_f32 v148, v164, v148, v168
	v_mul_f32_e32 v148, v212, v148
	v_fmac_f32_e32 v148, v211, v80
	global_store_dword v131, v148, s[86:87] offset:-4096
	v_sub_f32_e32 v149, v149, v160
	v_mul_f32_e32 v149, v149, v161
	v_fma_f32 v149, v165, v149, v169
	v_mul_f32_e32 v149, v212, v149
	v_fmac_f32_e32 v149, v211, v76
	global_store_dword v131, v149, s[86:87] offset:-4032
	v_sub_f32_e32 v150, v150, v160
	v_mul_f32_e32 v150, v150, v161
	v_fma_f32 v150, v166, v150, v170
	v_mul_f32_e32 v150, v212, v150
	v_fmac_f32_e32 v150, v211, v72
	global_store_dword v131, v150, s[86:87] offset:-3968
	v_sub_f32_e32 v151, v151, v160
	v_mul_f32_e32 v151, v151, v161
	v_fma_f32 v151, v167, v151, v171
	v_mul_f32_e32 v151, v212, v151
	v_fmac_f32_e32 v151, v211, v68
	global_store_dword v131, v151, s[86:87] offset:-3904
	v_sub_f32_e32 v152, v152, v162
	v_mul_f32_e32 v152, v152, v163
	v_fma_f32 v152, v164, v152, v168
	v_mul_f32_e32 v152, v212, v152
	v_fmac_f32_e32 v152, v211, v81
	global_store_dword v131, v152, s[86:87]
	v_sub_f32_e32 v153, v153, v162
	v_mul_f32_e32 v153, v153, v163
	v_fma_f32 v153, v165, v153, v169
	v_mul_f32_e32 v153, v212, v153
	v_fmac_f32_e32 v153, v211, v77
	global_store_dword v131, v153, s[86:87] offset:64
	v_sub_f32_e32 v154, v154, v162
	v_mul_f32_e32 v154, v154, v163
	v_fma_f32 v154, v166, v154, v170
	v_mul_f32_e32 v154, v212, v154
	v_fmac_f32_e32 v154, v211, v73
	global_store_dword v131, v154, s[86:87] offset:128
	v_sub_f32_e32 v155, v155, v162
	v_mul_f32_e32 v155, v155, v163
	v_fma_f32 v155, v167, v155, v171
	v_mul_f32_e32 v155, v212, v155
	v_fmac_f32_e32 v155, v211, v69
	global_store_dword v131, v155, s[86:87] offset:192
	v_add_u32_e32 v131, 0x42000, v138
	global_load_dword v148, v131, s[86:87] offset:-4096
	global_load_dword v149, v131, s[86:87] offset:-4032
	global_load_dword v150, v131, s[86:87] offset:-3968
	global_load_dword v151, v131, s[86:87] offset:-3904
	global_load_dword v152, v131, s[86:87]
	global_load_dword v153, v131, s[86:87] offset:64
	global_load_dword v154, v131, s[86:87] offset:128
	global_load_dword v155, v131, s[86:87] offset:192
	global_load_dwordx4 v[160:163], v132, s[4:5] offset:528
	s_waitcnt vmcnt(17)
; DEV void phase_ln(const Params& P, const float* __restrict__ g, const float* __restrict__ bta, u16* __restrict__ xb, bool zero_kc) {
;     ...
;         y.x = v[r][i].x * rs * gv[i].x + bv[i].x;
;         y.y = v[r][i].y * rs * gv[i].y + bv[i].y;
;         y.z = v[r][i].z * rs * gv[i].z + bv[i].z;
;         y.w = v[r][i].w * rs * gv[i].w + bv[i].w;
;     ...
; #pragma unroll
;     for (int ms = 0; ms < 8; ++ms) {
;       asm volatile("" ::: "memory");
; #pragma unroll
;       for (int ns = 0; ns < 4; ++ns)
; #pragma unroll
;         for (int j = 0; j < 4; ++j) {
;           int row = m0 + wm * 128 + ms * 16 + quad * 4 + j;
;           int col = n0 + wn * 64 + ns * 16 + l15;
;           const size_t xi = (size_t)row * D + col;
;           const float xv = xin ? xin[xi] : P.out[xi];
;           P.out[xi] = alpha * xv + sc * acc[ms][ns][j];
;         }
	v_sub_f32_e32 v140, v140, v156
	v_mul_f32_e32 v140, v140, v157
	v_fma_f32 v140, v164, v140, v168
	v_mul_f32_e32 v140, v212, v140
	v_fmac_f32_e32 v140, v211, v62
	global_store_dword v130, v140, s[86:87] offset:-4096
	v_sub_f32_e32 v141, v141, v156
	v_mul_f32_e32 v141, v141, v157
	v_fma_f32 v141, v165, v141, v169
	v_mul_f32_e32 v141, v212, v141
	v_fmac_f32_e32 v141, v211, v58
	global_store_dword v130, v141, s[86:87] offset:-4032
	v_sub_f32_e32 v142, v142, v156
	v_mul_f32_e32 v142, v142, v157
	v_fma_f32 v142, v166, v142, v170
	v_mul_f32_e32 v142, v212, v142
	v_fmac_f32_e32 v142, v211, v54
	global_store_dword v130, v142, s[86:87] offset:-3968
	v_sub_f32_e32 v143, v143, v156
	v_mul_f32_e32 v143, v143, v157
	v_fma_f32 v143, v167, v143, v171
	v_mul_f32_e32 v143, v212, v143
	v_fmac_f32_e32 v143, v211, v50
	global_store_dword v130, v143, s[86:87] offset:-3904
	v_sub_f32_e32 v144, v144, v158
	v_mul_f32_e32 v144, v144, v159
	v_fma_f32 v144, v164, v144, v168
	v_mul_f32_e32 v144, v212, v144
	v_fmac_f32_e32 v144, v211, v63
	global_store_dword v130, v144, s[86:87]
	v_sub_f32_e32 v145, v145, v158
	v_mul_f32_e32 v145, v145, v159
	v_fma_f32 v145, v165, v145, v169
	v_mul_f32_e32 v145, v212, v145
	v_fmac_f32_e32 v145, v211, v59
	global_store_dword v130, v145, s[86:87] offset:64
	v_sub_f32_e32 v146, v146, v158
	v_mul_f32_e32 v146, v146, v159
	v_fma_f32 v146, v166, v146, v170
	v_mul_f32_e32 v146, v212, v146
	v_fmac_f32_e32 v146, v211, v55
	global_store_dword v130, v146, s[86:87] offset:128
	v_sub_f32_e32 v147, v147, v158
	v_mul_f32_e32 v147, v147, v159
	v_fma_f32 v147, v167, v147, v171
	v_mul_f32_e32 v147, v212, v147
	v_fmac_f32_e32 v147, v211, v51
	global_store_dword v130, v147, s[86:87] offset:192
	v_add_u32_e32 v130, 0x50000, v138
	global_load_dword v140, v130, s[86:87] offset:-4096
	global_load_dword v141, v130, s[86:87] offset:-4032
	global_load_dword v142, v130, s[86:87] offset:-3968
	global_load_dword v143, v130, s[86:87] offset:-3904
	global_load_dword v144, v130, s[86:87]
	global_load_dword v145, v130, s[86:87] offset:64
	global_load_dword v146, v130, s[86:87] offset:128
	global_load_dword v147, v130, s[86:87] offset:192
	global_load_dwordx4 v[156:159], v132, s[4:5] offset:640
	s_waitcnt vmcnt(17)
	v_sub_f32_e32 v148, v148, v160
	v_mul_f32_e32 v148, v148, v161
	v_fma_f32 v148, v164, v148, v168
	v_mul_f32_e32 v148, v212, v148
	v_fmac_f32_e32 v148, v211, v64
	global_store_dword v131, v148, s[86:87] offset:-4096
	v_sub_f32_e32 v149, v149, v160
	v_mul_f32_e32 v149, v149, v161
	v_fma_f32 v149, v165, v149, v169
	v_mul_f32_e32 v149, v212, v149
	v_fmac_f32_e32 v149, v211, v60
	global_store_dword v131, v149, s[86:87] offset:-4032
	v_sub_f32_e32 v150, v150, v160
	v_mul_f32_e32 v150, v150, v161
	v_fma_f32 v150, v166, v150, v170
	v_mul_f32_e32 v150, v212, v150
	v_fmac_f32_e32 v150, v211, v56
	global_store_dword v131, v150, s[86:87] offset:-3968
	v_sub_f32_e32 v151, v151, v160
	v_mul_f32_e32 v151, v151, v161
	v_fma_f32 v151, v167, v151, v171
	v_mul_f32_e32 v151, v212, v151
	v_fmac_f32_e32 v151, v211, v52
	global_store_dword v131, v151, s[86:87] offset:-3904
	v_sub_f32_e32 v152, v152, v162
	v_mul_f32_e32 v152, v152, v163
	v_fma_f32 v152, v164, v152, v168
	v_mul_f32_e32 v152, v212, v152
	v_fmac_f32_e32 v152, v211, v65
	global_store_dword v131, v152, s[86:87]
	v_sub_f32_e32 v153, v153, v162
	v_mul_f32_e32 v153, v153, v163
	v_fma_f32 v153, v165, v153, v169
	v_mul_f32_e32 v153, v212, v153
	v_fmac_f32_e32 v153, v211, v61
	global_store_dword v131, v153, s[86:87] offset:64
	v_sub_f32_e32 v154, v154, v162
	v_mul_f32_e32 v154, v154, v163
	v_fma_f32 v154, v166, v154, v170
	v_mul_f32_e32 v154, v212, v154
	v_fmac_f32_e32 v154, v211, v57
	global_store_dword v131, v154, s[86:87] offset:128
	v_sub_f32_e32 v155, v155, v162
	v_mul_f32_e32 v155, v155, v163
	v_fma_f32 v155, v167, v155, v171
	v_mul_f32_e32 v155, v212, v155
	v_fmac_f32_e32 v155, v211, v53
	global_store_dword v131, v155, s[86:87] offset:192
	v_add_u32_e32 v131, 0x52000, v138
	global_load_dword v148, v131, s[86:87] offset:-4096
	global_load_dword v149, v131, s[86:87] offset:-4032
	global_load_dword v150, v131, s[86:87] offset:-3968
	global_load_dword v151, v131, s[86:87] offset:-3904
	global_load_dword v152, v131, s[86:87]
	global_load_dword v153, v131, s[86:87] offset:64
	global_load_dword v154, v131, s[86:87] offset:128
	global_load_dword v155, v131, s[86:87] offset:192
	global_load_dwordx4 v[160:163], v132, s[4:5] offset:656
	s_waitcnt vmcnt(17)
	v_sub_f32_e32 v140, v140, v156
	v_mul_f32_e32 v140, v140, v157
	v_fma_f32 v140, v164, v140, v168
	v_mul_f32_e32 v140, v212, v140
	v_fmac_f32_e32 v140, v211, v46
	global_store_dword v130, v140, s[86:87] offset:-4096
	v_sub_f32_e32 v141, v141, v156
	v_mul_f32_e32 v141, v141, v157
	v_fma_f32 v141, v165, v141, v169
	v_mul_f32_e32 v141, v212, v141
	v_fmac_f32_e32 v141, v211, v42
	global_store_dword v130, v141, s[86:87] offset:-4032
	v_sub_f32_e32 v142, v142, v156
	v_mul_f32_e32 v142, v142, v157
	v_fma_f32 v142, v166, v142, v170
	v_mul_f32_e32 v142, v212, v142
	v_fmac_f32_e32 v142, v211, v38
	global_store_dword v130, v142, s[86:87] offset:-3968
	v_sub_f32_e32 v143, v143, v156
	v_mul_f32_e32 v143, v143, v157
	v_fma_f32 v143, v167, v143, v171
	v_mul_f32_e32 v143, v212, v143
	v_fmac_f32_e32 v143, v211, v34
	global_store_dword v130, v143, s[86:87] offset:-3904
	v_sub_f32_e32 v144, v144, v158
	v_mul_f32_e32 v144, v144, v159
	v_fma_f32 v144, v164, v144, v168
	v_mul_f32_e32 v144, v212, v144
	v_fmac_f32_e32 v144, v211, v47
	global_store_dword v130, v144, s[86:87]
	v_sub_f32_e32 v145, v145, v158
	v_mul_f32_e32 v145, v145, v159
	v_fma_f32 v145, v165, v145, v169
	v_mul_f32_e32 v145, v212, v145
	v_fmac_f32_e32 v145, v211, v43
	global_store_dword v130, v145, s[86:87] offset:64
	v_sub_f32_e32 v146, v146, v158
	v_mul_f32_e32 v146, v146, v159
	v_fma_f32 v146, v166, v146, v170
	v_mul_f32_e32 v146, v212, v146
	v_fmac_f32_e32 v146, v211, v39
	global_store_dword v130, v146, s[86:87] offset:128
	v_sub_f32_e32 v147, v147, v158
	v_mul_f32_e32 v147, v147, v159
	v_fma_f32 v147, v167, v147, v171
	v_mul_f32_e32 v147, v212, v147
	v_fmac_f32_e32 v147, v211, v35
	global_store_dword v130, v147, s[86:87] offset:192
	v_add_u32_e32 v130, 0x60000, v138
	global_load_dword v140, v130, s[86:87] offset:-4096
	global_load_dword v141, v130, s[86:87] offset:-4032
	global_load_dword v142, v130, s[86:87] offset:-3968
	global_load_dword v143, v130, s[86:87] offset:-3904
	global_load_dword v144, v130, s[86:87]
	global_load_dword v145, v130, s[86:87] offset:64
	global_load_dword v146, v130, s[86:87] offset:128
	global_load_dword v147, v130, s[86:87] offset:192
	global_load_dwordx4 v[156:159], v132, s[4:5] offset:768
	s_waitcnt vmcnt(17)
; DEV void phase_ln(const Params& P, const float* __restrict__ g, const float* __restrict__ bta, u16* __restrict__ xb, bool zero_kc) {
;     ...
;         y.x = v[r][i].x * rs * gv[i].x + bv[i].x;
;         y.y = v[r][i].y * rs * gv[i].y + bv[i].y;
;         y.z = v[r][i].z * rs * gv[i].z + bv[i].z;
;         y.w = v[r][i].w * rs * gv[i].w + bv[i].w;
;     ...
; #pragma unroll
;     for (int ms = 0; ms < 8; ++ms) {
;       asm volatile("" ::: "memory");
; #pragma unroll
;       for (int ns = 0; ns < 4; ++ns)
; #pragma unroll
;         for (int j = 0; j < 4; ++j) {
;           int row = m0 + wm * 128 + ms * 16 + quad * 4 + j;
;           int col = n0 + wn * 64 + ns * 16 + l15;
;           const size_t xi = (size_t)row * D + col;
;           const float xv = xin ? xin[xi] : P.out[xi];
;           P.out[xi] = alpha * xv + sc * acc[ms][ns][j];
;         }
	v_sub_f32_e32 v148, v148, v160
	v_mul_f32_e32 v148, v148, v161
	v_fma_f32 v148, v164, v148, v168
	v_mul_f32_e32 v148, v212, v148
	v_fmac_f32_e32 v148, v211, v48
	global_store_dword v131, v148, s[86:87] offset:-4096
	v_sub_f32_e32 v149, v149, v160
	v_mul_f32_e32 v149, v149, v161
	v_fma_f32 v149, v165, v149, v169
	v_mul_f32_e32 v149, v212, v149
	v_fmac_f32_e32 v149, v211, v44
	global_store_dword v131, v149, s[86:87] offset:-4032
	v_sub_f32_e32 v150, v150, v160
	v_mul_f32_e32 v150, v150, v161
	v_fma_f32 v150, v166, v150, v170
	v_mul_f32_e32 v150, v212, v150
	v_fmac_f32_e32 v150, v211, v40
	global_store_dword v131, v150, s[86:87] offset:-3968
	v_sub_f32_e32 v151, v151, v160
	v_mul_f32_e32 v151, v151, v161
	v_fma_f32 v151, v167, v151, v171
	v_mul_f32_e32 v151, v212, v151
	v_fmac_f32_e32 v151, v211, v36
	global_store_dword v131, v151, s[86:87] offset:-3904
	v_sub_f32_e32 v152, v152, v162
	v_mul_f32_e32 v152, v152, v163
	v_fma_f32 v152, v164, v152, v168
	v_mul_f32_e32 v152, v212, v152
	v_fmac_f32_e32 v152, v211, v49
	global_store_dword v131, v152, s[86:87]
	v_sub_f32_e32 v153, v153, v162
	v_mul_f32_e32 v153, v153, v163
	v_fma_f32 v153, v165, v153, v169
	v_mul_f32_e32 v153, v212, v153
	v_fmac_f32_e32 v153, v211, v45
	global_store_dword v131, v153, s[86:87] offset:64
	v_sub_f32_e32 v154, v154, v162
	v_mul_f32_e32 v154, v154, v163
	v_fma_f32 v154, v166, v154, v170
	v_mul_f32_e32 v154, v212, v154
	v_fmac_f32_e32 v154, v211, v41
	global_store_dword v131, v154, s[86:87] offset:128
	v_sub_f32_e32 v155, v155, v162
	v_mul_f32_e32 v155, v155, v163
	v_fma_f32 v155, v167, v155, v171
	v_mul_f32_e32 v155, v212, v155
	v_fmac_f32_e32 v155, v211, v37
	global_store_dword v131, v155, s[86:87] offset:192
	v_add_u32_e32 v131, 0x62000, v138
	global_load_dword v148, v131, s[86:87] offset:-4096
	global_load_dword v149, v131, s[86:87] offset:-4032
	global_load_dword v150, v131, s[86:87] offset:-3968
	global_load_dword v151, v131, s[86:87] offset:-3904
	global_load_dword v152, v131, s[86:87]
	global_load_dword v153, v131, s[86:87] offset:64
	global_load_dword v154, v131, s[86:87] offset:128
	global_load_dword v155, v131, s[86:87] offset:192
	global_load_dwordx4 v[160:163], v132, s[4:5] offset:784
	s_waitcnt vmcnt(17)
	v_sub_f32_e32 v140, v140, v156
	v_mul_f32_e32 v140, v140, v157
	v_fma_f32 v140, v164, v140, v168
	v_mul_f32_e32 v140, v212, v140
	v_fmac_f32_e32 v140, v211, v30
	global_store_dword v130, v140, s[86:87] offset:-4096
	v_sub_f32_e32 v141, v141, v156
	v_mul_f32_e32 v141, v141, v157
	v_fma_f32 v141, v165, v141, v169
	v_mul_f32_e32 v141, v212, v141
	v_fmac_f32_e32 v141, v211, v26
	global_store_dword v130, v141, s[86:87] offset:-4032
	v_sub_f32_e32 v142, v142, v156
	v_mul_f32_e32 v142, v142, v157
	v_fma_f32 v142, v166, v142, v170
	v_mul_f32_e32 v142, v212, v142
	v_fmac_f32_e32 v142, v211, v22
	global_store_dword v130, v142, s[86:87] offset:-3968
	v_sub_f32_e32 v143, v143, v156
	v_mul_f32_e32 v143, v143, v157
	v_fma_f32 v143, v167, v143, v171
	v_mul_f32_e32 v143, v212, v143
	v_fmac_f32_e32 v143, v211, v18
	global_store_dword v130, v143, s[86:87] offset:-3904
	v_sub_f32_e32 v144, v144, v158
	v_mul_f32_e32 v144, v144, v159
	v_fma_f32 v144, v164, v144, v168
	v_mul_f32_e32 v144, v212, v144
	v_fmac_f32_e32 v144, v211, v31
	global_store_dword v130, v144, s[86:87]
	v_sub_f32_e32 v145, v145, v158
	v_mul_f32_e32 v145, v145, v159
	v_fma_f32 v145, v165, v145, v169
	v_mul_f32_e32 v145, v212, v145
	v_fmac_f32_e32 v145, v211, v27
	global_store_dword v130, v145, s[86:87] offset:64
	v_sub_f32_e32 v146, v146, v158
	v_mul_f32_e32 v146, v146, v159
	v_fma_f32 v146, v166, v146, v170
	v_mul_f32_e32 v146, v212, v146
	v_fmac_f32_e32 v146, v211, v23
	global_store_dword v130, v146, s[86:87] offset:128
	v_sub_f32_e32 v147, v147, v158
	v_mul_f32_e32 v147, v147, v159
	v_fma_f32 v147, v167, v147, v171
	v_mul_f32_e32 v147, v212, v147
	v_fmac_f32_e32 v147, v211, v19
	global_store_dword v130, v147, s[86:87] offset:192
	v_add_u32_e32 v130, 0x70000, v138
	global_load_dword v140, v130, s[86:87] offset:-4096
	global_load_dword v141, v130, s[86:87] offset:-4032
	global_load_dword v142, v130, s[86:87] offset:-3968
	global_load_dword v143, v130, s[86:87] offset:-3904
	global_load_dword v144, v130, s[86:87]
	global_load_dword v145, v130, s[86:87] offset:64
	global_load_dword v146, v130, s[86:87] offset:128
	global_load_dword v147, v130, s[86:87] offset:192
	global_load_dwordx4 v[156:159], v132, s[4:5] offset:896
	s_waitcnt vmcnt(17)
; DEV void phase_ln(const Params& P, const float* __restrict__ g, const float* __restrict__ bta, u16* __restrict__ xb, bool zero_kc) {
;     ...
;         y.x = v[r][i].x * rs * gv[i].x + bv[i].x;
;         y.y = v[r][i].y * rs * gv[i].y + bv[i].y;
;         y.z = v[r][i].z * rs * gv[i].z + bv[i].z;
;         y.w = v[r][i].w * rs * gv[i].w + bv[i].w;
;     ...
; #pragma unroll
;     for (int ms = 0; ms < 8; ++ms) {
;       asm volatile("" ::: "memory");
; #pragma unroll
;       for (int ns = 0; ns < 4; ++ns)
; #pragma unroll
;         for (int j = 0; j < 4; ++j) {
;           int row = m0 + wm * 128 + ms * 16 + quad * 4 + j;
;           int col = n0 + wn * 64 + ns * 16 + l15;
;           const size_t xi = (size_t)row * D + col;
;           const float xv = xin ? xin[xi] : P.out[xi];
;           P.out[xi] = alpha * xv + sc * acc[ms][ns][j];
;         }
	v_sub_f32_e32 v148, v148, v160
	v_mul_f32_e32 v148, v148, v161
	v_fma_f32 v148, v164, v148, v168
	v_mul_f32_e32 v148, v212, v148
	v_fmac_f32_e32 v148, v211, v32
	global_store_dword v131, v148, s[86:87] offset:-4096
	v_sub_f32_e32 v149, v149, v160
	v_mul_f32_e32 v149, v149, v161
	v_fma_f32 v149, v165, v149, v169
	v_mul_f32_e32 v149, v212, v149
	v_fmac_f32_e32 v149, v211, v28
	global_store_dword v131, v149, s[86:87] offset:-4032
	v_sub_f32_e32 v150, v150, v160
	v_mul_f32_e32 v150, v150, v161
	v_fma_f32 v150, v166, v150, v170
	v_mul_f32_e32 v150, v212, v150
	v_fmac_f32_e32 v150, v211, v24
	global_store_dword v131, v150, s[86:87] offset:-3968
	v_sub_f32_e32 v151, v151, v160
	v_mul_f32_e32 v151, v151, v161
	v_fma_f32 v151, v167, v151, v171
	v_mul_f32_e32 v151, v212, v151
	v_fmac_f32_e32 v151, v211, v20
	global_store_dword v131, v151, s[86:87] offset:-3904
	v_sub_f32_e32 v152, v152, v162
	v_mul_f32_e32 v152, v152, v163
	v_fma_f32 v152, v164, v152, v168
	v_mul_f32_e32 v152, v212, v152
	v_fmac_f32_e32 v152, v211, v33
	global_store_dword v131, v152, s[86:87]
	v_sub_f32_e32 v153, v153, v162
	v_mul_f32_e32 v153, v153, v163
	v_fma_f32 v153, v165, v153, v169
	v_mul_f32_e32 v153, v212, v153
	v_fmac_f32_e32 v153, v211, v29
	global_store_dword v131, v153, s[86:87] offset:64
	v_sub_f32_e32 v154, v154, v162
	v_mul_f32_e32 v154, v154, v163
	v_fma_f32 v154, v166, v154, v170
	v_mul_f32_e32 v154, v212, v154
	v_fmac_f32_e32 v154, v211, v25
	global_store_dword v131, v154, s[86:87] offset:128
	v_sub_f32_e32 v155, v155, v162
	v_mul_f32_e32 v155, v155, v163
	v_fma_f32 v155, v167, v155, v171
	v_mul_f32_e32 v155, v212, v155
	v_fmac_f32_e32 v155, v211, v21
	global_store_dword v131, v155, s[86:87] offset:192
	v_add_u32_e32 v131, 0x72000, v138
	global_load_dword v148, v131, s[86:87] offset:-4096
	global_load_dword v149, v131, s[86:87] offset:-4032
	global_load_dword v150, v131, s[86:87] offset:-3968
	global_load_dword v151, v131, s[86:87] offset:-3904
	global_load_dword v152, v131, s[86:87]
	global_load_dword v153, v131, s[86:87] offset:64
	global_load_dword v154, v131, s[86:87] offset:128
	global_load_dword v155, v131, s[86:87] offset:192
	global_load_dwordx4 v[160:163], v132, s[4:5] offset:912
	s_waitcnt vmcnt(17)
	v_sub_f32_e32 v140, v140, v156
	v_mul_f32_e32 v140, v140, v157
	v_fma_f32 v140, v164, v140, v168
	v_mul_f32_e32 v140, v212, v140
	v_fmac_f32_e32 v140, v211, v14
	global_store_dword v130, v140, s[86:87] offset:-4096
	v_sub_f32_e32 v141, v141, v156
	v_mul_f32_e32 v141, v141, v157
	v_fma_f32 v141, v165, v141, v169
	v_mul_f32_e32 v141, v212, v141
	v_fmac_f32_e32 v141, v211, v10
	global_store_dword v130, v141, s[86:87] offset:-4032
	v_sub_f32_e32 v142, v142, v156
	v_mul_f32_e32 v142, v142, v157
	v_fma_f32 v142, v166, v142, v170
	v_mul_f32_e32 v142, v212, v142
	v_fmac_f32_e32 v142, v211, v6
	global_store_dword v130, v142, s[86:87] offset:-3968
	v_sub_f32_e32 v143, v143, v156
	v_mul_f32_e32 v143, v143, v157
	v_fma_f32 v143, v167, v143, v171
	v_mul_f32_e32 v143, v212, v143
	v_fmac_f32_e32 v143, v211, v2
	global_store_dword v130, v143, s[86:87] offset:-3904
	v_sub_f32_e32 v144, v144, v158
	v_mul_f32_e32 v144, v144, v159
	v_fma_f32 v144, v164, v144, v168
	v_mul_f32_e32 v144, v212, v144
	v_fmac_f32_e32 v144, v211, v15
	global_store_dword v130, v144, s[86:87]
	v_sub_f32_e32 v145, v145, v158
	v_mul_f32_e32 v145, v145, v159
	v_fma_f32 v145, v165, v145, v169
	v_mul_f32_e32 v145, v212, v145
	v_fmac_f32_e32 v145, v211, v11
	global_store_dword v130, v145, s[86:87] offset:64
	v_sub_f32_e32 v146, v146, v158
	v_mul_f32_e32 v146, v146, v159
	v_fma_f32 v146, v166, v146, v170
	v_mul_f32_e32 v146, v212, v146
	v_fmac_f32_e32 v146, v211, v7
	global_store_dword v130, v146, s[86:87] offset:128
	v_sub_f32_e32 v147, v147, v158
	v_mul_f32_e32 v147, v147, v159
	v_fma_f32 v147, v167, v147, v171
	v_mul_f32_e32 v147, v212, v147
	v_fmac_f32_e32 v147, v211, v3
	global_store_dword v130, v147, s[86:87] offset:192
	s_waitcnt vmcnt(8)
	v_sub_f32_e32 v148, v148, v160
	v_mul_f32_e32 v148, v148, v161
	v_fma_f32 v148, v164, v148, v168
	v_mul_f32_e32 v148, v212, v148
	v_fmac_f32_e32 v148, v211, v16
	global_store_dword v131, v148, s[86:87] offset:-4096
	v_sub_f32_e32 v149, v149, v160
	v_mul_f32_e32 v149, v149, v161
	v_fma_f32 v149, v165, v149, v169
	v_mul_f32_e32 v149, v212, v149
	v_fmac_f32_e32 v149, v211, v12
	global_store_dword v131, v149, s[86:87] offset:-4032
	v_sub_f32_e32 v150, v150, v160
	v_mul_f32_e32 v150, v150, v161
	v_fma_f32 v150, v166, v150, v170
	v_mul_f32_e32 v150, v212, v150
	v_fmac_f32_e32 v150, v211, v8
	global_store_dword v131, v150, s[86:87] offset:-3968
	v_sub_f32_e32 v151, v151, v160
	v_mul_f32_e32 v151, v151, v161
	v_fma_f32 v151, v167, v151, v171
	v_mul_f32_e32 v151, v212, v151
	v_fmac_f32_e32 v151, v211, v4
	global_store_dword v131, v151, s[86:87] offset:-3904
	v_sub_f32_e32 v152, v152, v162
	v_mul_f32_e32 v152, v152, v163
	v_fma_f32 v152, v164, v152, v168
	v_mul_f32_e32 v152, v212, v152
	v_fmac_f32_e32 v152, v211, v17
	global_store_dword v131, v152, s[86:87]
	v_sub_f32_e32 v153, v153, v162
	v_mul_f32_e32 v153, v153, v163
	v_fma_f32 v153, v165, v153, v169
	v_mul_f32_e32 v153, v212, v153
	v_fmac_f32_e32 v153, v211, v13
	global_store_dword v131, v153, s[86:87] offset:64
	v_sub_f32_e32 v154, v154, v162
	v_mul_f32_e32 v154, v154, v163
	v_fma_f32 v154, v166, v154, v170
	v_mul_f32_e32 v154, v212, v154
	v_fmac_f32_e32 v154, v211, v9
	global_store_dword v131, v154, s[86:87] offset:128
	v_sub_f32_e32 v155, v155, v162
	v_mul_f32_e32 v155, v155, v163
	v_fma_f32 v155, v167, v155, v171
	v_mul_f32_e32 v155, v212, v155
	v_fmac_f32_e32 v155, v211, v5
	global_store_dword v131, v155, s[86:87] offset:192
	s_cbranch_vccnz .LBB0_159

; DEV int otid() { int t = threadIdx.x; asm volatile("" : "+v"(t)); return t; }
; DEV void phase_ln(const Params& P, const float* __restrict__ g, const float* __restrict__ bta, u16* __restrict__ xb, bool zero_kc) {
;   const int lane = otid() & 63;
;   const int gw = blockIdx.x * 4 + (otid() >> 6), nw = gridDim.x * 4;
;   if (zero_kc) {
;     float4* kc = (float4*)(P.ws + OFF_KC);
;     const size_t n4 = 2ull * NB * 256 * 64 / 4;
;     for (size_t i = (size_t)blockIdx.x * 256 + otid(); i < n4; i += (size_t)gridDim.x * 256) kc[i] = make_float4(0.f, 0.f, 0.f, 0.f);
;   }
;   float4 gv[4], bv[4];
; #pragma unroll
;   for (int i = 0; i < 4; ++i) {
;     gv[i] = *(const float4*)(g + i * 256 + lane * 4);
;     bv[i] = *(const float4*)(bta + i * 256 + lane * 4);
;   }
;   for (int row = gw; row < T; row += 2 * nw) {
.LBB0_281:
.LBB0_282:
	v_readfirstlane_b32 s4, v34
	v_readlane_b32 s5, v254, 3
	s_mul_i32 s4, s4, 4
	s_mul_i32 s5, s5, 4
	v_and_b32_e32 v35, 63, v210
	v_lshlrev_b32_e32 v35, 4, v35
	v_add_u32_e32 v36, v52, v0
	v_add_u32_e32 v37, 0x20000, v36
	v_add_u32_e32 v38, 0x40000, v36
	v_add_u32_e32 v39, 0x60000, v36
	v_readlane_b32 s12, v255, 8
	s_add_i32 s12, s12, 2
	s_and_b32 s12, s12, 3
	s_lshl_b32 s12, s12, 24
	s_add_u32 s12, s12, 0x25040000
	s_add_u32 s12, s38, s12
	s_addc_u32 s13, s39, 0

; DEV void phase_ln(const Params& P, const float* __restrict__ g, const float* __restrict__ bta, u16* __restrict__ xb, bool zero_kc) {
;     ...
;         y.x = v[r][i].x * rs * gv[i].x + bv[i].x;
;         y.y = v[r][i].y * rs * gv[i].y + bv[i].y;
;         y.z = v[r][i].z * rs * gv[i].z + bv[i].z;
;         y.w = v[r][i].w * rs * gv[i].w + bv[i].w;
;     ...
; #pragma unroll
;     for (int ms = 0; ms < 8; ++ms) {
;       asm volatile("" ::: "memory");
; #pragma unroll
;       for (int ns = 0; ns < 4; ++ns)
; #pragma unroll
;         for (int j = 0; j < 4; ++j) {
;           int row = m0 + wm * 128 + ms * 16 + quad * 4 + j;
;           int col = n0 + wn * 64 + ns * 16 + l15;
;           const size_t xi = (size_t)row * D + col;
;           const float xv = xin ? xin[xi] : P.out[xi];
;           P.out[xi] = alpha * xv + sc * acc[ms][ns][j];
;         }
.LBB0_289:
	v_add_u32_e32 v136, s8, v207
	v_or_b32_e32 v130, s12, v208
	v_lshlrev_b32_e32 v132, 3, v136
	v_lshlrev_b32_e32 v133, 2, v130
	v_lshlrev_b32_e32 v136, 12, v136
	v_lshl_add_u32 v138, v130, 2, v136
	v_add_u32_e32 v138, 0x1000, v138
	s_and_b64 vcc, exec, s[10:11]
	v_readlane_b32 s4, v255, 10
	v_readlane_b32 s5, v255, 11
	s_add_u32 s4, s4, 0x0
	s_addc_u32 s5, s5, 0
	s_nop 1
	global_load_dword v164, v133, s[4:5]
	global_load_dword v165, v133, s[4:5] offset:64
	global_load_dword v166, v133, s[4:5] offset:128
	global_load_dword v167, v133, s[4:5] offset:192
	v_readlane_b32 s4, v255, 12
	v_readlane_b32 s5, v255, 13
	s_add_u32 s4, s4, 0x0
	s_addc_u32 s5, s5, 0
	s_nop 1
	global_load_dword v168, v133, s[4:5]
	global_load_dword v169, v133, s[4:5] offset:64
	global_load_dword v170, v133, s[4:5] offset:128
	global_load_dword v171, v133, s[4:5] offset:192
	v_readlane_b32 s4, v255, 8
	s_add_i32 s4, s4, 2
	s_and_b32 s4, s4, 3
	s_lshl_b32 s4, s4, 24
	s_add_u32 s4, s4, 0x25000000
	s_add_u32 s4, s38, s4
	s_addc_u32 s5, s39, 0
	s_nop 1
	v_mov_b32_e32 v130, v138
	global_load_dword v140, v130, s[86:87] offset:-4096
	global_load_dword v141, v130, s[86:87] offset:-4032
	global_load_dword v142, v130, s[86:87] offset:-3968
	global_load_dword v143, v130, s[86:87] offset:-3904
	global_load_dword v144, v130, s[86:87]
	global_load_dword v145, v130, s[86:87] offset:64
	global_load_dword v146, v130, s[86:87] offset:128
	global_load_dword v147, v130, s[86:87] offset:192
	global_load_dwordx4 v[156:159], v132, s[4:5]
	v_add_u32_e32 v131, 0x2000, v138
	global_load_dword v148, v131, s[86:87] offset:-4096
	global_load_dword v149, v131, s[86:87] offset:-4032
	global_load_dword v150, v131, s[86:87] offset:-3968
	global_load_dword v151, v131, s[86:87] offset:-3904
	global_load_dword v152, v131, s[86:87]
	global_load_dword v153, v131, s[86:87] offset:64
	global_load_dword v154, v131, s[86:87] offset:128
	global_load_dword v155, v131, s[86:87] offset:192
	global_load_dwordx4 v[160:163], v132, s[4:5] offset:16
	s_waitcnt vmcnt(9)
	v_sub_f32_e32 v140, v140, v156
	v_mul_f32_e32 v140, v140, v157
	v_fma_f32 v140, v164, v140, v168
	v_mul_f32_e32 v140, v212, v140
	v_fmac_f32_e32 v140, v181, v126
	global_store_dword v130, v140, s[86:87] offset:-4096
	v_sub_f32_e32 v141, v141, v156
	v_mul_f32_e32 v141, v141, v157
	v_fma_f32 v141, v165, v141, v169
	v_mul_f32_e32 v141, v212, v141
	v_fmac_f32_e32 v141, v181, v122
	global_store_dword v130, v141, s[86:87] offset:-4032
	v_sub_f32_e32 v142, v142, v156
	v_mul_f32_e32 v142, v142, v157
	v_fma_f32 v142, v166, v142, v170
	v_mul_f32_e32 v142, v212, v142
	v_fmac_f32_e32 v142, v181, v118
	global_store_dword v130, v142, s[86:87] offset:-3968
	v_sub_f32_e32 v143, v143, v156
	v_mul_f32_e32 v143, v143, v157
	v_fma_f32 v143, v167, v143, v171
	v_mul_f32_e32 v143, v212, v143
	v_fmac_f32_e32 v143, v181, v114
	global_store_dword v130, v143, s[86:87] offset:-3904
	v_sub_f32_e32 v144, v144, v158
	v_mul_f32_e32 v144, v144, v159
	v_fma_f32 v144, v164, v144, v168
	v_mul_f32_e32 v144, v212, v144
	v_fmac_f32_e32 v144, v181, v127
	global_store_dword v130, v144, s[86:87]
	v_sub_f32_e32 v145, v145, v158
	v_mul_f32_e32 v145, v145, v159
	v_fma_f32 v145, v165, v145, v169
	v_mul_f32_e32 v145, v212, v145
	v_fmac_f32_e32 v145, v181, v123
	global_store_dword v130, v145, s[86:87] offset:64
	v_sub_f32_e32 v146, v146, v158
	v_mul_f32_e32 v146, v146, v159
	v_fma_f32 v146, v166, v146, v170
	v_mul_f32_e32 v146, v212, v146
	v_fmac_f32_e32 v146, v181, v119
	global_store_dword v130, v146, s[86:87] offset:128
	v_sub_f32_e32 v147, v147, v158
	v_mul_f32_e32 v147, v147, v159
	v_fma_f32 v147, v167, v147, v171
	v_mul_f32_e32 v147, v212, v147
	v_fmac_f32_e32 v147, v181, v115
	global_store_dword v130, v147, s[86:87] offset:192
	v_add_u32_e32 v130, 0x10000, v138
	global_load_dword v140, v130, s[86:87] offset:-4096
	global_load_dword v141, v130, s[86:87] offset:-4032
	global_load_dword v142, v130, s[86:87] offset:-3968
	global_load_dword v143, v130, s[86:87] offset:-3904
	global_load_dword v144, v130, s[86:87]
	global_load_dword v145, v130, s[86:87] offset:64
	global_load_dword v146, v130, s[86:87] offset:128
	global_load_dword v147, v130, s[86:87] offset:192
	global_load_dwordx4 v[156:159], v132, s[4:5] offset:128
	s_waitcnt vmcnt(17)
	v_sub_f32_e32 v148, v148, v160
	v_mul_f32_e32 v148, v148, v161
	v_fma_f32 v148, v164, v148, v168
	v_mul_f32_e32 v148, v212, v148
	v_fmac_f32_e32 v148, v181, v128
	global_store_dword v131, v148, s[86:87] offset:-4096
	v_sub_f32_e32 v149, v149, v160
	v_mul_f32_e32 v149, v149, v161
	v_fma_f32 v149, v165, v149, v169
	v_mul_f32_e32 v149, v212, v149
	v_fmac_f32_e32 v149, v181, v124
	global_store_dword v131, v149, s[86:87] offset:-4032
	v_sub_f32_e32 v150, v150, v160
	v_mul_f32_e32 v150, v150, v161
	v_fma_f32 v150, v166, v150, v170
	v_mul_f32_e32 v150, v212, v150
	v_fmac_f32_e32 v150, v181, v120
	global_store_dword v131, v150, s[86:87] offset:-3968
	v_sub_f32_e32 v151, v151, v160
	v_mul_f32_e32 v151, v151, v161
	v_fma_f32 v151, v167, v151, v171
	v_mul_f32_e32 v151, v212, v151
	v_fmac_f32_e32 v151, v181, v116
	global_store_dword v131, v151, s[86:87] offset:-3904
	v_sub_f32_e32 v152, v152, v162
	v_mul_f32_e32 v152, v152, v163
	v_fma_f32 v152, v164, v152, v168
	v_mul_f32_e32 v152, v212, v152
	v_fmac_f32_e32 v152, v181, v129
	global_store_dword v131, v152, s[86:87]
	v_sub_f32_e32 v153, v153, v162
	v_mul_f32_e32 v153, v153, v163
	v_fma_f32 v153, v165, v153, v169
	v_mul_f32_e32 v153, v212, v153
	v_fmac_f32_e32 v153, v181, v125
	global_store_dword v131, v153, s[86:87] offset:64
	v_sub_f32_e32 v154, v154, v162
	v_mul_f32_e32 v154, v154, v163
	v_fma_f32 v154, v166, v154, v170
	v_mul_f32_e32 v154, v212, v154
	v_fmac_f32_e32 v154, v181, v121
	global_store_dword v131, v154, s[86:87] offset:128
	v_sub_f32_e32 v155, v155, v162
	v_mul_f32_e32 v155, v155, v163
	v_fma_f32 v155, v167, v155, v171
	v_mul_f32_e32 v155, v212, v155
	v_fmac_f32_e32 v155, v181, v117
	global_store_dword v131, v155, s[86:87] offset:192
	v_add_u32_e32 v131, 0x12000, v138
	global_load_dword v148, v131, s[86:87] offset:-4096
	global_load_dword v149, v131, s[86:87] offset:-4032
	global_load_dword v150, v131, s[86:87] offset:-3968
	global_load_dword v151, v131, s[86:87] offset:-3904
	global_load_dword v152, v131, s[86:87]
	global_load_dword v153, v131, s[86:87] offset:64
	global_load_dword v154, v131, s[86:87] offset:128
	global_load_dword v155, v131, s[86:87] offset:192
	global_load_dwordx4 v[160:163], v132, s[4:5] offset:144
	s_waitcnt vmcnt(17)
;     ...
; #pragma unroll
;     for (int ms = 0; ms < 8; ++ms) {
;       asm volatile("" ::: "memory");
; #pragma unroll
;       for (int ns = 0; ns < 4; ++ns)
; #pragma unroll
;         for (int j = 0; j < 4; ++j) {
;           int row = m0 + wm * 128 + ms * 16 + quad * 4 + j;
;           int col = n0 + wn * 64 + ns * 16 + l15;
;           const size_t xi = (size_t)row * D + col;
;           const float xv = xin ? xin[xi] : P.out[xi];
;           P.out[xi] = alpha * xv + sc * acc[ms][ns][j];
;         }
	v_sub_f32_e32 v140, v140, v156
	v_mul_f32_e32 v140, v140, v157
	v_fma_f32 v140, v164, v140, v168
	v_mul_f32_e32 v140, v212, v140
	v_fmac_f32_e32 v140, v181, v110
	global_store_dword v130, v140, s[86:87] offset:-4096
	v_sub_f32_e32 v141, v141, v156
	v_mul_f32_e32 v141, v141, v157
	v_fma_f32 v141, v165, v141, v169
	v_mul_f32_e32 v141, v212, v141
	v_fmac_f32_e32 v141, v181, v106
	global_store_dword v130, v141, s[86:87] offset:-4032
	v_sub_f32_e32 v142, v142, v156
	v_mul_f32_e32 v142, v142, v157
	v_fma_f32 v142, v166, v142, v170
	v_mul_f32_e32 v142, v212, v142
	v_fmac_f32_e32 v142, v181, v102
	global_store_dword v130, v142, s[86:87] offset:-3968
	v_sub_f32_e32 v143, v143, v156
	v_mul_f32_e32 v143, v143, v157
	v_fma_f32 v143, v167, v143, v171
	v_mul_f32_e32 v143, v212, v143
	v_fmac_f32_e32 v143, v181, v98
	global_store_dword v130, v143, s[86:87] offset:-3904
	v_sub_f32_e32 v144, v144, v158
	v_mul_f32_e32 v144, v144, v159
	v_fma_f32 v144, v164, v144, v168
	v_mul_f32_e32 v144, v212, v144
	v_fmac_f32_e32 v144, v181, v111
	global_store_dword v130, v144, s[86:87]
	v_sub_f32_e32 v145, v145, v158
	v_mul_f32_e32 v145, v145, v159
	v_fma_f32 v145, v165, v145, v169
	v_mul_f32_e32 v145, v212, v145
	v_fmac_f32_e32 v145, v181, v107
	global_store_dword v130, v145, s[86:87] offset:64
	v_sub_f32_e32 v146, v146, v158
	v_mul_f32_e32 v146, v146, v159
	v_fma_f32 v146, v166, v146, v170
	v_mul_f32_e32 v146, v212, v146
	v_fmac_f32_e32 v146, v181, v103
	global_store_dword v130, v146, s[86:87] offset:128
	v_sub_f32_e32 v147, v147, v158
	v_mul_f32_e32 v147, v147, v159
	v_fma_f32 v147, v167, v147, v171
	v_mul_f32_e32 v147, v212, v147
	v_fmac_f32_e32 v147, v181, v99
	global_store_dword v130, v147, s[86:87] offset:192
	v_add_u32_e32 v130, 0x20000, v138
	global_load_dword v140, v130, s[86:87] offset:-4096
	global_load_dword v141, v130, s[86:87] offset:-4032
	global_load_dword v142, v130, s[86:87] offset:-3968
	global_load_dword v143, v130, s[86:87] offset:-3904
	global_load_dword v144, v130, s[86:87]
	global_load_dword v145, v130, s[86:87] offset:64
	global_load_dword v146, v130, s[86:87] offset:128
	global_load_dword v147, v130, s[86:87] offset:192
	global_load_dwordx4 v[156:159], v132, s[4:5] offset:256
	s_waitcnt vmcnt(17)
	v_sub_f32_e32 v148, v148, v160
	v_mul_f32_e32 v148, v148, v161
	v_fma_f32 v148, v164, v148, v168
	v_mul_f32_e32 v148, v212, v148
	v_fmac_f32_e32 v148, v181, v112
	global_store_dword v131, v148, s[86:87] offset:-4096
	v_sub_f32_e32 v149, v149, v160
	v_mul_f32_e32 v149, v149, v161
	v_fma_f32 v149, v165, v149, v169
	v_mul_f32_e32 v149, v212, v149
	v_fmac_f32_e32 v149, v181, v108
	global_store_dword v131, v149, s[86:87] offset:-4032
	v_sub_f32_e32 v150, v150, v160
	v_mul_f32_e32 v150, v150, v161
	v_fma_f32 v150, v166, v150, v170
	v_mul_f32_e32 v150, v212, v150
	v_fmac_f32_e32 v150, v181, v104
	global_store_dword v131, v150, s[86:87] offset:-3968
	v_sub_f32_e32 v151, v151, v160
	v_mul_f32_e32 v151, v151, v161
	v_fma_f32 v151, v167, v151, v171
	v_mul_f32_e32 v151, v212, v151
	v_fmac_f32_e32 v151, v181, v100
	global_store_dword v131, v151, s[86:87] offset:-3904
	v_sub_f32_e32 v152, v152, v162
	v_mul_f32_e32 v152, v152, v163
	v_fma_f32 v152, v164, v152, v168
	v_mul_f32_e32 v152, v212, v152
	v_fmac_f32_e32 v152, v181, v113
	global_store_dword v131, v152, s[86:87]
	v_sub_f32_e32 v153, v153, v162
	v_mul_f32_e32 v153, v153, v163
	v_fma_f32 v153, v165, v153, v169
	v_mul_f32_e32 v153, v212, v153
	v_fmac_f32_e32 v153, v181, v109
	global_store_dword v131, v153, s[86:87] offset:64
	v_sub_f32_e32 v154, v154, v162
	v_mul_f32_e32 v154, v154, v163
	v_fma_f32 v154, v166, v154, v170
	v_mul_f32_e32 v154, v212, v154
	v_fmac_f32_e32 v154, v181, v105
	global_store_dword v131, v154, s[86:87] offset:128
	v_sub_f32_e32 v155, v155, v162
	v_mul_f32_e32 v155, v155, v163
	v_fma_f32 v155, v167, v155, v171
	v_mul_f32_e32 v155, v212, v155
	v_fmac_f32_e32 v155, v181, v101
	global_store_dword v131, v155, s[86:87] offset:192
	v_add_u32_e32 v131, 0x22000, v138
	global_load_dword v148, v131, s[86:87] offset:-4096
	global_load_dword v149, v131, s[86:87] offset:-4032
	global_load_dword v150, v131, s[86:87] offset:-3968
	global_load_dword v151, v131, s[86:87] offset:-3904
	global_load_dword v152, v131, s[86:87]
	global_load_dword v153, v131, s[86:87] offset:64
	global_load_dword v154, v131, s[86:87] offset:128
	global_load_dword v155, v131, s[86:87] offset:192
	global_load_dwordx4 v[160:163], v132, s[4:5] offset:272
	s_waitcnt vmcnt(17)
	v_sub_f32_e32 v140, v140, v156
	v_mul_f32_e32 v140, v140, v157
	v_fma_f32 v140, v164, v140, v168
	v_mul_f32_e32 v140, v212, v140
	v_fmac_f32_e32 v140, v181, v94
	global_store_dword v130, v140, s[86:87] offset:-4096
	v_sub_f32_e32 v141, v141, v156
	v_mul_f32_e32 v141, v141, v157
	v_fma_f32 v141, v165, v141, v169
	v_mul_f32_e32 v141, v212, v141
	v_fmac_f32_e32 v141, v181, v90
	global_store_dword v130, v141, s[86:87] offset:-4032
	v_sub_f32_e32 v142, v142, v156
	v_mul_f32_e32 v142, v142, v157
	v_fma_f32 v142, v166, v142, v170
	v_mul_f32_e32 v142, v212, v142
	v_fmac_f32_e32 v142, v181, v86
	global_store_dword v130, v142, s[86:87] offset:-3968
	v_sub_f32_e32 v143, v143, v156
	v_mul_f32_e32 v143, v143, v157
	v_fma_f32 v143, v167, v143, v171
	v_mul_f32_e32 v143, v212, v143
	v_fmac_f32_e32 v143, v181, v82
	global_store_dword v130, v143, s[86:87] offset:-3904
	v_sub_f32_e32 v144, v144, v158
	v_mul_f32_e32 v144, v144, v159
	v_fma_f32 v144, v164, v144, v168
	v_mul_f32_e32 v144, v212, v144
	v_fmac_f32_e32 v144, v181, v95
	global_store_dword v130, v144, s[86:87]
	v_sub_f32_e32 v145, v145, v158
	v_mul_f32_e32 v145, v145, v159
	v_fma_f32 v145, v165, v145, v169
	v_mul_f32_e32 v145, v212, v145
	v_fmac_f32_e32 v145, v181, v91
	global_store_dword v130, v145, s[86:87] offset:64
	v_sub_f32_e32 v146, v146, v158
	v_mul_f32_e32 v146, v146, v159
	v_fma_f32 v146, v166, v146, v170
	v_mul_f32_e32 v146, v212, v146
	v_fmac_f32_e32 v146, v181, v87
	global_store_dword v130, v146, s[86:87] offset:128
	v_sub_f32_e32 v147, v147, v158
	v_mul_f32_e32 v147, v147, v159
	v_fma_f32 v147, v167, v147, v171
	v_mul_f32_e32 v147, v212, v147
	v_fmac_f32_e32 v147, v181, v83
	global_store_dword v130, v147, s[86:87] offset:192
	v_add_u32_e32 v130, 0x30000, v138
	global_load_dword v140, v130, s[86:87] offset:-4096
	global_load_dword v141, v130, s[86:87] offset:-4032
	global_load_dword v142, v130, s[86:87] offset:-3968
	global_load_dword v143, v130, s[86:87] offset:-3904
	global_load_dword v144, v130, s[86:87]
	global_load_dword v145, v130, s[86:87] offset:64
	global_load_dword v146, v130, s[86:87] offset:128
	global_load_dword v147, v130, s[86:87] offset:192
	global_load_dwordx4 v[156:159], v132, s[4:5] offset:384
	s_waitcnt vmcnt(17)
;     ...
; #pragma unroll
;     for (int ms = 0; ms < 8; ++ms) {
;       asm volatile("" ::: "memory");
; #pragma unroll
;       for (int ns = 0; ns < 4; ++ns)
; #pragma unroll
;         for (int j = 0; j < 4; ++j) {
;           int row = m0 + wm * 128 + ms * 16 + quad * 4 + j;
;           int col = n0 + wn * 64 + ns * 16 + l15;
;           const size_t xi = (size_t)row * D + col;
;           const float xv = xin ? xin[xi] : P.out[xi];
;           P.out[xi] = alpha * xv + sc * acc[ms][ns][j];
;         }
	v_sub_f32_e32 v148, v148, v160
	v_mul_f32_e32 v148, v148, v161
	v_fma_f32 v148, v164, v148, v168
	v_mul_f32_e32 v148, v212, v148
	v_fmac_f32_e32 v148, v181, v96
	global_store_dword v131, v148, s[86:87] offset:-4096
	v_sub_f32_e32 v149, v149, v160
	v_mul_f32_e32 v149, v149, v161
	v_fma_f32 v149, v165, v149, v169
	v_mul_f32_e32 v149, v212, v149
	v_fmac_f32_e32 v149, v181, v92
	global_store_dword v131, v149, s[86:87] offset:-4032
	v_sub_f32_e32 v150, v150, v160
	v_mul_f32_e32 v150, v150, v161
	v_fma_f32 v150, v166, v150, v170
	v_mul_f32_e32 v150, v212, v150
	v_fmac_f32_e32 v150, v181, v88
	global_store_dword v131, v150, s[86:87] offset:-3968
	v_sub_f32_e32 v151, v151, v160
	v_mul_f32_e32 v151, v151, v161
	v_fma_f32 v151, v167, v151, v171
	v_mul_f32_e32 v151, v212, v151
	v_fmac_f32_e32 v151, v181, v84
	global_store_dword v131, v151, s[86:87] offset:-3904
	v_sub_f32_e32 v152, v152, v162
	v_mul_f32_e32 v152, v152, v163
	v_fma_f32 v152, v164, v152, v168
	v_mul_f32_e32 v152, v212, v152
	v_fmac_f32_e32 v152, v181, v97
	global_store_dword v131, v152, s[86:87]
	v_sub_f32_e32 v153, v153, v162
	v_mul_f32_e32 v153, v153, v163
	v_fma_f32 v153, v165, v153, v169
	v_mul_f32_e32 v153, v212, v153
	v_fmac_f32_e32 v153, v181, v93
	global_store_dword v131, v153, s[86:87] offset:64
	v_sub_f32_e32 v154, v154, v162
	v_mul_f32_e32 v154, v154, v163
	v_fma_f32 v154, v166, v154, v170
	v_mul_f32_e32 v154, v212, v154
	v_fmac_f32_e32 v154, v181, v89
	global_store_dword v131, v154, s[86:87] offset:128
	v_sub_f32_e32 v155, v155, v162
	v_mul_f32_e32 v155, v155, v163
	v_fma_f32 v155, v167, v155, v171
	v_mul_f32_e32 v155, v212, v155
	v_fmac_f32_e32 v155, v181, v85
	global_store_dword v131, v155, s[86:87] offset:192
	v_add_u32_e32 v131, 0x32000, v138
	global_load_dword v148, v131, s[86:87] offset:-4096
	global_load_dword v149, v131, s[86:87] offset:-4032
	global_load_dword v150, v131, s[86:87] offset:-3968
	global_load_dword v151, v131, s[86:87] offset:-3904
	global_load_dword v152, v131, s[86:87]
	global_load_dword v153, v131, s[86:87] offset:64
	global_load_dword v154, v131, s[86:87] offset:128
	global_load_dword v155, v131, s[86:87] offset:192
	global_load_dwordx4 v[160:163], v132, s[4:5] offset:400
	s_waitcnt vmcnt(17)
	v_sub_f32_e32 v140, v140, v156
	v_mul_f32_e32 v140, v140, v157
	v_fma_f32 v140, v164, v140, v168
	v_mul_f32_e32 v140, v212, v140
	v_fmac_f32_e32 v140, v181, v78
	global_store_dword v130, v140, s[86:87] offset:-4096
	v_sub_f32_e32 v141, v141, v156
	v_mul_f32_e32 v141, v141, v157
	v_fma_f32 v141, v165, v141, v169
	v_mul_f32_e32 v141, v212, v141
	v_fmac_f32_e32 v141, v181, v74
	global_store_dword v130, v141, s[86:87] offset:-4032
	v_sub_f32_e32 v142, v142, v156
	v_mul_f32_e32 v142, v142, v157
	v_fma_f32 v142, v166, v142, v170
	v_mul_f32_e32 v142, v212, v142
	v_fmac_f32_e32 v142, v181, v70
	global_store_dword v130, v142, s[86:87] offset:-3968
	v_sub_f32_e32 v143, v143, v156
	v_mul_f32_e32 v143, v143, v157
	v_fma_f32 v143, v167, v143, v171
	v_mul_f32_e32 v143, v212, v143
	v_fmac_f32_e32 v143, v181, v66
	global_store_dword v130, v143, s[86:87] offset:-3904
	v_sub_f32_e32 v144, v144, v158
	v_mul_f32_e32 v144, v144, v159
	v_fma_f32 v144, v164, v144, v168
	v_mul_f32_e32 v144, v212, v144
	v_fmac_f32_e32 v144, v181, v79
	global_store_dword v130, v144, s[86:87]
	v_sub_f32_e32 v145, v145, v158
	v_mul_f32_e32 v145, v145, v159
	v_fma_f32 v145, v165, v145, v169
	v_mul_f32_e32 v145, v212, v145
	v_fmac_f32_e32 v145, v181, v75
	global_store_dword v130, v145, s[86:87] offset:64
	v_sub_f32_e32 v146, v146, v158
	v_mul_f32_e32 v146, v146, v159
	v_fma_f32 v146, v166, v146, v170
	v_mul_f32_e32 v146, v212, v146
	v_fmac_f32_e32 v146, v181, v71
	global_store_dword v130, v146, s[86:87] offset:128
	v_sub_f32_e32 v147, v147, v158
	v_mul_f32_e32 v147, v147, v159
	v_fma_f32 v147, v167, v147, v171
	v_mul_f32_e32 v147, v212, v147
	v_fmac_f32_e32 v147, v181, v67
	global_store_dword v130, v147, s[86:87] offset:192
	v_add_u32_e32 v130, 0x40000, v138
	global_load_dword v140, v130, s[86:87] offset:-4096
	global_load_dword v141, v130, s[86:87] offset:-4032
	global_load_dword v142, v130, s[86:87] offset:-3968
	global_load_dword v143, v130, s[86:87] offset:-3904
	global_load_dword v144, v130, s[86:87]
	global_load_dword v145, v130, s[86:87] offset:64
	global_load_dword v146, v130, s[86:87] offset:128
	global_load_dword v147, v130, s[86:87] offset:192
	global_load_dwordx4 v[156:159], v132, s[4:5] offset:512
	s_waitcnt vmcnt(17)
	v_sub_f32_e32 v148, v148, v160
	v_mul_f32_e32 v148, v148, v161
	v_fma_f32 v148, v164, v148, v168
	v_mul_f32_e32 v148, v212, v148
	v_fmac_f32_e32 v148, v181, v80
	global_store_dword v131, v148, s[86:87] offset:-4096
	v_sub_f32_e32 v149, v149, v160
	v_mul_f32_e32 v149, v149, v161
	v_fma_f32 v149, v165, v149, v169
	v_mul_f32_e32 v149, v212, v149
	v_fmac_f32_e32 v149, v181, v76
	global_store_dword v131, v149, s[86:87] offset:-4032
	v_sub_f32_e32 v150, v150, v160
	v_mul_f32_e32 v150, v150, v161
	v_fma_f32 v150, v166, v150, v170
	v_mul_f32_e32 v150, v212, v150
	v_fmac_f32_e32 v150, v181, v72
	global_store_dword v131, v150, s[86:87] offset:-3968
	v_sub_f32_e32 v151, v151, v160
	v_mul_f32_e32 v151, v151, v161
	v_fma_f32 v151, v167, v151, v171
	v_mul_f32_e32 v151, v212, v151
	v_fmac_f32_e32 v151, v181, v68
	global_store_dword v131, v151, s[86:87] offset:-3904
	v_sub_f32_e32 v152, v152, v162
	v_mul_f32_e32 v152, v152, v163
	v_fma_f32 v152, v164, v152, v168
	v_mul_f32_e32 v152, v212, v152
	v_fmac_f32_e32 v152, v181, v81
	global_store_dword v131, v152, s[86:87]
	v_sub_f32_e32 v153, v153, v162
	v_mul_f32_e32 v153, v153, v163
	v_fma_f32 v153, v165, v153, v169
	v_mul_f32_e32 v153, v212, v153
	v_fmac_f32_e32 v153, v181, v77
	global_store_dword v131, v153, s[86:87] offset:64
	v_sub_f32_e32 v154, v154, v162
	v_mul_f32_e32 v154, v154, v163
	v_fma_f32 v154, v166, v154, v170
	v_mul_f32_e32 v154, v212, v154
	v_fmac_f32_e32 v154, v181, v73
	global_store_dword v131, v154, s[86:87] offset:128
	v_sub_f32_e32 v155, v155, v162
	v_mul_f32_e32 v155, v155, v163
	v_fma_f32 v155, v167, v155, v171
	v_mul_f32_e32 v155, v212, v155
	v_fmac_f32_e32 v155, v181, v69
	global_store_dword v131, v155, s[86:87] offset:192
	v_add_u32_e32 v131, 0x42000, v138
	global_load_dword v148, v131, s[86:87] offset:-4096
	global_load_dword v149, v131, s[86:87] offset:-4032
	global_load_dword v150, v131, s[86:87] offset:-3968
	global_load_dword v151, v131, s[86:87] offset:-3904
	global_load_dword v152, v131, s[86:87]
	global_load_dword v153, v131, s[86:87] offset:64
	global_load_dword v154, v131, s[86:87] offset:128
	global_load_dword v155, v131, s[86:87] offset:192
	global_load_dwordx4 v[160:163], v132, s[4:5] offset:528
	s_waitcnt vmcnt(17)
;     ...
; #pragma unroll
;     for (int ms = 0; ms < 8; ++ms) {
;       asm volatile("" ::: "memory");
; #pragma unroll
;       for (int ns = 0; ns < 4; ++ns)
; #pragma unroll
;         for (int j = 0; j < 4; ++j) {
;           int row = m0 + wm * 128 + ms * 16 + quad * 4 + j;
;           int col = n0 + wn * 64 + ns * 16 + l15;
;           const size_t xi = (size_t)row * D + col;
;           const float xv = xin ? xin[xi] : P.out[xi];
;           P.out[xi] = alpha * xv + sc * acc[ms][ns][j];
;         }
	v_sub_f32_e32 v140, v140, v156
	v_mul_f32_e32 v140, v140, v157
	v_fma_f32 v140, v164, v140, v168
	v_mul_f32_e32 v140, v212, v140
	v_fmac_f32_e32 v140, v181, v62
	global_store_dword v130, v140, s[86:87] offset:-4096
	v_sub_f32_e32 v141, v141, v156
	v_mul_f32_e32 v141, v141, v157
	v_fma_f32 v141, v165, v141, v169
	v_mul_f32_e32 v141, v212, v141
	v_fmac_f32_e32 v141, v181, v58
	global_store_dword v130, v141, s[86:87] offset:-4032
	v_sub_f32_e32 v142, v142, v156
	v_mul_f32_e32 v142, v142, v157
	v_fma_f32 v142, v166, v142, v170
	v_mul_f32_e32 v142, v212, v142
	v_fmac_f32_e32 v142, v181, v54
	global_store_dword v130, v142, s[86:87] offset:-3968
	v_sub_f32_e32 v143, v143, v156
	v_mul_f32_e32 v143, v143, v157
	v_fma_f32 v143, v167, v143, v171
	v_mul_f32_e32 v143, v212, v143
	v_fmac_f32_e32 v143, v181, v50
	global_store_dword v130, v143, s[86:87] offset:-3904
	v_sub_f32_e32 v144, v144, v158
	v_mul_f32_e32 v144, v144, v159
	v_fma_f32 v144, v164, v144, v168
	v_mul_f32_e32 v144, v212, v144
	v_fmac_f32_e32 v144, v181, v63
	global_store_dword v130, v144, s[86:87]
	v_sub_f32_e32 v145, v145, v158
	v_mul_f32_e32 v145, v145, v159
	v_fma_f32 v145, v165, v145, v169
	v_mul_f32_e32 v145, v212, v145
	v_fmac_f32_e32 v145, v181, v59
	global_store_dword v130, v145, s[86:87] offset:64
	v_sub_f32_e32 v146, v146, v158
	v_mul_f32_e32 v146, v146, v159
	v_fma_f32 v146, v166, v146, v170
	v_mul_f32_e32 v146, v212, v146
	v_fmac_f32_e32 v146, v181, v55
	global_store_dword v130, v146, s[86:87] offset:128
	v_sub_f32_e32 v147, v147, v158
	v_mul_f32_e32 v147, v147, v159
	v_fma_f32 v147, v167, v147, v171
	v_mul_f32_e32 v147, v212, v147
	v_fmac_f32_e32 v147, v181, v51
	global_store_dword v130, v147, s[86:87] offset:192
	v_add_u32_e32 v130, 0x50000, v138
	global_load_dword v140, v130, s[86:87] offset:-4096
	global_load_dword v141, v130, s[86:87] offset:-4032
	global_load_dword v142, v130, s[86:87] offset:-3968
	global_load_dword v143, v130, s[86:87] offset:-3904
	global_load_dword v144, v130, s[86:87]
	global_load_dword v145, v130, s[86:87] offset:64
	global_load_dword v146, v130, s[86:87] offset:128
	global_load_dword v147, v130, s[86:87] offset:192
	global_load_dwordx4 v[156:159], v132, s[4:5] offset:640
	s_waitcnt vmcnt(17)
	v_sub_f32_e32 v148, v148, v160
	v_mul_f32_e32 v148, v148, v161
	v_fma_f32 v148, v164, v148, v168
	v_mul_f32_e32 v148, v212, v148
	v_fmac_f32_e32 v148, v181, v64
	global_store_dword v131, v148, s[86:87] offset:-4096
	v_sub_f32_e32 v149, v149, v160
	v_mul_f32_e32 v149, v149, v161
	v_fma_f32 v149, v165, v149, v169
	v_mul_f32_e32 v149, v212, v149
	v_fmac_f32_e32 v149, v181, v60
	global_store_dword v131, v149, s[86:87] offset:-4032
	v_sub_f32_e32 v150, v150, v160
	v_mul_f32_e32 v150, v150, v161
	v_fma_f32 v150, v166, v150, v170
	v_mul_f32_e32 v150, v212, v150
	v_fmac_f32_e32 v150, v181, v56
	global_store_dword v131, v150, s[86:87] offset:-3968
	v_sub_f32_e32 v151, v151, v160
	v_mul_f32_e32 v151, v151, v161
	v_fma_f32 v151, v167, v151, v171
	v_mul_f32_e32 v151, v212, v151
	v_fmac_f32_e32 v151, v181, v52
	global_store_dword v131, v151, s[86:87] offset:-3904
	v_sub_f32_e32 v152, v152, v162
	v_mul_f32_e32 v152, v152, v163
	v_fma_f32 v152, v164, v152, v168
	v_mul_f32_e32 v152, v212, v152
	v_fmac_f32_e32 v152, v181, v65
	global_store_dword v131, v152, s[86:87]
	v_sub_f32_e32 v153, v153, v162
	v_mul_f32_e32 v153, v153, v163
	v_fma_f32 v153, v165, v153, v169
	v_mul_f32_e32 v153, v212, v153
	v_fmac_f32_e32 v153, v181, v61
	global_store_dword v131, v153, s[86:87] offset:64
	v_sub_f32_e32 v154, v154, v162
	v_mul_f32_e32 v154, v154, v163
	v_fma_f32 v154, v166, v154, v170
	v_mul_f32_e32 v154, v212, v154
	v_fmac_f32_e32 v154, v181, v57
	global_store_dword v131, v154, s[86:87] offset:128
	v_sub_f32_e32 v155, v155, v162
	v_mul_f32_e32 v155, v155, v163
	v_fma_f32 v155, v167, v155, v171
	v_mul_f32_e32 v155, v212, v155
	v_fmac_f32_e32 v155, v181, v53
	global_store_dword v131, v155, s[86:87] offset:192
	v_add_u32_e32 v131, 0x52000, v138
	global_load_dword v148, v131, s[86:87] offset:-4096
	global_load_dword v149, v131, s[86:87] offset:-4032
	global_load_dword v150, v131, s[86:87] offset:-3968
	global_load_dword v151, v131, s[86:87] offset:-3904
	global_load_dword v152, v131, s[86:87]
	global_load_dword v153, v131, s[86:87] offset:64
	global_load_dword v154, v131, s[86:87] offset:128
	global_load_dword v155, v131, s[86:87] offset:192
	global_load_dwordx4 v[160:163], v132, s[4:5] offset:656
	s_waitcnt vmcnt(17)
	v_sub_f32_e32 v140, v140, v156
	v_mul_f32_e32 v140, v140, v157
	v_fma_f32 v140, v164, v140, v168
	v_mul_f32_e32 v140, v212, v140
	v_fmac_f32_e32 v140, v181, v46
	global_store_dword v130, v140, s[86:87] offset:-4096
	v_sub_f32_e32 v141, v141, v156
	v_mul_f32_e32 v141, v141, v157
	v_fma_f32 v141, v165, v141, v169
	v_mul_f32_e32 v141, v212, v141
	v_fmac_f32_e32 v141, v181, v42
	global_store_dword v130, v141, s[86:87] offset:-4032
	v_sub_f32_e32 v142, v142, v156
	v_mul_f32_e32 v142, v142, v157
	v_fma_f32 v142, v166, v142, v170
	v_mul_f32_e32 v142, v212, v142
	v_fmac_f32_e32 v142, v181, v38
	global_store_dword v130, v142, s[86:87] offset:-3968
	v_sub_f32_e32 v143, v143, v156
	v_mul_f32_e32 v143, v143, v157
	v_fma_f32 v143, v167, v143, v171
	v_mul_f32_e32 v143, v212, v143
	v_fmac_f32_e32 v143, v181, v34
	global_store_dword v130, v143, s[86:87] offset:-3904
	v_sub_f32_e32 v144, v144, v158
	v_mul_f32_e32 v144, v144, v159
	v_fma_f32 v144, v164, v144, v168
	v_mul_f32_e32 v144, v212, v144
	v_fmac_f32_e32 v144, v181, v47
	global_store_dword v130, v144, s[86:87]
	v_sub_f32_e32 v145, v145, v158
	v_mul_f32_e32 v145, v145, v159
	v_fma_f32 v145, v165, v145, v169
	v_mul_f32_e32 v145, v212, v145
	v_fmac_f32_e32 v145, v181, v43
	global_store_dword v130, v145, s[86:87] offset:64
	v_sub_f32_e32 v146, v146, v158
	v_mul_f32_e32 v146, v146, v159
	v_fma_f32 v146, v166, v146, v170
	v_mul_f32_e32 v146, v212, v146
	v_fmac_f32_e32 v146, v181, v39
	global_store_dword v130, v146, s[86:87] offset:128
	v_sub_f32_e32 v147, v147, v158
	v_mul_f32_e32 v147, v147, v159
	v_fma_f32 v147, v167, v147, v171
	v_mul_f32_e32 v147, v212, v147
	v_fmac_f32_e32 v147, v181, v35
	global_store_dword v130, v147, s[86:87] offset:192
	v_add_u32_e32 v130, 0x60000, v138
	global_load_dword v140, v130, s[86:87] offset:-4096
	global_load_dword v141, v130, s[86:87] offset:-4032
	global_load_dword v142, v130, s[86:87] offset:-3968
	global_load_dword v143, v130, s[86:87] offset:-3904
	global_load_dword v144, v130, s[86:87]
	global_load_dword v145, v130, s[86:87] offset:64
	global_load_dword v146, v130, s[86:87] offset:128
	global_load_dword v147, v130, s[86:87] offset:192
	global_load_dwordx4 v[156:159], v132, s[4:5] offset:768
	s_waitcnt vmcnt(17)
;     ...
; #pragma unroll
;     for (int ms = 0; ms < 8; ++ms) {
;       asm volatile("" ::: "memory");
; #pragma unroll
;       for (int ns = 0; ns < 4; ++ns)
; #pragma unroll
;         for (int j = 0; j < 4; ++j) {
;           int row = m0 + wm * 128 + ms * 16 + quad * 4 + j;
;           int col = n0 + wn * 64 + ns * 16 + l15;
;           const size_t xi = (size_t)row * D + col;
;           const float xv = xin ? xin[xi] : P.out[xi];
;           P.out[xi] = alpha * xv + sc * acc[ms][ns][j];
;         }
	v_sub_f32_e32 v148, v148, v160
	v_mul_f32_e32 v148, v148, v161
	v_fma_f32 v148, v164, v148, v168
	v_mul_f32_e32 v148, v212, v148
	v_fmac_f32_e32 v148, v181, v48
	global_store_dword v131, v148, s[86:87] offset:-4096
	v_sub_f32_e32 v149, v149, v160
	v_mul_f32_e32 v149, v149, v161
	v_fma_f32 v149, v165, v149, v169
	v_mul_f32_e32 v149, v212, v149
	v_fmac_f32_e32 v149, v181, v44
	global_store_dword v131, v149, s[86:87] offset:-4032
	v_sub_f32_e32 v150, v150, v160
	v_mul_f32_e32 v150, v150, v161
	v_fma_f32 v150, v166, v150, v170
	v_mul_f32_e32 v150, v212, v150
	v_fmac_f32_e32 v150, v181, v40
	global_store_dword v131, v150, s[86:87] offset:-3968
	v_sub_f32_e32 v151, v151, v160
	v_mul_f32_e32 v151, v151, v161
	v_fma_f32 v151, v167, v151, v171
	v_mul_f32_e32 v151, v212, v151
	v_fmac_f32_e32 v151, v181, v36
	global_store_dword v131, v151, s[86:87] offset:-3904
	v_sub_f32_e32 v152, v152, v162
	v_mul_f32_e32 v152, v152, v163
	v_fma_f32 v152, v164, v152, v168
	v_mul_f32_e32 v152, v212, v152
	v_fmac_f32_e32 v152, v181, v49
	global_store_dword v131, v152, s[86:87]
	v_sub_f32_e32 v153, v153, v162
	v_mul_f32_e32 v153, v153, v163
	v_fma_f32 v153, v165, v153, v169
	v_mul_f32_e32 v153, v212, v153
	v_fmac_f32_e32 v153, v181, v45
	global_store_dword v131, v153, s[86:87] offset:64
	v_sub_f32_e32 v154, v154, v162
	v_mul_f32_e32 v154, v154, v163
	v_fma_f32 v154, v166, v154, v170
	v_mul_f32_e32 v154, v212, v154
	v_fmac_f32_e32 v154, v181, v41
	global_store_dword v131, v154, s[86:87] offset:128
	v_sub_f32_e32 v155, v155, v162
	v_mul_f32_e32 v155, v155, v163
	v_fma_f32 v155, v167, v155, v171
	v_mul_f32_e32 v155, v212, v155
	v_fmac_f32_e32 v155, v181, v37
	global_store_dword v131, v155, s[86:87] offset:192
	v_add_u32_e32 v131, 0x62000, v138
	global_load_dword v148, v131, s[86:87] offset:-4096
	global_load_dword v149, v131, s[86:87] offset:-4032
	global_load_dword v150, v131, s[86:87] offset:-3968
	global_load_dword v151, v131, s[86:87] offset:-3904
	global_load_dword v152, v131, s[86:87]
	global_load_dword v153, v131, s[86:87] offset:64
	global_load_dword v154, v131, s[86:87] offset:128
	global_load_dword v155, v131, s[86:87] offset:192
	global_load_dwordx4 v[160:163], v132, s[4:5] offset:784
	s_waitcnt vmcnt(17)
	v_sub_f32_e32 v140, v140, v156
	v_mul_f32_e32 v140, v140, v157
	v_fma_f32 v140, v164, v140, v168
	v_mul_f32_e32 v140, v212, v140
	v_fmac_f32_e32 v140, v181, v30
	global_store_dword v130, v140, s[86:87] offset:-4096
	v_sub_f32_e32 v141, v141, v156
	v_mul_f32_e32 v141, v141, v157
	v_fma_f32 v141, v165, v141, v169
	v_mul_f32_e32 v141, v212, v141
	v_fmac_f32_e32 v141, v181, v26
	global_store_dword v130, v141, s[86:87] offset:-4032
	v_sub_f32_e32 v142, v142, v156
	v_mul_f32_e32 v142, v142, v157
	v_fma_f32 v142, v166, v142, v170
	v_mul_f32_e32 v142, v212, v142
	v_fmac_f32_e32 v142, v181, v22
	global_store_dword v130, v142, s[86:87] offset:-3968
	v_sub_f32_e32 v143, v143, v156
	v_mul_f32_e32 v143, v143, v157
	v_fma_f32 v143, v167, v143, v171
	v_mul_f32_e32 v143, v212, v143
	v_fmac_f32_e32 v143, v181, v18
	global_store_dword v130, v143, s[86:87] offset:-3904
	v_sub_f32_e32 v144, v144, v158
	v_mul_f32_e32 v144, v144, v159
	v_fma_f32 v144, v164, v144, v168
	v_mul_f32_e32 v144, v212, v144
	v_fmac_f32_e32 v144, v181, v31
	global_store_dword v130, v144, s[86:87]
	v_sub_f32_e32 v145, v145, v158
	v_mul_f32_e32 v145, v145, v159
	v_fma_f32 v145, v165, v145, v169
	v_mul_f32_e32 v145, v212, v145
	v_fmac_f32_e32 v145, v181, v27
	global_store_dword v130, v145, s[86:87] offset:64
	v_sub_f32_e32 v146, v146, v158
	v_mul_f32_e32 v146, v146, v159
	v_fma_f32 v146, v166, v146, v170
	v_mul_f32_e32 v146, v212, v146
	v_fmac_f32_e32 v146, v181, v23
	global_store_dword v130, v146, s[86:87] offset:128
	v_sub_f32_e32 v147, v147, v158
	v_mul_f32_e32 v147, v147, v159
	v_fma_f32 v147, v167, v147, v171
	v_mul_f32_e32 v147, v212, v147
	v_fmac_f32_e32 v147, v181, v19
	global_store_dword v130, v147, s[86:87] offset:192
	v_add_u32_e32 v130, 0x70000, v138
	global_load_dword v140, v130, s[86:87] offset:-4096
	global_load_dword v141, v130, s[86:87] offset:-4032
	global_load_dword v142, v130, s[86:87] offset:-3968
	global_load_dword v143, v130, s[86:87] offset:-3904
	global_load_dword v144, v130, s[86:87]
	global_load_dword v145, v130, s[86:87] offset:64
	global_load_dword v146, v130, s[86:87] offset:128
	global_load_dword v147, v130, s[86:87] offset:192
	global_load_dwordx4 v[156:159], v132, s[4:5] offset:896
	s_waitcnt vmcnt(17)
;     ...
; #pragma unroll
;     for (int ms = 0; ms < 8; ++ms) {
;       asm volatile("" ::: "memory");
; #pragma unroll
;       for (int ns = 0; ns < 4; ++ns)
; #pragma unroll
;         for (int j = 0; j < 4; ++j) {
;           int row = m0 + wm * 128 + ms * 16 + quad * 4 + j;
;           int col = n0 + wn * 64 + ns * 16 + l15;
;           const size_t xi = (size_t)row * D + col;
;           const float xv = xin ? xin[xi] : P.out[xi];
;           P.out[xi] = alpha * xv + sc * acc[ms][ns][j];
;         }
	v_sub_f32_e32 v148, v148, v160
	v_mul_f32_e32 v148, v148, v161
	v_fma_f32 v148, v164, v148, v168
	v_mul_f32_e32 v148, v212, v148
	v_fmac_f32_e32 v148, v181, v32
	global_store_dword v131, v148, s[86:87] offset:-4096
	v_sub_f32_e32 v149, v149, v160
	v_mul_f32_e32 v149, v149, v161
	v_fma_f32 v149, v165, v149, v169
	v_mul_f32_e32 v149, v212, v149
	v_fmac_f32_e32 v149, v181, v28
	global_store_dword v131, v149, s[86:87] offset:-4032
	v_sub_f32_e32 v150, v150, v160
	v_mul_f32_e32 v150, v150, v161
	v_fma_f32 v150, v166, v150, v170
	v_mul_f32_e32 v150, v212, v150
	v_fmac_f32_e32 v150, v181, v24
	global_store_dword v131, v150, s[86:87] offset:-3968
	v_sub_f32_e32 v151, v151, v160
	v_mul_f32_e32 v151, v151, v161
	v_fma_f32 v151, v167, v151, v171
	v_mul_f32_e32 v151, v212, v151
	v_fmac_f32_e32 v151, v181, v20
	global_store_dword v131, v151, s[86:87] offset:-3904
	v_sub_f32_e32 v152, v152, v162
	v_mul_f32_e32 v152, v152, v163
	v_fma_f32 v152, v164, v152, v168
	v_mul_f32_e32 v152, v212, v152
	v_fmac_f32_e32 v152, v181, v33
	global_store_dword v131, v152, s[86:87]
	v_sub_f32_e32 v153, v153, v162
	v_mul_f32_e32 v153, v153, v163
	v_fma_f32 v153, v165, v153, v169
	v_mul_f32_e32 v153, v212, v153
	v_fmac_f32_e32 v153, v181, v29
	global_store_dword v131, v153, s[86:87] offset:64
	v_sub_f32_e32 v154, v154, v162
	v_mul_f32_e32 v154, v154, v163
	v_fma_f32 v154, v166, v154, v170
	v_mul_f32_e32 v154, v212, v154
	v_fmac_f32_e32 v154, v181, v25
	global_store_dword v131, v154, s[86:87] offset:128
	v_sub_f32_e32 v155, v155, v162
	v_mul_f32_e32 v155, v155, v163
	v_fma_f32 v155, v167, v155, v171
	v_mul_f32_e32 v155, v212, v155
	v_fmac_f32_e32 v155, v181, v21
	global_store_dword v131, v155, s[86:87] offset:192
	v_add_u32_e32 v131, 0x72000, v138
	global_load_dword v148, v131, s[86:87] offset:-4096
	global_load_dword v149, v131, s[86:87] offset:-4032
	global_load_dword v150, v131, s[86:87] offset:-3968
	global_load_dword v151, v131, s[86:87] offset:-3904
	global_load_dword v152, v131, s[86:87]
	global_load_dword v153, v131, s[86:87] offset:64
	global_load_dword v154, v131, s[86:87] offset:128
	global_load_dword v155, v131, s[86:87] offset:192
	global_load_dwordx4 v[160:163], v132, s[4:5] offset:912
	s_waitcnt vmcnt(17)
	v_sub_f32_e32 v140, v140, v156
	v_mul_f32_e32 v140, v140, v157
	v_fma_f32 v140, v164, v140, v168
	v_mul_f32_e32 v140, v212, v140
	v_fmac_f32_e32 v140, v181, v14
	global_store_dword v130, v140, s[86:87] offset:-4096
	v_sub_f32_e32 v141, v141, v156
	v_mul_f32_e32 v141, v141, v157
	v_fma_f32 v141, v165, v141, v169
	v_mul_f32_e32 v141, v212, v141
	v_fmac_f32_e32 v141, v181, v10
	global_store_dword v130, v141, s[86:87] offset:-4032
	v_sub_f32_e32 v142, v142, v156
	v_mul_f32_e32 v142, v142, v157
	v_fma_f32 v142, v166, v142, v170
	v_mul_f32_e32 v142, v212, v142
	v_fmac_f32_e32 v142, v181, v6
	global_store_dword v130, v142, s[86:87] offset:-3968
	v_sub_f32_e32 v143, v143, v156
	v_mul_f32_e32 v143, v143, v157
	v_fma_f32 v143, v167, v143, v171
	v_mul_f32_e32 v143, v212, v143
	v_fmac_f32_e32 v143, v181, v2
	global_store_dword v130, v143, s[86:87] offset:-3904
	v_sub_f32_e32 v144, v144, v158
	v_mul_f32_e32 v144, v144, v159
	v_fma_f32 v144, v164, v144, v168
	v_mul_f32_e32 v144, v212, v144
	v_fmac_f32_e32 v144, v181, v15
	global_store_dword v130, v144, s[86:87]
	v_sub_f32_e32 v145, v145, v158
	v_mul_f32_e32 v145, v145, v159
	v_fma_f32 v145, v165, v145, v169
	v_mul_f32_e32 v145, v212, v145
	v_fmac_f32_e32 v145, v181, v11
	global_store_dword v130, v145, s[86:87] offset:64
	v_sub_f32_e32 v146, v146, v158
	v_mul_f32_e32 v146, v146, v159
	v_fma_f32 v146, v166, v146, v170
	v_mul_f32_e32 v146, v212, v146
	v_fmac_f32_e32 v146, v181, v7
	global_store_dword v130, v146, s[86:87] offset:128
	v_sub_f32_e32 v147, v147, v158
	v_mul_f32_e32 v147, v147, v159
	v_fma_f32 v147, v167, v147, v171
	v_mul_f32_e32 v147, v212, v147
	v_fmac_f32_e32 v147, v181, v3
	global_store_dword v130, v147, s[86:87] offset:192
	s_waitcnt vmcnt(8)
	v_sub_f32_e32 v148, v148, v160
	v_mul_f32_e32 v148, v148, v161
	v_fma_f32 v148, v164, v148, v168
	v_mul_f32_e32 v148, v212, v148
	v_fmac_f32_e32 v148, v181, v16
	global_store_dword v131, v148, s[86:87] offset:-4096
	v_sub_f32_e32 v149, v149, v160
	v_mul_f32_e32 v149, v149, v161
	v_fma_f32 v149, v165, v149, v169
	v_mul_f32_e32 v149, v212, v149
	v_fmac_f32_e32 v149, v181, v12
	global_store_dword v131, v149, s[86:87] offset:-4032
	v_sub_f32_e32 v150, v150, v160
	v_mul_f32_e32 v150, v150, v161
	v_fma_f32 v150, v166, v150, v170
	v_mul_f32_e32 v150, v212, v150
	v_fmac_f32_e32 v150, v181, v8
	global_store_dword v131, v150, s[86:87] offset:-3968
	v_sub_f32_e32 v151, v151, v160
	v_mul_f32_e32 v151, v151, v161
	v_fma_f32 v151, v167, v151, v171
	v_mul_f32_e32 v151, v212, v151
	v_fmac_f32_e32 v151, v181, v4
	global_store_dword v131, v151, s[86:87] offset:-3904
	v_sub_f32_e32 v152, v152, v162
	v_mul_f32_e32 v152, v152, v163
	v_fma_f32 v152, v164, v152, v168
	v_mul_f32_e32 v152, v212, v152
	v_fmac_f32_e32 v152, v181, v17
	global_store_dword v131, v152, s[86:87]
	v_sub_f32_e32 v153, v153, v162
	v_mul_f32_e32 v153, v153, v163
	v_fma_f32 v153, v165, v153, v169
	v_mul_f32_e32 v153, v212, v153
	v_fmac_f32_e32 v153, v181, v13
	global_store_dword v131, v153, s[86:87] offset:64
	v_sub_f32_e32 v154, v154, v162
	v_mul_f32_e32 v154, v154, v163
	v_fma_f32 v154, v166, v154, v170
	v_mul_f32_e32 v154, v212, v154
	v_fmac_f32_e32 v154, v181, v9
	global_store_dword v131, v154, s[86:87] offset:128
	v_sub_f32_e32 v155, v155, v162
	v_mul_f32_e32 v155, v155, v163
	v_fma_f32 v155, v167, v155, v171
	v_mul_f32_e32 v155, v212, v155
	v_fmac_f32_e32 v155, v181, v5
	global_store_dword v131, v155, s[86:87] offset:192
	s_cbranch_vccnz .LBB0_314

;     ...
; #pragma unroll
;     for (int ms = 0; ms < 8; ++ms) {
;       asm volatile("" ::: "memory");
; #pragma unroll
;       for (int ns = 0; ns < 4; ++ns)
; #pragma unroll
;         for (int j = 0; j < 4; ++j) {
;           int row = m0 + wm * 128 + ms * 16 + quad * 4 + j;
;           int col = n0 + wn * 64 + ns * 16 + l15;
;           const size_t xi = (size_t)row * D + col;
;           const float xv = xin ? xin[xi] : P.out[xi];
;           P.out[xi] = alpha * xv + sc * acc[ms][ns][j];
;         }
.LBB0_318:
	v_add_u32_e32 v136, s8, v183
	v_or_b32_e32 v130, s12, v178
	v_lshlrev_b32_e32 v132, 3, v136
	v_lshlrev_b32_e32 v133, 2, v130
	v_lshlrev_b32_e32 v136, 12, v136
	v_lshl_add_u32 v138, v130, 2, v136
	v_add_u32_e32 v138, 0x1000, v138
	s_and_b64 vcc, exec, s[10:11]
	v_readlane_b32 s4, v255, 10
	v_readlane_b32 s5, v255, 11
	s_add_u32 s4, s4, 0x0
	s_addc_u32 s5, s5, 0
	s_nop 1
	global_load_dword v164, v133, s[4:5]
	global_load_dword v165, v133, s[4:5] offset:64
	global_load_dword v166, v133, s[4:5] offset:128
	global_load_dword v167, v133, s[4:5] offset:192
	v_readlane_b32 s4, v255, 12
	v_readlane_b32 s5, v255, 13
	s_add_u32 s4, s4, 0x0
	s_addc_u32 s5, s5, 0
	s_nop 1
	global_load_dword v168, v133, s[4:5]
	global_load_dword v169, v133, s[4:5] offset:64
	global_load_dword v170, v133, s[4:5] offset:128
	global_load_dword v171, v133, s[4:5] offset:192
	v_readlane_b32 s4, v255, 8
	s_add_i32 s4, s4, 2
	s_and_b32 s4, s4, 3
	s_lshl_b32 s4, s4, 24
	s_add_u32 s4, s4, 0x25000000
	s_add_u32 s4, s38, s4
	s_addc_u32 s5, s39, 0
	s_nop 1
	v_mov_b32_e32 v130, v138
	global_load_dword v140, v130, s[86:87] offset:-4096
	global_load_dword v141, v130, s[86:87] offset:-4032
	global_load_dword v142, v130, s[86:87] offset:-3968
	global_load_dword v143, v130, s[86:87] offset:-3904
	global_load_dword v144, v130, s[86:87]
	global_load_dword v145, v130, s[86:87] offset:64
	global_load_dword v146, v130, s[86:87] offset:128
	global_load_dword v147, v130, s[86:87] offset:192
	global_load_dwordx4 v[156:159], v132, s[4:5]
	v_add_u32_e32 v131, 0x2000, v138
	global_load_dword v148, v131, s[86:87] offset:-4096
	global_load_dword v149, v131, s[86:87] offset:-4032
	global_load_dword v150, v131, s[86:87] offset:-3968
	global_load_dword v151, v131, s[86:87] offset:-3904
	global_load_dword v152, v131, s[86:87]
	global_load_dword v153, v131, s[86:87] offset:64
	global_load_dword v154, v131, s[86:87] offset:128
	global_load_dword v155, v131, s[86:87] offset:192
	global_load_dwordx4 v[160:163], v132, s[4:5] offset:16
	s_waitcnt vmcnt(9)
	v_sub_f32_e32 v140, v140, v156
	v_mul_f32_e32 v140, v140, v157
	v_fma_f32 v140, v164, v140, v168
	v_mul_f32_e32 v140, v212, v140
	v_fmac_f32_e32 v140, v181, v126
	global_store_dword v130, v140, s[86:87] offset:-4096
	v_sub_f32_e32 v141, v141, v156
	v_mul_f32_e32 v141, v141, v157
	v_fma_f32 v141, v165, v141, v169
	v_mul_f32_e32 v141, v212, v141
	v_fmac_f32_e32 v141, v181, v122
	global_store_dword v130, v141, s[86:87] offset:-4032
	v_sub_f32_e32 v142, v142, v156
	v_mul_f32_e32 v142, v142, v157
	v_fma_f32 v142, v166, v142, v170
	v_mul_f32_e32 v142, v212, v142
	v_fmac_f32_e32 v142, v181, v118
	global_store_dword v130, v142, s[86:87] offset:-3968
	v_sub_f32_e32 v143, v143, v156
	v_mul_f32_e32 v143, v143, v157
	v_fma_f32 v143, v167, v143, v171
	v_mul_f32_e32 v143, v212, v143
	v_fmac_f32_e32 v143, v181, v114
	global_store_dword v130, v143, s[86:87] offset:-3904
	v_sub_f32_e32 v144, v144, v158
	v_mul_f32_e32 v144, v144, v159
	v_fma_f32 v144, v164, v144, v168
	v_mul_f32_e32 v144, v212, v144
	v_fmac_f32_e32 v144, v181, v127
	global_store_dword v130, v144, s[86:87]
	v_sub_f32_e32 v145, v145, v158
	v_mul_f32_e32 v145, v145, v159
	v_fma_f32 v145, v165, v145, v169
	v_mul_f32_e32 v145, v212, v145
	v_fmac_f32_e32 v145, v181, v123
	global_store_dword v130, v145, s[86:87] offset:64
	v_sub_f32_e32 v146, v146, v158
	v_mul_f32_e32 v146, v146, v159
	v_fma_f32 v146, v166, v146, v170
	v_mul_f32_e32 v146, v212, v146
	v_fmac_f32_e32 v146, v181, v119
	global_store_dword v130, v146, s[86:87] offset:128
	v_sub_f32_e32 v147, v147, v158
	v_mul_f32_e32 v147, v147, v159
	v_fma_f32 v147, v167, v147, v171
	v_mul_f32_e32 v147, v212, v147
	v_fmac_f32_e32 v147, v181, v115
	global_store_dword v130, v147, s[86:87] offset:192
	v_add_u32_e32 v130, 0x10000, v138
	global_load_dword v140, v130, s[86:87] offset:-4096
	global_load_dword v141, v130, s[86:87] offset:-4032
	global_load_dword v142, v130, s[86:87] offset:-3968
	global_load_dword v143, v130, s[86:87] offset:-3904
	global_load_dword v144, v130, s[86:87]
	global_load_dword v145, v130, s[86:87] offset:64
	global_load_dword v146, v130, s[86:87] offset:128
	global_load_dword v147, v130, s[86:87] offset:192
	global_load_dwordx4 v[156:159], v132, s[4:5] offset:128
	s_waitcnt vmcnt(17)
	v_sub_f32_e32 v148, v148, v160
	v_mul_f32_e32 v148, v148, v161
	v_fma_f32 v148, v164, v148, v168
	v_mul_f32_e32 v148, v212, v148
	v_fmac_f32_e32 v148, v181, v128
	global_store_dword v131, v148, s[86:87] offset:-4096
	v_sub_f32_e32 v149, v149, v160
	v_mul_f32_e32 v149, v149, v161
	v_fma_f32 v149, v165, v149, v169
	v_mul_f32_e32 v149, v212, v149
	v_fmac_f32_e32 v149, v181, v124
	global_store_dword v131, v149, s[86:87] offset:-4032
	v_sub_f32_e32 v150, v150, v160
	v_mul_f32_e32 v150, v150, v161
	v_fma_f32 v150, v166, v150, v170
	v_mul_f32_e32 v150, v212, v150
	v_fmac_f32_e32 v150, v181, v120
	global_store_dword v131, v150, s[86:87] offset:-3968
	v_sub_f32_e32 v151, v151, v160
	v_mul_f32_e32 v151, v151, v161
	v_fma_f32 v151, v167, v151, v171
	v_mul_f32_e32 v151, v212, v151
	v_fmac_f32_e32 v151, v181, v116
	global_store_dword v131, v151, s[86:87] offset:-3904
	v_sub_f32_e32 v152, v152, v162
	v_mul_f32_e32 v152, v152, v163
	v_fma_f32 v152, v164, v152, v168
	v_mul_f32_e32 v152, v212, v152
	v_fmac_f32_e32 v152, v181, v129
	global_store_dword v131, v152, s[86:87]
	v_sub_f32_e32 v153, v153, v162
	v_mul_f32_e32 v153, v153, v163
	v_fma_f32 v153, v165, v153, v169
	v_mul_f32_e32 v153, v212, v153
	v_fmac_f32_e32 v153, v181, v125
	global_store_dword v131, v153, s[86:87] offset:64
	v_sub_f32_e32 v154, v154, v162
	v_mul_f32_e32 v154, v154, v163
	v_fma_f32 v154, v166, v154, v170
	v_mul_f32_e32 v154, v212, v154
	v_fmac_f32_e32 v154, v181, v121
	global_store_dword v131, v154, s[86:87] offset:128
	v_sub_f32_e32 v155, v155, v162
	v_mul_f32_e32 v155, v155, v163
	v_fma_f32 v155, v167, v155, v171
	v_mul_f32_e32 v155, v212, v155
	v_fmac_f32_e32 v155, v181, v117
	global_store_dword v131, v155, s[86:87] offset:192
	v_add_u32_e32 v131, 0x12000, v138
	global_load_dword v148, v131, s[86:87] offset:-4096
	global_load_dword v149, v131, s[86:87] offset:-4032
	global_load_dword v150, v131, s[86:87] offset:-3968
	global_load_dword v151, v131, s[86:87] offset:-3904
	global_load_dword v152, v131, s[86:87]
	global_load_dword v153, v131, s[86:87] offset:64
	global_load_dword v154, v131, s[86:87] offset:128
	global_load_dword v155, v131, s[86:87] offset:192
	global_load_dwordx4 v[160:163], v132, s[4:5] offset:144
	s_waitcnt vmcnt(17)
;     ...
; #pragma unroll
;     for (int ms = 0; ms < 8; ++ms) {
;       asm volatile("" ::: "memory");
; #pragma unroll
;       for (int ns = 0; ns < 4; ++ns)
; #pragma unroll
;         for (int j = 0; j < 4; ++j) {
;           int row = m0 + wm * 128 + ms * 16 + quad * 4 + j;
;           int col = n0 + wn * 64 + ns * 16 + l15;
;           const size_t xi = (size_t)row * D + col;
;           const float xv = xin ? xin[xi] : P.out[xi];
;           P.out[xi] = alpha * xv + sc * acc[ms][ns][j];
;         }
	v_sub_f32_e32 v140, v140, v156
	v_mul_f32_e32 v140, v140, v157
	v_fma_f32 v140, v164, v140, v168
	v_mul_f32_e32 v140, v212, v140
	v_fmac_f32_e32 v140, v181, v110
	global_store_dword v130, v140, s[86:87] offset:-4096
	v_sub_f32_e32 v141, v141, v156
	v_mul_f32_e32 v141, v141, v157
	v_fma_f32 v141, v165, v141, v169
	v_mul_f32_e32 v141, v212, v141
	v_fmac_f32_e32 v141, v181, v106
	global_store_dword v130, v141, s[86:87] offset:-4032
	v_sub_f32_e32 v142, v142, v156
	v_mul_f32_e32 v142, v142, v157
	v_fma_f32 v142, v166, v142, v170
	v_mul_f32_e32 v142, v212, v142
	v_fmac_f32_e32 v142, v181, v102
	global_store_dword v130, v142, s[86:87] offset:-3968
	v_sub_f32_e32 v143, v143, v156
	v_mul_f32_e32 v143, v143, v157
	v_fma_f32 v143, v167, v143, v171
	v_mul_f32_e32 v143, v212, v143
	v_fmac_f32_e32 v143, v181, v98
	global_store_dword v130, v143, s[86:87] offset:-3904
	v_sub_f32_e32 v144, v144, v158
	v_mul_f32_e32 v144, v144, v159
	v_fma_f32 v144, v164, v144, v168
	v_mul_f32_e32 v144, v212, v144
	v_fmac_f32_e32 v144, v181, v111
	global_store_dword v130, v144, s[86:87]
	v_sub_f32_e32 v145, v145, v158
	v_mul_f32_e32 v145, v145, v159
	v_fma_f32 v145, v165, v145, v169
	v_mul_f32_e32 v145, v212, v145
	v_fmac_f32_e32 v145, v181, v107
	global_store_dword v130, v145, s[86:87] offset:64
	v_sub_f32_e32 v146, v146, v158
	v_mul_f32_e32 v146, v146, v159
	v_fma_f32 v146, v166, v146, v170
	v_mul_f32_e32 v146, v212, v146
	v_fmac_f32_e32 v146, v181, v103
	global_store_dword v130, v146, s[86:87] offset:128
	v_sub_f32_e32 v147, v147, v158
	v_mul_f32_e32 v147, v147, v159
	v_fma_f32 v147, v167, v147, v171
	v_mul_f32_e32 v147, v212, v147
	v_fmac_f32_e32 v147, v181, v99
	global_store_dword v130, v147, s[86:87] offset:192
	v_add_u32_e32 v130, 0x20000, v138
	global_load_dword v140, v130, s[86:87] offset:-4096
	global_load_dword v141, v130, s[86:87] offset:-4032
	global_load_dword v142, v130, s[86:87] offset:-3968
	global_load_dword v143, v130, s[86:87] offset:-3904
	global_load_dword v144, v130, s[86:87]
	global_load_dword v145, v130, s[86:87] offset:64
	global_load_dword v146, v130, s[86:87] offset:128
	global_load_dword v147, v130, s[86:87] offset:192
	global_load_dwordx4 v[156:159], v132, s[4:5] offset:256
	s_waitcnt vmcnt(17)
	v_sub_f32_e32 v148, v148, v160
	v_mul_f32_e32 v148, v148, v161
	v_fma_f32 v148, v164, v148, v168
	v_mul_f32_e32 v148, v212, v148
	v_fmac_f32_e32 v148, v181, v112
	global_store_dword v131, v148, s[86:87] offset:-4096
	v_sub_f32_e32 v149, v149, v160
	v_mul_f32_e32 v149, v149, v161
	v_fma_f32 v149, v165, v149, v169
	v_mul_f32_e32 v149, v212, v149
	v_fmac_f32_e32 v149, v181, v108
	global_store_dword v131, v149, s[86:87] offset:-4032
	v_sub_f32_e32 v150, v150, v160
	v_mul_f32_e32 v150, v150, v161
	v_fma_f32 v150, v166, v150, v170
	v_mul_f32_e32 v150, v212, v150
	v_fmac_f32_e32 v150, v181, v104
	global_store_dword v131, v150, s[86:87] offset:-3968
	v_sub_f32_e32 v151, v151, v160
	v_mul_f32_e32 v151, v151, v161
	v_fma_f32 v151, v167, v151, v171
	v_mul_f32_e32 v151, v212, v151
	v_fmac_f32_e32 v151, v181, v100
	global_store_dword v131, v151, s[86:87] offset:-3904
	v_sub_f32_e32 v152, v152, v162
	v_mul_f32_e32 v152, v152, v163
	v_fma_f32 v152, v164, v152, v168
	v_mul_f32_e32 v152, v212, v152
	v_fmac_f32_e32 v152, v181, v113
	global_store_dword v131, v152, s[86:87]
	v_sub_f32_e32 v153, v153, v162
	v_mul_f32_e32 v153, v153, v163
	v_fma_f32 v153, v165, v153, v169
	v_mul_f32_e32 v153, v212, v153
	v_fmac_f32_e32 v153, v181, v109
	global_store_dword v131, v153, s[86:87] offset:64
	v_sub_f32_e32 v154, v154, v162
	v_mul_f32_e32 v154, v154, v163
	v_fma_f32 v154, v166, v154, v170
	v_mul_f32_e32 v154, v212, v154
	v_fmac_f32_e32 v154, v181, v105
	global_store_dword v131, v154, s[86:87] offset:128
	v_sub_f32_e32 v155, v155, v162
	v_mul_f32_e32 v155, v155, v163
	v_fma_f32 v155, v167, v155, v171
	v_mul_f32_e32 v155, v212, v155
	v_fmac_f32_e32 v155, v181, v101
	global_store_dword v131, v155, s[86:87] offset:192
	v_add_u32_e32 v131, 0x22000, v138
	global_load_dword v148, v131, s[86:87] offset:-4096
	global_load_dword v149, v131, s[86:87] offset:-4032
	global_load_dword v150, v131, s[86:87] offset:-3968
	global_load_dword v151, v131, s[86:87] offset:-3904
	global_load_dword v152, v131, s[86:87]
	global_load_dword v153, v131, s[86:87] offset:64
	global_load_dword v154, v131, s[86:87] offset:128
	global_load_dword v155, v131, s[86:87] offset:192
	global_load_dwordx4 v[160:163], v132, s[4:5] offset:272
	s_waitcnt vmcnt(17)
	v_sub_f32_e32 v140, v140, v156
	v_mul_f32_e32 v140, v140, v157
	v_fma_f32 v140, v164, v140, v168
	v_mul_f32_e32 v140, v212, v140
	v_fmac_f32_e32 v140, v181, v94
	global_store_dword v130, v140, s[86:87] offset:-4096
	v_sub_f32_e32 v141, v141, v156
	v_mul_f32_e32 v141, v141, v157
	v_fma_f32 v141, v165, v141, v169
	v_mul_f32_e32 v141, v212, v141
	v_fmac_f32_e32 v141, v181, v90
	global_store_dword v130, v141, s[86:87] offset:-4032
	v_sub_f32_e32 v142, v142, v156
	v_mul_f32_e32 v142, v142, v157
	v_fma_f32 v142, v166, v142, v170
	v_mul_f32_e32 v142, v212, v142
	v_fmac_f32_e32 v142, v181, v86
	global_store_dword v130, v142, s[86:87] offset:-3968
	v_sub_f32_e32 v143, v143, v156
	v_mul_f32_e32 v143, v143, v157
	v_fma_f32 v143, v167, v143, v171
	v_mul_f32_e32 v143, v212, v143
	v_fmac_f32_e32 v143, v181, v82
	global_store_dword v130, v143, s[86:87] offset:-3904
	v_sub_f32_e32 v144, v144, v158
	v_mul_f32_e32 v144, v144, v159
	v_fma_f32 v144, v164, v144, v168
	v_mul_f32_e32 v144, v212, v144
	v_fmac_f32_e32 v144, v181, v95
	global_store_dword v130, v144, s[86:87]
	v_sub_f32_e32 v145, v145, v158
	v_mul_f32_e32 v145, v145, v159
	v_fma_f32 v145, v165, v145, v169
	v_mul_f32_e32 v145, v212, v145
	v_fmac_f32_e32 v145, v181, v91
	global_store_dword v130, v145, s[86:87] offset:64
	v_sub_f32_e32 v146, v146, v158
	v_mul_f32_e32 v146, v146, v159
	v_fma_f32 v146, v166, v146, v170
	v_mul_f32_e32 v146, v212, v146
	v_fmac_f32_e32 v146, v181, v87
	global_store_dword v130, v146, s[86:87] offset:128
	v_sub_f32_e32 v147, v147, v158
	v_mul_f32_e32 v147, v147, v159
	v_fma_f32 v147, v167, v147, v171
	v_mul_f32_e32 v147, v212, v147
	v_fmac_f32_e32 v147, v181, v83
	global_store_dword v130, v147, s[86:87] offset:192
	v_add_u32_e32 v130, 0x30000, v138
	global_load_dword v140, v130, s[86:87] offset:-4096
	global_load_dword v141, v130, s[86:87] offset:-4032
	global_load_dword v142, v130, s[86:87] offset:-3968
	global_load_dword v143, v130, s[86:87] offset:-3904
	global_load_dword v144, v130, s[86:87]
	global_load_dword v145, v130, s[86:87] offset:64
	global_load_dword v146, v130, s[86:87] offset:128
	global_load_dword v147, v130, s[86:87] offset:192
	global_load_dwordx4 v[156:159], v132, s[4:5] offset:384
	s_waitcnt vmcnt(17)
;     ...
; #pragma unroll
;     for (int ms = 0; ms < 8; ++ms) {
;       asm volatile("" ::: "memory");
; #pragma unroll
;       for (int ns = 0; ns < 4; ++ns)
; #pragma unroll
;         for (int j = 0; j < 4; ++j) {
;           int row = m0 + wm * 128 + ms * 16 + quad * 4 + j;
;           int col = n0 + wn * 64 + ns * 16 + l15;
;           const size_t xi = (size_t)row * D + col;
;           const float xv = xin ? xin[xi] : P.out[xi];
;           P.out[xi] = alpha * xv + sc * acc[ms][ns][j];
;         }
	v_sub_f32_e32 v148, v148, v160
	v_mul_f32_e32 v148, v148, v161
	v_fma_f32 v148, v164, v148, v168
	v_mul_f32_e32 v148, v212, v148
	v_fmac_f32_e32 v148, v181, v96
	global_store_dword v131, v148, s[86:87] offset:-4096
	v_sub_f32_e32 v149, v149, v160
	v_mul_f32_e32 v149, v149, v161
	v_fma_f32 v149, v165, v149, v169
	v_mul_f32_e32 v149, v212, v149
	v_fmac_f32_e32 v149, v181, v92
	global_store_dword v131, v149, s[86:87] offset:-4032
	v_sub_f32_e32 v150, v150, v160
	v_mul_f32_e32 v150, v150, v161
	v_fma_f32 v150, v166, v150, v170
	v_mul_f32_e32 v150, v212, v150
	v_fmac_f32_e32 v150, v181, v88
	global_store_dword v131, v150, s[86:87] offset:-3968
	v_sub_f32_e32 v151, v151, v160
	v_mul_f32_e32 v151, v151, v161
	v_fma_f32 v151, v167, v151, v171
	v_mul_f32_e32 v151, v212, v151
	v_fmac_f32_e32 v151, v181, v84
	global_store_dword v131, v151, s[86:87] offset:-3904
	v_sub_f32_e32 v152, v152, v162
	v_mul_f32_e32 v152, v152, v163
	v_fma_f32 v152, v164, v152, v168
	v_mul_f32_e32 v152, v212, v152
	v_fmac_f32_e32 v152, v181, v97
	global_store_dword v131, v152, s[86:87]
	v_sub_f32_e32 v153, v153, v162
	v_mul_f32_e32 v153, v153, v163
	v_fma_f32 v153, v165, v153, v169
	v_mul_f32_e32 v153, v212, v153
	v_fmac_f32_e32 v153, v181, v93
	global_store_dword v131, v153, s[86:87] offset:64
	v_sub_f32_e32 v154, v154, v162
	v_mul_f32_e32 v154, v154, v163
	v_fma_f32 v154, v166, v154, v170
	v_mul_f32_e32 v154, v212, v154
	v_fmac_f32_e32 v154, v181, v89
	global_store_dword v131, v154, s[86:87] offset:128
	v_sub_f32_e32 v155, v155, v162
	v_mul_f32_e32 v155, v155, v163
	v_fma_f32 v155, v167, v155, v171
	v_mul_f32_e32 v155, v212, v155
	v_fmac_f32_e32 v155, v181, v85
	global_store_dword v131, v155, s[86:87] offset:192
	v_add_u32_e32 v131, 0x32000, v138
	global_load_dword v148, v131, s[86:87] offset:-4096
	global_load_dword v149, v131, s[86:87] offset:-4032
	global_load_dword v150, v131, s[86:87] offset:-3968
	global_load_dword v151, v131, s[86:87] offset:-3904
	global_load_dword v152, v131, s[86:87]
	global_load_dword v153, v131, s[86:87] offset:64
	global_load_dword v154, v131, s[86:87] offset:128
	global_load_dword v155, v131, s[86:87] offset:192
	global_load_dwordx4 v[160:163], v132, s[4:5] offset:400
	s_waitcnt vmcnt(17)
	v_sub_f32_e32 v140, v140, v156
	v_mul_f32_e32 v140, v140, v157
	v_fma_f32 v140, v164, v140, v168
	v_mul_f32_e32 v140, v212, v140
	v_fmac_f32_e32 v140, v181, v78
	global_store_dword v130, v140, s[86:87] offset:-4096
	v_sub_f32_e32 v141, v141, v156
	v_mul_f32_e32 v141, v141, v157
	v_fma_f32 v141, v165, v141, v169
	v_mul_f32_e32 v141, v212, v141
	v_fmac_f32_e32 v141, v181, v74
	global_store_dword v130, v141, s[86:87] offset:-4032
	v_sub_f32_e32 v142, v142, v156
	v_mul_f32_e32 v142, v142, v157
	v_fma_f32 v142, v166, v142, v170
	v_mul_f32_e32 v142, v212, v142
	v_fmac_f32_e32 v142, v181, v70
	global_store_dword v130, v142, s[86:87] offset:-3968
	v_sub_f32_e32 v143, v143, v156
	v_mul_f32_e32 v143, v143, v157
	v_fma_f32 v143, v167, v143, v171
	v_mul_f32_e32 v143, v212, v143
	v_fmac_f32_e32 v143, v181, v66
	global_store_dword v130, v143, s[86:87] offset:-3904
	v_sub_f32_e32 v144, v144, v158
	v_mul_f32_e32 v144, v144, v159
	v_fma_f32 v144, v164, v144, v168
	v_mul_f32_e32 v144, v212, v144
	v_fmac_f32_e32 v144, v181, v79
	global_store_dword v130, v144, s[86:87]
	v_sub_f32_e32 v145, v145, v158
	v_mul_f32_e32 v145, v145, v159
	v_fma_f32 v145, v165, v145, v169
	v_mul_f32_e32 v145, v212, v145
	v_fmac_f32_e32 v145, v181, v75
	global_store_dword v130, v145, s[86:87] offset:64
	v_sub_f32_e32 v146, v146, v158
	v_mul_f32_e32 v146, v146, v159
	v_fma_f32 v146, v166, v146, v170
	v_mul_f32_e32 v146, v212, v146
	v_fmac_f32_e32 v146, v181, v71
	global_store_dword v130, v146, s[86:87] offset:128
	v_sub_f32_e32 v147, v147, v158
	v_mul_f32_e32 v147, v147, v159
	v_fma_f32 v147, v167, v147, v171
	v_mul_f32_e32 v147, v212, v147
	v_fmac_f32_e32 v147, v181, v67
	global_store_dword v130, v147, s[86:87] offset:192
	v_add_u32_e32 v130, 0x40000, v138
	global_load_dword v140, v130, s[86:87] offset:-4096
	global_load_dword v141, v130, s[86:87] offset:-4032
	global_load_dword v142, v130, s[86:87] offset:-3968
	global_load_dword v143, v130, s[86:87] offset:-3904
	global_load_dword v144, v130, s[86:87]
	global_load_dword v145, v130, s[86:87] offset:64
	global_load_dword v146, v130, s[86:87] offset:128
	global_load_dword v147, v130, s[86:87] offset:192
	global_load_dwordx4 v[156:159], v132, s[4:5] offset:512
	s_waitcnt vmcnt(17)
	v_sub_f32_e32 v148, v148, v160
	v_mul_f32_e32 v148, v148, v161
	v_fma_f32 v148, v164, v148, v168
	v_mul_f32_e32 v148, v212, v148
	v_fmac_f32_e32 v148, v181, v80
	global_store_dword v131, v148, s[86:87] offset:-4096
	v_sub_f32_e32 v149, v149, v160
	v_mul_f32_e32 v149, v149, v161
	v_fma_f32 v149, v165, v149, v169
	v_mul_f32_e32 v149, v212, v149
	v_fmac_f32_e32 v149, v181, v76
	global_store_dword v131, v149, s[86:87] offset:-4032
	v_sub_f32_e32 v150, v150, v160
	v_mul_f32_e32 v150, v150, v161
	v_fma_f32 v150, v166, v150, v170
	v_mul_f32_e32 v150, v212, v150
	v_fmac_f32_e32 v150, v181, v72
	global_store_dword v131, v150, s[86:87] offset:-3968
	v_sub_f32_e32 v151, v151, v160
	v_mul_f32_e32 v151, v151, v161
	v_fma_f32 v151, v167, v151, v171
	v_mul_f32_e32 v151, v212, v151
	v_fmac_f32_e32 v151, v181, v68
	global_store_dword v131, v151, s[86:87] offset:-3904
	v_sub_f32_e32 v152, v152, v162
	v_mul_f32_e32 v152, v152, v163
	v_fma_f32 v152, v164, v152, v168
	v_mul_f32_e32 v152, v212, v152
	v_fmac_f32_e32 v152, v181, v81
	global_store_dword v131, v152, s[86:87]
	v_sub_f32_e32 v153, v153, v162
	v_mul_f32_e32 v153, v153, v163
	v_fma_f32 v153, v165, v153, v169
	v_mul_f32_e32 v153, v212, v153
	v_fmac_f32_e32 v153, v181, v77
	global_store_dword v131, v153, s[86:87] offset:64
	v_sub_f32_e32 v154, v154, v162
	v_mul_f32_e32 v154, v154, v163
	v_fma_f32 v154, v166, v154, v170
	v_mul_f32_e32 v154, v212, v154
	v_fmac_f32_e32 v154, v181, v73
	global_store_dword v131, v154, s[86:87] offset:128
	v_sub_f32_e32 v155, v155, v162
	v_mul_f32_e32 v155, v155, v163
	v_fma_f32 v155, v167, v155, v171
	v_mul_f32_e32 v155, v212, v155
	v_fmac_f32_e32 v155, v181, v69
	global_store_dword v131, v155, s[86:87] offset:192
	v_add_u32_e32 v131, 0x42000, v138
	global_load_dword v148, v131, s[86:87] offset:-4096
	global_load_dword v149, v131, s[86:87] offset:-4032
	global_load_dword v150, v131, s[86:87] offset:-3968
	global_load_dword v151, v131, s[86:87] offset:-3904
	global_load_dword v152, v131, s[86:87]
	global_load_dword v153, v131, s[86:87] offset:64
	global_load_dword v154, v131, s[86:87] offset:128
	global_load_dword v155, v131, s[86:87] offset:192
	global_load_dwordx4 v[160:163], v132, s[4:5] offset:528
	s_waitcnt vmcnt(17)
;     ...
; #pragma unroll
;     for (int ms = 0; ms < 8; ++ms) {
;       asm volatile("" ::: "memory");
; #pragma unroll
;       for (int ns = 0; ns < 4; ++ns)
; #pragma unroll
;         for (int j = 0; j < 4; ++j) {
;           int row = m0 + wm * 128 + ms * 16 + quad * 4 + j;
;           int col = n0 + wn * 64 + ns * 16 + l15;
;           const size_t xi = (size_t)row * D + col;
;           const float xv = xin ? xin[xi] : P.out[xi];
;           P.out[xi] = alpha * xv + sc * acc[ms][ns][j];
;         }
	v_sub_f32_e32 v140, v140, v156
	v_mul_f32_e32 v140, v140, v157
	v_fma_f32 v140, v164, v140, v168
	v_mul_f32_e32 v140, v212, v140
	v_fmac_f32_e32 v140, v181, v62
	global_store_dword v130, v140, s[86:87] offset:-4096
	v_sub_f32_e32 v141, v141, v156
	v_mul_f32_e32 v141, v141, v157
	v_fma_f32 v141, v165, v141, v169
	v_mul_f32_e32 v141, v212, v141
	v_fmac_f32_e32 v141, v181, v58
	global_store_dword v130, v141, s[86:87] offset:-4032
	v_sub_f32_e32 v142, v142, v156
	v_mul_f32_e32 v142, v142, v157
	v_fma_f32 v142, v166, v142, v170
	v_mul_f32_e32 v142, v212, v142
	v_fmac_f32_e32 v142, v181, v54
	global_store_dword v130, v142, s[86:87] offset:-3968
	v_sub_f32_e32 v143, v143, v156
	v_mul_f32_e32 v143, v143, v157
	v_fma_f32 v143, v167, v143, v171
	v_mul_f32_e32 v143, v212, v143
	v_fmac_f32_e32 v143, v181, v50
	global_store_dword v130, v143, s[86:87] offset:-3904
	v_sub_f32_e32 v144, v144, v158
	v_mul_f32_e32 v144, v144, v159
	v_fma_f32 v144, v164, v144, v168
	v_mul_f32_e32 v144, v212, v144
	v_fmac_f32_e32 v144, v181, v63
	global_store_dword v130, v144, s[86:87]
	v_sub_f32_e32 v145, v145, v158
	v_mul_f32_e32 v145, v145, v159
	v_fma_f32 v145, v165, v145, v169
	v_mul_f32_e32 v145, v212, v145
	v_fmac_f32_e32 v145, v181, v59
	global_store_dword v130, v145, s[86:87] offset:64
	v_sub_f32_e32 v146, v146, v158
	v_mul_f32_e32 v146, v146, v159
	v_fma_f32 v146, v166, v146, v170
	v_mul_f32_e32 v146, v212, v146
	v_fmac_f32_e32 v146, v181, v55
	global_store_dword v130, v146, s[86:87] offset:128
	v_sub_f32_e32 v147, v147, v158
	v_mul_f32_e32 v147, v147, v159
	v_fma_f32 v147, v167, v147, v171
	v_mul_f32_e32 v147, v212, v147
	v_fmac_f32_e32 v147, v181, v51
	global_store_dword v130, v147, s[86:87] offset:192
	v_add_u32_e32 v130, 0x50000, v138
	global_load_dword v140, v130, s[86:87] offset:-4096
	global_load_dword v141, v130, s[86:87] offset:-4032
	global_load_dword v142, v130, s[86:87] offset:-3968
	global_load_dword v143, v130, s[86:87] offset:-3904
	global_load_dword v144, v130, s[86:87]
	global_load_dword v145, v130, s[86:87] offset:64
	global_load_dword v146, v130, s[86:87] offset:128
	global_load_dword v147, v130, s[86:87] offset:192
	global_load_dwordx4 v[156:159], v132, s[4:5] offset:640
	s_waitcnt vmcnt(17)
	v_sub_f32_e32 v148, v148, v160
	v_mul_f32_e32 v148, v148, v161
	v_fma_f32 v148, v164, v148, v168
	v_mul_f32_e32 v148, v212, v148
	v_fmac_f32_e32 v148, v181, v64
	global_store_dword v131, v148, s[86:87] offset:-4096
	v_sub_f32_e32 v149, v149, v160
	v_mul_f32_e32 v149, v149, v161
	v_fma_f32 v149, v165, v149, v169
	v_mul_f32_e32 v149, v212, v149
	v_fmac_f32_e32 v149, v181, v60
	global_store_dword v131, v149, s[86:87] offset:-4032
	v_sub_f32_e32 v150, v150, v160
	v_mul_f32_e32 v150, v150, v161
	v_fma_f32 v150, v166, v150, v170
	v_mul_f32_e32 v150, v212, v150
	v_fmac_f32_e32 v150, v181, v56
	global_store_dword v131, v150, s[86:87] offset:-3968
	v_sub_f32_e32 v151, v151, v160
	v_mul_f32_e32 v151, v151, v161
	v_fma_f32 v151, v167, v151, v171
	v_mul_f32_e32 v151, v212, v151
	v_fmac_f32_e32 v151, v181, v52
	global_store_dword v131, v151, s[86:87] offset:-3904
	v_sub_f32_e32 v152, v152, v162
	v_mul_f32_e32 v152, v152, v163
	v_fma_f32 v152, v164, v152, v168
	v_mul_f32_e32 v152, v212, v152
	v_fmac_f32_e32 v152, v181, v65
	global_store_dword v131, v152, s[86:87]
	v_sub_f32_e32 v153, v153, v162
	v_mul_f32_e32 v153, v153, v163
	v_fma_f32 v153, v165, v153, v169
	v_mul_f32_e32 v153, v212, v153
	v_fmac_f32_e32 v153, v181, v61
	global_store_dword v131, v153, s[86:87] offset:64
	v_sub_f32_e32 v154, v154, v162
	v_mul_f32_e32 v154, v154, v163
	v_fma_f32 v154, v166, v154, v170
	v_mul_f32_e32 v154, v212, v154
	v_fmac_f32_e32 v154, v181, v57
	global_store_dword v131, v154, s[86:87] offset:128
	v_sub_f32_e32 v155, v155, v162
	v_mul_f32_e32 v155, v155, v163
	v_fma_f32 v155, v167, v155, v171
	v_mul_f32_e32 v155, v212, v155
	v_fmac_f32_e32 v155, v181, v53
	global_store_dword v131, v155, s[86:87] offset:192
	v_add_u32_e32 v131, 0x52000, v138
	global_load_dword v148, v131, s[86:87] offset:-4096
	global_load_dword v149, v131, s[86:87] offset:-4032
	global_load_dword v150, v131, s[86:87] offset:-3968
	global_load_dword v151, v131, s[86:87] offset:-3904
	global_load_dword v152, v131, s[86:87]
	global_load_dword v153, v131, s[86:87] offset:64
	global_load_dword v154, v131, s[86:87] offset:128
	global_load_dword v155, v131, s[86:87] offset:192
	global_load_dwordx4 v[160:163], v132, s[4:5] offset:656
	s_waitcnt vmcnt(17)
	v_sub_f32_e32 v140, v140, v156
	v_mul_f32_e32 v140, v140, v157
	v_fma_f32 v140, v164, v140, v168
	v_mul_f32_e32 v140, v212, v140
	v_fmac_f32_e32 v140, v181, v46
	global_store_dword v130, v140, s[86:87] offset:-4096
	v_sub_f32_e32 v141, v141, v156
	v_mul_f32_e32 v141, v141, v157
	v_fma_f32 v141, v165, v141, v169
	v_mul_f32_e32 v141, v212, v141
	v_fmac_f32_e32 v141, v181, v42
	global_store_dword v130, v141, s[86:87] offset:-4032
	v_sub_f32_e32 v142, v142, v156
	v_mul_f32_e32 v142, v142, v157
	v_fma_f32 v142, v166, v142, v170
	v_mul_f32_e32 v142, v212, v142
	v_fmac_f32_e32 v142, v181, v38
	global_store_dword v130, v142, s[86:87] offset:-3968
	v_sub_f32_e32 v143, v143, v156
	v_mul_f32_e32 v143, v143, v157
	v_fma_f32 v143, v167, v143, v171
	v_mul_f32_e32 v143, v212, v143
	v_fmac_f32_e32 v143, v181, v34
	global_store_dword v130, v143, s[86:87] offset:-3904
	v_sub_f32_e32 v144, v144, v158
	v_mul_f32_e32 v144, v144, v159
	v_fma_f32 v144, v164, v144, v168
	v_mul_f32_e32 v144, v212, v144
	v_fmac_f32_e32 v144, v181, v47
	global_store_dword v130, v144, s[86:87]
	v_sub_f32_e32 v145, v145, v158
	v_mul_f32_e32 v145, v145, v159
	v_fma_f32 v145, v165, v145, v169
	v_mul_f32_e32 v145, v212, v145
	v_fmac_f32_e32 v145, v181, v43
	global_store_dword v130, v145, s[86:87] offset:64
	v_sub_f32_e32 v146, v146, v158
	v_mul_f32_e32 v146, v146, v159
	v_fma_f32 v146, v166, v146, v170
	v_mul_f32_e32 v146, v212, v146
	v_fmac_f32_e32 v146, v181, v39
	global_store_dword v130, v146, s[86:87] offset:128
	v_sub_f32_e32 v147, v147, v158
	v_mul_f32_e32 v147, v147, v159
	v_fma_f32 v147, v167, v147, v171
	v_mul_f32_e32 v147, v212, v147
	v_fmac_f32_e32 v147, v181, v35
	global_store_dword v130, v147, s[86:87] offset:192
	v_add_u32_e32 v130, 0x60000, v138
	global_load_dword v140, v130, s[86:87] offset:-4096
	global_load_dword v141, v130, s[86:87] offset:-4032
	global_load_dword v142, v130, s[86:87] offset:-3968
	global_load_dword v143, v130, s[86:87] offset:-3904
	global_load_dword v144, v130, s[86:87]
	global_load_dword v145, v130, s[86:87] offset:64
	global_load_dword v146, v130, s[86:87] offset:128
	global_load_dword v147, v130, s[86:87] offset:192
	global_load_dwordx4 v[156:159], v132, s[4:5] offset:768
	s_waitcnt vmcnt(17)
;     ...
; #pragma unroll
;     for (int ms = 0; ms < 8; ++ms) {
;       asm volatile("" ::: "memory");
; #pragma unroll
;       for (int ns = 0; ns < 4; ++ns)
; #pragma unroll
;         for (int j = 0; j < 4; ++j) {
;           int row = m0 + wm * 128 + ms * 16 + quad * 4 + j;
;           int col = n0 + wn * 64 + ns * 16 + l15;
;           const size_t xi = (size_t)row * D + col;
;           const float xv = xin ? xin[xi] : P.out[xi];
;           P.out[xi] = alpha * xv + sc * acc[ms][ns][j];
;         }
	v_sub_f32_e32 v148, v148, v160
	v_mul_f32_e32 v148, v148, v161
	v_fma_f32 v148, v164, v148, v168
	v_mul_f32_e32 v148, v212, v148
	v_fmac_f32_e32 v148, v181, v48
	global_store_dword v131, v148, s[86:87] offset:-4096
	v_sub_f32_e32 v149, v149, v160
	v_mul_f32_e32 v149, v149, v161
	v_fma_f32 v149, v165, v149, v169
	v_mul_f32_e32 v149, v212, v149
	v_fmac_f32_e32 v149, v181, v44
	global_store_dword v131, v149, s[86:87] offset:-4032
	v_sub_f32_e32 v150, v150, v160
	v_mul_f32_e32 v150, v150, v161
	v_fma_f32 v150, v166, v150, v170
	v_mul_f32_e32 v150, v212, v150
	v_fmac_f32_e32 v150, v181, v40
	global_store_dword v131, v150, s[86:87] offset:-3968
	v_sub_f32_e32 v151, v151, v160
	v_mul_f32_e32 v151, v151, v161
	v_fma_f32 v151, v167, v151, v171
	v_mul_f32_e32 v151, v212, v151
	v_fmac_f32_e32 v151, v181, v36
	global_store_dword v131, v151, s[86:87] offset:-3904
	v_sub_f32_e32 v152, v152, v162
	v_mul_f32_e32 v152, v152, v163
	v_fma_f32 v152, v164, v152, v168
	v_mul_f32_e32 v152, v212, v152
	v_fmac_f32_e32 v152, v181, v49
	global_store_dword v131, v152, s[86:87]
	v_sub_f32_e32 v153, v153, v162
	v_mul_f32_e32 v153, v153, v163
	v_fma_f32 v153, v165, v153, v169
	v_mul_f32_e32 v153, v212, v153
	v_fmac_f32_e32 v153, v181, v45
	global_store_dword v131, v153, s[86:87] offset:64
	v_sub_f32_e32 v154, v154, v162
	v_mul_f32_e32 v154, v154, v163
	v_fma_f32 v154, v166, v154, v170
	v_mul_f32_e32 v154, v212, v154
	v_fmac_f32_e32 v154, v181, v41
	global_store_dword v131, v154, s[86:87] offset:128
	v_sub_f32_e32 v155, v155, v162
	v_mul_f32_e32 v155, v155, v163
	v_fma_f32 v155, v167, v155, v171
	v_mul_f32_e32 v155, v212, v155
	v_fmac_f32_e32 v155, v181, v37
	global_store_dword v131, v155, s[86:87] offset:192
	v_add_u32_e32 v131, 0x62000, v138
	global_load_dword v148, v131, s[86:87] offset:-4096
	global_load_dword v149, v131, s[86:87] offset:-4032
	global_load_dword v150, v131, s[86:87] offset:-3968
	global_load_dword v151, v131, s[86:87] offset:-3904
	global_load_dword v152, v131, s[86:87]
	global_load_dword v153, v131, s[86:87] offset:64
	global_load_dword v154, v131, s[86:87] offset:128
	global_load_dword v155, v131, s[86:87] offset:192
	global_load_dwordx4 v[160:163], v132, s[4:5] offset:784
	s_waitcnt vmcnt(17)
	v_sub_f32_e32 v140, v140, v156
	v_mul_f32_e32 v140, v140, v157
	v_fma_f32 v140, v164, v140, v168
	v_mul_f32_e32 v140, v212, v140
	v_fmac_f32_e32 v140, v181, v30
	global_store_dword v130, v140, s[86:87] offset:-4096
	v_sub_f32_e32 v141, v141, v156
	v_mul_f32_e32 v141, v141, v157
	v_fma_f32 v141, v165, v141, v169
	v_mul_f32_e32 v141, v212, v141
	v_fmac_f32_e32 v141, v181, v26
	global_store_dword v130, v141, s[86:87] offset:-4032
	v_sub_f32_e32 v142, v142, v156
	v_mul_f32_e32 v142, v142, v157
	v_fma_f32 v142, v166, v142, v170
	v_mul_f32_e32 v142, v212, v142
	v_fmac_f32_e32 v142, v181, v22
	global_store_dword v130, v142, s[86:87] offset:-3968
	v_sub_f32_e32 v143, v143, v156
	v_mul_f32_e32 v143, v143, v157
	v_fma_f32 v143, v167, v143, v171
	v_mul_f32_e32 v143, v212, v143
	v_fmac_f32_e32 v143, v181, v18
	global_store_dword v130, v143, s[86:87] offset:-3904
	v_sub_f32_e32 v144, v144, v158
	v_mul_f32_e32 v144, v144, v159
	v_fma_f32 v144, v164, v144, v168
	v_mul_f32_e32 v144, v212, v144
	v_fmac_f32_e32 v144, v181, v31
	global_store_dword v130, v144, s[86:87]
	v_sub_f32_e32 v145, v145, v158
	v_mul_f32_e32 v145, v145, v159
	v_fma_f32 v145, v165, v145, v169
	v_mul_f32_e32 v145, v212, v145
	v_fmac_f32_e32 v145, v181, v27
	global_store_dword v130, v145, s[86:87] offset:64
	v_sub_f32_e32 v146, v146, v158
	v_mul_f32_e32 v146, v146, v159
	v_fma_f32 v146, v166, v146, v170
	v_mul_f32_e32 v146, v212, v146
	v_fmac_f32_e32 v146, v181, v23
	global_store_dword v130, v146, s[86:87] offset:128
	v_sub_f32_e32 v147, v147, v158
	v_mul_f32_e32 v147, v147, v159
	v_fma_f32 v147, v167, v147, v171
	v_mul_f32_e32 v147, v212, v147
	v_fmac_f32_e32 v147, v181, v19
	global_store_dword v130, v147, s[86:87] offset:192
	v_add_u32_e32 v130, 0x70000, v138
	global_load_dword v140, v130, s[86:87] offset:-4096
	global_load_dword v141, v130, s[86:87] offset:-4032
	global_load_dword v142, v130, s[86:87] offset:-3968
	global_load_dword v143, v130, s[86:87] offset:-3904
	global_load_dword v144, v130, s[86:87]
	global_load_dword v145, v130, s[86:87] offset:64
	global_load_dword v146, v130, s[86:87] offset:128
	global_load_dword v147, v130, s[86:87] offset:192
	global_load_dwordx4 v[156:159], v132, s[4:5] offset:896
	s_waitcnt vmcnt(17)
;     ...
; #pragma unroll
;     for (int ms = 0; ms < 8; ++ms) {
;       asm volatile("" ::: "memory");
; #pragma unroll
;       for (int ns = 0; ns < 4; ++ns)
; #pragma unroll
;         for (int j = 0; j < 4; ++j) {
;           int row = m0 + wm * 128 + ms * 16 + quad * 4 + j;
;           int col = n0 + wn * 64 + ns * 16 + l15;
;           const size_t xi = (size_t)row * D + col;
;           const float xv = xin ? xin[xi] : P.out[xi];
;           P.out[xi] = alpha * xv + sc * acc[ms][ns][j];
;         }
	v_sub_f32_e32 v148, v148, v160
	v_mul_f32_e32 v148, v148, v161
	v_fma_f32 v148, v164, v148, v168
	v_mul_f32_e32 v148, v212, v148
	v_fmac_f32_e32 v148, v181, v32
	global_store_dword v131, v148, s[86:87] offset:-4096
	v_sub_f32_e32 v149, v149, v160
	v_mul_f32_e32 v149, v149, v161
	v_fma_f32 v149, v165, v149, v169
	v_mul_f32_e32 v149, v212, v149
	v_fmac_f32_e32 v149, v181, v28
	global_store_dword v131, v149, s[86:87] offset:-4032
	v_sub_f32_e32 v150, v150, v160
	v_mul_f32_e32 v150, v150, v161
	v_fma_f32 v150, v166, v150, v170
	v_mul_f32_e32 v150, v212, v150
	v_fmac_f32_e32 v150, v181, v24
	global_store_dword v131, v150, s[86:87] offset:-3968
	v_sub_f32_e32 v151, v151, v160
	v_mul_f32_e32 v151, v151, v161
	v_fma_f32 v151, v167, v151, v171
	v_mul_f32_e32 v151, v212, v151
	v_fmac_f32_e32 v151, v181, v20
	global_store_dword v131, v151, s[86:87] offset:-3904
	v_sub_f32_e32 v152, v152, v162
	v_mul_f32_e32 v152, v152, v163
	v_fma_f32 v152, v164, v152, v168
	v_mul_f32_e32 v152, v212, v152
	v_fmac_f32_e32 v152, v181, v33
	global_store_dword v131, v152, s[86:87]
	v_sub_f32_e32 v153, v153, v162
	v_mul_f32_e32 v153, v153, v163
	v_fma_f32 v153, v165, v153, v169
	v_mul_f32_e32 v153, v212, v153
	v_fmac_f32_e32 v153, v181, v29
	global_store_dword v131, v153, s[86:87] offset:64
	v_sub_f32_e32 v154, v154, v162
	v_mul_f32_e32 v154, v154, v163
	v_fma_f32 v154, v166, v154, v170
	v_mul_f32_e32 v154, v212, v154
	v_fmac_f32_e32 v154, v181, v25
	global_store_dword v131, v154, s[86:87] offset:128
	v_sub_f32_e32 v155, v155, v162
	v_mul_f32_e32 v155, v155, v163
	v_fma_f32 v155, v167, v155, v171
	v_mul_f32_e32 v155, v212, v155
	v_fmac_f32_e32 v155, v181, v21
	global_store_dword v131, v155, s[86:87] offset:192
	v_add_u32_e32 v131, 0x72000, v138
	global_load_dword v148, v131, s[86:87] offset:-4096
	global_load_dword v149, v131, s[86:87] offset:-4032
	global_load_dword v150, v131, s[86:87] offset:-3968
	global_load_dword v151, v131, s[86:87] offset:-3904
	global_load_dword v152, v131, s[86:87]
	global_load_dword v153, v131, s[86:87] offset:64
	global_load_dword v154, v131, s[86:87] offset:128
	global_load_dword v155, v131, s[86:87] offset:192
	global_load_dwordx4 v[160:163], v132, s[4:5] offset:912
	s_waitcnt vmcnt(17)
	v_sub_f32_e32 v140, v140, v156
	v_mul_f32_e32 v140, v140, v157
	v_fma_f32 v140, v164, v140, v168
	v_mul_f32_e32 v140, v212, v140
	v_fmac_f32_e32 v140, v181, v14
	global_store_dword v130, v140, s[86:87] offset:-4096
	v_sub_f32_e32 v141, v141, v156
	v_mul_f32_e32 v141, v141, v157
	v_fma_f32 v141, v165, v141, v169
	v_mul_f32_e32 v141, v212, v141
	v_fmac_f32_e32 v141, v181, v10
	global_store_dword v130, v141, s[86:87] offset:-4032
	v_sub_f32_e32 v142, v142, v156
	v_mul_f32_e32 v142, v142, v157
	v_fma_f32 v142, v166, v142, v170
	v_mul_f32_e32 v142, v212, v142
	v_fmac_f32_e32 v142, v181, v6
	global_store_dword v130, v142, s[86:87] offset:-3968
	v_sub_f32_e32 v143, v143, v156
	v_mul_f32_e32 v143, v143, v157
	v_fma_f32 v143, v167, v143, v171
	v_mul_f32_e32 v143, v212, v143
	v_fmac_f32_e32 v143, v181, v2
	global_store_dword v130, v143, s[86:87] offset:-3904
	v_sub_f32_e32 v144, v144, v158
	v_mul_f32_e32 v144, v144, v159
	v_fma_f32 v144, v164, v144, v168
	v_mul_f32_e32 v144, v212, v144
	v_fmac_f32_e32 v144, v181, v15
	global_store_dword v130, v144, s[86:87]
	v_sub_f32_e32 v145, v145, v158
	v_mul_f32_e32 v145, v145, v159
	v_fma_f32 v145, v165, v145, v169
	v_mul_f32_e32 v145, v212, v145
	v_fmac_f32_e32 v145, v181, v11
	global_store_dword v130, v145, s[86:87] offset:64
	v_sub_f32_e32 v146, v146, v158
	v_mul_f32_e32 v146, v146, v159
	v_fma_f32 v146, v166, v146, v170
	v_mul_f32_e32 v146, v212, v146
	v_fmac_f32_e32 v146, v181, v7
	global_store_dword v130, v146, s[86:87] offset:128
	v_sub_f32_e32 v147, v147, v158
	v_mul_f32_e32 v147, v147, v159
	v_fma_f32 v147, v167, v147, v171
	v_mul_f32_e32 v147, v212, v147
	v_fmac_f32_e32 v147, v181, v3
	global_store_dword v130, v147, s[86:87] offset:192
	s_waitcnt vmcnt(8)
	v_sub_f32_e32 v148, v148, v160
	v_mul_f32_e32 v148, v148, v161
	v_fma_f32 v148, v164, v148, v168
	v_mul_f32_e32 v148, v212, v148
	v_fmac_f32_e32 v148, v181, v16
	global_store_dword v131, v148, s[86:87] offset:-4096
	v_sub_f32_e32 v149, v149, v160
	v_mul_f32_e32 v149, v149, v161
	v_fma_f32 v149, v165, v149, v169
	v_mul_f32_e32 v149, v212, v149
	v_fmac_f32_e32 v149, v181, v12
	global_store_dword v131, v149, s[86:87] offset:-4032
	v_sub_f32_e32 v150, v150, v160
	v_mul_f32_e32 v150, v150, v161
	v_fma_f32 v150, v166, v150, v170
	v_mul_f32_e32 v150, v212, v150
	v_fmac_f32_e32 v150, v181, v8
	global_store_dword v131, v150, s[86:87] offset:-3968
	v_sub_f32_e32 v151, v151, v160
	v_mul_f32_e32 v151, v151, v161
	v_fma_f32 v151, v167, v151, v171
	v_mul_f32_e32 v151, v212, v151
	v_fmac_f32_e32 v151, v181, v4
	global_store_dword v131, v151, s[86:87] offset:-3904
	v_sub_f32_e32 v152, v152, v162
	v_mul_f32_e32 v152, v152, v163
	v_fma_f32 v152, v164, v152, v168
	v_mul_f32_e32 v152, v212, v152
	v_fmac_f32_e32 v152, v181, v17
	global_store_dword v131, v152, s[86:87]
	v_sub_f32_e32 v153, v153, v162
	v_mul_f32_e32 v153, v153, v163
	v_fma_f32 v153, v165, v153, v169
	v_mul_f32_e32 v153, v212, v153
	v_fmac_f32_e32 v153, v181, v13
	global_store_dword v131, v153, s[86:87] offset:64
	v_sub_f32_e32 v154, v154, v162
	v_mul_f32_e32 v154, v154, v163
	v_fma_f32 v154, v166, v154, v170
	v_mul_f32_e32 v154, v212, v154
	v_fmac_f32_e32 v154, v181, v9
	global_store_dword v131, v154, s[86:87] offset:128
	v_sub_f32_e32 v155, v155, v162
	v_mul_f32_e32 v155, v155, v163
	v_fma_f32 v155, v167, v155, v171
	v_mul_f32_e32 v155, v212, v155
	v_fmac_f32_e32 v155, v181, v5
	global_store_dword v131, v155, s[86:87] offset:192
	s_cbranch_vccnz .LBB0_343

; DEV void phase_ln(const Params& P, const float* __restrict__ g, const float* __restrict__ bta, u16* __restrict__ xb, bool zero_kc) {
;     ...
;   for (int row = gw; row < T; row += 2 * nw) {
;     const bool hasB = (row + nw) < T;
;     const int rows[2] = {row, hasB ? row + nw : row};
;     float4 v[2][4];
; #pragma unroll
;     for (int r = 0; r < 2; ++r) {
;       const float* xr = P.out + (size_t)rows[r] * D + lane * 4;
; #pragma unroll
;       for (int i = 0; i < 4; ++i) v[r][i] = *(const float4*)(xr + i * 256);
;     }
;     float s[2] = {0.f, 0.f};
; #pragma unroll
;     for (int r = 0; r < 2; ++r)
; #pragma unroll
;       for (int i = 0; i < 4; ++i) s[r] += v[r][i].x + v[r][i].y + v[r][i].z + v[r][i].w;
; #pragma unroll
;     for (int o = 32; o >= 1; o >>= 1) {
;       s[0] += __shfl_xor(s[0], o);
;       s[1] += __shfl_xor(s[1], o);
;     }
.LBB0_2219:
.LBB0_2220:
	v_readfirstlane_b32 s4, v34
	v_readlane_b32 s5, v254, 3
	s_mul_i32 s4, s4, 4
	s_mul_i32 s5, s5, 4
	v_and_b32_e32 v35, 63, v210
	v_lshlrev_b32_e32 v35, 4, v35
	v_add_u32_e32 v36, v52, v0
	v_add_u32_e32 v37, 0x20000, v36
	v_add_u32_e32 v38, 0x40000, v36
	v_add_u32_e32 v39, 0x60000, v36
	v_readlane_b32 s12, v255, 8
	s_add_i32 s12, s12, 2
	s_and_b32 s12, s12, 3
	s_lshl_b32 s12, s12, 24
	s_add_u32 s12, s12, 0x25000000
	s_add_u32 s12, s38, s12
	s_addc_u32 s13, s39, 0
.Lln_loop_3:
	s_add_i32 s8, s4, 0
	s_min_i32 s8, s8, 0x7fff
	s_lshl_b32 s8, s8, 12
	v_add_u32_e32 v72, s8, v35
	global_load_dwordx4 v[108:111], v72, s[86:87]
	global_load_dwordx4 v[112:115], v72, s[86:87] offset:1024
	global_load_dwordx4 v[116:119], v72, s[86:87] offset:2048
	global_load_dwordx4 v[120:123], v72, s[86:87] offset:3072
	s_add_i32 s8, s4, 1
	s_min_i32 s8, s8, 0x7fff
	s_lshl_b32 s8, s8, 12
	v_add_u32_e32 v73, s8, v35
	global_load_dwordx4 v[124:127], v73, s[86:87]
	global_load_dwordx4 v[128:131], v73, s[86:87] offset:1024
	global_load_dwordx4 v[132:135], v73, s[86:87] offset:2048
	global_load_dwordx4 v[136:139], v73, s[86:87] offset:3072
	s_add_i32 s8, s4, 2
	s_min_i32 s8, s8, 0x7fff
	s_lshl_b32 s8, s8, 12
	v_add_u32_e32 v74, s8, v35
	global_load_dwordx4 v[140:143], v74, s[86:87]
	global_load_dwordx4 v[144:147], v74, s[86:87] offset:1024
	global_load_dwordx4 v[148:151], v74, s[86:87] offset:2048
	global_load_dwordx4 v[152:155], v74, s[86:87] offset:3072
	s_add_i32 s8, s4, 3
	s_min_i32 s8, s8, 0x7fff
	s_lshl_b32 s8, s8, 12
	v_add_u32_e32 v75, s8, v35
	global_load_dwordx4 v[156:159], v75, s[86:87]
	global_load_dwordx4 v[160:163], v75, s[86:87] offset:1024
	global_load_dwordx4 v[164:167], v75, s[86:87] offset:2048
	global_load_dwordx4 v[168:171], v75, s[86:87] offset:3072
	s_waitcnt vmcnt(0)
	v_add_f32_e32 v42, v108, v109
	v_add_f32_e32 v42, v42, v110
	v_add_f32_e32 v42, v42, v111
	v_add_f32_e32 v60, v112, v113
	v_add_f32_e32 v60, v60, v114
	v_add_f32_e32 v60, v60, v115
	v_add_f32_e32 v42, v42, v60
	v_add_f32_e32 v60, v116, v117
	v_add_f32_e32 v60, v60, v118
	v_add_f32_e32 v60, v60, v119
	v_add_f32_e32 v42, v42, v60
	v_add_f32_e32 v60, v120, v121
	v_add_f32_e32 v60, v60, v122
	v_add_f32_e32 v60, v60, v123
	v_add_f32_e32 v42, v42, v60
	v_add_f32_e32 v43, v124, v125
	v_add_f32_e32 v43, v43, v126
	v_add_f32_e32 v43, v43, v127
	v_add_f32_e32 v61, v128, v129
	v_add_f32_e32 v61, v61, v130
	v_add_f32_e32 v61, v61, v131
	v_add_f32_e32 v43, v43, v61
	v_add_f32_e32 v61, v132, v133
	v_add_f32_e32 v61, v61, v134
	v_add_f32_e32 v61, v61, v135
	v_add_f32_e32 v43, v43, v61
	v_add_f32_e32 v61, v136, v137
	v_add_f32_e32 v61, v61, v138
	v_add_f32_e32 v61, v61, v139
	v_add_f32_e32 v43, v43, v61
	v_add_f32_e32 v44, v140, v141
	v_add_f32_e32 v44, v44, v142
	v_add_f32_e32 v44, v44, v143
	v_add_f32_e32 v62, v144, v145
	v_add_f32_e32 v62, v62, v146
	v_add_f32_e32 v62, v62, v147
	v_add_f32_e32 v44, v44, v62
	v_add_f32_e32 v62, v148, v149
	v_add_f32_e32 v62, v62, v150
	v_add_f32_e32 v62, v62, v151
	v_add_f32_e32 v44, v44, v62
	v_add_f32_e32 v62, v152, v153
	v_add_f32_e32 v62, v62, v154
	v_add_f32_e32 v62, v62, v155
	v_add_f32_e32 v44, v44, v62
	v_add_f32_e32 v45, v156, v157
	v_add_f32_e32 v45, v45, v158
	v_add_f32_e32 v45, v45, v159
	v_add_f32_e32 v63, v160, v161
	v_add_f32_e32 v63, v63, v162
	v_add_f32_e32 v63, v63, v163
	v_add_f32_e32 v45, v45, v63
	v_add_f32_e32 v63, v164, v165
	v_add_f32_e32 v63, v63, v166
	v_add_f32_e32 v63, v63, v167
	v_add_f32_e32 v45, v45, v63
	v_add_f32_e32 v63, v168, v169
	v_add_f32_e32 v63, v63, v170
	v_add_f32_e32 v63, v63, v171
	v_add_f32_e32 v45, v45, v63
	ds_bpermute_b32 v60, v96, v42
	ds_bpermute_b32 v61, v96, v43
	ds_bpermute_b32 v62, v96, v44
	ds_bpermute_b32 v63, v96, v45
	s_waitcnt lgkmcnt(3)
	v_add_f32_e32 v42, v42, v60
	s_waitcnt lgkmcnt(2)
	v_add_f32_e32 v43, v43, v61
	s_waitcnt lgkmcnt(1)
	v_add_f32_e32 v44, v44, v62
	s_waitcnt lgkmcnt(0)
	v_add_f32_e32 v45, v45, v63
	ds_bpermute_b32 v60, v97, v42
	ds_bpermute_b32 v61, v97, v43
	ds_bpermute_b32 v62, v97, v44
	ds_bpermute_b32 v63, v97, v45
	s_waitcnt lgkmcnt(3)
	v_add_f32_e32 v42, v42, v60
	s_waitcnt lgkmcnt(2)
	v_add_f32_e32 v43, v43, v61
	s_waitcnt lgkmcnt(1)
	v_add_f32_e32 v44, v44, v62
	s_waitcnt lgkmcnt(0)
	v_add_f32_e32 v45, v45, v63
	ds_bpermute_b32 v60, v98, v42
	ds_bpermute_b32 v61, v98, v43
	ds_bpermute_b32 v62, v98, v44
	ds_bpermute_b32 v63, v98, v45
	s_waitcnt lgkmcnt(3)
	v_add_f32_e32 v42, v42, v60
	s_waitcnt lgkmcnt(2)
	v_add_f32_e32 v43, v43, v61
	s_waitcnt lgkmcnt(1)
	v_add_f32_e32 v44, v44, v62
	s_waitcnt lgkmcnt(0)
	v_add_f32_e32 v45, v45, v63
	ds_bpermute_b32 v60, v99, v42
	ds_bpermute_b32 v61, v99, v43
	ds_bpermute_b32 v62, v99, v44
	ds_bpermute_b32 v63, v99, v45
	s_waitcnt lgkmcnt(3)
	v_add_f32_e32 v42, v42, v60
	s_waitcnt lgkmcnt(2)
	v_add_f32_e32 v43, v43, v61
	s_waitcnt lgkmcnt(1)
	v_add_f32_e32 v44, v44, v62
	s_waitcnt lgkmcnt(0)
	v_add_f32_e32 v45, v45, v63
	ds_bpermute_b32 v60, v100, v42
	ds_bpermute_b32 v61, v100, v43
	ds_bpermute_b32 v62, v100, v44
	ds_bpermute_b32 v63, v100, v45
	s_waitcnt lgkmcnt(3)
	v_add_f32_e32 v42, v42, v60
	s_waitcnt lgkmcnt(2)
	v_add_f32_e32 v43, v43, v61
	s_waitcnt lgkmcnt(1)
	v_add_f32_e32 v44, v44, v62
	s_waitcnt lgkmcnt(0)
	v_add_f32_e32 v45, v45, v63
	ds_bpermute_b32 v60, v101, v42
	ds_bpermute_b32 v61, v101, v43
	ds_bpermute_b32 v62, v101, v44
	ds_bpermute_b32 v63, v101, v45
	s_waitcnt lgkmcnt(3)
	v_add_f32_e32 v42, v42, v60
	s_waitcnt lgkmcnt(2)
	v_add_f32_e32 v43, v43, v61
	s_waitcnt lgkmcnt(1)
	v_add_f32_e32 v44, v44, v62
	s_waitcnt lgkmcnt(0)
; DEV void phase_ln(const Params& P, const float* __restrict__ g, const float* __restrict__ bta, u16* __restrict__ xb, bool zero_kc) {
;     ...
;     float q[2] = {0.f, 0.f};
; #pragma unroll
;     for (int r = 0; r < 2; ++r) {
;       const float mu = s[r] * (1.f / 1024.f);
; #pragma unroll
;       for (int i = 0; i < 4; ++i) {
;         v[r][i].x -= mu; v[r][i].y -= mu; v[r][i].z -= mu; v[r][i].w -= mu;
;         q[r] += v[r][i].x * v[r][i].x + v[r][i].y * v[r][i].y + v[r][i].z * v[r][i].z + v[r][i].w * v[r][i].w;
;       }
;     }
; #pragma unroll
;     for (int o = 32; o >= 1; o >>= 1) {
;       q[0] += __shfl_xor(q[0], o);
;       q[1] += __shfl_xor(q[1], o);
;     }
	v_add_f32_e32 v45, v45, v63
	v_mul_f32_e32 v42, 0x3a800000, v42
	v_mul_f32_e32 v43, 0x3a800000, v43
	v_mul_f32_e32 v44, 0x3a800000, v44
	v_mul_f32_e32 v45, 0x3a800000, v45
	v_sub_f32_e32 v108, v108, v42
	v_sub_f32_e32 v109, v109, v42
	v_sub_f32_e32 v110, v110, v42
	v_sub_f32_e32 v111, v111, v42
	v_mul_f32_e32 v46, v108, v108
	v_fmac_f32_e32 v46, v109, v109
	v_fmac_f32_e32 v46, v110, v110
	v_fmac_f32_e32 v46, v111, v111
	v_sub_f32_e32 v112, v112, v42
	v_sub_f32_e32 v113, v113, v42
	v_sub_f32_e32 v114, v114, v42
	v_sub_f32_e32 v115, v115, v42
	v_mul_f32_e32 v60, v112, v112
	v_fmac_f32_e32 v60, v113, v113
	v_fmac_f32_e32 v60, v114, v114
	v_fmac_f32_e32 v60, v115, v115
	v_add_f32_e32 v46, v46, v60
	v_sub_f32_e32 v116, v116, v42
	v_sub_f32_e32 v117, v117, v42
	v_sub_f32_e32 v118, v118, v42
	v_sub_f32_e32 v119, v119, v42
	v_mul_f32_e32 v60, v116, v116
	v_fmac_f32_e32 v60, v117, v117
	v_fmac_f32_e32 v60, v118, v118
	v_fmac_f32_e32 v60, v119, v119
	v_add_f32_e32 v46, v46, v60
	v_sub_f32_e32 v120, v120, v42
	v_sub_f32_e32 v121, v121, v42
	v_sub_f32_e32 v122, v122, v42
	v_sub_f32_e32 v123, v123, v42
	v_mul_f32_e32 v60, v120, v120
	v_fmac_f32_e32 v60, v121, v121
	v_fmac_f32_e32 v60, v122, v122
	v_fmac_f32_e32 v60, v123, v123
	v_add_f32_e32 v46, v46, v60
	v_sub_f32_e32 v124, v124, v43
	v_sub_f32_e32 v125, v125, v43
	v_sub_f32_e32 v126, v126, v43
	v_sub_f32_e32 v127, v127, v43
	v_mul_f32_e32 v48, v124, v124
	v_fmac_f32_e32 v48, v125, v125
	v_fmac_f32_e32 v48, v126, v126
	v_fmac_f32_e32 v48, v127, v127
	v_sub_f32_e32 v128, v128, v43
	v_sub_f32_e32 v129, v129, v43
	v_sub_f32_e32 v130, v130, v43
	v_sub_f32_e32 v131, v131, v43
	v_mul_f32_e32 v61, v128, v128
	v_fmac_f32_e32 v61, v129, v129
	v_fmac_f32_e32 v61, v130, v130
	v_fmac_f32_e32 v61, v131, v131
	v_add_f32_e32 v48, v48, v61
	v_sub_f32_e32 v132, v132, v43
	v_sub_f32_e32 v133, v133, v43
	v_sub_f32_e32 v134, v134, v43
	v_sub_f32_e32 v135, v135, v43
	v_mul_f32_e32 v61, v132, v132
	v_fmac_f32_e32 v61, v133, v133
	v_fmac_f32_e32 v61, v134, v134
	v_fmac_f32_e32 v61, v135, v135
	v_add_f32_e32 v48, v48, v61
	v_sub_f32_e32 v136, v136, v43
	v_sub_f32_e32 v137, v137, v43
	v_sub_f32_e32 v138, v138, v43
	v_sub_f32_e32 v139, v139, v43
	v_mul_f32_e32 v61, v136, v136
	v_fmac_f32_e32 v61, v137, v137
	v_fmac_f32_e32 v61, v138, v138
	v_fmac_f32_e32 v61, v139, v139
	v_add_f32_e32 v48, v48, v61
	v_sub_f32_e32 v140, v140, v44
	v_sub_f32_e32 v141, v141, v44
	v_sub_f32_e32 v142, v142, v44
	v_sub_f32_e32 v143, v143, v44
	v_mul_f32_e32 v50, v140, v140
	v_fmac_f32_e32 v50, v141, v141
	v_fmac_f32_e32 v50, v142, v142
	v_fmac_f32_e32 v50, v143, v143
	v_sub_f32_e32 v144, v144, v44
	v_sub_f32_e32 v145, v145, v44
	v_sub_f32_e32 v146, v146, v44
	v_sub_f32_e32 v147, v147, v44
	v_mul_f32_e32 v62, v144, v144
	v_fmac_f32_e32 v62, v145, v145
	v_fmac_f32_e32 v62, v146, v146
	v_fmac_f32_e32 v62, v147, v147
	v_add_f32_e32 v50, v50, v62
	v_sub_f32_e32 v148, v148, v44
	v_sub_f32_e32 v149, v149, v44
	v_sub_f32_e32 v150, v150, v44
	v_sub_f32_e32 v151, v151, v44
	v_mul_f32_e32 v62, v148, v148
	v_fmac_f32_e32 v62, v149, v149
	v_fmac_f32_e32 v62, v150, v150
	v_fmac_f32_e32 v62, v151, v151
	v_add_f32_e32 v50, v50, v62
	v_sub_f32_e32 v152, v152, v44
	v_sub_f32_e32 v153, v153, v44
	v_sub_f32_e32 v154, v154, v44
	v_sub_f32_e32 v155, v155, v44
	v_mul_f32_e32 v62, v152, v152
	v_fmac_f32_e32 v62, v153, v153
	v_fmac_f32_e32 v62, v154, v154
	v_fmac_f32_e32 v62, v155, v155
	v_add_f32_e32 v50, v50, v62
	v_sub_f32_e32 v156, v156, v45
	v_sub_f32_e32 v157, v157, v45
	v_sub_f32_e32 v158, v158, v45
	v_sub_f32_e32 v159, v159, v45
	v_mul_f32_e32 v52, v156, v156
	v_fmac_f32_e32 v52, v157, v157
	v_fmac_f32_e32 v52, v158, v158
	v_fmac_f32_e32 v52, v159, v159
	v_sub_f32_e32 v160, v160, v45
	v_sub_f32_e32 v161, v161, v45
	v_sub_f32_e32 v162, v162, v45
	v_sub_f32_e32 v163, v163, v45
	v_mul_f32_e32 v63, v160, v160
	v_fmac_f32_e32 v63, v161, v161
	v_fmac_f32_e32 v63, v162, v162
	v_fmac_f32_e32 v63, v163, v163
	v_add_f32_e32 v52, v52, v63
	v_sub_f32_e32 v164, v164, v45
	v_sub_f32_e32 v165, v165, v45
	v_sub_f32_e32 v166, v166, v45
	v_sub_f32_e32 v167, v167, v45
	v_mul_f32_e32 v63, v164, v164
	v_fmac_f32_e32 v63, v165, v165
	v_fmac_f32_e32 v63, v166, v166
	v_fmac_f32_e32 v63, v167, v167
	v_add_f32_e32 v52, v52, v63
	v_sub_f32_e32 v168, v168, v45
	v_sub_f32_e32 v169, v169, v45
	v_sub_f32_e32 v170, v170, v45
	v_sub_f32_e32 v171, v171, v45
	v_mul_f32_e32 v63, v168, v168
	v_fmac_f32_e32 v63, v169, v169
	v_fmac_f32_e32 v63, v170, v170
	v_fmac_f32_e32 v63, v171, v171
	v_add_f32_e32 v52, v52, v63
	ds_bpermute_b32 v60, v96, v46
	ds_bpermute_b32 v61, v96, v48
	ds_bpermute_b32 v62, v96, v50
	ds_bpermute_b32 v63, v96, v52
	s_waitcnt lgkmcnt(3)
	v_add_f32_e32 v46, v46, v60
	s_waitcnt lgkmcnt(2)
	v_add_f32_e32 v48, v48, v61
	s_waitcnt lgkmcnt(1)
	v_add_f32_e32 v50, v50, v62
	s_waitcnt lgkmcnt(0)
	v_add_f32_e32 v52, v52, v63
	ds_bpermute_b32 v60, v97, v46
	ds_bpermute_b32 v61, v97, v48
	ds_bpermute_b32 v62, v97, v50
	ds_bpermute_b32 v63, v97, v52
	s_waitcnt lgkmcnt(3)
	v_add_f32_e32 v46, v46, v60
	s_waitcnt lgkmcnt(2)
	v_add_f32_e32 v48, v48, v61
	s_waitcnt lgkmcnt(1)
	v_add_f32_e32 v50, v50, v62
	s_waitcnt lgkmcnt(0)
	v_add_f32_e32 v52, v52, v63
	ds_bpermute_b32 v60, v98, v46
	ds_bpermute_b32 v61, v98, v48
	ds_bpermute_b32 v62, v98, v50
	ds_bpermute_b32 v63, v98, v52
	s_waitcnt lgkmcnt(3)
	v_add_f32_e32 v46, v46, v60
	s_waitcnt lgkmcnt(2)
	v_add_f32_e32 v48, v48, v61
	s_waitcnt lgkmcnt(1)
	v_add_f32_e32 v50, v50, v62
	s_waitcnt lgkmcnt(0)
	v_add_f32_e32 v52, v52, v63
	ds_bpermute_b32 v60, v99, v46
	ds_bpermute_b32 v61, v99, v48
	ds_bpermute_b32 v62, v99, v50
	ds_bpermute_b32 v63, v99, v52
	s_waitcnt lgkmcnt(3)
; DEV void phase_ln(const Params& P, const float* __restrict__ g, const float* __restrict__ bta, u16* __restrict__ xb, bool zero_kc) {
;     ...
; #pragma unroll
;     for (int r = 0; r < 2; ++r) {
;       if (r == 1 && !hasB) break;
;       const float rs = rsqrtf(q[r] * (1.f / 1024.f) + 1e-5f);
;       const int rw = rows[r];
;       float* xr = P.out + (size_t)rw * D;
; #pragma unroll
;       for (int i = 0; i < 4; ++i) {
;         float4 y;
;         y.x = v[r][i].x * rs * gv[i].x + bv[i].x;
;         y.y = v[r][i].y * rs * gv[i].y + bv[i].y;
;         y.z = v[r][i].z * rs * gv[i].z + bv[i].z;
;         y.w = v[r][i].w * rs * gv[i].w + bv[i].w;
;         *(float4*)(xr + i * 256 + lane * 4) = y;
;         const int col = i * 256 + lane * 4;
;         *(uint2*)(xb + (size_t)(rw >> 8) * (256 * D) + (size_t)(col >> 5) * 8192 + (rw & 255) * 32 + (col & 31)) = make_uint2(pack2(y.x, y.y), pack2(y.z, y.w));
;       }
;     }
	v_add_f32_e32 v46, v46, v60
	s_waitcnt lgkmcnt(2)
	v_add_f32_e32 v48, v48, v61
	s_waitcnt lgkmcnt(1)
	v_add_f32_e32 v50, v50, v62
	s_waitcnt lgkmcnt(0)
	v_add_f32_e32 v52, v52, v63
	ds_bpermute_b32 v60, v100, v46
	ds_bpermute_b32 v61, v100, v48
	ds_bpermute_b32 v62, v100, v50
	ds_bpermute_b32 v63, v100, v52
	s_waitcnt lgkmcnt(3)
	v_add_f32_e32 v46, v46, v60
	s_waitcnt lgkmcnt(2)
	v_add_f32_e32 v48, v48, v61
	s_waitcnt lgkmcnt(1)
	v_add_f32_e32 v50, v50, v62
	s_waitcnt lgkmcnt(0)
	v_add_f32_e32 v52, v52, v63
	ds_bpermute_b32 v60, v101, v46
	ds_bpermute_b32 v61, v101, v48
	ds_bpermute_b32 v62, v101, v50
	ds_bpermute_b32 v63, v101, v52
	s_waitcnt lgkmcnt(3)
	v_add_f32_e32 v46, v46, v60
	s_waitcnt lgkmcnt(2)
	v_add_f32_e32 v48, v48, v61
	s_waitcnt lgkmcnt(1)
	v_add_f32_e32 v50, v50, v62
	s_waitcnt lgkmcnt(0)
	v_add_f32_e32 v52, v52, v63
	s_mov_b32 s2, 0x800000
	v_fmamk_f32 v46, v46, 0x3a800000, v216
	v_cmp_gt_f32_e32 vcc, s2, v46
	v_mul_f32_e32 v60, 0x4b800000, v46
	s_nop 1
	v_cndmask_b32_e32 v46, v46, v60, vcc
	v_rsq_f32_e32 v46, v46
	s_nop 0
	v_mul_f32_e32 v60, 0x45800000, v46
	s_nop 0
	v_cndmask_b32_e32 v46, v46, v60, vcc
	v_fmamk_f32 v48, v48, 0x3a800000, v216
	v_cmp_gt_f32_e32 vcc, s2, v48
	v_mul_f32_e32 v61, 0x4b800000, v48
	s_nop 1
	v_cndmask_b32_e32 v48, v48, v61, vcc
	v_rsq_f32_e32 v48, v48
	s_nop 0
	v_mul_f32_e32 v61, 0x45800000, v48
	s_nop 0
	v_cndmask_b32_e32 v48, v48, v61, vcc
	v_fmamk_f32 v50, v50, 0x3a800000, v216
	v_cmp_gt_f32_e32 vcc, s2, v50
	v_mul_f32_e32 v62, 0x4b800000, v50
	s_nop 1
	v_cndmask_b32_e32 v50, v50, v62, vcc
	v_rsq_f32_e32 v50, v50
	s_nop 0
	v_mul_f32_e32 v62, 0x45800000, v50
	s_nop 0
	v_cndmask_b32_e32 v50, v50, v62, vcc
	v_fmamk_f32 v52, v52, 0x3a800000, v216
	v_cmp_gt_f32_e32 vcc, s2, v52
	v_mul_f32_e32 v63, 0x4b800000, v52
	s_nop 1
	v_cndmask_b32_e32 v52, v52, v63, vcc
	v_rsq_f32_e32 v52, v52
	s_nop 0
	v_mul_f32_e32 v63, 0x45800000, v52
	s_nop 0
	v_cndmask_b32_e32 v52, v52, v63, vcc
	s_add_i32 s9, s4, 0
	s_cmp_lt_i32 s9, 0x8000
	s_cbranch_scc0 .Lln_skip_3_0
	s_lshr_b32 s8, s9, 8
	s_lshl_b32 s8, s8, 19
	s_and_b32 s2, s9, 0xff
	s_lshl_b32 s2, s2, 6
	s_add_i32 s8, s8, s2
	v_mov_b32_e32 v64, v42
	v_mov_b32_e32 v65, v46
	s_lshl_b32 s2, s9, 3
	v_mov_b32_e32 v70, s2
	global_store_dwordx2 v70, v[64:65], s[12:13]
	v_pk_mul_f32 v[64:65], v[108:109], v[46:47] op_sel_hi:[1,0]
	v_pk_mul_f32 v[66:67], v[110:111], v[46:47] op_sel_hi:[1,0]
	v_pk_fma_f32 v[64:65], v[2:3], v[64:65], v[10:11]
	v_pk_fma_f32 v[66:67], v[4:5], v[66:67], v[12:13]
	v_add_u32_e32 v70, s8, v36
	v_cvt_pk_bf16_f32 v68, v64, v65
	v_cvt_pk_bf16_f32 v69, v66, v67
	global_store_dwordx2 v70, v[68:69], s[42:43]
	v_pk_mul_f32 v[64:65], v[112:113], v[46:47] op_sel_hi:[1,0]
	v_pk_mul_f32 v[66:67], v[114:115], v[46:47] op_sel_hi:[1,0]
	v_pk_fma_f32 v[64:65], v[6:7], v[64:65], v[14:15]
	v_pk_fma_f32 v[66:67], v[8:9], v[66:67], v[16:17]
	v_add_u32_e32 v70, s8, v37
	v_cvt_pk_bf16_f32 v68, v64, v65
	v_cvt_pk_bf16_f32 v69, v66, v67
	global_store_dwordx2 v70, v[68:69], s[42:43]
	v_pk_mul_f32 v[64:65], v[116:117], v[46:47] op_sel_hi:[1,0]
	v_pk_mul_f32 v[66:67], v[118:119], v[46:47] op_sel_hi:[1,0]
	v_pk_fma_f32 v[64:65], v[18:19], v[64:65], v[26:27]
	v_pk_fma_f32 v[66:67], v[20:21], v[66:67], v[28:29]
	v_add_u32_e32 v70, s8, v38
	v_cvt_pk_bf16_f32 v68, v64, v65
	v_cvt_pk_bf16_f32 v69, v66, v67
	global_store_dwordx2 v70, v[68:69], s[42:43]
	v_pk_mul_f32 v[64:65], v[120:121], v[46:47] op_sel_hi:[1,0]
	v_pk_mul_f32 v[66:67], v[122:123], v[46:47] op_sel_hi:[1,0]
	v_pk_fma_f32 v[64:65], v[22:23], v[64:65], v[30:31]
	v_pk_fma_f32 v[66:67], v[24:25], v[66:67], v[32:33]
	v_add_u32_e32 v70, s8, v39
	v_cvt_pk_bf16_f32 v68, v64, v65
	v_cvt_pk_bf16_f32 v69, v66, v67
	global_store_dwordx2 v70, v[68:69], s[42:43]
; DEV void phase_ln(const Params& P, const float* __restrict__ g, const float* __restrict__ bta, u16* __restrict__ xb, bool zero_kc) {
;     ...
;     for (int r = 0; r < 2; ++r) {
;       if (r == 1 && !hasB) break;
;       const float rs = rsqrtf(q[r] * (1.f / 1024.f) + 1e-5f);
;       const int rw = rows[r];
;       float* xr = P.out + (size_t)rw * D;
; #pragma unroll
;       for (int i = 0; i < 4; ++i) {
;         float4 y;
;         y.x = v[r][i].x * rs * gv[i].x + bv[i].x;
;         y.y = v[r][i].y * rs * gv[i].y + bv[i].y;
;         y.z = v[r][i].z * rs * gv[i].z + bv[i].z;
;         y.w = v[r][i].w * rs * gv[i].w + bv[i].w;
;         *(float4*)(xr + i * 256 + lane * 4) = y;
;         const int col = i * 256 + lane * 4;
;         *(uint2*)(xb + (size_t)(rw >> 8) * (256 * D) + (size_t)(col >> 5) * 8192 + (rw & 255) * 32 + (col & 31)) = make_uint2(pack2(y.x, y.y), pack2(y.z, y.w));
;       }
;     }
.Lln_skip_3_0:
	s_add_i32 s9, s4, 1
	s_cmp_lt_i32 s9, 0x8000
	s_cbranch_scc0 .Lln_skip_3_1
	s_lshr_b32 s8, s9, 8
	s_lshl_b32 s8, s8, 19
	s_and_b32 s2, s9, 0xff
	s_lshl_b32 s2, s2, 6
	s_add_i32 s8, s8, s2
	v_mov_b32_e32 v64, v43
	v_mov_b32_e32 v65, v48
	s_lshl_b32 s2, s9, 3
	v_mov_b32_e32 v70, s2
	global_store_dwordx2 v70, v[64:65], s[12:13]
	v_pk_mul_f32 v[64:65], v[124:125], v[48:49] op_sel_hi:[1,0]
	v_pk_mul_f32 v[66:67], v[126:127], v[48:49] op_sel_hi:[1,0]
	v_pk_fma_f32 v[64:65], v[2:3], v[64:65], v[10:11]
	v_pk_fma_f32 v[66:67], v[4:5], v[66:67], v[12:13]
	v_add_u32_e32 v70, s8, v36
	v_cvt_pk_bf16_f32 v68, v64, v65
	v_cvt_pk_bf16_f32 v69, v66, v67
	global_store_dwordx2 v70, v[68:69], s[42:43]
	v_pk_mul_f32 v[64:65], v[128:129], v[48:49] op_sel_hi:[1,0]
	v_pk_mul_f32 v[66:67], v[130:131], v[48:49] op_sel_hi:[1,0]
	v_pk_fma_f32 v[64:65], v[6:7], v[64:65], v[14:15]
	v_pk_fma_f32 v[66:67], v[8:9], v[66:67], v[16:17]
	v_add_u32_e32 v70, s8, v37
	v_cvt_pk_bf16_f32 v68, v64, v65
	v_cvt_pk_bf16_f32 v69, v66, v67
	global_store_dwordx2 v70, v[68:69], s[42:43]
	v_pk_mul_f32 v[64:65], v[132:133], v[48:49] op_sel_hi:[1,0]
	v_pk_mul_f32 v[66:67], v[134:135], v[48:49] op_sel_hi:[1,0]
	v_pk_fma_f32 v[64:65], v[18:19], v[64:65], v[26:27]
	v_pk_fma_f32 v[66:67], v[20:21], v[66:67], v[28:29]
	v_add_u32_e32 v70, s8, v38
	v_cvt_pk_bf16_f32 v68, v64, v65
	v_cvt_pk_bf16_f32 v69, v66, v67
	global_store_dwordx2 v70, v[68:69], s[42:43]
	v_pk_mul_f32 v[64:65], v[136:137], v[48:49] op_sel_hi:[1,0]
	v_pk_mul_f32 v[66:67], v[138:139], v[48:49] op_sel_hi:[1,0]
	v_pk_fma_f32 v[64:65], v[22:23], v[64:65], v[30:31]
	v_pk_fma_f32 v[66:67], v[24:25], v[66:67], v[32:33]
	v_add_u32_e32 v70, s8, v39
	v_cvt_pk_bf16_f32 v68, v64, v65
	v_cvt_pk_bf16_f32 v69, v66, v67
	global_store_dwordx2 v70, v[68:69], s[42:43]
.Lln_skip_3_1:
	s_add_i32 s9, s4, 2
	s_cmp_lt_i32 s9, 0x8000
	s_cbranch_scc0 .Lln_skip_3_2
	s_lshr_b32 s8, s9, 8
	s_lshl_b32 s8, s8, 19
	s_and_b32 s2, s9, 0xff
	s_lshl_b32 s2, s2, 6
	s_add_i32 s8, s8, s2
	v_mov_b32_e32 v64, v44
	v_mov_b32_e32 v65, v50
	s_lshl_b32 s2, s9, 3
	v_mov_b32_e32 v70, s2
	global_store_dwordx2 v70, v[64:65], s[12:13]
	v_pk_mul_f32 v[64:65], v[140:141], v[50:51] op_sel_hi:[1,0]
	v_pk_mul_f32 v[66:67], v[142:143], v[50:51] op_sel_hi:[1,0]
	v_pk_fma_f32 v[64:65], v[2:3], v[64:65], v[10:11]
	v_pk_fma_f32 v[66:67], v[4:5], v[66:67], v[12:13]
	v_add_u32_e32 v70, s8, v36
	v_cvt_pk_bf16_f32 v68, v64, v65
	v_cvt_pk_bf16_f32 v69, v66, v67
	global_store_dwordx2 v70, v[68:69], s[42:43]
	v_pk_mul_f32 v[64:65], v[144:145], v[50:51] op_sel_hi:[1,0]
	v_pk_mul_f32 v[66:67], v[146:147], v[50:51] op_sel_hi:[1,0]
	v_pk_fma_f32 v[64:65], v[6:7], v[64:65], v[14:15]
	v_pk_fma_f32 v[66:67], v[8:9], v[66:67], v[16:17]
	v_add_u32_e32 v70, s8, v37
	v_cvt_pk_bf16_f32 v68, v64, v65
	v_cvt_pk_bf16_f32 v69, v66, v67
	global_store_dwordx2 v70, v[68:69], s[42:43]
	v_pk_mul_f32 v[64:65], v[148:149], v[50:51] op_sel_hi:[1,0]
	v_pk_mul_f32 v[66:67], v[150:151], v[50:51] op_sel_hi:[1,0]
	v_pk_fma_f32 v[64:65], v[18:19], v[64:65], v[26:27]
	v_pk_fma_f32 v[66:67], v[20:21], v[66:67], v[28:29]
	v_add_u32_e32 v70, s8, v38
	v_cvt_pk_bf16_f32 v68, v64, v65
	v_cvt_pk_bf16_f32 v69, v66, v67
	global_store_dwordx2 v70, v[68:69], s[42:43]
	v_pk_mul_f32 v[64:65], v[152:153], v[50:51] op_sel_hi:[1,0]
	v_pk_mul_f32 v[66:67], v[154:155], v[50:51] op_sel_hi:[1,0]
	v_pk_fma_f32 v[64:65], v[22:23], v[64:65], v[30:31]
	v_pk_fma_f32 v[66:67], v[24:25], v[66:67], v[32:33]
	v_add_u32_e32 v70, s8, v39
	v_cvt_pk_bf16_f32 v68, v64, v65
	v_cvt_pk_bf16_f32 v69, v66, v67
	global_store_dwordx2 v70, v[68:69], s[42:43]
.Lln_skip_3_2:
	s_add_i32 s9, s4, 3
	s_cmp_lt_i32 s9, 0x8000
	s_cbranch_scc0 .Lln_skip_3_3
	s_lshr_b32 s8, s9, 8
	s_lshl_b32 s8, s8, 19
	s_and_b32 s2, s9, 0xff
	s_lshl_b32 s2, s2, 6
	s_add_i32 s8, s8, s2
	v_mov_b32_e32 v64, v45
	v_mov_b32_e32 v65, v52
	s_lshl_b32 s2, s9, 3
	v_mov_b32_e32 v70, s2
	global_store_dwordx2 v70, v[64:65], s[12:13]
	v_pk_mul_f32 v[64:65], v[156:157], v[52:53] op_sel_hi:[1,0]
	v_pk_mul_f32 v[66:67], v[158:159], v[52:53] op_sel_hi:[1,0]
	v_pk_fma_f32 v[64:65], v[2:3], v[64:65], v[10:11]
	v_pk_fma_f32 v[66:67], v[4:5], v[66:67], v[12:13]
	v_add_u32_e32 v70, s8, v36
	v_cvt_pk_bf16_f32 v68, v64, v65
	v_cvt_pk_bf16_f32 v69, v66, v67
	global_store_dwordx2 v70, v[68:69], s[42:43]
	v_pk_mul_f32 v[64:65], v[160:161], v[52:53] op_sel_hi:[1,0]
	v_pk_mul_f32 v[66:67], v[162:163], v[52:53] op_sel_hi:[1,0]
	v_pk_fma_f32 v[64:65], v[6:7], v[64:65], v[14:15]
	v_pk_fma_f32 v[66:67], v[8:9], v[66:67], v[16:17]
	v_add_u32_e32 v70, s8, v37
	v_cvt_pk_bf16_f32 v68, v64, v65
	v_cvt_pk_bf16_f32 v69, v66, v67
	global_store_dwordx2 v70, v[68:69], s[42:43]
	v_pk_mul_f32 v[64:65], v[164:165], v[52:53] op_sel_hi:[1,0]
	v_pk_mul_f32 v[66:67], v[166:167], v[52:53] op_sel_hi:[1,0]
	v_pk_fma_f32 v[64:65], v[18:19], v[64:65], v[26:27]
	v_pk_fma_f32 v[66:67], v[20:21], v[66:67], v[28:29]
	v_add_u32_e32 v70, s8, v38
	v_cvt_pk_bf16_f32 v68, v64, v65
	v_cvt_pk_bf16_f32 v69, v66, v67
	global_store_dwordx2 v70, v[68:69], s[42:43]
	v_pk_mul_f32 v[64:65], v[168:169], v[52:53] op_sel_hi:[1,0]
	v_pk_mul_f32 v[66:67], v[170:171], v[52:53] op_sel_hi:[1,0]
	v_pk_fma_f32 v[64:65], v[22:23], v[64:65], v[30:31]
	v_pk_fma_f32 v[66:67], v[24:25], v[66:67], v[32:33]
	v_add_u32_e32 v70, s8, v39
	v_cvt_pk_bf16_f32 v68, v64, v65
	v_cvt_pk_bf16_f32 v69, v66, v67
	global_store_dwordx2 v70, v[68:69], s[42:43]
